# v28 minus the mid-burst s_setprio 0/1 pairs and the redundant post-barrier lgkmcnt wait
# speedup vs baseline: 1.0011x; 1.0011x over previous
.LBB0_379:
	v_add_u32_e32 v14, s56, v140
	v_add_u32_e32 v30, s57, v140
	ds_read_b128 v[2:5], v14
	ds_read_b128 v[6:9], v14 offset:1024
	ds_read_b128 v[10:13], v14 offset:2048
	ds_read_b128 v[14:17], v14 offset:3072
	ds_read_b128 v[18:21], v30
	ds_read_b128 v[22:25], v30 offset:1024
	ds_read_b128 v[26:29], v30 offset:2048
	ds_read_b128 v[30:33], v30 offset:3072
	v_add_u32_e32 v141, 0, v1
	ds_read_b128 v[34:37], v141
	ds_read_b128 v[38:41], v141 offset:1024
	ds_read_b128 v[42:45], v141 offset:2048
	ds_read_b128 v[46:49], v141 offset:3072
	ds_read_b128 v[50:53], v141 offset:4096
	ds_read_b128 v[54:57], v141 offset:5120
	ds_read_b128 v[58:61], v141 offset:6144
	ds_read_b128 v[62:65], v141 offset:7168
	s_waitcnt vmcnt(8)
	s_waitcnt lgkmcnt(0)
	s_barrier
	s_setprio 1
	v_mfma_f32_16x16x32_bf16 v[66:69], v[2:5], v[34:37], 0
	v_mfma_f32_16x16x32_bf16 v[66:69], v[6:9], v[38:41], v[66:69]
	v_mfma_f32_16x16x32_bf16 v[70:73], v[10:13], v[34:37], 0
	v_mfma_f32_16x16x32_bf16 v[70:73], v[14:17], v[38:41], v[70:73]
	v_mfma_f32_16x16x32_bf16 v[78:81], v[10:13], v[42:45], 0
	v_mfma_f32_16x16x32_bf16 v[78:81], v[14:17], v[46:49], v[78:81]
	v_mfma_f32_16x16x32_bf16 v[74:77], v[2:5], v[42:45], 0
	v_mfma_f32_16x16x32_bf16 v[74:77], v[6:9], v[46:49], v[74:77]
	v_mfma_f32_16x16x32_bf16 v[82:85], v[2:5], v[50:53], 0
	v_mfma_f32_16x16x32_bf16 v[82:85], v[6:9], v[54:57], v[82:85]
	v_mfma_f32_16x16x32_bf16 v[86:89], v[10:13], v[50:53], 0
	v_mfma_f32_16x16x32_bf16 v[86:89], v[14:17], v[54:57], v[86:89]
	v_mfma_f32_16x16x32_bf16 v[94:97], v[10:13], v[58:61], 0
	v_mfma_f32_16x16x32_bf16 v[94:97], v[14:17], v[62:65], v[94:97]
	v_mfma_f32_16x16x32_bf16 v[90:93], v[2:5], v[58:61], 0
	v_mfma_f32_16x16x32_bf16 v[90:93], v[6:9], v[62:65], v[90:93]
	v_mfma_f32_16x16x32_bf16 v[98:101], v[18:21], v[34:37], 0
	v_mfma_f32_16x16x32_bf16 v[34:37], v[26:29], v[34:37], 0
	v_mfma_f32_16x16x32_bf16 v[102:105], v[18:21], v[42:45], 0
	v_mfma_f32_16x16x32_bf16 v[42:45], v[26:29], v[42:45], 0
	v_mfma_f32_16x16x32_bf16 v[106:109], v[18:21], v[50:53], 0
	v_mfma_f32_16x16x32_bf16 v[50:53], v[26:29], v[50:53], 0
	v_mfma_f32_16x16x32_bf16 v[110:113], v[18:21], v[58:61], 0
	v_mfma_f32_16x16x32_bf16 v[58:61], v[26:29], v[58:61], 0
	v_mfma_f32_16x16x32_bf16 v[98:101], v[22:25], v[38:41], v[98:101]
	v_mfma_f32_16x16x32_bf16 v[38:41], v[30:33], v[38:41], v[34:37]
	v_mfma_f32_16x16x32_bf16 v[102:105], v[22:25], v[46:49], v[102:105]
	v_mfma_f32_16x16x32_bf16 v[46:49], v[30:33], v[46:49], v[42:45]
	v_mfma_f32_16x16x32_bf16 v[106:109], v[22:25], v[54:57], v[106:109]
	v_mfma_f32_16x16x32_bf16 v[54:57], v[30:33], v[54:57], v[50:53]
	s_setprio 2
	s_barrier
	v_mfma_f32_16x16x32_bf16 v[110:113], v[22:25], v[62:65], v[110:113]
	v_mfma_f32_16x16x32_bf16 v[62:65], v[30:33], v[62:65], v[58:61]
	s_setprio 0
	v_lshl_add_u64 v[136:137], s[38:39], 0, v[130:131]
	s_add_i32 s60, s56, s21
	v_mov_b32_e32 v135, v131
	v_lshl_add_u64 v[142:143], v[136:137], 0, s[10:11]
	s_mov_b32 m0, s60
	v_lshl_add_u64 v[244:245], s[38:39], 0, v[134:135]
	ds_read_b128 v[34:37], v141 offset:16384
	ds_read_b128 v[42:45], v141 offset:17408
	ds_read_b128 v[50:53], v141 offset:18432
	ds_read_b128 v[58:61], v141 offset:19456
	ds_read_b128 v[114:117], v141 offset:20480
	ds_read_b128 v[118:121], v141 offset:21504
	ds_read_b128 v[122:125], v141 offset:22528
	ds_read_b128 v[126:129], v141 offset:23552
	global_load_lds_dwordx4 v[142:143], off
	v_lshl_add_u64 v[142:143], v[244:245], 0, s[10:11]
	s_add_i32 m0, s60, 0x2000
	s_add_i32 s60, s57, s21
	global_load_lds_dwordx4 v[142:143], off
	s_mov_b32 m0, s60
	v_mov_b32_e32 v139, v131
	global_load_lds_dwordx4 v130, s[40:41]
	s_add_i32 m0, s60, 0x2000
	v_lshl_add_u64 v[246:247], s[36:37], 0, v[138:139]
	v_mov_b32_e32 v133, v131
	global_load_lds_dwordx4 v134, s[40:41]
	v_lshl_add_u64 v[142:143], v[246:247], 0, s[10:11]
	s_mov_b32 m0, s33
	v_lshl_add_u64 v[248:249], s[36:37], 0, v[132:133]
	global_load_lds_dwordx4 v[142:143], off
	v_lshl_add_u64 v[142:143], v[248:249], 0, s[10:11]
	s_mov_b32 m0, s46
	s_nop 0
	global_load_lds_dwordx4 v[142:143], off
	s_waitcnt vmcnt(8)
	s_waitcnt lgkmcnt(0)
	s_barrier
	s_setprio 1
	v_mfma_f32_16x16x32_bf16 v[142:145], v[2:5], v[34:37], 0
	v_mfma_f32_16x16x32_bf16 v[148:151], v[10:13], v[34:37], 0
	v_mfma_f32_16x16x32_bf16 v[152:155], v[2:5], v[50:53], 0
	v_mfma_f32_16x16x32_bf16 v[156:159], v[10:13], v[50:53], 0
	v_mfma_f32_16x16x32_bf16 v[160:163], v[2:5], v[114:117], 0
	v_mfma_f32_16x16x32_bf16 v[164:167], v[10:13], v[114:117], 0
	v_mfma_f32_16x16x32_bf16 v[2:5], v[2:5], v[122:125], 0
	v_mfma_f32_16x16x32_bf16 v[10:13], v[10:13], v[122:125], 0
	v_mfma_f32_16x16x32_bf16 v[142:145], v[6:9], v[42:45], v[142:145]
	v_mfma_f32_16x16x32_bf16 v[148:151], v[14:17], v[42:45], v[148:151]
	v_mfma_f32_16x16x32_bf16 v[152:155], v[6:9], v[58:61], v[152:155]
	v_mfma_f32_16x16x32_bf16 v[156:159], v[14:17], v[58:61], v[156:159]
	v_mfma_f32_16x16x32_bf16 v[160:163], v[6:9], v[118:121], v[160:163]
	v_mfma_f32_16x16x32_bf16 v[164:167], v[14:17], v[118:121], v[164:167]
	v_mfma_f32_16x16x32_bf16 v[168:171], v[6:9], v[126:129], v[2:5]
	v_mfma_f32_16x16x32_bf16 v[172:175], v[14:17], v[126:129], v[10:13]
	v_mfma_f32_16x16x32_bf16 v[2:5], v[18:21], v[34:37], 0
	v_mfma_f32_16x16x32_bf16 v[6:9], v[26:29], v[34:37], 0
	v_mfma_f32_16x16x32_bf16 v[10:13], v[18:21], v[50:53], 0
	v_mfma_f32_16x16x32_bf16 v[14:17], v[26:29], v[50:53], 0
	v_mfma_f32_16x16x32_bf16 v[34:37], v[18:21], v[114:117], 0
	v_mfma_f32_16x16x32_bf16 v[50:53], v[26:29], v[114:117], 0
	v_mfma_f32_16x16x32_bf16 v[18:21], v[18:21], v[122:125], 0
	v_mfma_f32_16x16x32_bf16 v[26:29], v[26:29], v[122:125], 0
	v_mfma_f32_16x16x32_bf16 v[114:117], v[22:25], v[42:45], v[2:5]
	v_mfma_f32_16x16x32_bf16 v[188:191], v[22:25], v[118:121], v[34:37]
	v_mfma_f32_16x16x32_bf16 v[118:121], v[30:33], v[118:121], v[50:53]
	v_mfma_f32_16x16x32_bf16 v[176:179], v[30:33], v[42:45], v[6:9]
	v_mfma_f32_16x16x32_bf16 v[180:183], v[22:25], v[58:61], v[10:13]
	v_mfma_f32_16x16x32_bf16 v[184:187], v[30:33], v[58:61], v[14:17]
	s_setprio 2
	s_barrier
	v_mfma_f32_16x16x32_bf16 v[192:195], v[22:25], v[126:129], v[18:21]
	v_mfma_f32_16x16x32_bf16 v[196:199], v[30:33], v[126:129], v[26:29]
	s_setprio 0
	s_add_i32 s60, 0, 0x18000
	v_add_u32_e32 v2, s60, v140
	s_add_i32 s61, 0, 0x1c000
	ds_read_b128 v[200:203], v2
	ds_read_b128 v[204:207], v2 offset:1024
	ds_read_b128 v[208:211], v2 offset:2048
	ds_read_b128 v[212:215], v2 offset:3072
	v_add_u32_e32 v2, s61, v140
	ds_read_b128 v[216:219], v2
	ds_read_b128 v[220:223], v2 offset:1024
	ds_read_b128 v[224:227], v2 offset:2048
	ds_read_b128 v[228:231], v2 offset:3072
	s_mov_b32 m0, s47
	ds_read_b128 v[42:45], v141 offset:32768
	ds_read_b128 v[50:53], v141 offset:33792
	ds_read_b128 v[58:61], v141 offset:34816
	ds_read_b128 v[122:125], v141 offset:35840
	ds_read_b128 v[126:129], v141 offset:36864
	ds_read_b128 v[232:235], v141 offset:37888
	ds_read_b128 v[236:239], v141 offset:38912
	ds_read_b128 v[240:243], v141 offset:39936
	global_load_lds_dwordx4 v138, s[42:43]
	s_mov_b32 m0, s48
	s_nop 0
	global_load_lds_dwordx4 v132, s[42:43]
	s_waitcnt vmcnt(8)
	s_waitcnt lgkmcnt(0)
	s_barrier
	s_setprio 1
	v_mfma_f32_16x16x32_bf16 v[2:5], v[200:203], v[42:45], v[66:69]
	v_mfma_f32_16x16x32_bf16 v[6:9], v[208:211], v[42:45], v[70:73]
	v_mfma_f32_16x16x32_bf16 v[10:13], v[200:203], v[58:61], v[74:77]
	v_mfma_f32_16x16x32_bf16 v[14:17], v[208:211], v[58:61], v[78:81]
	v_mfma_f32_16x16x32_bf16 v[18:21], v[200:203], v[126:129], v[82:85]
	v_mfma_f32_16x16x32_bf16 v[22:25], v[208:211], v[126:129], v[86:89]
	v_mfma_f32_16x16x32_bf16 v[26:29], v[200:203], v[236:239], v[90:93]
	v_mfma_f32_16x16x32_bf16 v[30:33], v[208:211], v[236:239], v[94:97]
	v_mfma_f32_16x16x32_bf16 v[2:5], v[204:207], v[50:53], v[2:5]
	v_mfma_f32_16x16x32_bf16 v[6:9], v[212:215], v[50:53], v[6:9]
	v_mfma_f32_16x16x32_bf16 v[10:13], v[204:207], v[122:125], v[10:13]
	v_mfma_f32_16x16x32_bf16 v[14:17], v[212:215], v[122:125], v[14:17]
	v_mfma_f32_16x16x32_bf16 v[18:21], v[204:207], v[232:235], v[18:21]
	v_mfma_f32_16x16x32_bf16 v[22:25], v[212:215], v[232:235], v[22:25]
	v_mfma_f32_16x16x32_bf16 v[26:29], v[204:207], v[240:243], v[26:29]
	v_mfma_f32_16x16x32_bf16 v[30:33], v[212:215], v[240:243], v[30:33]
	v_mfma_f32_16x16x32_bf16 v[34:37], v[216:219], v[42:45], v[98:101]
	v_mfma_f32_16x16x32_bf16 v[38:41], v[224:227], v[42:45], v[38:41]
	v_mfma_f32_16x16x32_bf16 v[34:37], v[220:223], v[50:53], v[34:37]
	v_mfma_f32_16x16x32_bf16 v[38:41], v[228:231], v[50:53], v[38:41]
	v_mfma_f32_16x16x32_bf16 v[42:45], v[216:219], v[58:61], v[102:105]
	v_mfma_f32_16x16x32_bf16 v[46:49], v[224:227], v[58:61], v[46:49]
	v_mfma_f32_16x16x32_bf16 v[50:53], v[216:219], v[126:129], v[106:109]
	v_mfma_f32_16x16x32_bf16 v[54:57], v[224:227], v[126:129], v[54:57]
	v_mfma_f32_16x16x32_bf16 v[58:61], v[216:219], v[236:239], v[110:113]
	v_mfma_f32_16x16x32_bf16 v[62:65], v[224:227], v[236:239], v[62:65]
	v_mfma_f32_16x16x32_bf16 v[42:45], v[220:223], v[122:125], v[42:45]
	v_mfma_f32_16x16x32_bf16 v[46:49], v[228:231], v[122:125], v[46:49]
	v_mfma_f32_16x16x32_bf16 v[50:53], v[220:223], v[232:235], v[50:53]
	v_mfma_f32_16x16x32_bf16 v[54:57], v[228:231], v[232:235], v[54:57]
	s_setprio 2
	s_barrier
	v_mfma_f32_16x16x32_bf16 v[58:61], v[220:223], v[240:243], v[58:61]
	v_mfma_f32_16x16x32_bf16 v[62:65], v[228:231], v[240:243], v[62:65]
	s_setprio 0
	s_add_i32 s60, s60, s21
	v_lshl_add_u64 v[66:67], v[136:137], 0, s[12:13]
	s_mov_b32 m0, s60
	ds_read_b128 v[94:97], v141 offset:49152
	ds_read_b128 v[98:101], v141 offset:50176
	ds_read_b128 v[102:105], v141 offset:51200
	ds_read_b128 v[106:109], v141 offset:52224
	ds_read_b128 v[110:113], v141 offset:53248
	ds_read_b128 v[232:235], v141 offset:54272
	ds_read_b128 v[236:239], v141 offset:55296
	ds_read_b128 v[240:243], v141 offset:56320
	global_load_lds_dwordx4 v[66:67], off
	v_lshl_add_u64 v[66:67], v[244:245], 0, s[12:13]
	s_add_i32 m0, s60, 0x2000
	s_add_i32 s60, s61, s21
	global_load_lds_dwordx4 v[66:67], off
	s_mov_b32 m0, s60
	v_lshl_add_u64 v[66:67], v[246:247], 0, s[12:13]
	global_load_lds_dwordx4 v130, s[44:45]
	s_add_i32 m0, s60, 0x2000
	s_nop 0
	global_load_lds_dwordx4 v134, s[44:45]
	s_mov_b32 m0, s52
	s_nop 0
	global_load_lds_dwordx4 v[66:67], off
	v_lshl_add_u64 v[66:67], v[248:249], 0, s[12:13]
	s_mov_b32 m0, s53
	s_nop 0
	global_load_lds_dwordx4 v[66:67], off
	s_waitcnt vmcnt(8)
	s_waitcnt lgkmcnt(0)
	s_barrier
	s_setprio 1
	v_mfma_f32_16x16x32_bf16 v[66:69], v[200:203], v[94:97], v[142:145]
	v_mfma_f32_16x16x32_bf16 v[122:125], v[204:207], v[98:101], v[66:69]
	v_mfma_f32_16x16x32_bf16 v[66:69], v[208:211], v[94:97], v[148:151]
	v_mfma_f32_16x16x32_bf16 v[126:129], v[212:215], v[98:101], v[66:69]
	v_mfma_f32_16x16x32_bf16 v[66:69], v[200:203], v[102:105], v[152:155]
	v_mfma_f32_16x16x32_bf16 v[70:73], v[208:211], v[102:105], v[156:159]
	v_mfma_f32_16x16x32_bf16 v[74:77], v[200:203], v[110:113], v[160:163]
	v_mfma_f32_16x16x32_bf16 v[78:81], v[208:211], v[110:113], v[164:167]
	v_mfma_f32_16x16x32_bf16 v[82:85], v[200:203], v[236:239], v[168:171]
	v_mfma_f32_16x16x32_bf16 v[86:89], v[208:211], v[236:239], v[172:175]
	v_mfma_f32_16x16x32_bf16 v[66:69], v[204:207], v[106:109], v[66:69]
	v_mfma_f32_16x16x32_bf16 v[70:73], v[212:215], v[106:109], v[70:73]
	v_mfma_f32_16x16x32_bf16 v[74:77], v[204:207], v[232:235], v[74:77]
	v_mfma_f32_16x16x32_bf16 v[78:81], v[212:215], v[232:235], v[78:81]
	v_mfma_f32_16x16x32_bf16 v[82:85], v[204:207], v[240:243], v[82:85]
	v_mfma_f32_16x16x32_bf16 v[86:89], v[212:215], v[240:243], v[86:89]
	v_mfma_f32_16x16x32_bf16 v[90:93], v[216:219], v[94:97], v[114:117]
	v_mfma_f32_16x16x32_bf16 v[94:97], v[224:227], v[94:97], v[176:179]
	v_mfma_f32_16x16x32_bf16 v[90:93], v[220:223], v[98:101], v[90:93]
	v_mfma_f32_16x16x32_bf16 v[94:97], v[228:231], v[98:101], v[94:97]
	v_mfma_f32_16x16x32_bf16 v[98:101], v[216:219], v[102:105], v[180:183]
	v_mfma_f32_16x16x32_bf16 v[102:105], v[224:227], v[102:105], v[184:187]
	v_mfma_f32_16x16x32_bf16 v[98:101], v[220:223], v[106:109], v[98:101]
	v_mfma_f32_16x16x32_bf16 v[102:105], v[228:231], v[106:109], v[102:105]
	v_mfma_f32_16x16x32_bf16 v[106:109], v[216:219], v[110:113], v[188:191]
	v_mfma_f32_16x16x32_bf16 v[110:113], v[224:227], v[110:113], v[118:121]
	v_mfma_f32_16x16x32_bf16 v[114:117], v[216:219], v[236:239], v[192:195]
	v_mfma_f32_16x16x32_bf16 v[118:121], v[224:227], v[236:239], v[196:199]
	v_mfma_f32_16x16x32_bf16 v[106:109], v[220:223], v[232:235], v[106:109]
	v_mfma_f32_16x16x32_bf16 v[110:113], v[228:231], v[232:235], v[110:113]
	s_setprio 2
	s_barrier
	v_mfma_f32_16x16x32_bf16 v[114:117], v[220:223], v[240:243], v[114:117]
	v_mfma_f32_16x16x32_bf16 v[118:121], v[228:231], v[240:243], v[118:121]
	s_setprio 0
	s_add_i32 s59, s59, 2
	s_cmp_ge_i32 s59, s15
	s_cbranch_scc0 .LBB0_379
	v_mov_b32_e32 v136, v130
	s_branch .LBB0_382

.LBB0_383:
	v_add_u32_e32 v133, s56, v140
	ds_read_b128 v[142:145], v133
	ds_read_b128 v[148:151], v133 offset:1024
	ds_read_b128 v[152:155], v133 offset:2048
	ds_read_b128 v[156:159], v133 offset:3072
	v_add_u32_e32 v133, s57, v140
	ds_read_b128 v[160:163], v133
	ds_read_b128 v[164:167], v133 offset:1024
	ds_read_b128 v[168:171], v133 offset:2048
	ds_read_b128 v[172:175], v133 offset:3072
	s_add_u32 s38, s36, 0xfff80080
	s_addc_u32 s39, s37, -1
	s_cmp_eq_u32 s43, 28
	s_cselect_b32 s41, s31, s39
	s_cselect_b32 s40, s30, s38
	s_cselect_b32 s39, s35, s42
	s_cselect_b32 s38, s34, s15
	s_mov_b32 m0, s54
	v_add_u32_e32 v141, 0, v1
	ds_read_b128 v[176:179], v141
	ds_read_b128 v[180:183], v141 offset:1024
	ds_read_b128 v[184:187], v141 offset:2048
	ds_read_b128 v[188:191], v141 offset:3072
	ds_read_b128 v[192:195], v141 offset:4096
	ds_read_b128 v[196:199], v141 offset:5120
	ds_read_b128 v[200:203], v141 offset:6144
	ds_read_b128 v[204:207], v141 offset:7168
	global_load_lds_dwordx4 v130, s[36:37]
	s_mov_b32 m0, s55
	v_mov_b32_e32 v133, v131
	global_load_lds_dwordx4 v132, s[36:37]
	s_waitcnt vmcnt(8)
	s_waitcnt lgkmcnt(0)
	s_barrier
	s_setprio 1
	v_mfma_f32_16x16x32_bf16 v[2:5], v[142:145], v[176:179], v[2:5]
	v_mfma_f32_16x16x32_bf16 v[2:5], v[148:151], v[180:183], v[2:5]
	v_mfma_f32_16x16x32_bf16 v[6:9], v[156:159], v[180:183], v[6:9]
	v_mfma_f32_16x16x32_bf16 v[6:9], v[152:155], v[176:179], v[6:9]
	v_mfma_f32_16x16x32_bf16 v[14:17], v[152:155], v[184:187], v[14:17]
	v_mfma_f32_16x16x32_bf16 v[14:17], v[156:159], v[188:191], v[14:17]
	v_mfma_f32_16x16x32_bf16 v[10:13], v[148:151], v[188:191], v[10:13]
	v_mfma_f32_16x16x32_bf16 v[10:13], v[142:145], v[184:187], v[10:13]
	v_mfma_f32_16x16x32_bf16 v[18:21], v[142:145], v[192:195], v[18:21]
	v_mfma_f32_16x16x32_bf16 v[18:21], v[148:151], v[196:199], v[18:21]
	v_mfma_f32_16x16x32_bf16 v[22:25], v[156:159], v[196:199], v[22:25]
	v_mfma_f32_16x16x32_bf16 v[22:25], v[152:155], v[192:195], v[22:25]
	v_mfma_f32_16x16x32_bf16 v[30:33], v[152:155], v[200:203], v[30:33]
	v_mfma_f32_16x16x32_bf16 v[30:33], v[156:159], v[204:207], v[30:33]
	v_mfma_f32_16x16x32_bf16 v[26:29], v[148:151], v[204:207], v[26:29]
	v_mfma_f32_16x16x32_bf16 v[26:29], v[142:145], v[200:203], v[26:29]
	v_mfma_f32_16x16x32_bf16 v[34:37], v[160:163], v[176:179], v[34:37]
	v_mfma_f32_16x16x32_bf16 v[34:37], v[164:167], v[180:183], v[34:37]
	v_mfma_f32_16x16x32_bf16 v[38:41], v[172:175], v[180:183], v[38:41]
	v_mfma_f32_16x16x32_bf16 v[38:41], v[168:171], v[176:179], v[38:41]
	v_mfma_f32_16x16x32_bf16 v[46:49], v[168:171], v[184:187], v[46:49]
	v_mfma_f32_16x16x32_bf16 v[46:49], v[172:175], v[188:191], v[46:49]
	v_mfma_f32_16x16x32_bf16 v[42:45], v[164:167], v[188:191], v[42:45]
	v_mfma_f32_16x16x32_bf16 v[42:45], v[160:163], v[184:187], v[42:45]
	v_mfma_f32_16x16x32_bf16 v[50:53], v[160:163], v[192:195], v[50:53]
	v_mfma_f32_16x16x32_bf16 v[50:53], v[164:167], v[196:199], v[50:53]
	v_mfma_f32_16x16x32_bf16 v[54:57], v[172:175], v[196:199], v[54:57]
	v_mfma_f32_16x16x32_bf16 v[54:57], v[168:171], v[192:195], v[54:57]
	v_mfma_f32_16x16x32_bf16 v[62:65], v[168:171], v[200:203], v[62:65]
	v_mfma_f32_16x16x32_bf16 v[62:65], v[172:175], v[204:207], v[62:65]
	s_setprio 2
	s_barrier
	v_mfma_f32_16x16x32_bf16 v[58:61], v[164:167], v[204:207], v[58:61]
	v_mfma_f32_16x16x32_bf16 v[58:61], v[160:163], v[200:203], v[58:61]
	s_setprio 0
	s_add_i32 s44, s56, s21
	s_mov_b32 m0, s44
	ds_read_b128 v[176:179], v141 offset:16384
	ds_read_b128 v[180:183], v141 offset:17408
	ds_read_b128 v[184:187], v141 offset:18432
	ds_read_b128 v[188:191], v141 offset:19456
	ds_read_b128 v[192:195], v141 offset:20480
	ds_read_b128 v[196:199], v141 offset:21504
	ds_read_b128 v[200:203], v141 offset:22528
	ds_read_b128 v[204:207], v141 offset:23552
	global_load_lds_dwordx4 v136, s[38:39]
	s_add_i32 m0, s44, 0x2000
	s_add_u32 s44, s38, 0x80000
	s_addc_u32 s45, s39, 0
	s_add_i32 s59, s57, s21
	global_load_lds_dwordx4 v134, s[38:39]
	s_mov_b32 m0, s59
	v_mov_b32_e32 v137, v131
	global_load_lds_dwordx4 v136, s[44:45]
	s_add_i32 m0, s59, 0x2000
	v_mov_b32_e32 v135, v131
	global_load_lds_dwordx4 v134, s[44:45]
	s_mov_b32 m0, s33
	v_lshl_add_u64 v[138:139], s[38:39], 0, v[136:137]
	global_load_lds_dwordx4 v130, s[40:41]
	s_mov_b32 m0, s46
	v_lshl_add_u64 v[208:209], s[38:39], 0, v[134:135]
	global_load_lds_dwordx4 v132, s[40:41]
	s_waitcnt vmcnt(8)
	s_waitcnt lgkmcnt(0)
	v_lshl_add_u64 v[210:211], s[40:41], 0, v[130:131]
	v_lshl_add_u64 v[212:213], s[40:41], 0, v[132:133]
	s_barrier
	s_setprio 1
	v_mfma_f32_16x16x32_bf16 v[122:125], v[142:145], v[176:179], v[122:125]
	v_mfma_f32_16x16x32_bf16 v[122:125], v[148:151], v[180:183], v[122:125]
	v_mfma_f32_16x16x32_bf16 v[126:129], v[156:159], v[180:183], v[126:129]
	v_mfma_f32_16x16x32_bf16 v[126:129], v[152:155], v[176:179], v[126:129]
	v_mfma_f32_16x16x32_bf16 v[70:73], v[152:155], v[184:187], v[70:73]
	v_mfma_f32_16x16x32_bf16 v[70:73], v[156:159], v[188:191], v[70:73]
	v_mfma_f32_16x16x32_bf16 v[66:69], v[148:151], v[188:191], v[66:69]
	v_mfma_f32_16x16x32_bf16 v[66:69], v[142:145], v[184:187], v[66:69]
	v_mfma_f32_16x16x32_bf16 v[74:77], v[142:145], v[192:195], v[74:77]
	v_mfma_f32_16x16x32_bf16 v[74:77], v[148:151], v[196:199], v[74:77]
	v_mfma_f32_16x16x32_bf16 v[78:81], v[156:159], v[196:199], v[78:81]
	v_mfma_f32_16x16x32_bf16 v[78:81], v[152:155], v[192:195], v[78:81]
	v_mfma_f32_16x16x32_bf16 v[86:89], v[152:155], v[200:203], v[86:89]
	v_mfma_f32_16x16x32_bf16 v[86:89], v[156:159], v[204:207], v[86:89]
	v_mfma_f32_16x16x32_bf16 v[82:85], v[148:151], v[204:207], v[82:85]
	v_mfma_f32_16x16x32_bf16 v[82:85], v[142:145], v[200:203], v[82:85]
	v_mfma_f32_16x16x32_bf16 v[90:93], v[160:163], v[176:179], v[90:93]
	v_mfma_f32_16x16x32_bf16 v[90:93], v[164:167], v[180:183], v[90:93]
	v_mfma_f32_16x16x32_bf16 v[94:97], v[172:175], v[180:183], v[94:97]
	v_mfma_f32_16x16x32_bf16 v[94:97], v[168:171], v[176:179], v[94:97]
	v_mfma_f32_16x16x32_bf16 v[102:105], v[168:171], v[184:187], v[102:105]
	v_mfma_f32_16x16x32_bf16 v[102:105], v[172:175], v[188:191], v[102:105]
	v_mfma_f32_16x16x32_bf16 v[98:101], v[164:167], v[188:191], v[98:101]
	v_mfma_f32_16x16x32_bf16 v[98:101], v[160:163], v[184:187], v[98:101]
	v_mfma_f32_16x16x32_bf16 v[106:109], v[160:163], v[192:195], v[106:109]
	v_mfma_f32_16x16x32_bf16 v[106:109], v[164:167], v[196:199], v[106:109]
	v_mfma_f32_16x16x32_bf16 v[110:113], v[172:175], v[196:199], v[110:113]
	v_mfma_f32_16x16x32_bf16 v[110:113], v[168:171], v[192:195], v[110:113]
	v_mfma_f32_16x16x32_bf16 v[118:121], v[168:171], v[200:203], v[118:121]
	v_mfma_f32_16x16x32_bf16 v[118:121], v[172:175], v[204:207], v[118:121]
	s_setprio 2
	s_barrier
	v_mfma_f32_16x16x32_bf16 v[114:117], v[164:167], v[204:207], v[114:117]
	v_mfma_f32_16x16x32_bf16 v[114:117], v[160:163], v[200:203], v[114:117]
	s_setprio 0
	s_add_i32 s44, 0, 0x18000
	v_add_u32_e32 v135, s44, v140
	s_add_i32 s45, 0, 0x1c000
	ds_read_b128 v[142:145], v135
	ds_read_b128 v[148:151], v135 offset:1024
	ds_read_b128 v[152:155], v135 offset:2048
	ds_read_b128 v[156:159], v135 offset:3072
	v_add_u32_e32 v135, s45, v140
	ds_read_b128 v[160:163], v135
	ds_read_b128 v[164:167], v135 offset:1024
	ds_read_b128 v[168:171], v135 offset:2048
	ds_read_b128 v[172:175], v135 offset:3072
	s_add_u32 s40, s40, 0x80000
	s_addc_u32 s41, s41, 0
	s_mov_b32 m0, s47
	ds_read_b128 v[176:179], v141 offset:32768
	ds_read_b128 v[180:183], v141 offset:33792
	ds_read_b128 v[184:187], v141 offset:34816
	ds_read_b128 v[188:191], v141 offset:35840
	ds_read_b128 v[192:195], v141 offset:36864
	ds_read_b128 v[196:199], v141 offset:37888
	ds_read_b128 v[200:203], v141 offset:38912
	ds_read_b128 v[204:207], v141 offset:39936
	global_load_lds_dwordx4 v130, s[40:41]
	s_mov_b32 m0, s48
	s_nop 0
	global_load_lds_dwordx4 v132, s[40:41]
	s_waitcnt vmcnt(8)
	s_waitcnt lgkmcnt(0)
	s_barrier
	s_setprio 1
	v_mfma_f32_16x16x32_bf16 v[2:5], v[142:145], v[176:179], v[2:5]
	v_mfma_f32_16x16x32_bf16 v[2:5], v[148:151], v[180:183], v[2:5]
	v_mfma_f32_16x16x32_bf16 v[6:9], v[156:159], v[180:183], v[6:9]
	v_mfma_f32_16x16x32_bf16 v[6:9], v[152:155], v[176:179], v[6:9]
	v_mfma_f32_16x16x32_bf16 v[14:17], v[152:155], v[184:187], v[14:17]
	v_mfma_f32_16x16x32_bf16 v[14:17], v[156:159], v[188:191], v[14:17]
	v_mfma_f32_16x16x32_bf16 v[10:13], v[148:151], v[188:191], v[10:13]
	v_mfma_f32_16x16x32_bf16 v[10:13], v[142:145], v[184:187], v[10:13]
	v_mfma_f32_16x16x32_bf16 v[18:21], v[142:145], v[192:195], v[18:21]
	v_mfma_f32_16x16x32_bf16 v[18:21], v[148:151], v[196:199], v[18:21]
	v_mfma_f32_16x16x32_bf16 v[22:25], v[156:159], v[196:199], v[22:25]
	v_mfma_f32_16x16x32_bf16 v[22:25], v[152:155], v[192:195], v[22:25]
	v_mfma_f32_16x16x32_bf16 v[30:33], v[152:155], v[200:203], v[30:33]
	v_mfma_f32_16x16x32_bf16 v[30:33], v[156:159], v[204:207], v[30:33]
	v_mfma_f32_16x16x32_bf16 v[26:29], v[148:151], v[204:207], v[26:29]
	v_mfma_f32_16x16x32_bf16 v[26:29], v[142:145], v[200:203], v[26:29]
	v_mfma_f32_16x16x32_bf16 v[34:37], v[160:163], v[176:179], v[34:37]
	v_mfma_f32_16x16x32_bf16 v[34:37], v[164:167], v[180:183], v[34:37]
	v_mfma_f32_16x16x32_bf16 v[38:41], v[172:175], v[180:183], v[38:41]
	v_mfma_f32_16x16x32_bf16 v[38:41], v[168:171], v[176:179], v[38:41]
	v_mfma_f32_16x16x32_bf16 v[46:49], v[168:171], v[184:187], v[46:49]
	v_mfma_f32_16x16x32_bf16 v[46:49], v[172:175], v[188:191], v[46:49]
	v_mfma_f32_16x16x32_bf16 v[42:45], v[164:167], v[188:191], v[42:45]
	v_mfma_f32_16x16x32_bf16 v[42:45], v[160:163], v[184:187], v[42:45]
	v_mfma_f32_16x16x32_bf16 v[50:53], v[160:163], v[192:195], v[50:53]
	v_mfma_f32_16x16x32_bf16 v[50:53], v[164:167], v[196:199], v[50:53]
	v_mfma_f32_16x16x32_bf16 v[54:57], v[172:175], v[196:199], v[54:57]
	v_mfma_f32_16x16x32_bf16 v[54:57], v[168:171], v[192:195], v[54:57]
	v_mfma_f32_16x16x32_bf16 v[62:65], v[168:171], v[200:203], v[62:65]
	v_mfma_f32_16x16x32_bf16 v[62:65], v[172:175], v[204:207], v[62:65]
	s_setprio 2
	s_barrier
	v_mfma_f32_16x16x32_bf16 v[58:61], v[164:167], v[204:207], v[58:61]
	v_mfma_f32_16x16x32_bf16 v[58:61], v[160:163], v[200:203], v[58:61]
	s_setprio 0
	s_add_i32 s40, s44, s21
	v_lshl_add_u64 v[138:139], v[138:139], 0, s[6:7]
	s_mov_b32 m0, s40
	ds_read_b128 v[176:179], v141 offset:49152
	ds_read_b128 v[180:183], v141 offset:50176
	ds_read_b128 v[184:187], v141 offset:51200
	ds_read_b128 v[188:191], v141 offset:52224
	ds_read_b128 v[192:195], v141 offset:53248
	ds_read_b128 v[196:199], v141 offset:54272
	ds_read_b128 v[200:203], v141 offset:55296
	ds_read_b128 v[204:207], v141 offset:56320
	global_load_lds_dwordx4 v[138:139], off
	s_add_i32 m0, s40, 0x2000
	s_add_u32 s38, s38, 0x80080
	v_lshl_add_u64 v[138:139], v[208:209], 0, s[6:7]
	s_addc_u32 s39, s39, 0
	s_add_i32 s40, s45, s21
	global_load_lds_dwordx4 v[138:139], off
	s_mov_b32 m0, s40
	v_lshl_add_u64 v[138:139], v[210:211], 0, s[6:7]
	global_load_lds_dwordx4 v136, s[38:39]
	s_add_i32 m0, s40, 0x2000
	s_nop 0
	global_load_lds_dwordx4 v134, s[38:39]
	s_mov_b32 m0, s52
	s_nop 0
	global_load_lds_dwordx4 v[138:139], off
	v_lshl_add_u64 v[138:139], v[212:213], 0, s[6:7]
	s_mov_b32 m0, s53
	s_nop 0
	global_load_lds_dwordx4 v[138:139], off
	s_waitcnt vmcnt(8)
	s_waitcnt lgkmcnt(0)
	s_barrier
	s_setprio 1
	v_mfma_f32_16x16x32_bf16 v[122:125], v[142:145], v[176:179], v[122:125]
	v_mfma_f32_16x16x32_bf16 v[122:125], v[148:151], v[180:183], v[122:125]
	v_mfma_f32_16x16x32_bf16 v[126:129], v[156:159], v[180:183], v[126:129]
	v_mfma_f32_16x16x32_bf16 v[126:129], v[152:155], v[176:179], v[126:129]
	v_mfma_f32_16x16x32_bf16 v[70:73], v[152:155], v[184:187], v[70:73]
	v_mfma_f32_16x16x32_bf16 v[70:73], v[156:159], v[188:191], v[70:73]
	v_mfma_f32_16x16x32_bf16 v[66:69], v[148:151], v[188:191], v[66:69]
	v_mfma_f32_16x16x32_bf16 v[66:69], v[142:145], v[184:187], v[66:69]
	v_mfma_f32_16x16x32_bf16 v[74:77], v[142:145], v[192:195], v[74:77]
	v_mfma_f32_16x16x32_bf16 v[74:77], v[148:151], v[196:199], v[74:77]
	v_mfma_f32_16x16x32_bf16 v[78:81], v[156:159], v[196:199], v[78:81]
	v_mfma_f32_16x16x32_bf16 v[78:81], v[152:155], v[192:195], v[78:81]
	v_mfma_f32_16x16x32_bf16 v[86:89], v[152:155], v[200:203], v[86:89]
	v_mfma_f32_16x16x32_bf16 v[86:89], v[156:159], v[204:207], v[86:89]
	v_mfma_f32_16x16x32_bf16 v[82:85], v[148:151], v[204:207], v[82:85]
	v_mfma_f32_16x16x32_bf16 v[82:85], v[142:145], v[200:203], v[82:85]
	v_mfma_f32_16x16x32_bf16 v[90:93], v[160:163], v[176:179], v[90:93]
	v_mfma_f32_16x16x32_bf16 v[90:93], v[164:167], v[180:183], v[90:93]
	v_mfma_f32_16x16x32_bf16 v[94:97], v[172:175], v[180:183], v[94:97]
	v_mfma_f32_16x16x32_bf16 v[94:97], v[168:171], v[176:179], v[94:97]
	v_mfma_f32_16x16x32_bf16 v[102:105], v[168:171], v[184:187], v[102:105]
	v_mfma_f32_16x16x32_bf16 v[102:105], v[172:175], v[188:191], v[102:105]
	v_mfma_f32_16x16x32_bf16 v[98:101], v[164:167], v[188:191], v[98:101]
	v_mfma_f32_16x16x32_bf16 v[98:101], v[160:163], v[184:187], v[98:101]
	v_mfma_f32_16x16x32_bf16 v[106:109], v[160:163], v[192:195], v[106:109]
	v_mfma_f32_16x16x32_bf16 v[106:109], v[164:167], v[196:199], v[106:109]
	v_mfma_f32_16x16x32_bf16 v[110:113], v[172:175], v[196:199], v[110:113]
	v_mfma_f32_16x16x32_bf16 v[110:113], v[168:171], v[192:195], v[110:113]
	v_mfma_f32_16x16x32_bf16 v[118:121], v[168:171], v[200:203], v[118:121]
	v_mfma_f32_16x16x32_bf16 v[118:121], v[172:175], v[204:207], v[118:121]
	s_setprio 2
	s_barrier
	v_mfma_f32_16x16x32_bf16 v[114:117], v[164:167], v[204:207], v[114:117]
	v_mfma_f32_16x16x32_bf16 v[114:117], v[160:163], v[200:203], v[114:117]
	s_setprio 0
	s_add_i32 s43, s43, 2
	s_add_u32 s36, s36, 0x100
	s_addc_u32 s37, s37, 0
	s_add_u32 s15, s15, 0x100
	s_addc_u32 s42, s42, 0
	s_cmp_gt_u32 s43, 29
	s_cbranch_scc0 .LBB0_383
	s_and_b64 vcc, exec, s[8:9]
	s_cbranch_vccz .LBB0_386
	s_barrier

.LBB0_462:
	v_add_u32_e32 v14, s54, v140
	v_add_u32_e32 v30, s55, v140
	ds_read_b128 v[2:5], v14
	ds_read_b128 v[6:9], v14 offset:1024
	ds_read_b128 v[10:13], v14 offset:2048
	ds_read_b128 v[14:17], v14 offset:3072
	ds_read_b128 v[18:21], v30
	ds_read_b128 v[22:25], v30 offset:1024
	ds_read_b128 v[26:29], v30 offset:2048
	ds_read_b128 v[30:33], v30 offset:3072
	v_add_u32_e32 v141, 0, v1
	ds_read_b128 v[34:37], v141
	ds_read_b128 v[38:41], v141 offset:1024
	ds_read_b128 v[42:45], v141 offset:2048
	ds_read_b128 v[46:49], v141 offset:3072
	ds_read_b128 v[50:53], v141 offset:4096
	ds_read_b128 v[54:57], v141 offset:5120
	ds_read_b128 v[58:61], v141 offset:6144
	ds_read_b128 v[62:65], v141 offset:7168
	s_waitcnt vmcnt(8)
	s_waitcnt lgkmcnt(0)
	s_barrier
	s_setprio 1
	v_mfma_f32_16x16x32_bf16 v[66:69], v[2:5], v[34:37], 0
	v_mfma_f32_16x16x32_bf16 v[66:69], v[6:9], v[38:41], v[66:69]
	v_mfma_f32_16x16x32_bf16 v[70:73], v[10:13], v[34:37], 0
	v_mfma_f32_16x16x32_bf16 v[70:73], v[14:17], v[38:41], v[70:73]
	v_mfma_f32_16x16x32_bf16 v[78:81], v[10:13], v[42:45], 0
	v_mfma_f32_16x16x32_bf16 v[78:81], v[14:17], v[46:49], v[78:81]
	v_mfma_f32_16x16x32_bf16 v[74:77], v[2:5], v[42:45], 0
	v_mfma_f32_16x16x32_bf16 v[74:77], v[6:9], v[46:49], v[74:77]
	v_mfma_f32_16x16x32_bf16 v[82:85], v[2:5], v[50:53], 0
	v_mfma_f32_16x16x32_bf16 v[82:85], v[6:9], v[54:57], v[82:85]
	v_mfma_f32_16x16x32_bf16 v[86:89], v[10:13], v[50:53], 0
	v_mfma_f32_16x16x32_bf16 v[86:89], v[14:17], v[54:57], v[86:89]
	v_mfma_f32_16x16x32_bf16 v[94:97], v[10:13], v[58:61], 0
	v_mfma_f32_16x16x32_bf16 v[94:97], v[14:17], v[62:65], v[94:97]
	v_mfma_f32_16x16x32_bf16 v[90:93], v[2:5], v[58:61], 0
	v_mfma_f32_16x16x32_bf16 v[90:93], v[6:9], v[62:65], v[90:93]
	v_mfma_f32_16x16x32_bf16 v[98:101], v[18:21], v[34:37], 0
	v_mfma_f32_16x16x32_bf16 v[34:37], v[26:29], v[34:37], 0
	v_mfma_f32_16x16x32_bf16 v[102:105], v[18:21], v[42:45], 0
	v_mfma_f32_16x16x32_bf16 v[42:45], v[26:29], v[42:45], 0
	v_mfma_f32_16x16x32_bf16 v[106:109], v[18:21], v[50:53], 0
	v_mfma_f32_16x16x32_bf16 v[50:53], v[26:29], v[50:53], 0
	v_mfma_f32_16x16x32_bf16 v[110:113], v[18:21], v[58:61], 0
	v_mfma_f32_16x16x32_bf16 v[58:61], v[26:29], v[58:61], 0
	v_mfma_f32_16x16x32_bf16 v[98:101], v[22:25], v[38:41], v[98:101]
	v_mfma_f32_16x16x32_bf16 v[38:41], v[30:33], v[38:41], v[34:37]
	v_mfma_f32_16x16x32_bf16 v[102:105], v[22:25], v[46:49], v[102:105]
	v_mfma_f32_16x16x32_bf16 v[46:49], v[30:33], v[46:49], v[42:45]
	v_mfma_f32_16x16x32_bf16 v[106:109], v[22:25], v[54:57], v[106:109]
	v_mfma_f32_16x16x32_bf16 v[54:57], v[30:33], v[54:57], v[50:53]
	s_setprio 2
	s_barrier
	v_mfma_f32_16x16x32_bf16 v[110:113], v[22:25], v[62:65], v[110:113]
	v_mfma_f32_16x16x32_bf16 v[62:65], v[30:33], v[62:65], v[58:61]
	s_setprio 0
	v_lshl_add_u64 v[136:137], s[36:37], 0, v[130:131]
	s_add_i32 s62, s54, s21
	v_mov_b32_e32 v135, v131
	v_lshl_add_u64 v[142:143], v[136:137], 0, s[12:13]
	s_mov_b32 m0, s62
	v_lshl_add_u64 v[244:245], s[36:37], 0, v[134:135]
	ds_read_b128 v[34:37], v141 offset:16384
	ds_read_b128 v[42:45], v141 offset:17408
	ds_read_b128 v[50:53], v141 offset:18432
	ds_read_b128 v[58:61], v141 offset:19456
	ds_read_b128 v[114:117], v141 offset:20480
	ds_read_b128 v[118:121], v141 offset:21504
	ds_read_b128 v[122:125], v141 offset:22528
	ds_read_b128 v[126:129], v141 offset:23552
	global_load_lds_dwordx4 v[142:143], off
	v_lshl_add_u64 v[142:143], v[244:245], 0, s[12:13]
	s_add_i32 m0, s62, 0x2000
	s_add_i32 s62, s55, s21
	global_load_lds_dwordx4 v[142:143], off
	s_mov_b32 m0, s62
	v_mov_b32_e32 v139, v131
	global_load_lds_dwordx4 v130, s[38:39]
	s_add_i32 m0, s62, 0x2000
	v_lshl_add_u64 v[246:247], s[34:35], 0, v[138:139]
	v_mov_b32_e32 v133, v131
	global_load_lds_dwordx4 v134, s[38:39]
	v_lshl_add_u64 v[142:143], v[246:247], 0, s[12:13]
	s_mov_b32 m0, s33
	v_lshl_add_u64 v[248:249], s[34:35], 0, v[132:133]
	global_load_lds_dwordx4 v[142:143], off
	v_lshl_add_u64 v[142:143], v[248:249], 0, s[12:13]
	s_mov_b32 m0, s44
	s_nop 0
	global_load_lds_dwordx4 v[142:143], off
	s_waitcnt vmcnt(8)
	s_waitcnt lgkmcnt(0)
	s_barrier
	s_setprio 1
	v_mfma_f32_16x16x32_bf16 v[142:145], v[2:5], v[34:37], 0
	v_mfma_f32_16x16x32_bf16 v[148:151], v[10:13], v[34:37], 0
	v_mfma_f32_16x16x32_bf16 v[152:155], v[2:5], v[50:53], 0
	v_mfma_f32_16x16x32_bf16 v[156:159], v[10:13], v[50:53], 0
	v_mfma_f32_16x16x32_bf16 v[160:163], v[2:5], v[114:117], 0
	v_mfma_f32_16x16x32_bf16 v[164:167], v[10:13], v[114:117], 0
	v_mfma_f32_16x16x32_bf16 v[2:5], v[2:5], v[122:125], 0
	v_mfma_f32_16x16x32_bf16 v[10:13], v[10:13], v[122:125], 0
	v_mfma_f32_16x16x32_bf16 v[142:145], v[6:9], v[42:45], v[142:145]
	v_mfma_f32_16x16x32_bf16 v[148:151], v[14:17], v[42:45], v[148:151]
	v_mfma_f32_16x16x32_bf16 v[152:155], v[6:9], v[58:61], v[152:155]
	v_mfma_f32_16x16x32_bf16 v[156:159], v[14:17], v[58:61], v[156:159]
	v_mfma_f32_16x16x32_bf16 v[160:163], v[6:9], v[118:121], v[160:163]
	v_mfma_f32_16x16x32_bf16 v[164:167], v[14:17], v[118:121], v[164:167]
	v_mfma_f32_16x16x32_bf16 v[168:171], v[6:9], v[126:129], v[2:5]
	v_mfma_f32_16x16x32_bf16 v[172:175], v[14:17], v[126:129], v[10:13]
	v_mfma_f32_16x16x32_bf16 v[2:5], v[18:21], v[34:37], 0
	v_mfma_f32_16x16x32_bf16 v[6:9], v[26:29], v[34:37], 0
	v_mfma_f32_16x16x32_bf16 v[10:13], v[18:21], v[50:53], 0
	v_mfma_f32_16x16x32_bf16 v[14:17], v[26:29], v[50:53], 0
	v_mfma_f32_16x16x32_bf16 v[34:37], v[18:21], v[114:117], 0
	v_mfma_f32_16x16x32_bf16 v[50:53], v[26:29], v[114:117], 0
	v_mfma_f32_16x16x32_bf16 v[18:21], v[18:21], v[122:125], 0
	v_mfma_f32_16x16x32_bf16 v[26:29], v[26:29], v[122:125], 0
	v_mfma_f32_16x16x32_bf16 v[114:117], v[22:25], v[42:45], v[2:5]
	v_mfma_f32_16x16x32_bf16 v[122:125], v[30:33], v[42:45], v[6:9]
	v_mfma_f32_16x16x32_bf16 v[184:187], v[22:25], v[118:121], v[34:37]
	v_mfma_f32_16x16x32_bf16 v[118:121], v[30:33], v[118:121], v[50:53]
	v_mfma_f32_16x16x32_bf16 v[188:191], v[22:25], v[126:129], v[18:21]
	v_mfma_f32_16x16x32_bf16 v[126:129], v[30:33], v[126:129], v[26:29]
	s_setprio 2
	s_barrier
	v_mfma_f32_16x16x32_bf16 v[176:179], v[22:25], v[58:61], v[10:13]
	v_mfma_f32_16x16x32_bf16 v[180:183], v[30:33], v[58:61], v[14:17]
	s_setprio 0
	s_add_i32 s62, 0, 0x18000
	v_add_u32_e32 v2, s62, v140
	s_add_i32 s63, 0, 0x1c000
	ds_read_b128 v[192:195], v2
	ds_read_b128 v[196:199], v2 offset:1024
	ds_read_b128 v[200:203], v2 offset:2048
	ds_read_b128 v[204:207], v2 offset:3072
	v_add_u32_e32 v2, s63, v140
	ds_read_b128 v[208:211], v2
	ds_read_b128 v[212:215], v2 offset:1024
	ds_read_b128 v[216:219], v2 offset:2048
	ds_read_b128 v[220:223], v2 offset:3072
	s_mov_b32 m0, s45
	ds_read_b128 v[42:45], v141 offset:32768
	ds_read_b128 v[50:53], v141 offset:33792
	ds_read_b128 v[58:61], v141 offset:34816
	ds_read_b128 v[224:227], v141 offset:35840
	ds_read_b128 v[228:231], v141 offset:36864
	ds_read_b128 v[232:235], v141 offset:37888
	ds_read_b128 v[236:239], v141 offset:38912
	ds_read_b128 v[240:243], v141 offset:39936
	global_load_lds_dwordx4 v138, s[40:41]
	s_mov_b32 m0, s46
	s_nop 0
	global_load_lds_dwordx4 v132, s[40:41]
	s_waitcnt vmcnt(8)
	s_waitcnt lgkmcnt(0)
	s_barrier
	s_setprio 1
	v_mfma_f32_16x16x32_bf16 v[2:5], v[192:195], v[42:45], v[66:69]
	v_mfma_f32_16x16x32_bf16 v[6:9], v[200:203], v[42:45], v[70:73]
	v_mfma_f32_16x16x32_bf16 v[10:13], v[192:195], v[58:61], v[74:77]
	v_mfma_f32_16x16x32_bf16 v[14:17], v[200:203], v[58:61], v[78:81]
	v_mfma_f32_16x16x32_bf16 v[18:21], v[192:195], v[228:231], v[82:85]
	v_mfma_f32_16x16x32_bf16 v[22:25], v[200:203], v[228:231], v[86:89]
	v_mfma_f32_16x16x32_bf16 v[26:29], v[192:195], v[236:239], v[90:93]
	v_mfma_f32_16x16x32_bf16 v[30:33], v[200:203], v[236:239], v[94:97]
	v_mfma_f32_16x16x32_bf16 v[2:5], v[196:199], v[50:53], v[2:5]
	v_mfma_f32_16x16x32_bf16 v[6:9], v[204:207], v[50:53], v[6:9]
	v_mfma_f32_16x16x32_bf16 v[10:13], v[196:199], v[224:227], v[10:13]
	v_mfma_f32_16x16x32_bf16 v[14:17], v[204:207], v[224:227], v[14:17]
	v_mfma_f32_16x16x32_bf16 v[18:21], v[196:199], v[232:235], v[18:21]
	v_mfma_f32_16x16x32_bf16 v[22:25], v[204:207], v[232:235], v[22:25]
	v_mfma_f32_16x16x32_bf16 v[26:29], v[196:199], v[240:243], v[26:29]
	v_mfma_f32_16x16x32_bf16 v[30:33], v[204:207], v[240:243], v[30:33]
	v_mfma_f32_16x16x32_bf16 v[34:37], v[208:211], v[42:45], v[98:101]
	v_mfma_f32_16x16x32_bf16 v[38:41], v[216:219], v[42:45], v[38:41]
	v_mfma_f32_16x16x32_bf16 v[34:37], v[212:215], v[50:53], v[34:37]
	v_mfma_f32_16x16x32_bf16 v[38:41], v[220:223], v[50:53], v[38:41]
	v_mfma_f32_16x16x32_bf16 v[42:45], v[208:211], v[58:61], v[102:105]
	v_mfma_f32_16x16x32_bf16 v[46:49], v[216:219], v[58:61], v[46:49]
	v_mfma_f32_16x16x32_bf16 v[50:53], v[208:211], v[228:231], v[106:109]
	v_mfma_f32_16x16x32_bf16 v[54:57], v[216:219], v[228:231], v[54:57]
	v_mfma_f32_16x16x32_bf16 v[58:61], v[208:211], v[236:239], v[110:113]
	v_mfma_f32_16x16x32_bf16 v[62:65], v[216:219], v[236:239], v[62:65]
	v_mfma_f32_16x16x32_bf16 v[42:45], v[212:215], v[224:227], v[42:45]
	v_mfma_f32_16x16x32_bf16 v[46:49], v[220:223], v[224:227], v[46:49]
	v_mfma_f32_16x16x32_bf16 v[50:53], v[212:215], v[232:235], v[50:53]
	v_mfma_f32_16x16x32_bf16 v[54:57], v[220:223], v[232:235], v[54:57]
	s_setprio 2
	s_barrier
	v_mfma_f32_16x16x32_bf16 v[58:61], v[212:215], v[240:243], v[58:61]
	v_mfma_f32_16x16x32_bf16 v[62:65], v[220:223], v[240:243], v[62:65]
	s_setprio 0
	s_add_i32 s62, s62, s21
	v_lshl_add_u64 v[66:67], v[136:137], 0, s[14:15]
	s_mov_b32 m0, s62
	ds_read_b128 v[102:105], v141 offset:49152
	ds_read_b128 v[106:109], v141 offset:50176
	ds_read_b128 v[110:113], v141 offset:51200
	ds_read_b128 v[224:227], v141 offset:52224
	ds_read_b128 v[228:231], v141 offset:53248
	ds_read_b128 v[232:235], v141 offset:54272
	ds_read_b128 v[236:239], v141 offset:55296
	ds_read_b128 v[240:243], v141 offset:56320
	global_load_lds_dwordx4 v[66:67], off
	v_lshl_add_u64 v[66:67], v[244:245], 0, s[14:15]
	s_add_i32 m0, s62, 0x2000
	s_add_i32 s62, s63, s21
	global_load_lds_dwordx4 v[66:67], off
	s_mov_b32 m0, s62
	v_lshl_add_u64 v[66:67], v[246:247], 0, s[14:15]
	global_load_lds_dwordx4 v130, s[42:43]
	s_add_i32 m0, s62, 0x2000
	s_nop 0
	global_load_lds_dwordx4 v134, s[42:43]
	s_mov_b32 m0, s50
	s_nop 0
	global_load_lds_dwordx4 v[66:67], off
	v_lshl_add_u64 v[66:67], v[248:249], 0, s[14:15]
	s_mov_b32 m0, s51
	s_nop 0
	global_load_lds_dwordx4 v[66:67], off
	s_waitcnt vmcnt(8)
	s_waitcnt lgkmcnt(0)
	s_barrier
	s_setprio 1
	v_mfma_f32_16x16x32_bf16 v[66:69], v[192:195], v[102:105], v[142:145]
	v_mfma_f32_16x16x32_bf16 v[70:73], v[200:203], v[102:105], v[148:151]
	v_mfma_f32_16x16x32_bf16 v[74:77], v[192:195], v[110:113], v[152:155]
	v_mfma_f32_16x16x32_bf16 v[78:81], v[200:203], v[110:113], v[156:159]
	v_mfma_f32_16x16x32_bf16 v[82:85], v[192:195], v[228:231], v[160:163]
	v_mfma_f32_16x16x32_bf16 v[86:89], v[200:203], v[228:231], v[164:167]
	v_mfma_f32_16x16x32_bf16 v[90:93], v[192:195], v[236:239], v[168:171]
	v_mfma_f32_16x16x32_bf16 v[94:97], v[200:203], v[236:239], v[172:175]
	v_mfma_f32_16x16x32_bf16 v[66:69], v[196:199], v[106:109], v[66:69]
	v_mfma_f32_16x16x32_bf16 v[70:73], v[204:207], v[106:109], v[70:73]
	v_mfma_f32_16x16x32_bf16 v[74:77], v[196:199], v[224:227], v[74:77]
	v_mfma_f32_16x16x32_bf16 v[78:81], v[204:207], v[224:227], v[78:81]
	v_mfma_f32_16x16x32_bf16 v[82:85], v[196:199], v[232:235], v[82:85]
	v_mfma_f32_16x16x32_bf16 v[86:89], v[204:207], v[232:235], v[86:89]
	v_mfma_f32_16x16x32_bf16 v[90:93], v[196:199], v[240:243], v[90:93]
	v_mfma_f32_16x16x32_bf16 v[94:97], v[204:207], v[240:243], v[94:97]
	v_mfma_f32_16x16x32_bf16 v[98:101], v[208:211], v[102:105], v[114:117]
	v_mfma_f32_16x16x32_bf16 v[102:105], v[216:219], v[102:105], v[122:125]
	v_mfma_f32_16x16x32_bf16 v[98:101], v[212:215], v[106:109], v[98:101]
	v_mfma_f32_16x16x32_bf16 v[102:105], v[220:223], v[106:109], v[102:105]
	v_mfma_f32_16x16x32_bf16 v[106:109], v[208:211], v[110:113], v[176:179]
	v_mfma_f32_16x16x32_bf16 v[110:113], v[216:219], v[110:113], v[180:183]
	v_mfma_f32_16x16x32_bf16 v[114:117], v[208:211], v[228:231], v[184:187]
	v_mfma_f32_16x16x32_bf16 v[118:121], v[216:219], v[228:231], v[118:121]
	v_mfma_f32_16x16x32_bf16 v[122:125], v[208:211], v[236:239], v[188:191]
	v_mfma_f32_16x16x32_bf16 v[126:129], v[216:219], v[236:239], v[126:129]
	v_mfma_f32_16x16x32_bf16 v[106:109], v[212:215], v[224:227], v[106:109]
	v_mfma_f32_16x16x32_bf16 v[110:113], v[220:223], v[224:227], v[110:113]
	v_mfma_f32_16x16x32_bf16 v[114:117], v[212:215], v[232:235], v[114:117]
	v_mfma_f32_16x16x32_bf16 v[118:121], v[220:223], v[232:235], v[118:121]
	s_setprio 2
	s_barrier
	v_mfma_f32_16x16x32_bf16 v[122:125], v[212:215], v[240:243], v[122:125]
	v_mfma_f32_16x16x32_bf16 v[126:129], v[220:223], v[240:243], v[126:129]
	s_setprio 0
	s_add_i32 s61, s61, 2
	s_cmp_ge_i32 s61, s60
	s_cbranch_scc0 .LBB0_462
	v_mov_b32_e32 v136, v130
	s_branch .LBB0_465

.LBB0_466:
	v_add_u32_e32 v133, s54, v140
	ds_read_b128 v[142:145], v133
	ds_read_b128 v[148:151], v133 offset:1024
	ds_read_b128 v[152:155], v133 offset:2048
	ds_read_b128 v[156:159], v133 offset:3072
	v_add_u32_e32 v133, s55, v140
	ds_read_b128 v[160:163], v133
	ds_read_b128 v[164:167], v133 offset:1024
	ds_read_b128 v[168:171], v133 offset:2048
	ds_read_b128 v[172:175], v133 offset:3072
	s_add_u32 s36, s34, 0xffc00080
	s_addc_u32 s37, s35, -1
	s_cmp_eq_u32 s42, 4
	s_cselect_b32 s39, s29, s37
	s_cselect_b32 s38, s28, s36
	s_cselect_b32 s37, s31, s41
	s_cselect_b32 s36, s30, s40
	s_mov_b32 m0, s52
	v_add_u32_e32 v141, 0, v1
	ds_read_b128 v[176:179], v141
	ds_read_b128 v[180:183], v141 offset:1024
	ds_read_b128 v[184:187], v141 offset:2048
	ds_read_b128 v[188:191], v141 offset:3072
	ds_read_b128 v[192:195], v141 offset:4096
	ds_read_b128 v[196:199], v141 offset:5120
	ds_read_b128 v[200:203], v141 offset:6144
	ds_read_b128 v[204:207], v141 offset:7168
	global_load_lds_dwordx4 v130, s[34:35]
	s_mov_b32 m0, s53
	v_mov_b32_e32 v133, v131
	global_load_lds_dwordx4 v132, s[34:35]
	s_waitcnt vmcnt(8)
	s_waitcnt lgkmcnt(0)
	s_barrier
	s_setprio 1
	v_mfma_f32_16x16x32_bf16 v[2:5], v[142:145], v[176:179], v[2:5]
	v_mfma_f32_16x16x32_bf16 v[2:5], v[148:151], v[180:183], v[2:5]
	v_mfma_f32_16x16x32_bf16 v[6:9], v[156:159], v[180:183], v[6:9]
	v_mfma_f32_16x16x32_bf16 v[6:9], v[152:155], v[176:179], v[6:9]
	v_mfma_f32_16x16x32_bf16 v[14:17], v[152:155], v[184:187], v[14:17]
	v_mfma_f32_16x16x32_bf16 v[14:17], v[156:159], v[188:191], v[14:17]
	v_mfma_f32_16x16x32_bf16 v[10:13], v[148:151], v[188:191], v[10:13]
	v_mfma_f32_16x16x32_bf16 v[10:13], v[142:145], v[184:187], v[10:13]
	v_mfma_f32_16x16x32_bf16 v[18:21], v[142:145], v[192:195], v[18:21]
	v_mfma_f32_16x16x32_bf16 v[18:21], v[148:151], v[196:199], v[18:21]
	v_mfma_f32_16x16x32_bf16 v[22:25], v[156:159], v[196:199], v[22:25]
	v_mfma_f32_16x16x32_bf16 v[22:25], v[152:155], v[192:195], v[22:25]
	v_mfma_f32_16x16x32_bf16 v[30:33], v[152:155], v[200:203], v[30:33]
	v_mfma_f32_16x16x32_bf16 v[30:33], v[156:159], v[204:207], v[30:33]
	v_mfma_f32_16x16x32_bf16 v[26:29], v[148:151], v[204:207], v[26:29]
	v_mfma_f32_16x16x32_bf16 v[26:29], v[142:145], v[200:203], v[26:29]
	v_mfma_f32_16x16x32_bf16 v[34:37], v[160:163], v[176:179], v[34:37]
	v_mfma_f32_16x16x32_bf16 v[34:37], v[164:167], v[180:183], v[34:37]
	v_mfma_f32_16x16x32_bf16 v[38:41], v[172:175], v[180:183], v[38:41]
	v_mfma_f32_16x16x32_bf16 v[38:41], v[168:171], v[176:179], v[38:41]
	v_mfma_f32_16x16x32_bf16 v[46:49], v[168:171], v[184:187], v[46:49]
	v_mfma_f32_16x16x32_bf16 v[46:49], v[172:175], v[188:191], v[46:49]
	v_mfma_f32_16x16x32_bf16 v[42:45], v[164:167], v[188:191], v[42:45]
	v_mfma_f32_16x16x32_bf16 v[42:45], v[160:163], v[184:187], v[42:45]
	v_mfma_f32_16x16x32_bf16 v[50:53], v[160:163], v[192:195], v[50:53]
	v_mfma_f32_16x16x32_bf16 v[50:53], v[164:167], v[196:199], v[50:53]
	v_mfma_f32_16x16x32_bf16 v[54:57], v[172:175], v[196:199], v[54:57]
	v_mfma_f32_16x16x32_bf16 v[54:57], v[168:171], v[192:195], v[54:57]
	v_mfma_f32_16x16x32_bf16 v[62:65], v[168:171], v[200:203], v[62:65]
	v_mfma_f32_16x16x32_bf16 v[62:65], v[172:175], v[204:207], v[62:65]
	s_setprio 2
	s_barrier
	v_mfma_f32_16x16x32_bf16 v[58:61], v[164:167], v[204:207], v[58:61]
	v_mfma_f32_16x16x32_bf16 v[58:61], v[160:163], v[200:203], v[58:61]
	s_setprio 0
	s_add_i32 s43, s54, s21
	s_mov_b32 m0, s43
	ds_read_b128 v[176:179], v141 offset:16384
	ds_read_b128 v[180:183], v141 offset:17408
	ds_read_b128 v[184:187], v141 offset:18432
	ds_read_b128 v[188:191], v141 offset:19456
	ds_read_b128 v[192:195], v141 offset:20480
	ds_read_b128 v[196:199], v141 offset:21504
	ds_read_b128 v[200:203], v141 offset:22528
	ds_read_b128 v[204:207], v141 offset:23552
	global_load_lds_dwordx4 v136, s[36:37]
	s_add_i32 m0, s43, 0x2000
	s_add_u32 s60, s36, 0x80000
	s_addc_u32 s61, s37, 0
	s_add_i32 s43, s55, s21
	global_load_lds_dwordx4 v134, s[36:37]
	s_mov_b32 m0, s43
	v_mov_b32_e32 v137, v131
	global_load_lds_dwordx4 v136, s[60:61]
	s_add_i32 m0, s43, 0x2000
	v_mov_b32_e32 v135, v131
	global_load_lds_dwordx4 v134, s[60:61]
	s_mov_b32 m0, s33
	v_lshl_add_u64 v[138:139], s[36:37], 0, v[136:137]
	global_load_lds_dwordx4 v130, s[38:39]
	s_mov_b32 m0, s44
	v_lshl_add_u64 v[208:209], s[36:37], 0, v[134:135]
	global_load_lds_dwordx4 v132, s[38:39]
	s_waitcnt vmcnt(8)
	s_waitcnt lgkmcnt(0)
	v_lshl_add_u64 v[210:211], s[38:39], 0, v[130:131]
	v_lshl_add_u64 v[212:213], s[38:39], 0, v[132:133]
	s_barrier
	s_setprio 1
	v_mfma_f32_16x16x32_bf16 v[66:69], v[142:145], v[176:179], v[66:69]
	v_mfma_f32_16x16x32_bf16 v[66:69], v[148:151], v[180:183], v[66:69]
	v_mfma_f32_16x16x32_bf16 v[70:73], v[156:159], v[180:183], v[70:73]
	v_mfma_f32_16x16x32_bf16 v[70:73], v[152:155], v[176:179], v[70:73]
	v_mfma_f32_16x16x32_bf16 v[78:81], v[152:155], v[184:187], v[78:81]
	v_mfma_f32_16x16x32_bf16 v[78:81], v[156:159], v[188:191], v[78:81]
	v_mfma_f32_16x16x32_bf16 v[74:77], v[148:151], v[188:191], v[74:77]
	v_mfma_f32_16x16x32_bf16 v[74:77], v[142:145], v[184:187], v[74:77]
	v_mfma_f32_16x16x32_bf16 v[82:85], v[142:145], v[192:195], v[82:85]
	v_mfma_f32_16x16x32_bf16 v[82:85], v[148:151], v[196:199], v[82:85]
	v_mfma_f32_16x16x32_bf16 v[86:89], v[156:159], v[196:199], v[86:89]
	v_mfma_f32_16x16x32_bf16 v[86:89], v[152:155], v[192:195], v[86:89]
	v_mfma_f32_16x16x32_bf16 v[94:97], v[152:155], v[200:203], v[94:97]
	v_mfma_f32_16x16x32_bf16 v[94:97], v[156:159], v[204:207], v[94:97]
	v_mfma_f32_16x16x32_bf16 v[90:93], v[148:151], v[204:207], v[90:93]
	v_mfma_f32_16x16x32_bf16 v[90:93], v[142:145], v[200:203], v[90:93]
	v_mfma_f32_16x16x32_bf16 v[98:101], v[160:163], v[176:179], v[98:101]
	v_mfma_f32_16x16x32_bf16 v[98:101], v[164:167], v[180:183], v[98:101]
	v_mfma_f32_16x16x32_bf16 v[102:105], v[172:175], v[180:183], v[102:105]
	v_mfma_f32_16x16x32_bf16 v[102:105], v[168:171], v[176:179], v[102:105]
	v_mfma_f32_16x16x32_bf16 v[110:113], v[168:171], v[184:187], v[110:113]
	v_mfma_f32_16x16x32_bf16 v[110:113], v[172:175], v[188:191], v[110:113]
	v_mfma_f32_16x16x32_bf16 v[106:109], v[164:167], v[188:191], v[106:109]
	v_mfma_f32_16x16x32_bf16 v[106:109], v[160:163], v[184:187], v[106:109]
	v_mfma_f32_16x16x32_bf16 v[114:117], v[160:163], v[192:195], v[114:117]
	v_mfma_f32_16x16x32_bf16 v[114:117], v[164:167], v[196:199], v[114:117]
	v_mfma_f32_16x16x32_bf16 v[118:121], v[172:175], v[196:199], v[118:121]
	v_mfma_f32_16x16x32_bf16 v[118:121], v[168:171], v[192:195], v[118:121]
	v_mfma_f32_16x16x32_bf16 v[126:129], v[168:171], v[200:203], v[126:129]
	v_mfma_f32_16x16x32_bf16 v[126:129], v[172:175], v[204:207], v[126:129]
	s_setprio 2
	s_barrier
	v_mfma_f32_16x16x32_bf16 v[122:125], v[164:167], v[204:207], v[122:125]
	v_mfma_f32_16x16x32_bf16 v[122:125], v[160:163], v[200:203], v[122:125]
	s_setprio 0
	s_add_i32 s43, 0, 0x18000
	v_add_u32_e32 v135, s43, v140
	s_add_i32 s60, 0, 0x1c000
	ds_read_b128 v[142:145], v135
	ds_read_b128 v[148:151], v135 offset:1024
	ds_read_b128 v[152:155], v135 offset:2048
	ds_read_b128 v[156:159], v135 offset:3072
	v_add_u32_e32 v135, s60, v140
	ds_read_b128 v[160:163], v135
	ds_read_b128 v[164:167], v135 offset:1024
	ds_read_b128 v[168:171], v135 offset:2048
	ds_read_b128 v[172:175], v135 offset:3072
	s_add_u32 s38, s38, 0x400000
	s_addc_u32 s39, s39, 0
	s_mov_b32 m0, s45
	ds_read_b128 v[176:179], v141 offset:32768
	ds_read_b128 v[180:183], v141 offset:33792
	ds_read_b128 v[184:187], v141 offset:34816
	ds_read_b128 v[188:191], v141 offset:35840
	ds_read_b128 v[192:195], v141 offset:36864
	ds_read_b128 v[196:199], v141 offset:37888
	ds_read_b128 v[200:203], v141 offset:38912
	ds_read_b128 v[204:207], v141 offset:39936
	global_load_lds_dwordx4 v130, s[38:39]
	s_mov_b32 m0, s46
	s_nop 0
	global_load_lds_dwordx4 v132, s[38:39]
	s_waitcnt vmcnt(8)
	s_waitcnt lgkmcnt(0)
	s_barrier
	s_setprio 1
	v_mfma_f32_16x16x32_bf16 v[2:5], v[142:145], v[176:179], v[2:5]
	v_mfma_f32_16x16x32_bf16 v[2:5], v[148:151], v[180:183], v[2:5]
	v_mfma_f32_16x16x32_bf16 v[6:9], v[156:159], v[180:183], v[6:9]
	v_mfma_f32_16x16x32_bf16 v[6:9], v[152:155], v[176:179], v[6:9]
	v_mfma_f32_16x16x32_bf16 v[14:17], v[152:155], v[184:187], v[14:17]
	v_mfma_f32_16x16x32_bf16 v[14:17], v[156:159], v[188:191], v[14:17]
	v_mfma_f32_16x16x32_bf16 v[10:13], v[148:151], v[188:191], v[10:13]
	v_mfma_f32_16x16x32_bf16 v[10:13], v[142:145], v[184:187], v[10:13]
	v_mfma_f32_16x16x32_bf16 v[18:21], v[142:145], v[192:195], v[18:21]
	v_mfma_f32_16x16x32_bf16 v[18:21], v[148:151], v[196:199], v[18:21]
	v_mfma_f32_16x16x32_bf16 v[22:25], v[156:159], v[196:199], v[22:25]
	v_mfma_f32_16x16x32_bf16 v[22:25], v[152:155], v[192:195], v[22:25]
	v_mfma_f32_16x16x32_bf16 v[30:33], v[152:155], v[200:203], v[30:33]
	v_mfma_f32_16x16x32_bf16 v[30:33], v[156:159], v[204:207], v[30:33]
	v_mfma_f32_16x16x32_bf16 v[26:29], v[148:151], v[204:207], v[26:29]
	v_mfma_f32_16x16x32_bf16 v[26:29], v[142:145], v[200:203], v[26:29]
	v_mfma_f32_16x16x32_bf16 v[34:37], v[160:163], v[176:179], v[34:37]
	v_mfma_f32_16x16x32_bf16 v[34:37], v[164:167], v[180:183], v[34:37]
	v_mfma_f32_16x16x32_bf16 v[38:41], v[172:175], v[180:183], v[38:41]
	v_mfma_f32_16x16x32_bf16 v[38:41], v[168:171], v[176:179], v[38:41]
	v_mfma_f32_16x16x32_bf16 v[46:49], v[168:171], v[184:187], v[46:49]
	v_mfma_f32_16x16x32_bf16 v[46:49], v[172:175], v[188:191], v[46:49]
	v_mfma_f32_16x16x32_bf16 v[42:45], v[164:167], v[188:191], v[42:45]
	v_mfma_f32_16x16x32_bf16 v[42:45], v[160:163], v[184:187], v[42:45]
	v_mfma_f32_16x16x32_bf16 v[50:53], v[160:163], v[192:195], v[50:53]
	v_mfma_f32_16x16x32_bf16 v[50:53], v[164:167], v[196:199], v[50:53]
	v_mfma_f32_16x16x32_bf16 v[54:57], v[172:175], v[196:199], v[54:57]
	v_mfma_f32_16x16x32_bf16 v[54:57], v[168:171], v[192:195], v[54:57]
	v_mfma_f32_16x16x32_bf16 v[62:65], v[168:171], v[200:203], v[62:65]
	v_mfma_f32_16x16x32_bf16 v[62:65], v[172:175], v[204:207], v[62:65]
	s_setprio 2
	s_barrier
	v_mfma_f32_16x16x32_bf16 v[58:61], v[164:167], v[204:207], v[58:61]
	v_mfma_f32_16x16x32_bf16 v[58:61], v[160:163], v[200:203], v[58:61]
	s_setprio 0
	s_add_i32 s38, s43, s21
	v_lshl_add_u64 v[138:139], v[138:139], 0, s[8:9]
	s_mov_b32 m0, s38
	ds_read_b128 v[176:179], v141 offset:49152
	ds_read_b128 v[180:183], v141 offset:50176
	ds_read_b128 v[184:187], v141 offset:51200
	ds_read_b128 v[188:191], v141 offset:52224
	ds_read_b128 v[192:195], v141 offset:53248
	ds_read_b128 v[196:199], v141 offset:54272
	ds_read_b128 v[200:203], v141 offset:55296
	ds_read_b128 v[204:207], v141 offset:56320
	global_load_lds_dwordx4 v[138:139], off
	s_add_i32 m0, s38, 0x2000
	s_add_u32 s36, s36, 0x80080
	v_lshl_add_u64 v[138:139], v[208:209], 0, s[8:9]
	s_addc_u32 s37, s37, 0
	s_add_i32 s38, s60, s21
	global_load_lds_dwordx4 v[138:139], off
	s_mov_b32 m0, s38
	v_lshl_add_u64 v[138:139], v[210:211], 0, s[8:9]
	global_load_lds_dwordx4 v136, s[36:37]
	s_add_i32 m0, s38, 0x2000
	s_nop 0
	global_load_lds_dwordx4 v134, s[36:37]
	s_mov_b32 m0, s50
	s_nop 0
	global_load_lds_dwordx4 v[138:139], off
	v_lshl_add_u64 v[138:139], v[212:213], 0, s[8:9]
	s_mov_b32 m0, s51
	s_nop 0
	global_load_lds_dwordx4 v[138:139], off
	s_waitcnt vmcnt(8)
	s_waitcnt lgkmcnt(0)
	s_barrier
	s_setprio 1
	v_mfma_f32_16x16x32_bf16 v[66:69], v[142:145], v[176:179], v[66:69]
	v_mfma_f32_16x16x32_bf16 v[66:69], v[148:151], v[180:183], v[66:69]
	v_mfma_f32_16x16x32_bf16 v[70:73], v[156:159], v[180:183], v[70:73]
	v_mfma_f32_16x16x32_bf16 v[70:73], v[152:155], v[176:179], v[70:73]
	v_mfma_f32_16x16x32_bf16 v[78:81], v[152:155], v[184:187], v[78:81]
	v_mfma_f32_16x16x32_bf16 v[78:81], v[156:159], v[188:191], v[78:81]
	v_mfma_f32_16x16x32_bf16 v[74:77], v[148:151], v[188:191], v[74:77]
	v_mfma_f32_16x16x32_bf16 v[74:77], v[142:145], v[184:187], v[74:77]
	v_mfma_f32_16x16x32_bf16 v[82:85], v[142:145], v[192:195], v[82:85]
	v_mfma_f32_16x16x32_bf16 v[82:85], v[148:151], v[196:199], v[82:85]
	v_mfma_f32_16x16x32_bf16 v[86:89], v[156:159], v[196:199], v[86:89]
	v_mfma_f32_16x16x32_bf16 v[86:89], v[152:155], v[192:195], v[86:89]
	v_mfma_f32_16x16x32_bf16 v[94:97], v[152:155], v[200:203], v[94:97]
	v_mfma_f32_16x16x32_bf16 v[94:97], v[156:159], v[204:207], v[94:97]
	v_mfma_f32_16x16x32_bf16 v[90:93], v[148:151], v[204:207], v[90:93]
	v_mfma_f32_16x16x32_bf16 v[90:93], v[142:145], v[200:203], v[90:93]
	v_mfma_f32_16x16x32_bf16 v[98:101], v[160:163], v[176:179], v[98:101]
	v_mfma_f32_16x16x32_bf16 v[98:101], v[164:167], v[180:183], v[98:101]
	v_mfma_f32_16x16x32_bf16 v[102:105], v[172:175], v[180:183], v[102:105]
	v_mfma_f32_16x16x32_bf16 v[102:105], v[168:171], v[176:179], v[102:105]
	v_mfma_f32_16x16x32_bf16 v[110:113], v[168:171], v[184:187], v[110:113]
	v_mfma_f32_16x16x32_bf16 v[110:113], v[172:175], v[188:191], v[110:113]
	v_mfma_f32_16x16x32_bf16 v[106:109], v[164:167], v[188:191], v[106:109]
	v_mfma_f32_16x16x32_bf16 v[106:109], v[160:163], v[184:187], v[106:109]
	v_mfma_f32_16x16x32_bf16 v[114:117], v[160:163], v[192:195], v[114:117]
	v_mfma_f32_16x16x32_bf16 v[114:117], v[164:167], v[196:199], v[114:117]
	v_mfma_f32_16x16x32_bf16 v[118:121], v[172:175], v[196:199], v[118:121]
	v_mfma_f32_16x16x32_bf16 v[118:121], v[168:171], v[192:195], v[118:121]
	v_mfma_f32_16x16x32_bf16 v[126:129], v[168:171], v[200:203], v[126:129]
	v_mfma_f32_16x16x32_bf16 v[126:129], v[172:175], v[204:207], v[126:129]
	s_setprio 2
	s_barrier
	v_mfma_f32_16x16x32_bf16 v[122:125], v[164:167], v[204:207], v[122:125]
	v_mfma_f32_16x16x32_bf16 v[122:125], v[160:163], v[200:203], v[122:125]
	s_setprio 0
	s_add_i32 s42, s42, 2
	s_add_u32 s34, s34, 0x100
	s_addc_u32 s35, s35, 0
	s_add_u32 s40, s40, 0x100
	s_addc_u32 s41, s41, 0
	s_cmp_gt_u32 s42, 5
	s_cbranch_scc0 .LBB0_466
	s_and_b64 vcc, exec, s[10:11]
	s_cbranch_vccz .LBB0_469
	s_barrier

.LBB0_495:
	v_add_u32_e32 v14, s58, v140
	v_add_u32_e32 v30, s59, v140
	ds_read_b128 v[2:5], v14
	ds_read_b128 v[6:9], v14 offset:1024
	ds_read_b128 v[10:13], v14 offset:2048
	ds_read_b128 v[14:17], v14 offset:3072
	ds_read_b128 v[18:21], v30
	ds_read_b128 v[22:25], v30 offset:1024
	ds_read_b128 v[26:29], v30 offset:2048
	ds_read_b128 v[30:33], v30 offset:3072
	v_add_u32_e32 v141, 0, v1
	ds_read_b128 v[34:37], v141
	ds_read_b128 v[38:41], v141 offset:1024
	ds_read_b128 v[42:45], v141 offset:2048
	ds_read_b128 v[46:49], v141 offset:3072
	ds_read_b128 v[50:53], v141 offset:4096
	ds_read_b128 v[54:57], v141 offset:5120
	ds_read_b128 v[58:61], v141 offset:6144
	ds_read_b128 v[62:65], v141 offset:7168
	s_waitcnt vmcnt(8)
	s_waitcnt lgkmcnt(0)
	s_barrier
	s_setprio 1
	v_mfma_f32_16x16x32_bf16 v[66:69], v[2:5], v[34:37], 0
	v_mfma_f32_16x16x32_bf16 v[66:69], v[6:9], v[38:41], v[66:69]
	v_mfma_f32_16x16x32_bf16 v[70:73], v[10:13], v[34:37], 0
	v_mfma_f32_16x16x32_bf16 v[70:73], v[14:17], v[38:41], v[70:73]
	v_mfma_f32_16x16x32_bf16 v[78:81], v[10:13], v[42:45], 0
	v_mfma_f32_16x16x32_bf16 v[78:81], v[14:17], v[46:49], v[78:81]
	v_mfma_f32_16x16x32_bf16 v[74:77], v[2:5], v[42:45], 0
	v_mfma_f32_16x16x32_bf16 v[74:77], v[6:9], v[46:49], v[74:77]
	v_mfma_f32_16x16x32_bf16 v[82:85], v[2:5], v[50:53], 0
	v_mfma_f32_16x16x32_bf16 v[82:85], v[6:9], v[54:57], v[82:85]
	v_mfma_f32_16x16x32_bf16 v[86:89], v[10:13], v[50:53], 0
	v_mfma_f32_16x16x32_bf16 v[86:89], v[14:17], v[54:57], v[86:89]
	v_mfma_f32_16x16x32_bf16 v[94:97], v[10:13], v[58:61], 0
	v_mfma_f32_16x16x32_bf16 v[94:97], v[14:17], v[62:65], v[94:97]
	v_mfma_f32_16x16x32_bf16 v[90:93], v[2:5], v[58:61], 0
	v_mfma_f32_16x16x32_bf16 v[90:93], v[6:9], v[62:65], v[90:93]
	v_mfma_f32_16x16x32_bf16 v[98:101], v[18:21], v[34:37], 0
	v_mfma_f32_16x16x32_bf16 v[34:37], v[26:29], v[34:37], 0
	v_mfma_f32_16x16x32_bf16 v[102:105], v[18:21], v[42:45], 0
	v_mfma_f32_16x16x32_bf16 v[42:45], v[26:29], v[42:45], 0
	v_mfma_f32_16x16x32_bf16 v[106:109], v[18:21], v[50:53], 0
	v_mfma_f32_16x16x32_bf16 v[50:53], v[26:29], v[50:53], 0
	v_mfma_f32_16x16x32_bf16 v[110:113], v[18:21], v[58:61], 0
	v_mfma_f32_16x16x32_bf16 v[58:61], v[26:29], v[58:61], 0
	v_mfma_f32_16x16x32_bf16 v[98:101], v[22:25], v[38:41], v[98:101]
	v_mfma_f32_16x16x32_bf16 v[38:41], v[30:33], v[38:41], v[34:37]
	v_mfma_f32_16x16x32_bf16 v[102:105], v[22:25], v[46:49], v[102:105]
	v_mfma_f32_16x16x32_bf16 v[46:49], v[30:33], v[46:49], v[42:45]
	v_mfma_f32_16x16x32_bf16 v[106:109], v[22:25], v[54:57], v[106:109]
	v_mfma_f32_16x16x32_bf16 v[54:57], v[30:33], v[54:57], v[50:53]
	s_setprio 2
	s_barrier
	v_mfma_f32_16x16x32_bf16 v[110:113], v[22:25], v[62:65], v[110:113]
	v_mfma_f32_16x16x32_bf16 v[62:65], v[30:33], v[62:65], v[58:61]
	s_setprio 0
	v_lshl_add_u64 v[136:137], s[38:39], 0, v[130:131]
	s_add_i32 s62, s58, s46
	v_mov_b32_e32 v135, v131
	v_lshl_add_u64 v[142:143], v[136:137], 0, s[10:11]
	s_mov_b32 m0, s62
	v_lshl_add_u64 v[244:245], s[38:39], 0, v[134:135]
	ds_read_b128 v[34:37], v141 offset:16384
	ds_read_b128 v[42:45], v141 offset:17408
	ds_read_b128 v[50:53], v141 offset:18432
	ds_read_b128 v[58:61], v141 offset:19456
	ds_read_b128 v[114:117], v141 offset:20480
	ds_read_b128 v[118:121], v141 offset:21504
	ds_read_b128 v[122:125], v141 offset:22528
	ds_read_b128 v[126:129], v141 offset:23552
	global_load_lds_dwordx4 v[142:143], off
	v_lshl_add_u64 v[142:143], v[244:245], 0, s[10:11]
	s_add_i32 m0, s62, 0x2000
	s_add_i32 s62, s59, s46
	global_load_lds_dwordx4 v[142:143], off
	s_mov_b32 m0, s62
	v_mov_b32_e32 v139, v131
	global_load_lds_dwordx4 v130, s[40:41]
	s_add_i32 m0, s62, 0x2000
	v_lshl_add_u64 v[246:247], s[36:37], 0, v[138:139]
	v_mov_b32_e32 v133, v131
	global_load_lds_dwordx4 v134, s[40:41]
	v_lshl_add_u64 v[142:143], v[246:247], 0, s[10:11]
	s_mov_b32 m0, s47
	v_lshl_add_u64 v[248:249], s[36:37], 0, v[132:133]
	global_load_lds_dwordx4 v[142:143], off
	v_lshl_add_u64 v[142:143], v[248:249], 0, s[10:11]
	s_mov_b32 m0, s48
	s_nop 0
	global_load_lds_dwordx4 v[142:143], off
	s_waitcnt vmcnt(8)
	s_waitcnt lgkmcnt(0)
	s_barrier
	s_setprio 1
	v_mfma_f32_16x16x32_bf16 v[142:145], v[2:5], v[34:37], 0
	v_mfma_f32_16x16x32_bf16 v[148:151], v[10:13], v[34:37], 0
	v_mfma_f32_16x16x32_bf16 v[152:155], v[2:5], v[50:53], 0
	v_mfma_f32_16x16x32_bf16 v[156:159], v[10:13], v[50:53], 0
	v_mfma_f32_16x16x32_bf16 v[160:163], v[2:5], v[114:117], 0
	v_mfma_f32_16x16x32_bf16 v[164:167], v[10:13], v[114:117], 0
	v_mfma_f32_16x16x32_bf16 v[2:5], v[2:5], v[122:125], 0
	v_mfma_f32_16x16x32_bf16 v[10:13], v[10:13], v[122:125], 0
	v_mfma_f32_16x16x32_bf16 v[142:145], v[6:9], v[42:45], v[142:145]
	v_mfma_f32_16x16x32_bf16 v[148:151], v[14:17], v[42:45], v[148:151]
	v_mfma_f32_16x16x32_bf16 v[152:155], v[6:9], v[58:61], v[152:155]
	v_mfma_f32_16x16x32_bf16 v[156:159], v[14:17], v[58:61], v[156:159]
	v_mfma_f32_16x16x32_bf16 v[160:163], v[6:9], v[118:121], v[160:163]
	v_mfma_f32_16x16x32_bf16 v[164:167], v[14:17], v[118:121], v[164:167]
	v_mfma_f32_16x16x32_bf16 v[168:171], v[6:9], v[126:129], v[2:5]
	v_mfma_f32_16x16x32_bf16 v[172:175], v[14:17], v[126:129], v[10:13]
	v_mfma_f32_16x16x32_bf16 v[2:5], v[18:21], v[34:37], 0
	v_mfma_f32_16x16x32_bf16 v[6:9], v[26:29], v[34:37], 0
	v_mfma_f32_16x16x32_bf16 v[10:13], v[18:21], v[50:53], 0
	v_mfma_f32_16x16x32_bf16 v[14:17], v[26:29], v[50:53], 0
	v_mfma_f32_16x16x32_bf16 v[34:37], v[18:21], v[114:117], 0
	v_mfma_f32_16x16x32_bf16 v[50:53], v[26:29], v[114:117], 0
	v_mfma_f32_16x16x32_bf16 v[18:21], v[18:21], v[122:125], 0
	v_mfma_f32_16x16x32_bf16 v[26:29], v[26:29], v[122:125], 0
	v_mfma_f32_16x16x32_bf16 v[114:117], v[22:25], v[42:45], v[2:5]
	v_mfma_f32_16x16x32_bf16 v[122:125], v[30:33], v[42:45], v[6:9]
	v_mfma_f32_16x16x32_bf16 v[184:187], v[22:25], v[118:121], v[34:37]
	v_mfma_f32_16x16x32_bf16 v[118:121], v[30:33], v[118:121], v[50:53]
	v_mfma_f32_16x16x32_bf16 v[188:191], v[22:25], v[126:129], v[18:21]
	v_mfma_f32_16x16x32_bf16 v[126:129], v[30:33], v[126:129], v[26:29]
	s_setprio 2
	s_barrier
	v_mfma_f32_16x16x32_bf16 v[176:179], v[22:25], v[58:61], v[10:13]
	v_mfma_f32_16x16x32_bf16 v[180:183], v[30:33], v[58:61], v[14:17]
	s_setprio 0
	s_add_i32 s62, 0, 0x18000
	v_add_u32_e32 v2, s62, v140
	s_add_i32 s63, 0, 0x1c000
	ds_read_b128 v[192:195], v2
	ds_read_b128 v[196:199], v2 offset:1024
	ds_read_b128 v[200:203], v2 offset:2048
	ds_read_b128 v[204:207], v2 offset:3072
	v_add_u32_e32 v2, s63, v140
	ds_read_b128 v[208:211], v2
	ds_read_b128 v[212:215], v2 offset:1024
	ds_read_b128 v[216:219], v2 offset:2048
	ds_read_b128 v[220:223], v2 offset:3072
	s_mov_b32 m0, s49
	ds_read_b128 v[42:45], v141 offset:32768
	ds_read_b128 v[50:53], v141 offset:33792
	ds_read_b128 v[58:61], v141 offset:34816
	ds_read_b128 v[224:227], v141 offset:35840
	ds_read_b128 v[228:231], v141 offset:36864
	ds_read_b128 v[232:235], v141 offset:37888
	ds_read_b128 v[236:239], v141 offset:38912
	ds_read_b128 v[240:243], v141 offset:39936
	global_load_lds_dwordx4 v138, s[42:43]
	s_mov_b32 m0, s50
	s_nop 0
	global_load_lds_dwordx4 v132, s[42:43]
	s_waitcnt vmcnt(8)
	s_waitcnt lgkmcnt(0)
	s_barrier
	s_setprio 1
	v_mfma_f32_16x16x32_bf16 v[2:5], v[192:195], v[42:45], v[66:69]
	v_mfma_f32_16x16x32_bf16 v[6:9], v[200:203], v[42:45], v[70:73]
	v_mfma_f32_16x16x32_bf16 v[10:13], v[192:195], v[58:61], v[74:77]
	v_mfma_f32_16x16x32_bf16 v[14:17], v[200:203], v[58:61], v[78:81]
	v_mfma_f32_16x16x32_bf16 v[18:21], v[192:195], v[228:231], v[82:85]
	v_mfma_f32_16x16x32_bf16 v[22:25], v[200:203], v[228:231], v[86:89]
	v_mfma_f32_16x16x32_bf16 v[26:29], v[192:195], v[236:239], v[90:93]
	v_mfma_f32_16x16x32_bf16 v[30:33], v[200:203], v[236:239], v[94:97]
	v_mfma_f32_16x16x32_bf16 v[2:5], v[196:199], v[50:53], v[2:5]
	v_mfma_f32_16x16x32_bf16 v[6:9], v[204:207], v[50:53], v[6:9]
	v_mfma_f32_16x16x32_bf16 v[10:13], v[196:199], v[224:227], v[10:13]
	v_mfma_f32_16x16x32_bf16 v[14:17], v[204:207], v[224:227], v[14:17]
	v_mfma_f32_16x16x32_bf16 v[18:21], v[196:199], v[232:235], v[18:21]
	v_mfma_f32_16x16x32_bf16 v[22:25], v[204:207], v[232:235], v[22:25]
	v_mfma_f32_16x16x32_bf16 v[26:29], v[196:199], v[240:243], v[26:29]
	v_mfma_f32_16x16x32_bf16 v[30:33], v[204:207], v[240:243], v[30:33]
	v_mfma_f32_16x16x32_bf16 v[34:37], v[208:211], v[42:45], v[98:101]
	v_mfma_f32_16x16x32_bf16 v[38:41], v[216:219], v[42:45], v[38:41]
	v_mfma_f32_16x16x32_bf16 v[34:37], v[212:215], v[50:53], v[34:37]
	v_mfma_f32_16x16x32_bf16 v[38:41], v[220:223], v[50:53], v[38:41]
	v_mfma_f32_16x16x32_bf16 v[42:45], v[208:211], v[58:61], v[102:105]
	v_mfma_f32_16x16x32_bf16 v[46:49], v[216:219], v[58:61], v[46:49]
	v_mfma_f32_16x16x32_bf16 v[50:53], v[208:211], v[228:231], v[106:109]
	v_mfma_f32_16x16x32_bf16 v[54:57], v[216:219], v[228:231], v[54:57]
	v_mfma_f32_16x16x32_bf16 v[58:61], v[208:211], v[236:239], v[110:113]
	v_mfma_f32_16x16x32_bf16 v[62:65], v[216:219], v[236:239], v[62:65]
	v_mfma_f32_16x16x32_bf16 v[42:45], v[212:215], v[224:227], v[42:45]
	v_mfma_f32_16x16x32_bf16 v[46:49], v[220:223], v[224:227], v[46:49]
	v_mfma_f32_16x16x32_bf16 v[50:53], v[212:215], v[232:235], v[50:53]
	v_mfma_f32_16x16x32_bf16 v[54:57], v[220:223], v[232:235], v[54:57]
	s_setprio 2
	s_barrier
	v_mfma_f32_16x16x32_bf16 v[58:61], v[212:215], v[240:243], v[58:61]
	v_mfma_f32_16x16x32_bf16 v[62:65], v[220:223], v[240:243], v[62:65]
	s_setprio 0
	s_add_i32 s62, s62, s46
	v_lshl_add_u64 v[66:67], v[136:137], 0, s[12:13]
	s_mov_b32 m0, s62
	ds_read_b128 v[102:105], v141 offset:49152
	ds_read_b128 v[106:109], v141 offset:50176
	ds_read_b128 v[110:113], v141 offset:51200
	ds_read_b128 v[224:227], v141 offset:52224
	ds_read_b128 v[228:231], v141 offset:53248
	ds_read_b128 v[232:235], v141 offset:54272
	ds_read_b128 v[236:239], v141 offset:55296
	ds_read_b128 v[240:243], v141 offset:56320
	global_load_lds_dwordx4 v[66:67], off
	v_lshl_add_u64 v[66:67], v[244:245], 0, s[12:13]
	s_add_i32 m0, s62, 0x2000
	s_add_i32 s62, s63, s46
	global_load_lds_dwordx4 v[66:67], off
	s_mov_b32 m0, s62
	v_lshl_add_u64 v[66:67], v[246:247], 0, s[12:13]
	global_load_lds_dwordx4 v130, s[44:45]
	s_add_i32 m0, s62, 0x2000
	s_nop 0
	global_load_lds_dwordx4 v134, s[44:45]
	s_mov_b32 m0, s54
	s_nop 0
	global_load_lds_dwordx4 v[66:67], off
	v_lshl_add_u64 v[66:67], v[248:249], 0, s[12:13]
	s_mov_b32 m0, s55
	s_nop 0
	global_load_lds_dwordx4 v[66:67], off
	s_waitcnt vmcnt(8)
	s_waitcnt lgkmcnt(0)
	s_barrier
	s_setprio 1
	v_mfma_f32_16x16x32_bf16 v[66:69], v[192:195], v[102:105], v[142:145]
	v_mfma_f32_16x16x32_bf16 v[70:73], v[200:203], v[102:105], v[148:151]
	v_mfma_f32_16x16x32_bf16 v[74:77], v[192:195], v[110:113], v[152:155]
	v_mfma_f32_16x16x32_bf16 v[78:81], v[200:203], v[110:113], v[156:159]
	v_mfma_f32_16x16x32_bf16 v[82:85], v[192:195], v[228:231], v[160:163]
	v_mfma_f32_16x16x32_bf16 v[86:89], v[200:203], v[228:231], v[164:167]
	v_mfma_f32_16x16x32_bf16 v[90:93], v[192:195], v[236:239], v[168:171]
	v_mfma_f32_16x16x32_bf16 v[94:97], v[200:203], v[236:239], v[172:175]
	v_mfma_f32_16x16x32_bf16 v[66:69], v[196:199], v[106:109], v[66:69]
	v_mfma_f32_16x16x32_bf16 v[70:73], v[204:207], v[106:109], v[70:73]
	v_mfma_f32_16x16x32_bf16 v[74:77], v[196:199], v[224:227], v[74:77]
	v_mfma_f32_16x16x32_bf16 v[78:81], v[204:207], v[224:227], v[78:81]
	v_mfma_f32_16x16x32_bf16 v[82:85], v[196:199], v[232:235], v[82:85]
	v_mfma_f32_16x16x32_bf16 v[86:89], v[204:207], v[232:235], v[86:89]
	v_mfma_f32_16x16x32_bf16 v[90:93], v[196:199], v[240:243], v[90:93]
	v_mfma_f32_16x16x32_bf16 v[94:97], v[204:207], v[240:243], v[94:97]
	v_mfma_f32_16x16x32_bf16 v[98:101], v[208:211], v[102:105], v[114:117]
	v_mfma_f32_16x16x32_bf16 v[102:105], v[216:219], v[102:105], v[122:125]
	v_mfma_f32_16x16x32_bf16 v[98:101], v[212:215], v[106:109], v[98:101]
	v_mfma_f32_16x16x32_bf16 v[102:105], v[220:223], v[106:109], v[102:105]
	v_mfma_f32_16x16x32_bf16 v[106:109], v[208:211], v[110:113], v[176:179]
	v_mfma_f32_16x16x32_bf16 v[110:113], v[216:219], v[110:113], v[180:183]
	v_mfma_f32_16x16x32_bf16 v[114:117], v[208:211], v[228:231], v[184:187]
	v_mfma_f32_16x16x32_bf16 v[118:121], v[216:219], v[228:231], v[118:121]
	v_mfma_f32_16x16x32_bf16 v[122:125], v[208:211], v[236:239], v[188:191]
	v_mfma_f32_16x16x32_bf16 v[126:129], v[216:219], v[236:239], v[126:129]
	v_mfma_f32_16x16x32_bf16 v[106:109], v[212:215], v[224:227], v[106:109]
	v_mfma_f32_16x16x32_bf16 v[110:113], v[220:223], v[224:227], v[110:113]
	v_mfma_f32_16x16x32_bf16 v[114:117], v[212:215], v[232:235], v[114:117]
	v_mfma_f32_16x16x32_bf16 v[118:121], v[220:223], v[232:235], v[118:121]
	s_setprio 2
	s_barrier
	v_mfma_f32_16x16x32_bf16 v[122:125], v[212:215], v[240:243], v[122:125]
	v_mfma_f32_16x16x32_bf16 v[126:129], v[220:223], v[240:243], v[126:129]
	s_setprio 0
	s_add_i32 s27, s27, 2
	s_cmp_ge_i32 s27, s15
	s_cbranch_scc0 .LBB0_495
	v_mov_b32_e32 v136, v130
	s_branch .LBB0_498

.LBB0_499:
	v_add_u32_e32 v133, s58, v140
	ds_read_b128 v[142:145], v133
	ds_read_b128 v[148:151], v133 offset:1024
	ds_read_b128 v[152:155], v133 offset:2048
	ds_read_b128 v[156:159], v133 offset:3072
	v_add_u32_e32 v133, s59, v140
	ds_read_b128 v[160:163], v133
	ds_read_b128 v[164:167], v133 offset:1024
	ds_read_b128 v[168:171], v133 offset:2048
	ds_read_b128 v[172:175], v133 offset:3072
	s_add_u32 s38, s36, 0xfff80080
	s_addc_u32 s39, s37, -1
	s_cmp_eq_u32 s42, 4
	s_cselect_b32 s41, s31, s39
	s_cselect_b32 s40, s30, s38
	s_cselect_b32 s39, s35, s27
	s_cselect_b32 s38, s34, s15
	s_mov_b32 m0, s56
	v_add_u32_e32 v141, 0, v1
	ds_read_b128 v[176:179], v141
	ds_read_b128 v[180:183], v141 offset:1024
	ds_read_b128 v[184:187], v141 offset:2048
	ds_read_b128 v[188:191], v141 offset:3072
	ds_read_b128 v[192:195], v141 offset:4096
	ds_read_b128 v[196:199], v141 offset:5120
	ds_read_b128 v[200:203], v141 offset:6144
	ds_read_b128 v[204:207], v141 offset:7168
	global_load_lds_dwordx4 v130, s[36:37]
	s_mov_b32 m0, s57
	v_mov_b32_e32 v133, v131
	global_load_lds_dwordx4 v132, s[36:37]
	s_waitcnt vmcnt(8)
	s_waitcnt lgkmcnt(0)
	s_barrier
	s_setprio 1
	v_mfma_f32_16x16x32_bf16 v[2:5], v[142:145], v[176:179], v[2:5]
	v_mfma_f32_16x16x32_bf16 v[2:5], v[148:151], v[180:183], v[2:5]
	v_mfma_f32_16x16x32_bf16 v[6:9], v[156:159], v[180:183], v[6:9]
	v_mfma_f32_16x16x32_bf16 v[6:9], v[152:155], v[176:179], v[6:9]
	v_mfma_f32_16x16x32_bf16 v[14:17], v[152:155], v[184:187], v[14:17]
	v_mfma_f32_16x16x32_bf16 v[14:17], v[156:159], v[188:191], v[14:17]
	v_mfma_f32_16x16x32_bf16 v[10:13], v[148:151], v[188:191], v[10:13]
	v_mfma_f32_16x16x32_bf16 v[10:13], v[142:145], v[184:187], v[10:13]
	v_mfma_f32_16x16x32_bf16 v[18:21], v[142:145], v[192:195], v[18:21]
	v_mfma_f32_16x16x32_bf16 v[18:21], v[148:151], v[196:199], v[18:21]
	v_mfma_f32_16x16x32_bf16 v[22:25], v[156:159], v[196:199], v[22:25]
	v_mfma_f32_16x16x32_bf16 v[22:25], v[152:155], v[192:195], v[22:25]
	v_mfma_f32_16x16x32_bf16 v[30:33], v[152:155], v[200:203], v[30:33]
	v_mfma_f32_16x16x32_bf16 v[30:33], v[156:159], v[204:207], v[30:33]
	v_mfma_f32_16x16x32_bf16 v[26:29], v[148:151], v[204:207], v[26:29]
	v_mfma_f32_16x16x32_bf16 v[26:29], v[142:145], v[200:203], v[26:29]
	v_mfma_f32_16x16x32_bf16 v[34:37], v[160:163], v[176:179], v[34:37]
	v_mfma_f32_16x16x32_bf16 v[34:37], v[164:167], v[180:183], v[34:37]
	v_mfma_f32_16x16x32_bf16 v[38:41], v[172:175], v[180:183], v[38:41]
	v_mfma_f32_16x16x32_bf16 v[38:41], v[168:171], v[176:179], v[38:41]
	v_mfma_f32_16x16x32_bf16 v[46:49], v[168:171], v[184:187], v[46:49]
	v_mfma_f32_16x16x32_bf16 v[46:49], v[172:175], v[188:191], v[46:49]
	v_mfma_f32_16x16x32_bf16 v[42:45], v[164:167], v[188:191], v[42:45]
	v_mfma_f32_16x16x32_bf16 v[42:45], v[160:163], v[184:187], v[42:45]
	v_mfma_f32_16x16x32_bf16 v[50:53], v[160:163], v[192:195], v[50:53]
	v_mfma_f32_16x16x32_bf16 v[50:53], v[164:167], v[196:199], v[50:53]
	v_mfma_f32_16x16x32_bf16 v[54:57], v[172:175], v[196:199], v[54:57]
	v_mfma_f32_16x16x32_bf16 v[54:57], v[168:171], v[192:195], v[54:57]
	v_mfma_f32_16x16x32_bf16 v[62:65], v[168:171], v[200:203], v[62:65]
	v_mfma_f32_16x16x32_bf16 v[62:65], v[172:175], v[204:207], v[62:65]
	s_setprio 2
	s_barrier
	v_mfma_f32_16x16x32_bf16 v[58:61], v[164:167], v[204:207], v[58:61]
	v_mfma_f32_16x16x32_bf16 v[58:61], v[160:163], v[200:203], v[58:61]
	s_setprio 0
	s_add_i32 s43, s58, s46
	s_mov_b32 m0, s43
	ds_read_b128 v[176:179], v141 offset:16384
	ds_read_b128 v[180:183], v141 offset:17408
	ds_read_b128 v[184:187], v141 offset:18432
	ds_read_b128 v[188:191], v141 offset:19456
	ds_read_b128 v[192:195], v141 offset:20480
	ds_read_b128 v[196:199], v141 offset:21504
	ds_read_b128 v[200:203], v141 offset:22528
	ds_read_b128 v[204:207], v141 offset:23552
	global_load_lds_dwordx4 v136, s[38:39]
	s_add_i32 m0, s43, 0x2000
	s_add_u32 s44, s38, 0x400000
	s_addc_u32 s45, s39, 0
	s_add_i32 s43, s59, s46
	global_load_lds_dwordx4 v134, s[38:39]
	s_mov_b32 m0, s43
	v_mov_b32_e32 v137, v131
	global_load_lds_dwordx4 v136, s[44:45]
	s_add_i32 m0, s43, 0x2000
	v_mov_b32_e32 v135, v131
	global_load_lds_dwordx4 v134, s[44:45]
	s_mov_b32 m0, s47
	v_lshl_add_u64 v[138:139], s[38:39], 0, v[136:137]
	global_load_lds_dwordx4 v130, s[40:41]
	s_mov_b32 m0, s48
	v_lshl_add_u64 v[208:209], s[38:39], 0, v[134:135]
	global_load_lds_dwordx4 v132, s[40:41]
	s_waitcnt vmcnt(8)
	s_waitcnt lgkmcnt(0)
	v_lshl_add_u64 v[210:211], s[40:41], 0, v[130:131]
	v_lshl_add_u64 v[212:213], s[40:41], 0, v[132:133]
	s_barrier
	s_setprio 1
	v_mfma_f32_16x16x32_bf16 v[66:69], v[142:145], v[176:179], v[66:69]
	v_mfma_f32_16x16x32_bf16 v[66:69], v[148:151], v[180:183], v[66:69]
	v_mfma_f32_16x16x32_bf16 v[70:73], v[156:159], v[180:183], v[70:73]
	v_mfma_f32_16x16x32_bf16 v[70:73], v[152:155], v[176:179], v[70:73]
	v_mfma_f32_16x16x32_bf16 v[78:81], v[152:155], v[184:187], v[78:81]
	v_mfma_f32_16x16x32_bf16 v[78:81], v[156:159], v[188:191], v[78:81]
	v_mfma_f32_16x16x32_bf16 v[74:77], v[148:151], v[188:191], v[74:77]
	v_mfma_f32_16x16x32_bf16 v[74:77], v[142:145], v[184:187], v[74:77]
	v_mfma_f32_16x16x32_bf16 v[82:85], v[142:145], v[192:195], v[82:85]
	v_mfma_f32_16x16x32_bf16 v[82:85], v[148:151], v[196:199], v[82:85]
	v_mfma_f32_16x16x32_bf16 v[86:89], v[156:159], v[196:199], v[86:89]
	v_mfma_f32_16x16x32_bf16 v[86:89], v[152:155], v[192:195], v[86:89]
	v_mfma_f32_16x16x32_bf16 v[94:97], v[152:155], v[200:203], v[94:97]
	v_mfma_f32_16x16x32_bf16 v[94:97], v[156:159], v[204:207], v[94:97]
	v_mfma_f32_16x16x32_bf16 v[90:93], v[148:151], v[204:207], v[90:93]
	v_mfma_f32_16x16x32_bf16 v[90:93], v[142:145], v[200:203], v[90:93]
	v_mfma_f32_16x16x32_bf16 v[98:101], v[160:163], v[176:179], v[98:101]
	v_mfma_f32_16x16x32_bf16 v[98:101], v[164:167], v[180:183], v[98:101]
	v_mfma_f32_16x16x32_bf16 v[102:105], v[172:175], v[180:183], v[102:105]
	v_mfma_f32_16x16x32_bf16 v[102:105], v[168:171], v[176:179], v[102:105]
	v_mfma_f32_16x16x32_bf16 v[110:113], v[168:171], v[184:187], v[110:113]
	v_mfma_f32_16x16x32_bf16 v[110:113], v[172:175], v[188:191], v[110:113]
	v_mfma_f32_16x16x32_bf16 v[106:109], v[164:167], v[188:191], v[106:109]
	v_mfma_f32_16x16x32_bf16 v[106:109], v[160:163], v[184:187], v[106:109]
	v_mfma_f32_16x16x32_bf16 v[114:117], v[160:163], v[192:195], v[114:117]
	v_mfma_f32_16x16x32_bf16 v[114:117], v[164:167], v[196:199], v[114:117]
	v_mfma_f32_16x16x32_bf16 v[118:121], v[172:175], v[196:199], v[118:121]
	v_mfma_f32_16x16x32_bf16 v[118:121], v[168:171], v[192:195], v[118:121]
	v_mfma_f32_16x16x32_bf16 v[126:129], v[168:171], v[200:203], v[126:129]
	v_mfma_f32_16x16x32_bf16 v[126:129], v[172:175], v[204:207], v[126:129]
	s_setprio 2
	s_barrier
	v_mfma_f32_16x16x32_bf16 v[122:125], v[164:167], v[204:207], v[122:125]
	v_mfma_f32_16x16x32_bf16 v[122:125], v[160:163], v[200:203], v[122:125]
	s_setprio 0
	s_add_i32 s43, 0, 0x18000
	v_add_u32_e32 v135, s43, v140
	s_add_i32 s44, 0, 0x1c000
	ds_read_b128 v[142:145], v135
	ds_read_b128 v[148:151], v135 offset:1024
	ds_read_b128 v[152:155], v135 offset:2048
	ds_read_b128 v[156:159], v135 offset:3072
	v_add_u32_e32 v135, s44, v140
	ds_read_b128 v[160:163], v135
	ds_read_b128 v[164:167], v135 offset:1024
	ds_read_b128 v[168:171], v135 offset:2048
	ds_read_b128 v[172:175], v135 offset:3072
	s_add_u32 s40, s40, 0x80000
	s_addc_u32 s41, s41, 0
	s_mov_b32 m0, s49
	ds_read_b128 v[176:179], v141 offset:32768
	ds_read_b128 v[180:183], v141 offset:33792
	ds_read_b128 v[184:187], v141 offset:34816
	ds_read_b128 v[188:191], v141 offset:35840
	ds_read_b128 v[192:195], v141 offset:36864
	ds_read_b128 v[196:199], v141 offset:37888
	ds_read_b128 v[200:203], v141 offset:38912
	ds_read_b128 v[204:207], v141 offset:39936
	global_load_lds_dwordx4 v130, s[40:41]
	s_mov_b32 m0, s50
	s_nop 0
	global_load_lds_dwordx4 v132, s[40:41]
	s_waitcnt vmcnt(8)
	s_waitcnt lgkmcnt(0)
	s_barrier
	s_setprio 1
	v_mfma_f32_16x16x32_bf16 v[2:5], v[142:145], v[176:179], v[2:5]
	v_mfma_f32_16x16x32_bf16 v[2:5], v[148:151], v[180:183], v[2:5]
	v_mfma_f32_16x16x32_bf16 v[6:9], v[156:159], v[180:183], v[6:9]
	v_mfma_f32_16x16x32_bf16 v[6:9], v[152:155], v[176:179], v[6:9]
	v_mfma_f32_16x16x32_bf16 v[14:17], v[152:155], v[184:187], v[14:17]
	v_mfma_f32_16x16x32_bf16 v[14:17], v[156:159], v[188:191], v[14:17]
	v_mfma_f32_16x16x32_bf16 v[10:13], v[148:151], v[188:191], v[10:13]
	v_mfma_f32_16x16x32_bf16 v[10:13], v[142:145], v[184:187], v[10:13]
	v_mfma_f32_16x16x32_bf16 v[18:21], v[142:145], v[192:195], v[18:21]
	v_mfma_f32_16x16x32_bf16 v[18:21], v[148:151], v[196:199], v[18:21]
	v_mfma_f32_16x16x32_bf16 v[22:25], v[156:159], v[196:199], v[22:25]
	v_mfma_f32_16x16x32_bf16 v[22:25], v[152:155], v[192:195], v[22:25]
	v_mfma_f32_16x16x32_bf16 v[30:33], v[152:155], v[200:203], v[30:33]
	v_mfma_f32_16x16x32_bf16 v[30:33], v[156:159], v[204:207], v[30:33]
	v_mfma_f32_16x16x32_bf16 v[26:29], v[148:151], v[204:207], v[26:29]
	v_mfma_f32_16x16x32_bf16 v[26:29], v[142:145], v[200:203], v[26:29]
	v_mfma_f32_16x16x32_bf16 v[34:37], v[160:163], v[176:179], v[34:37]
	v_mfma_f32_16x16x32_bf16 v[34:37], v[164:167], v[180:183], v[34:37]
	v_mfma_f32_16x16x32_bf16 v[38:41], v[172:175], v[180:183], v[38:41]
	v_mfma_f32_16x16x32_bf16 v[38:41], v[168:171], v[176:179], v[38:41]
	v_mfma_f32_16x16x32_bf16 v[46:49], v[168:171], v[184:187], v[46:49]
	v_mfma_f32_16x16x32_bf16 v[46:49], v[172:175], v[188:191], v[46:49]
	v_mfma_f32_16x16x32_bf16 v[42:45], v[164:167], v[188:191], v[42:45]
	v_mfma_f32_16x16x32_bf16 v[42:45], v[160:163], v[184:187], v[42:45]
	v_mfma_f32_16x16x32_bf16 v[50:53], v[160:163], v[192:195], v[50:53]
	v_mfma_f32_16x16x32_bf16 v[50:53], v[164:167], v[196:199], v[50:53]
	v_mfma_f32_16x16x32_bf16 v[54:57], v[172:175], v[196:199], v[54:57]
	v_mfma_f32_16x16x32_bf16 v[54:57], v[168:171], v[192:195], v[54:57]
	v_mfma_f32_16x16x32_bf16 v[62:65], v[168:171], v[200:203], v[62:65]
	v_mfma_f32_16x16x32_bf16 v[62:65], v[172:175], v[204:207], v[62:65]
	s_setprio 2
	s_barrier
	v_mfma_f32_16x16x32_bf16 v[58:61], v[164:167], v[204:207], v[58:61]
	v_mfma_f32_16x16x32_bf16 v[58:61], v[160:163], v[200:203], v[58:61]
	s_setprio 0
	s_add_i32 s40, s43, s46
	v_lshl_add_u64 v[138:139], v[138:139], 0, s[6:7]
	s_mov_b32 m0, s40
	ds_read_b128 v[176:179], v141 offset:49152
	ds_read_b128 v[180:183], v141 offset:50176
	ds_read_b128 v[184:187], v141 offset:51200
	ds_read_b128 v[188:191], v141 offset:52224
	ds_read_b128 v[192:195], v141 offset:53248
	ds_read_b128 v[196:199], v141 offset:54272
	ds_read_b128 v[200:203], v141 offset:55296
	ds_read_b128 v[204:207], v141 offset:56320
	global_load_lds_dwordx4 v[138:139], off
	s_add_i32 m0, s40, 0x2000
	s_add_u32 s38, s38, 0x400080
	v_lshl_add_u64 v[138:139], v[208:209], 0, s[6:7]
	s_addc_u32 s39, s39, 0
	s_add_i32 s40, s44, s46
	global_load_lds_dwordx4 v[138:139], off
	s_mov_b32 m0, s40
	v_lshl_add_u64 v[138:139], v[210:211], 0, s[6:7]
	global_load_lds_dwordx4 v136, s[38:39]
	s_add_i32 m0, s40, 0x2000
	s_nop 0
	global_load_lds_dwordx4 v134, s[38:39]
	s_mov_b32 m0, s54
	s_nop 0
	global_load_lds_dwordx4 v[138:139], off
	v_lshl_add_u64 v[138:139], v[212:213], 0, s[6:7]
	s_mov_b32 m0, s55
	s_nop 0
	global_load_lds_dwordx4 v[138:139], off
	s_waitcnt vmcnt(8)
	s_waitcnt lgkmcnt(0)
	s_barrier
	s_setprio 1
	v_mfma_f32_16x16x32_bf16 v[66:69], v[142:145], v[176:179], v[66:69]
	v_mfma_f32_16x16x32_bf16 v[66:69], v[148:151], v[180:183], v[66:69]
	v_mfma_f32_16x16x32_bf16 v[70:73], v[156:159], v[180:183], v[70:73]
	v_mfma_f32_16x16x32_bf16 v[70:73], v[152:155], v[176:179], v[70:73]
	v_mfma_f32_16x16x32_bf16 v[78:81], v[152:155], v[184:187], v[78:81]
	v_mfma_f32_16x16x32_bf16 v[78:81], v[156:159], v[188:191], v[78:81]
	v_mfma_f32_16x16x32_bf16 v[74:77], v[148:151], v[188:191], v[74:77]
	v_mfma_f32_16x16x32_bf16 v[74:77], v[142:145], v[184:187], v[74:77]
	v_mfma_f32_16x16x32_bf16 v[82:85], v[142:145], v[192:195], v[82:85]
	v_mfma_f32_16x16x32_bf16 v[82:85], v[148:151], v[196:199], v[82:85]
	v_mfma_f32_16x16x32_bf16 v[86:89], v[156:159], v[196:199], v[86:89]
	v_mfma_f32_16x16x32_bf16 v[86:89], v[152:155], v[192:195], v[86:89]
	v_mfma_f32_16x16x32_bf16 v[94:97], v[152:155], v[200:203], v[94:97]
	v_mfma_f32_16x16x32_bf16 v[94:97], v[156:159], v[204:207], v[94:97]
	v_mfma_f32_16x16x32_bf16 v[90:93], v[148:151], v[204:207], v[90:93]
	v_mfma_f32_16x16x32_bf16 v[90:93], v[142:145], v[200:203], v[90:93]
	v_mfma_f32_16x16x32_bf16 v[98:101], v[160:163], v[176:179], v[98:101]
	v_mfma_f32_16x16x32_bf16 v[98:101], v[164:167], v[180:183], v[98:101]
	v_mfma_f32_16x16x32_bf16 v[102:105], v[172:175], v[180:183], v[102:105]
	v_mfma_f32_16x16x32_bf16 v[102:105], v[168:171], v[176:179], v[102:105]
	v_mfma_f32_16x16x32_bf16 v[110:113], v[168:171], v[184:187], v[110:113]
	v_mfma_f32_16x16x32_bf16 v[110:113], v[172:175], v[188:191], v[110:113]
	v_mfma_f32_16x16x32_bf16 v[106:109], v[164:167], v[188:191], v[106:109]
	v_mfma_f32_16x16x32_bf16 v[106:109], v[160:163], v[184:187], v[106:109]
	v_mfma_f32_16x16x32_bf16 v[114:117], v[160:163], v[192:195], v[114:117]
	v_mfma_f32_16x16x32_bf16 v[114:117], v[164:167], v[196:199], v[114:117]
	v_mfma_f32_16x16x32_bf16 v[118:121], v[172:175], v[196:199], v[118:121]
	v_mfma_f32_16x16x32_bf16 v[118:121], v[168:171], v[192:195], v[118:121]
	v_mfma_f32_16x16x32_bf16 v[126:129], v[168:171], v[200:203], v[126:129]
	v_mfma_f32_16x16x32_bf16 v[126:129], v[172:175], v[204:207], v[126:129]
	s_setprio 2
	s_barrier
	v_mfma_f32_16x16x32_bf16 v[122:125], v[164:167], v[204:207], v[122:125]
	v_mfma_f32_16x16x32_bf16 v[122:125], v[160:163], v[200:203], v[122:125]
	s_setprio 0
	s_add_i32 s42, s42, 2
	s_add_u32 s36, s36, 0x100
	s_addc_u32 s37, s37, 0
	s_add_u32 s15, s15, 0x100
	s_addc_u32 s27, s27, 0
	s_cmp_gt_u32 s42, 5
	s_cbranch_scc0 .LBB0_499
	s_and_b64 vcc, exec, s[8:9]
	s_cbranch_vccz .LBB0_502
	s_barrier

.LBB0_528:
	s_add_i32 s53, 0, 0x10000
	s_add_i32 s72, 0, 0x14000
	v_add_u32_e32 v16, s53, v147
	v_add_u32_e32 v32, s72, v147
	ds_read_b128 v[4:7], v16
	ds_read_b128 v[8:11], v16 offset:1024
	ds_read_b128 v[12:15], v16 offset:2048
	ds_read_b128 v[16:19], v16 offset:3072
	ds_read_b128 v[20:23], v32
	ds_read_b128 v[24:27], v32 offset:1024
	ds_read_b128 v[28:31], v32 offset:2048
	ds_read_b128 v[32:35], v32 offset:3072
	v_add_u32_e32 v231, 0, v146
	ds_read_b128 v[36:39], v231
	ds_read_b128 v[40:43], v231 offset:1024
	ds_read_b128 v[44:47], v231 offset:2048
	ds_read_b128 v[48:51], v231 offset:3072
	ds_read_b128 v[52:55], v231 offset:4096
	ds_read_b128 v[56:59], v231 offset:5120
	ds_read_b128 v[60:63], v231 offset:6144
	ds_read_b128 v[64:67], v231 offset:7168
	s_waitcnt vmcnt(8)
	s_waitcnt lgkmcnt(0)
	s_barrier
	s_setprio 1
	v_mfma_f32_16x16x32_f16 v[68:71], v[4:7], v[36:39], 0
	v_mfma_f32_16x16x32_f16 v[68:71], v[8:11], v[40:43], v[68:71]
	v_mfma_f32_16x16x32_f16 v[72:75], v[12:15], v[36:39], 0
	v_mfma_f32_16x16x32_f16 v[72:75], v[16:19], v[40:43], v[72:75]
	v_mfma_f32_16x16x32_f16 v[80:83], v[12:15], v[44:47], 0
	v_mfma_f32_16x16x32_f16 v[80:83], v[16:19], v[48:51], v[80:83]
	v_mfma_f32_16x16x32_f16 v[76:79], v[4:7], v[44:47], 0
	v_mfma_f32_16x16x32_f16 v[76:79], v[8:11], v[48:51], v[76:79]
	v_mfma_f32_16x16x32_f16 v[84:87], v[4:7], v[52:55], 0
	v_mfma_f32_16x16x32_f16 v[84:87], v[8:11], v[56:59], v[84:87]
	v_mfma_f32_16x16x32_f16 v[88:91], v[12:15], v[52:55], 0
	v_mfma_f32_16x16x32_f16 v[88:91], v[16:19], v[56:59], v[88:91]
	v_mfma_f32_16x16x32_f16 v[96:99], v[12:15], v[60:63], 0
	v_mfma_f32_16x16x32_f16 v[96:99], v[16:19], v[64:67], v[96:99]
	v_mfma_f32_16x16x32_f16 v[92:95], v[4:7], v[60:63], 0
	v_mfma_f32_16x16x32_f16 v[92:95], v[8:11], v[64:67], v[92:95]
	v_mfma_f32_16x16x32_f16 v[100:103], v[20:23], v[36:39], 0
	v_mfma_f32_16x16x32_f16 v[36:39], v[28:31], v[36:39], 0
	v_mfma_f32_16x16x32_f16 v[104:107], v[20:23], v[44:47], 0
	v_mfma_f32_16x16x32_f16 v[44:47], v[28:31], v[44:47], 0
	v_mfma_f32_16x16x32_f16 v[108:111], v[20:23], v[52:55], 0
	v_mfma_f32_16x16x32_f16 v[52:55], v[28:31], v[52:55], 0
	v_mfma_f32_16x16x32_f16 v[112:115], v[20:23], v[60:63], 0
	v_mfma_f32_16x16x32_f16 v[60:63], v[28:31], v[60:63], 0
	v_mfma_f32_16x16x32_f16 v[100:103], v[24:27], v[40:43], v[100:103]
	v_mfma_f32_16x16x32_f16 v[40:43], v[32:35], v[40:43], v[36:39]
	v_mfma_f32_16x16x32_f16 v[104:107], v[24:27], v[48:51], v[104:107]
	v_mfma_f32_16x16x32_f16 v[48:51], v[32:35], v[48:51], v[44:47]
	v_mfma_f32_16x16x32_f16 v[108:111], v[24:27], v[56:59], v[108:111]
	v_mfma_f32_16x16x32_f16 v[56:59], v[32:35], v[56:59], v[52:55]
	s_setprio 2
	s_barrier
	v_mfma_f32_16x16x32_f16 v[112:115], v[24:27], v[64:67], v[112:115]
	v_mfma_f32_16x16x32_f16 v[64:67], v[32:35], v[64:67], v[60:63]
	s_setprio 0
	v_lshl_add_u64 v[136:137], s[6:7], 0, v[2:3]
	s_add_i32 s53, s53, s38
	v_mov_b32_e32 v135, v3
	v_lshl_add_u64 v[140:141], v[136:137], 0, s[74:75]
	s_mov_b32 m0, s53
	v_lshl_add_u64 v[144:145], s[6:7], 0, v[134:135]
	ds_read_b128 v[36:39], v231 offset:16384
	ds_read_b128 v[44:47], v231 offset:17408
	ds_read_b128 v[52:55], v231 offset:18432
	ds_read_b128 v[60:63], v231 offset:19456
	ds_read_b128 v[116:119], v231 offset:20480
	ds_read_b128 v[120:123], v231 offset:21504
	ds_read_b128 v[124:127], v231 offset:22528
	ds_read_b128 v[128:131], v231 offset:23552
	global_load_lds_dwordx4 v[140:141], off
	v_lshl_add_u64 v[140:141], v[144:145], 0, s[74:75]
	s_add_i32 m0, s53, 0x2000
	s_add_i32 s53, s72, s38
	global_load_lds_dwordx4 v[140:141], off
	s_mov_b32 m0, s53
	v_mov_b32_e32 v139, v3
	global_load_lds_dwordx4 v2, s[16:17]
	s_add_i32 m0, s53, 0x2000
	v_lshl_add_u64 v[248:249], s[8:9], 0, v[138:139]
	v_mov_b32_e32 v133, v3
	global_load_lds_dwordx4 v134, s[16:17]
	v_lshl_add_u64 v[140:141], v[248:249], 0, s[74:75]
	s_mov_b32 m0, s58
	v_lshl_add_u64 v[250:251], s[8:9], 0, v[132:133]
	global_load_lds_dwordx4 v[140:141], off
	v_lshl_add_u64 v[140:141], v[250:251], 0, s[74:75]
	s_mov_b32 m0, s59
	s_nop 0
	global_load_lds_dwordx4 v[140:141], off
	s_waitcnt vmcnt(8)
	s_waitcnt lgkmcnt(0)
	s_barrier
	s_setprio 1
	v_mfma_f32_16x16x32_f16 v[140:143], v[4:7], v[36:39], 0
	v_mfma_f32_16x16x32_f16 v[148:151], v[12:15], v[36:39], 0
	v_mfma_f32_16x16x32_f16 v[152:155], v[4:7], v[52:55], 0
	v_mfma_f32_16x16x32_f16 v[156:159], v[12:15], v[52:55], 0
	v_mfma_f32_16x16x32_f16 v[160:163], v[4:7], v[116:119], 0
	v_mfma_f32_16x16x32_f16 v[164:167], v[12:15], v[116:119], 0
	v_mfma_f32_16x16x32_f16 v[4:7], v[4:7], v[124:127], 0
	v_mfma_f32_16x16x32_f16 v[12:15], v[12:15], v[124:127], 0
	v_mfma_f32_16x16x32_f16 v[140:143], v[8:11], v[44:47], v[140:143]
	v_mfma_f32_16x16x32_f16 v[148:151], v[16:19], v[44:47], v[148:151]
	v_mfma_f32_16x16x32_f16 v[152:155], v[8:11], v[60:63], v[152:155]
	v_mfma_f32_16x16x32_f16 v[156:159], v[16:19], v[60:63], v[156:159]
	v_mfma_f32_16x16x32_f16 v[160:163], v[8:11], v[120:123], v[160:163]
	v_mfma_f32_16x16x32_f16 v[164:167], v[16:19], v[120:123], v[164:167]
	v_mfma_f32_16x16x32_f16 v[168:171], v[8:11], v[128:131], v[4:7]
	v_mfma_f32_16x16x32_f16 v[172:175], v[16:19], v[128:131], v[12:15]
	v_mfma_f32_16x16x32_f16 v[4:7], v[20:23], v[36:39], 0
	v_mfma_f32_16x16x32_f16 v[8:11], v[28:31], v[36:39], 0
	v_mfma_f32_16x16x32_f16 v[12:15], v[20:23], v[52:55], 0
	v_mfma_f32_16x16x32_f16 v[16:19], v[28:31], v[52:55], 0
	v_mfma_f32_16x16x32_f16 v[36:39], v[20:23], v[116:119], 0
	v_mfma_f32_16x16x32_f16 v[52:55], v[28:31], v[116:119], 0
	v_mfma_f32_16x16x32_f16 v[20:23], v[20:23], v[124:127], 0
	v_mfma_f32_16x16x32_f16 v[28:31], v[28:31], v[124:127], 0
	v_mfma_f32_16x16x32_f16 v[116:119], v[24:27], v[44:47], v[4:7]
	v_mfma_f32_16x16x32_f16 v[124:127], v[32:35], v[44:47], v[8:11]
	v_mfma_f32_16x16x32_f16 v[184:187], v[24:27], v[120:123], v[36:39]
	v_mfma_f32_16x16x32_f16 v[120:123], v[32:35], v[120:123], v[52:55]
	v_mfma_f32_16x16x32_f16 v[188:191], v[24:27], v[128:131], v[20:23]
	v_mfma_f32_16x16x32_f16 v[128:131], v[32:35], v[128:131], v[28:31]
	s_setprio 2
	s_barrier
	v_mfma_f32_16x16x32_f16 v[176:179], v[24:27], v[60:63], v[12:15]
	v_mfma_f32_16x16x32_f16 v[180:183], v[32:35], v[60:63], v[16:19]
	s_setprio 0
	s_add_i32 s53, 0, 0x18000
	v_add_u32_e32 v4, s53, v147
	s_add_i32 s72, 0, 0x1c000
	ds_read_b128 v[192:195], v4
	ds_read_b128 v[196:199], v4 offset:1024
	ds_read_b128 v[200:203], v4 offset:2048
	ds_read_b128 v[204:207], v4 offset:3072
	v_add_u32_e32 v4, s72, v147
	ds_read_b128 v[208:211], v4
	ds_read_b128 v[212:215], v4 offset:1024
	ds_read_b128 v[216:219], v4 offset:2048
	ds_read_b128 v[220:223], v4 offset:3072
	s_mov_b32 m0, s60
	ds_read_b128 v[44:47], v231 offset:32768
	ds_read_b128 v[52:55], v231 offset:33792
	ds_read_b128 v[60:63], v231 offset:34816
	ds_read_b128 v[224:227], v231 offset:35840
	ds_read_b128 v[232:235], v231 offset:36864
	ds_read_b128 v[236:239], v231 offset:37888
	ds_read_b128 v[240:243], v231 offset:38912
	ds_read_b128 v[244:247], v231 offset:39936
	global_load_lds_dwordx4 v138, s[26:27]
	s_mov_b32 m0, s61
	s_nop 0
	global_load_lds_dwordx4 v132, s[26:27]
	s_waitcnt vmcnt(8)
	s_waitcnt lgkmcnt(0)
	s_barrier
	s_setprio 1
	v_mfma_f32_16x16x32_f16 v[4:7], v[192:195], v[44:47], v[68:71]
	v_mfma_f32_16x16x32_f16 v[8:11], v[200:203], v[44:47], v[72:75]
	v_mfma_f32_16x16x32_f16 v[12:15], v[192:195], v[60:63], v[76:79]
	v_mfma_f32_16x16x32_f16 v[16:19], v[200:203], v[60:63], v[80:83]
	v_mfma_f32_16x16x32_f16 v[20:23], v[192:195], v[232:235], v[84:87]
	v_mfma_f32_16x16x32_f16 v[24:27], v[200:203], v[232:235], v[88:91]
	v_mfma_f32_16x16x32_f16 v[28:31], v[192:195], v[240:243], v[92:95]
	v_mfma_f32_16x16x32_f16 v[32:35], v[200:203], v[240:243], v[96:99]
	v_mfma_f32_16x16x32_f16 v[4:7], v[196:199], v[52:55], v[4:7]
	v_mfma_f32_16x16x32_f16 v[8:11], v[204:207], v[52:55], v[8:11]
	v_mfma_f32_16x16x32_f16 v[12:15], v[196:199], v[224:227], v[12:15]
	v_mfma_f32_16x16x32_f16 v[16:19], v[204:207], v[224:227], v[16:19]
	v_mfma_f32_16x16x32_f16 v[20:23], v[196:199], v[236:239], v[20:23]
	v_mfma_f32_16x16x32_f16 v[24:27], v[204:207], v[236:239], v[24:27]
	v_mfma_f32_16x16x32_f16 v[28:31], v[196:199], v[244:247], v[28:31]
	v_mfma_f32_16x16x32_f16 v[32:35], v[204:207], v[244:247], v[32:35]
	v_mfma_f32_16x16x32_f16 v[36:39], v[208:211], v[44:47], v[100:103]
	v_mfma_f32_16x16x32_f16 v[40:43], v[216:219], v[44:47], v[40:43]
	v_mfma_f32_16x16x32_f16 v[36:39], v[212:215], v[52:55], v[36:39]
	v_mfma_f32_16x16x32_f16 v[40:43], v[220:223], v[52:55], v[40:43]
	v_mfma_f32_16x16x32_f16 v[44:47], v[208:211], v[60:63], v[104:107]
	v_mfma_f32_16x16x32_f16 v[48:51], v[216:219], v[60:63], v[48:51]
	v_mfma_f32_16x16x32_f16 v[52:55], v[208:211], v[232:235], v[108:111]
	v_mfma_f32_16x16x32_f16 v[56:59], v[216:219], v[232:235], v[56:59]
	v_mfma_f32_16x16x32_f16 v[60:63], v[208:211], v[240:243], v[112:115]
	v_mfma_f32_16x16x32_f16 v[64:67], v[216:219], v[240:243], v[64:67]
	v_mfma_f32_16x16x32_f16 v[44:47], v[212:215], v[224:227], v[44:47]
	v_mfma_f32_16x16x32_f16 v[48:51], v[220:223], v[224:227], v[48:51]
	v_mfma_f32_16x16x32_f16 v[52:55], v[212:215], v[236:239], v[52:55]
	v_mfma_f32_16x16x32_f16 v[56:59], v[220:223], v[236:239], v[56:59]
	s_setprio 2
	s_barrier
	v_mfma_f32_16x16x32_f16 v[60:63], v[212:215], v[244:247], v[60:63]
	v_mfma_f32_16x16x32_f16 v[64:67], v[220:223], v[244:247], v[64:67]
	s_setprio 0
	s_add_i32 s53, s53, s38
	v_lshl_add_u64 v[68:69], v[136:137], 0, s[24:25]
	s_mov_b32 m0, s53
	ds_read_b128 v[104:107], v231 offset:49152
	ds_read_b128 v[108:111], v231 offset:50176
	ds_read_b128 v[112:115], v231 offset:51200
	ds_read_b128 v[224:227], v231 offset:52224
	ds_read_b128 v[232:235], v231 offset:53248
	ds_read_b128 v[236:239], v231 offset:54272
	ds_read_b128 v[240:243], v231 offset:55296
	ds_read_b128 v[244:247], v231 offset:56320
	global_load_lds_dwordx4 v[68:69], off
	v_lshl_add_u64 v[68:69], v[144:145], 0, s[24:25]
	s_add_i32 m0, s53, 0x2000
	s_add_i32 s53, s72, s38
	global_load_lds_dwordx4 v[68:69], off
	s_mov_b32 m0, s53
	v_lshl_add_u64 v[68:69], v[248:249], 0, s[24:25]
	global_load_lds_dwordx4 v2, s[28:29]
	s_add_i32 m0, s53, 0x2000
	s_nop 0
	global_load_lds_dwordx4 v134, s[28:29]
	s_mov_b32 m0, s64
	s_nop 0
	global_load_lds_dwordx4 v[68:69], off
	v_lshl_add_u64 v[68:69], v[250:251], 0, s[24:25]
	s_mov_b32 m0, s65
	s_nop 0
	global_load_lds_dwordx4 v[68:69], off
	s_waitcnt vmcnt(8)
	s_waitcnt lgkmcnt(0)
	s_barrier
	s_setprio 1
	v_mfma_f32_16x16x32_f16 v[68:71], v[192:195], v[104:107], v[140:143]
	v_mfma_f32_16x16x32_f16 v[72:75], v[200:203], v[104:107], v[148:151]
	v_mfma_f32_16x16x32_f16 v[76:79], v[192:195], v[112:115], v[152:155]
	v_mfma_f32_16x16x32_f16 v[80:83], v[200:203], v[112:115], v[156:159]
	v_mfma_f32_16x16x32_f16 v[84:87], v[192:195], v[232:235], v[160:163]
	v_mfma_f32_16x16x32_f16 v[88:91], v[200:203], v[232:235], v[164:167]
	v_mfma_f32_16x16x32_f16 v[92:95], v[192:195], v[240:243], v[168:171]
	v_mfma_f32_16x16x32_f16 v[96:99], v[200:203], v[240:243], v[172:175]
	v_mfma_f32_16x16x32_f16 v[68:71], v[196:199], v[108:111], v[68:71]
	v_mfma_f32_16x16x32_f16 v[72:75], v[204:207], v[108:111], v[72:75]
	v_mfma_f32_16x16x32_f16 v[76:79], v[196:199], v[224:227], v[76:79]
	v_mfma_f32_16x16x32_f16 v[80:83], v[204:207], v[224:227], v[80:83]
	v_mfma_f32_16x16x32_f16 v[84:87], v[196:199], v[236:239], v[84:87]
	v_mfma_f32_16x16x32_f16 v[88:91], v[204:207], v[236:239], v[88:91]
	v_mfma_f32_16x16x32_f16 v[92:95], v[196:199], v[244:247], v[92:95]
	v_mfma_f32_16x16x32_f16 v[96:99], v[204:207], v[244:247], v[96:99]
	v_mfma_f32_16x16x32_f16 v[100:103], v[208:211], v[104:107], v[116:119]
	v_mfma_f32_16x16x32_f16 v[104:107], v[216:219], v[104:107], v[124:127]
	v_mfma_f32_16x16x32_f16 v[100:103], v[212:215], v[108:111], v[100:103]
	v_mfma_f32_16x16x32_f16 v[104:107], v[220:223], v[108:111], v[104:107]
	v_mfma_f32_16x16x32_f16 v[108:111], v[208:211], v[112:115], v[176:179]
	v_mfma_f32_16x16x32_f16 v[112:115], v[216:219], v[112:115], v[180:183]
	v_mfma_f32_16x16x32_f16 v[116:119], v[208:211], v[232:235], v[184:187]
	v_mfma_f32_16x16x32_f16 v[120:123], v[216:219], v[232:235], v[120:123]
	v_mfma_f32_16x16x32_f16 v[124:127], v[208:211], v[240:243], v[188:191]
	v_mfma_f32_16x16x32_f16 v[128:131], v[216:219], v[240:243], v[128:131]
	v_mfma_f32_16x16x32_f16 v[108:111], v[212:215], v[224:227], v[108:111]
	v_mfma_f32_16x16x32_f16 v[112:115], v[220:223], v[224:227], v[112:115]
	v_mfma_f32_16x16x32_f16 v[116:119], v[212:215], v[236:239], v[116:119]
	v_mfma_f32_16x16x32_f16 v[120:123], v[220:223], v[236:239], v[120:123]
	s_setprio 2
	s_barrier
	v_mfma_f32_16x16x32_f16 v[124:127], v[212:215], v[244:247], v[124:127]
	v_mfma_f32_16x16x32_f16 v[128:131], v[220:223], v[244:247], v[128:131]
	s_setprio 0
	s_add_i32 s41, s41, 2
	s_cmp_ge_i32 s41, s40
	s_cbranch_scc0 .LBB0_528
	v_mov_b32_e32 v136, v2
	s_branch .LBB0_531

.LBB0_532:
	s_add_u32 s6, s8, 0xfff80080
	s_addc_u32 s7, s9, -1
	s_add_i32 s29, 0, 0x10000
	s_cmp_eq_u32 s28, 28
	s_cselect_b32 s17, s13, s7
	s_cselect_b32 s16, s12, s6
	v_add_u32_e32 v133, s29, v147
	s_cselect_b32 s7, s15, s27
	s_cselect_b32 s6, s14, s26
	s_add_i32 s53, 0, 0x14000
	ds_read_b128 v[138:141], v133
	ds_read_b128 v[142:145], v133 offset:1024
	ds_read_b128 v[148:151], v133 offset:2048
	ds_read_b128 v[152:155], v133 offset:3072
	v_add_u32_e32 v133, s53, v147
	ds_read_b128 v[156:159], v133
	ds_read_b128 v[160:163], v133 offset:1024
	ds_read_b128 v[164:167], v133 offset:2048
	ds_read_b128 v[168:171], v133 offset:3072
	s_mov_b32 m0, s66
	v_add_u32_e32 v212, 0, v146
	ds_read_b128 v[172:175], v212
	ds_read_b128 v[176:179], v212 offset:1024
	ds_read_b128 v[180:183], v212 offset:2048
	ds_read_b128 v[184:187], v212 offset:3072
	ds_read_b128 v[188:191], v212 offset:4096
	ds_read_b128 v[192:195], v212 offset:5120
	ds_read_b128 v[196:199], v212 offset:6144
	ds_read_b128 v[200:203], v212 offset:7168
	global_load_lds_dwordx4 v2, s[8:9]
	s_mov_b32 m0, s67
	v_mov_b32_e32 v133, v3
	global_load_lds_dwordx4 v132, s[8:9]
	s_waitcnt vmcnt(8)
	s_waitcnt lgkmcnt(0)
	s_barrier
	s_setprio 1
	v_mfma_f32_16x16x32_f16 v[4:7], v[138:141], v[172:175], v[4:7]
	v_mfma_f32_16x16x32_f16 v[4:7], v[142:145], v[176:179], v[4:7]
	v_mfma_f32_16x16x32_f16 v[8:11], v[152:155], v[176:179], v[8:11]
	v_mfma_f32_16x16x32_f16 v[8:11], v[148:151], v[172:175], v[8:11]
	v_mfma_f32_16x16x32_f16 v[16:19], v[148:151], v[180:183], v[16:19]
	v_mfma_f32_16x16x32_f16 v[16:19], v[152:155], v[184:187], v[16:19]
	v_mfma_f32_16x16x32_f16 v[12:15], v[142:145], v[184:187], v[12:15]
	v_mfma_f32_16x16x32_f16 v[12:15], v[138:141], v[180:183], v[12:15]
	v_mfma_f32_16x16x32_f16 v[20:23], v[138:141], v[188:191], v[20:23]
	v_mfma_f32_16x16x32_f16 v[20:23], v[142:145], v[192:195], v[20:23]
	v_mfma_f32_16x16x32_f16 v[24:27], v[152:155], v[192:195], v[24:27]
	v_mfma_f32_16x16x32_f16 v[24:27], v[148:151], v[188:191], v[24:27]
	v_mfma_f32_16x16x32_f16 v[32:35], v[148:151], v[196:199], v[32:35]
	v_mfma_f32_16x16x32_f16 v[32:35], v[152:155], v[200:203], v[32:35]
	v_mfma_f32_16x16x32_f16 v[28:31], v[142:145], v[200:203], v[28:31]
	v_mfma_f32_16x16x32_f16 v[28:31], v[138:141], v[196:199], v[28:31]
	v_mfma_f32_16x16x32_f16 v[36:39], v[156:159], v[172:175], v[36:39]
	v_mfma_f32_16x16x32_f16 v[36:39], v[160:163], v[176:179], v[36:39]
	v_mfma_f32_16x16x32_f16 v[40:43], v[168:171], v[176:179], v[40:43]
	v_mfma_f32_16x16x32_f16 v[40:43], v[164:167], v[172:175], v[40:43]
	v_mfma_f32_16x16x32_f16 v[48:51], v[164:167], v[180:183], v[48:51]
	v_mfma_f32_16x16x32_f16 v[48:51], v[168:171], v[184:187], v[48:51]
	v_mfma_f32_16x16x32_f16 v[44:47], v[160:163], v[184:187], v[44:47]
	v_mfma_f32_16x16x32_f16 v[44:47], v[156:159], v[180:183], v[44:47]
	v_mfma_f32_16x16x32_f16 v[52:55], v[156:159], v[188:191], v[52:55]
	v_mfma_f32_16x16x32_f16 v[52:55], v[160:163], v[192:195], v[52:55]
	v_mfma_f32_16x16x32_f16 v[56:59], v[168:171], v[192:195], v[56:59]
	v_mfma_f32_16x16x32_f16 v[56:59], v[164:167], v[188:191], v[56:59]
	v_mfma_f32_16x16x32_f16 v[64:67], v[164:167], v[196:199], v[64:67]
	v_mfma_f32_16x16x32_f16 v[64:67], v[168:171], v[200:203], v[64:67]
	s_setprio 2
	s_barrier
	v_mfma_f32_16x16x32_f16 v[60:63], v[160:163], v[200:203], v[60:63]
	v_mfma_f32_16x16x32_f16 v[60:63], v[156:159], v[196:199], v[60:63]
	s_setprio 0
	s_add_i32 s29, s29, s38
	s_mov_b32 m0, s29
	ds_read_b128 v[172:175], v212 offset:16384
	ds_read_b128 v[176:179], v212 offset:17408
	ds_read_b128 v[180:183], v212 offset:18432
	ds_read_b128 v[184:187], v212 offset:19456
	ds_read_b128 v[188:191], v212 offset:20480
	ds_read_b128 v[192:195], v212 offset:21504
	ds_read_b128 v[196:199], v212 offset:22528
	ds_read_b128 v[200:203], v212 offset:23552
	global_load_lds_dwordx4 v136, s[6:7]
	s_add_i32 m0, s29, 0x2000
	s_add_u32 s40, s6, 0x80000
	s_addc_u32 s41, s7, 0
	s_add_i32 s29, s53, s38
	global_load_lds_dwordx4 v134, s[6:7]
	s_mov_b32 m0, s29
	v_mov_b32_e32 v137, v3
	global_load_lds_dwordx4 v136, s[40:41]
	s_add_i32 m0, s29, 0x2000
	v_mov_b32_e32 v135, v3
	global_load_lds_dwordx4 v134, s[40:41]
	s_mov_b32 m0, s58
	v_lshl_add_u64 v[204:205], s[6:7], 0, v[136:137]
	global_load_lds_dwordx4 v2, s[16:17]
	s_mov_b32 m0, s59
	v_lshl_add_u64 v[206:207], s[6:7], 0, v[134:135]
	global_load_lds_dwordx4 v132, s[16:17]
	s_waitcnt vmcnt(8)
	s_waitcnt lgkmcnt(0)
	v_lshl_add_u64 v[208:209], s[16:17], 0, v[2:3]
	v_lshl_add_u64 v[210:211], s[16:17], 0, v[132:133]
	s_barrier
	s_setprio 1
	v_mfma_f32_16x16x32_f16 v[68:71], v[138:141], v[172:175], v[68:71]
	v_mfma_f32_16x16x32_f16 v[68:71], v[142:145], v[176:179], v[68:71]
	v_mfma_f32_16x16x32_f16 v[72:75], v[152:155], v[176:179], v[72:75]
	v_mfma_f32_16x16x32_f16 v[72:75], v[148:151], v[172:175], v[72:75]
	v_mfma_f32_16x16x32_f16 v[80:83], v[148:151], v[180:183], v[80:83]
	v_mfma_f32_16x16x32_f16 v[80:83], v[152:155], v[184:187], v[80:83]
	v_mfma_f32_16x16x32_f16 v[76:79], v[142:145], v[184:187], v[76:79]
	v_mfma_f32_16x16x32_f16 v[76:79], v[138:141], v[180:183], v[76:79]
	v_mfma_f32_16x16x32_f16 v[84:87], v[138:141], v[188:191], v[84:87]
	v_mfma_f32_16x16x32_f16 v[84:87], v[142:145], v[192:195], v[84:87]
	v_mfma_f32_16x16x32_f16 v[88:91], v[152:155], v[192:195], v[88:91]
	v_mfma_f32_16x16x32_f16 v[88:91], v[148:151], v[188:191], v[88:91]
	v_mfma_f32_16x16x32_f16 v[96:99], v[148:151], v[196:199], v[96:99]
	v_mfma_f32_16x16x32_f16 v[96:99], v[152:155], v[200:203], v[96:99]
	v_mfma_f32_16x16x32_f16 v[92:95], v[142:145], v[200:203], v[92:95]
	v_mfma_f32_16x16x32_f16 v[92:95], v[138:141], v[196:199], v[92:95]
	v_mfma_f32_16x16x32_f16 v[100:103], v[156:159], v[172:175], v[100:103]
	v_mfma_f32_16x16x32_f16 v[100:103], v[160:163], v[176:179], v[100:103]
	v_mfma_f32_16x16x32_f16 v[104:107], v[168:171], v[176:179], v[104:107]
	v_mfma_f32_16x16x32_f16 v[104:107], v[164:167], v[172:175], v[104:107]
	v_mfma_f32_16x16x32_f16 v[112:115], v[164:167], v[180:183], v[112:115]
	v_mfma_f32_16x16x32_f16 v[112:115], v[168:171], v[184:187], v[112:115]
	v_mfma_f32_16x16x32_f16 v[108:111], v[160:163], v[184:187], v[108:111]
	v_mfma_f32_16x16x32_f16 v[108:111], v[156:159], v[180:183], v[108:111]
	v_mfma_f32_16x16x32_f16 v[116:119], v[156:159], v[188:191], v[116:119]
	v_mfma_f32_16x16x32_f16 v[116:119], v[160:163], v[192:195], v[116:119]
	v_mfma_f32_16x16x32_f16 v[120:123], v[168:171], v[192:195], v[120:123]
	v_mfma_f32_16x16x32_f16 v[120:123], v[164:167], v[188:191], v[120:123]
	v_mfma_f32_16x16x32_f16 v[128:131], v[164:167], v[196:199], v[128:131]
	v_mfma_f32_16x16x32_f16 v[128:131], v[168:171], v[200:203], v[128:131]
	s_setprio 2
	s_barrier
	v_mfma_f32_16x16x32_f16 v[124:127], v[160:163], v[200:203], v[124:127]
	v_mfma_f32_16x16x32_f16 v[124:127], v[156:159], v[196:199], v[124:127]
	s_setprio 0
	s_add_i32 s29, 0, 0x18000
	v_add_u32_e32 v135, s29, v147
	s_add_i32 s40, 0, 0x1c000
	ds_read_b128 v[138:141], v135
	ds_read_b128 v[142:145], v135 offset:1024
	ds_read_b128 v[148:151], v135 offset:2048
	ds_read_b128 v[152:155], v135 offset:3072
	v_add_u32_e32 v135, s40, v147
	ds_read_b128 v[156:159], v135
	ds_read_b128 v[160:163], v135 offset:1024
	ds_read_b128 v[164:167], v135 offset:2048
	ds_read_b128 v[168:171], v135 offset:3072
	s_add_u32 s16, s16, 0x80000
	s_addc_u32 s17, s17, 0
	s_mov_b32 m0, s60
	ds_read_b128 v[172:175], v212 offset:32768
	ds_read_b128 v[176:179], v212 offset:33792
	ds_read_b128 v[180:183], v212 offset:34816
	ds_read_b128 v[184:187], v212 offset:35840
	ds_read_b128 v[188:191], v212 offset:36864
	ds_read_b128 v[192:195], v212 offset:37888
	ds_read_b128 v[196:199], v212 offset:38912
	ds_read_b128 v[200:203], v212 offset:39936
	global_load_lds_dwordx4 v2, s[16:17]
	s_mov_b32 m0, s61
	s_nop 0
	global_load_lds_dwordx4 v132, s[16:17]
	s_waitcnt vmcnt(8)
	s_waitcnt lgkmcnt(0)
	s_barrier
	s_setprio 1
	v_mfma_f32_16x16x32_f16 v[4:7], v[138:141], v[172:175], v[4:7]
	v_mfma_f32_16x16x32_f16 v[4:7], v[142:145], v[176:179], v[4:7]
	v_mfma_f32_16x16x32_f16 v[8:11], v[152:155], v[176:179], v[8:11]
	v_mfma_f32_16x16x32_f16 v[8:11], v[148:151], v[172:175], v[8:11]
	v_mfma_f32_16x16x32_f16 v[16:19], v[148:151], v[180:183], v[16:19]
	v_mfma_f32_16x16x32_f16 v[16:19], v[152:155], v[184:187], v[16:19]
	v_mfma_f32_16x16x32_f16 v[12:15], v[142:145], v[184:187], v[12:15]
	v_mfma_f32_16x16x32_f16 v[12:15], v[138:141], v[180:183], v[12:15]
	v_mfma_f32_16x16x32_f16 v[20:23], v[138:141], v[188:191], v[20:23]
	v_mfma_f32_16x16x32_f16 v[20:23], v[142:145], v[192:195], v[20:23]
	v_mfma_f32_16x16x32_f16 v[24:27], v[152:155], v[192:195], v[24:27]
	v_mfma_f32_16x16x32_f16 v[24:27], v[148:151], v[188:191], v[24:27]
	v_mfma_f32_16x16x32_f16 v[32:35], v[148:151], v[196:199], v[32:35]
	v_mfma_f32_16x16x32_f16 v[32:35], v[152:155], v[200:203], v[32:35]
	v_mfma_f32_16x16x32_f16 v[28:31], v[142:145], v[200:203], v[28:31]
	v_mfma_f32_16x16x32_f16 v[28:31], v[138:141], v[196:199], v[28:31]
	v_mfma_f32_16x16x32_f16 v[36:39], v[156:159], v[172:175], v[36:39]
	v_mfma_f32_16x16x32_f16 v[36:39], v[160:163], v[176:179], v[36:39]
	v_mfma_f32_16x16x32_f16 v[40:43], v[168:171], v[176:179], v[40:43]
	v_mfma_f32_16x16x32_f16 v[40:43], v[164:167], v[172:175], v[40:43]
	v_mfma_f32_16x16x32_f16 v[48:51], v[164:167], v[180:183], v[48:51]
	v_mfma_f32_16x16x32_f16 v[48:51], v[168:171], v[184:187], v[48:51]
	v_mfma_f32_16x16x32_f16 v[44:47], v[160:163], v[184:187], v[44:47]
	v_mfma_f32_16x16x32_f16 v[44:47], v[156:159], v[180:183], v[44:47]
	v_mfma_f32_16x16x32_f16 v[52:55], v[156:159], v[188:191], v[52:55]
	v_mfma_f32_16x16x32_f16 v[52:55], v[160:163], v[192:195], v[52:55]
	v_mfma_f32_16x16x32_f16 v[56:59], v[168:171], v[192:195], v[56:59]
	v_mfma_f32_16x16x32_f16 v[56:59], v[164:167], v[188:191], v[56:59]
	v_mfma_f32_16x16x32_f16 v[64:67], v[164:167], v[196:199], v[64:67]
	v_mfma_f32_16x16x32_f16 v[64:67], v[168:171], v[200:203], v[64:67]
	s_setprio 2
	s_barrier
	v_mfma_f32_16x16x32_f16 v[60:63], v[160:163], v[200:203], v[60:63]
	v_mfma_f32_16x16x32_f16 v[60:63], v[156:159], v[196:199], v[60:63]
	s_setprio 0
	s_add_i32 s16, s29, s38
	v_lshl_add_u64 v[204:205], v[204:205], 0, s[86:87]
	s_mov_b32 m0, s16
	ds_read_b128 v[172:175], v212 offset:49152
	ds_read_b128 v[176:179], v212 offset:50176
	ds_read_b128 v[180:183], v212 offset:51200
	ds_read_b128 v[184:187], v212 offset:52224
	ds_read_b128 v[188:191], v212 offset:53248
	ds_read_b128 v[192:195], v212 offset:54272
	ds_read_b128 v[196:199], v212 offset:55296
	ds_read_b128 v[200:203], v212 offset:56320
	global_load_lds_dwordx4 v[204:205], off
	s_add_i32 m0, s16, 0x2000
	s_add_u32 s6, s6, 0x80080
	v_lshl_add_u64 v[204:205], v[206:207], 0, s[86:87]
	s_addc_u32 s7, s7, 0
	s_add_i32 s16, s40, s38
	global_load_lds_dwordx4 v[204:205], off
	s_mov_b32 m0, s16
	v_lshl_add_u64 v[204:205], v[208:209], 0, s[86:87]
	global_load_lds_dwordx4 v136, s[6:7]
	s_add_i32 m0, s16, 0x2000
	s_nop 0
	global_load_lds_dwordx4 v134, s[6:7]
	s_mov_b32 m0, s64
	s_nop 0
	global_load_lds_dwordx4 v[204:205], off
	v_lshl_add_u64 v[204:205], v[210:211], 0, s[86:87]
	s_mov_b32 m0, s65
	s_nop 0
	global_load_lds_dwordx4 v[204:205], off
	s_waitcnt vmcnt(8)
	s_waitcnt lgkmcnt(0)
	s_barrier
	s_setprio 1
	v_mfma_f32_16x16x32_f16 v[68:71], v[138:141], v[172:175], v[68:71]
	v_mfma_f32_16x16x32_f16 v[68:71], v[142:145], v[176:179], v[68:71]
	v_mfma_f32_16x16x32_f16 v[72:75], v[152:155], v[176:179], v[72:75]
	v_mfma_f32_16x16x32_f16 v[72:75], v[148:151], v[172:175], v[72:75]
	v_mfma_f32_16x16x32_f16 v[80:83], v[148:151], v[180:183], v[80:83]
	v_mfma_f32_16x16x32_f16 v[80:83], v[152:155], v[184:187], v[80:83]
	v_mfma_f32_16x16x32_f16 v[76:79], v[142:145], v[184:187], v[76:79]
	v_mfma_f32_16x16x32_f16 v[76:79], v[138:141], v[180:183], v[76:79]
	v_mfma_f32_16x16x32_f16 v[84:87], v[138:141], v[188:191], v[84:87]
	v_mfma_f32_16x16x32_f16 v[84:87], v[142:145], v[192:195], v[84:87]
	v_mfma_f32_16x16x32_f16 v[88:91], v[152:155], v[192:195], v[88:91]
	v_mfma_f32_16x16x32_f16 v[88:91], v[148:151], v[188:191], v[88:91]
	v_mfma_f32_16x16x32_f16 v[96:99], v[148:151], v[196:199], v[96:99]
	v_mfma_f32_16x16x32_f16 v[96:99], v[152:155], v[200:203], v[96:99]
	v_mfma_f32_16x16x32_f16 v[92:95], v[142:145], v[200:203], v[92:95]
	v_mfma_f32_16x16x32_f16 v[92:95], v[138:141], v[196:199], v[92:95]
	v_mfma_f32_16x16x32_f16 v[100:103], v[156:159], v[172:175], v[100:103]
	v_mfma_f32_16x16x32_f16 v[100:103], v[160:163], v[176:179], v[100:103]
	v_mfma_f32_16x16x32_f16 v[104:107], v[168:171], v[176:179], v[104:107]
	v_mfma_f32_16x16x32_f16 v[104:107], v[164:167], v[172:175], v[104:107]
	v_mfma_f32_16x16x32_f16 v[112:115], v[164:167], v[180:183], v[112:115]
	v_mfma_f32_16x16x32_f16 v[112:115], v[168:171], v[184:187], v[112:115]
	v_mfma_f32_16x16x32_f16 v[108:111], v[160:163], v[184:187], v[108:111]
	v_mfma_f32_16x16x32_f16 v[108:111], v[156:159], v[180:183], v[108:111]
	v_mfma_f32_16x16x32_f16 v[116:119], v[156:159], v[188:191], v[116:119]
	v_mfma_f32_16x16x32_f16 v[116:119], v[160:163], v[192:195], v[116:119]
	v_mfma_f32_16x16x32_f16 v[120:123], v[168:171], v[192:195], v[120:123]
	v_mfma_f32_16x16x32_f16 v[120:123], v[164:167], v[188:191], v[120:123]
	v_mfma_f32_16x16x32_f16 v[128:131], v[164:167], v[196:199], v[128:131]
	v_mfma_f32_16x16x32_f16 v[128:131], v[168:171], v[200:203], v[128:131]
	s_setprio 2
	s_barrier
	v_mfma_f32_16x16x32_f16 v[124:127], v[160:163], v[200:203], v[124:127]
	v_mfma_f32_16x16x32_f16 v[124:127], v[156:159], v[196:199], v[124:127]
	s_setprio 0
	s_add_i32 s28, s28, 2
	s_add_u32 s8, s8, 0x100
	s_addc_u32 s9, s9, 0
	s_add_u32 s26, s26, 0x100
	s_addc_u32 s27, s27, 0
	s_cmp_gt_u32 s28, 29
	s_cbranch_scc0 .LBB0_532
	s_and_b64 vcc, exec, s[50:51]
	s_cbranch_vccz .LBB0_535
	s_barrier

.LBB0_641:
	s_add_i32 s43, 0, 0x10000
	s_add_i32 s71, 0, 0x14000
	v_add_u32_e32 v16, s43, v232
	v_add_u32_e32 v32, s71, v232
	ds_read_b128 v[4:7], v16
	ds_read_b128 v[8:11], v16 offset:1024
	ds_read_b128 v[12:15], v16 offset:2048
	ds_read_b128 v[16:19], v16 offset:3072
	ds_read_b128 v[20:23], v32
	ds_read_b128 v[24:27], v32 offset:1024
	ds_read_b128 v[28:31], v32 offset:2048
	ds_read_b128 v[32:35], v32 offset:3072
	v_add_u32_e32 v233, 0, v231
	ds_read_b128 v[36:39], v233
	ds_read_b128 v[40:43], v233 offset:1024
	ds_read_b128 v[44:47], v233 offset:2048
	ds_read_b128 v[48:51], v233 offset:3072
	ds_read_b128 v[52:55], v233 offset:4096
	ds_read_b128 v[56:59], v233 offset:5120
	ds_read_b128 v[60:63], v233 offset:6144
	ds_read_b128 v[64:67], v233 offset:7168
	s_waitcnt vmcnt(8)
	s_waitcnt lgkmcnt(0)
	s_barrier
	s_setprio 1
	v_mfma_f32_16x16x32_bf16 v[68:71], v[4:7], v[36:39], 0
	v_mfma_f32_16x16x32_bf16 v[68:71], v[8:11], v[40:43], v[68:71]
	v_mfma_f32_16x16x32_bf16 v[72:75], v[12:15], v[36:39], 0
	v_mfma_f32_16x16x32_bf16 v[72:75], v[16:19], v[40:43], v[72:75]
	v_mfma_f32_16x16x32_bf16 v[80:83], v[12:15], v[44:47], 0
	v_mfma_f32_16x16x32_bf16 v[80:83], v[16:19], v[48:51], v[80:83]
	v_mfma_f32_16x16x32_bf16 v[76:79], v[4:7], v[44:47], 0
	v_mfma_f32_16x16x32_bf16 v[76:79], v[8:11], v[48:51], v[76:79]
	v_mfma_f32_16x16x32_bf16 v[84:87], v[4:7], v[52:55], 0
	v_mfma_f32_16x16x32_bf16 v[84:87], v[8:11], v[56:59], v[84:87]
	v_mfma_f32_16x16x32_bf16 v[88:91], v[12:15], v[52:55], 0
	v_mfma_f32_16x16x32_bf16 v[88:91], v[16:19], v[56:59], v[88:91]
	v_mfma_f32_16x16x32_bf16 v[96:99], v[12:15], v[60:63], 0
	v_mfma_f32_16x16x32_bf16 v[96:99], v[16:19], v[64:67], v[96:99]
	v_mfma_f32_16x16x32_bf16 v[92:95], v[4:7], v[60:63], 0
	v_mfma_f32_16x16x32_bf16 v[92:95], v[8:11], v[64:67], v[92:95]
	v_mfma_f32_16x16x32_bf16 v[100:103], v[20:23], v[36:39], 0
	v_mfma_f32_16x16x32_bf16 v[36:39], v[28:31], v[36:39], 0
	v_mfma_f32_16x16x32_bf16 v[104:107], v[20:23], v[44:47], 0
	v_mfma_f32_16x16x32_bf16 v[44:47], v[28:31], v[44:47], 0
	v_mfma_f32_16x16x32_bf16 v[108:111], v[20:23], v[52:55], 0
	v_mfma_f32_16x16x32_bf16 v[52:55], v[28:31], v[52:55], 0
	v_mfma_f32_16x16x32_bf16 v[112:115], v[20:23], v[60:63], 0
	v_mfma_f32_16x16x32_bf16 v[60:63], v[28:31], v[60:63], 0
	v_mfma_f32_16x16x32_bf16 v[100:103], v[24:27], v[40:43], v[100:103]
	v_mfma_f32_16x16x32_bf16 v[40:43], v[32:35], v[40:43], v[36:39]
	v_mfma_f32_16x16x32_bf16 v[104:107], v[24:27], v[48:51], v[104:107]
	v_mfma_f32_16x16x32_bf16 v[48:51], v[32:35], v[48:51], v[44:47]
	v_mfma_f32_16x16x32_bf16 v[108:111], v[24:27], v[56:59], v[108:111]
	v_mfma_f32_16x16x32_bf16 v[56:59], v[32:35], v[56:59], v[52:55]
	s_setprio 2
	s_barrier
	v_mfma_f32_16x16x32_bf16 v[112:115], v[24:27], v[64:67], v[112:115]
	v_mfma_f32_16x16x32_bf16 v[64:67], v[32:35], v[64:67], v[60:63]
	s_setprio 0
	v_lshl_add_u64 v[186:187], s[8:9], 0, v[2:3]
	s_add_i32 s43, s43, s54
	v_mov_b32_e32 v191, v3
	v_lshl_add_u64 v[134:135], v[186:187], 0, s[80:81]
	s_mov_b32 m0, s43
	v_lshl_add_u64 v[246:247], s[8:9], 0, v[190:191]
	ds_read_b128 v[36:39], v233 offset:16384
	ds_read_b128 v[44:47], v233 offset:17408
	ds_read_b128 v[52:55], v233 offset:18432
	ds_read_b128 v[60:63], v233 offset:19456
	ds_read_b128 v[116:119], v233 offset:20480
	ds_read_b128 v[120:123], v233 offset:21504
	ds_read_b128 v[124:127], v233 offset:22528
	ds_read_b128 v[128:131], v233 offset:23552
	global_load_lds_dwordx4 v[134:135], off
	v_lshl_add_u64 v[134:135], v[246:247], 0, s[80:81]
	s_add_i32 m0, s43, 0x2000
	s_add_i32 s43, s71, s54
	global_load_lds_dwordx4 v[134:135], off
	s_mov_b32 m0, s43
	v_mov_b32_e32 v133, v3
	global_load_lds_dwordx4 v2, s[16:17]
	s_add_i32 m0, s43, 0x2000
	v_lshl_add_u64 v[248:249], s[6:7], 0, v[132:133]
	v_mov_b32_e32 v189, v3
	global_load_lds_dwordx4 v190, s[16:17]
	v_lshl_add_u64 v[134:135], v[248:249], 0, s[80:81]
	s_mov_b32 m0, s55
	v_lshl_add_u64 v[250:251], s[6:7], 0, v[188:189]
	global_load_lds_dwordx4 v[134:135], off
	v_lshl_add_u64 v[134:135], v[250:251], 0, s[80:81]
	s_mov_b32 m0, s56
	s_nop 0
	global_load_lds_dwordx4 v[134:135], off
	s_waitcnt vmcnt(8)
	s_waitcnt lgkmcnt(0)
	s_barrier
	s_setprio 1
	v_mfma_f32_16x16x32_bf16 v[134:137], v[4:7], v[36:39], 0
	v_mfma_f32_16x16x32_bf16 v[138:141], v[12:15], v[36:39], 0
	v_mfma_f32_16x16x32_bf16 v[142:145], v[4:7], v[52:55], 0
	v_mfma_f32_16x16x32_bf16 v[146:149], v[12:15], v[52:55], 0
	v_mfma_f32_16x16x32_bf16 v[150:153], v[4:7], v[116:119], 0
	v_mfma_f32_16x16x32_bf16 v[154:157], v[12:15], v[116:119], 0
	v_mfma_f32_16x16x32_bf16 v[4:7], v[4:7], v[124:127], 0
	v_mfma_f32_16x16x32_bf16 v[12:15], v[12:15], v[124:127], 0
	v_mfma_f32_16x16x32_bf16 v[134:137], v[8:11], v[44:47], v[134:137]
	v_mfma_f32_16x16x32_bf16 v[138:141], v[16:19], v[44:47], v[138:141]
	v_mfma_f32_16x16x32_bf16 v[142:145], v[8:11], v[60:63], v[142:145]
	v_mfma_f32_16x16x32_bf16 v[146:149], v[16:19], v[60:63], v[146:149]
	v_mfma_f32_16x16x32_bf16 v[150:153], v[8:11], v[120:123], v[150:153]
	v_mfma_f32_16x16x32_bf16 v[154:157], v[16:19], v[120:123], v[154:157]
	v_mfma_f32_16x16x32_bf16 v[158:161], v[8:11], v[128:131], v[4:7]
	v_mfma_f32_16x16x32_bf16 v[162:165], v[16:19], v[128:131], v[12:15]
	v_mfma_f32_16x16x32_bf16 v[4:7], v[20:23], v[36:39], 0
	v_mfma_f32_16x16x32_bf16 v[8:11], v[28:31], v[36:39], 0
	v_mfma_f32_16x16x32_bf16 v[12:15], v[20:23], v[52:55], 0
	v_mfma_f32_16x16x32_bf16 v[16:19], v[28:31], v[52:55], 0
	v_mfma_f32_16x16x32_bf16 v[36:39], v[20:23], v[116:119], 0
	v_mfma_f32_16x16x32_bf16 v[52:55], v[28:31], v[116:119], 0
	v_mfma_f32_16x16x32_bf16 v[20:23], v[20:23], v[124:127], 0
	v_mfma_f32_16x16x32_bf16 v[28:31], v[28:31], v[124:127], 0
	v_mfma_f32_16x16x32_bf16 v[116:119], v[24:27], v[44:47], v[4:7]
	v_mfma_f32_16x16x32_bf16 v[124:127], v[32:35], v[44:47], v[8:11]
	v_mfma_f32_16x16x32_bf16 v[174:177], v[24:27], v[120:123], v[36:39]
	v_mfma_f32_16x16x32_bf16 v[120:123], v[32:35], v[120:123], v[52:55]
	v_mfma_f32_16x16x32_bf16 v[178:181], v[24:27], v[128:131], v[20:23]
	v_mfma_f32_16x16x32_bf16 v[128:131], v[32:35], v[128:131], v[28:31]
	s_setprio 2
	s_barrier
	v_mfma_f32_16x16x32_bf16 v[166:169], v[24:27], v[60:63], v[12:15]
	v_mfma_f32_16x16x32_bf16 v[170:173], v[32:35], v[60:63], v[16:19]
	s_setprio 0
	s_add_i32 s43, 0, 0x18000
	v_add_u32_e32 v4, s43, v232
	s_add_i32 s71, 0, 0x1c000
	ds_read_b128 v[182:185], v4
	ds_read_b128 v[192:195], v4 offset:1024
	ds_read_b128 v[196:199], v4 offset:2048
	ds_read_b128 v[200:203], v4 offset:3072
	v_add_u32_e32 v4, s71, v232
	ds_read_b128 v[204:207], v4
	ds_read_b128 v[208:211], v4 offset:1024
	ds_read_b128 v[212:215], v4 offset:2048
	ds_read_b128 v[216:219], v4 offset:3072
	s_mov_b32 m0, s57
	ds_read_b128 v[44:47], v233 offset:32768
	ds_read_b128 v[52:55], v233 offset:33792
	ds_read_b128 v[60:63], v233 offset:34816
	ds_read_b128 v[220:223], v233 offset:35840
	ds_read_b128 v[224:227], v233 offset:36864
	ds_read_b128 v[234:237], v233 offset:37888
	ds_read_b128 v[238:241], v233 offset:38912
	ds_read_b128 v[242:245], v233 offset:39936
	global_load_lds_dwordx4 v132, s[26:27]
	s_mov_b32 m0, s58
	s_nop 0
	global_load_lds_dwordx4 v188, s[26:27]
	s_waitcnt vmcnt(8)
	s_waitcnt lgkmcnt(0)
	s_barrier
	s_setprio 1
	v_mfma_f32_16x16x32_bf16 v[4:7], v[182:185], v[44:47], v[68:71]
	v_mfma_f32_16x16x32_bf16 v[8:11], v[196:199], v[44:47], v[72:75]
	v_mfma_f32_16x16x32_bf16 v[12:15], v[182:185], v[60:63], v[76:79]
	v_mfma_f32_16x16x32_bf16 v[16:19], v[196:199], v[60:63], v[80:83]
	v_mfma_f32_16x16x32_bf16 v[20:23], v[182:185], v[224:227], v[84:87]
	v_mfma_f32_16x16x32_bf16 v[24:27], v[196:199], v[224:227], v[88:91]
	v_mfma_f32_16x16x32_bf16 v[28:31], v[182:185], v[238:241], v[92:95]
	v_mfma_f32_16x16x32_bf16 v[32:35], v[196:199], v[238:241], v[96:99]
	v_mfma_f32_16x16x32_bf16 v[4:7], v[192:195], v[52:55], v[4:7]
	v_mfma_f32_16x16x32_bf16 v[8:11], v[200:203], v[52:55], v[8:11]
	v_mfma_f32_16x16x32_bf16 v[12:15], v[192:195], v[220:223], v[12:15]
	v_mfma_f32_16x16x32_bf16 v[16:19], v[200:203], v[220:223], v[16:19]
	v_mfma_f32_16x16x32_bf16 v[20:23], v[192:195], v[234:237], v[20:23]
	v_mfma_f32_16x16x32_bf16 v[24:27], v[200:203], v[234:237], v[24:27]
	v_mfma_f32_16x16x32_bf16 v[28:31], v[192:195], v[242:245], v[28:31]
	v_mfma_f32_16x16x32_bf16 v[32:35], v[200:203], v[242:245], v[32:35]
	v_mfma_f32_16x16x32_bf16 v[36:39], v[204:207], v[44:47], v[100:103]
	v_mfma_f32_16x16x32_bf16 v[40:43], v[212:215], v[44:47], v[40:43]
	v_mfma_f32_16x16x32_bf16 v[36:39], v[208:211], v[52:55], v[36:39]
	v_mfma_f32_16x16x32_bf16 v[40:43], v[216:219], v[52:55], v[40:43]
	v_mfma_f32_16x16x32_bf16 v[44:47], v[204:207], v[60:63], v[104:107]
	v_mfma_f32_16x16x32_bf16 v[48:51], v[212:215], v[60:63], v[48:51]
	v_mfma_f32_16x16x32_bf16 v[52:55], v[204:207], v[224:227], v[108:111]
	v_mfma_f32_16x16x32_bf16 v[56:59], v[212:215], v[224:227], v[56:59]
	v_mfma_f32_16x16x32_bf16 v[60:63], v[204:207], v[238:241], v[112:115]
	v_mfma_f32_16x16x32_bf16 v[64:67], v[212:215], v[238:241], v[64:67]
	v_mfma_f32_16x16x32_bf16 v[44:47], v[208:211], v[220:223], v[44:47]
	v_mfma_f32_16x16x32_bf16 v[48:51], v[216:219], v[220:223], v[48:51]
	v_mfma_f32_16x16x32_bf16 v[52:55], v[208:211], v[234:237], v[52:55]
	v_mfma_f32_16x16x32_bf16 v[56:59], v[216:219], v[234:237], v[56:59]
	s_setprio 2
	s_barrier
	v_mfma_f32_16x16x32_bf16 v[60:63], v[208:211], v[242:245], v[60:63]
	v_mfma_f32_16x16x32_bf16 v[64:67], v[216:219], v[242:245], v[64:67]
	s_setprio 0
	s_add_i32 s43, s43, s54
	v_lshl_add_u64 v[68:69], v[186:187], 0, s[0:1]
	s_mov_b32 m0, s43
	ds_read_b128 v[104:107], v233 offset:49152
	ds_read_b128 v[108:111], v233 offset:50176
	ds_read_b128 v[112:115], v233 offset:51200
	ds_read_b128 v[220:223], v233 offset:52224
	ds_read_b128 v[224:227], v233 offset:53248
	ds_read_b128 v[234:237], v233 offset:54272
	ds_read_b128 v[238:241], v233 offset:55296
	ds_read_b128 v[242:245], v233 offset:56320
	global_load_lds_dwordx4 v[68:69], off
	v_lshl_add_u64 v[68:69], v[246:247], 0, s[0:1]
	s_add_i32 m0, s43, 0x2000
	s_add_i32 s43, s71, s54
	global_load_lds_dwordx4 v[68:69], off
	s_mov_b32 m0, s43
	v_lshl_add_u64 v[68:69], v[248:249], 0, s[0:1]
	global_load_lds_dwordx4 v2, s[28:29]
	s_add_i32 m0, s43, 0x2000
	s_nop 0
	global_load_lds_dwordx4 v190, s[28:29]
	s_mov_b32 m0, s62
	s_nop 0
	global_load_lds_dwordx4 v[68:69], off
	v_lshl_add_u64 v[68:69], v[250:251], 0, s[0:1]
	s_mov_b32 m0, s63
	s_nop 0
	global_load_lds_dwordx4 v[68:69], off
	s_waitcnt vmcnt(8)
	s_waitcnt lgkmcnt(0)
	s_barrier
	s_setprio 1
	v_mfma_f32_16x16x32_bf16 v[68:71], v[182:185], v[104:107], v[134:137]
	v_mfma_f32_16x16x32_bf16 v[72:75], v[196:199], v[104:107], v[138:141]
	v_mfma_f32_16x16x32_bf16 v[76:79], v[182:185], v[112:115], v[142:145]
	v_mfma_f32_16x16x32_bf16 v[80:83], v[196:199], v[112:115], v[146:149]
	v_mfma_f32_16x16x32_bf16 v[84:87], v[182:185], v[224:227], v[150:153]
	v_mfma_f32_16x16x32_bf16 v[88:91], v[196:199], v[224:227], v[154:157]
	v_mfma_f32_16x16x32_bf16 v[92:95], v[182:185], v[238:241], v[158:161]
	v_mfma_f32_16x16x32_bf16 v[96:99], v[196:199], v[238:241], v[162:165]
	v_mfma_f32_16x16x32_bf16 v[68:71], v[192:195], v[108:111], v[68:71]
	v_mfma_f32_16x16x32_bf16 v[72:75], v[200:203], v[108:111], v[72:75]
	v_mfma_f32_16x16x32_bf16 v[76:79], v[192:195], v[220:223], v[76:79]
	v_mfma_f32_16x16x32_bf16 v[80:83], v[200:203], v[220:223], v[80:83]
	v_mfma_f32_16x16x32_bf16 v[84:87], v[192:195], v[234:237], v[84:87]
	v_mfma_f32_16x16x32_bf16 v[88:91], v[200:203], v[234:237], v[88:91]
	v_mfma_f32_16x16x32_bf16 v[92:95], v[192:195], v[242:245], v[92:95]
	v_mfma_f32_16x16x32_bf16 v[96:99], v[200:203], v[242:245], v[96:99]
	v_mfma_f32_16x16x32_bf16 v[100:103], v[204:207], v[104:107], v[116:119]
	v_mfma_f32_16x16x32_bf16 v[104:107], v[212:215], v[104:107], v[124:127]
	v_mfma_f32_16x16x32_bf16 v[100:103], v[208:211], v[108:111], v[100:103]
	v_mfma_f32_16x16x32_bf16 v[104:107], v[216:219], v[108:111], v[104:107]
	v_mfma_f32_16x16x32_bf16 v[108:111], v[204:207], v[112:115], v[166:169]
	v_mfma_f32_16x16x32_bf16 v[112:115], v[212:215], v[112:115], v[170:173]
	v_mfma_f32_16x16x32_bf16 v[116:119], v[204:207], v[224:227], v[174:177]
	v_mfma_f32_16x16x32_bf16 v[120:123], v[212:215], v[224:227], v[120:123]
	v_mfma_f32_16x16x32_bf16 v[124:127], v[204:207], v[238:241], v[178:181]
	v_mfma_f32_16x16x32_bf16 v[128:131], v[212:215], v[238:241], v[128:131]
	v_mfma_f32_16x16x32_bf16 v[108:111], v[208:211], v[220:223], v[108:111]
	v_mfma_f32_16x16x32_bf16 v[112:115], v[216:219], v[220:223], v[112:115]
	v_mfma_f32_16x16x32_bf16 v[116:119], v[208:211], v[234:237], v[116:119]
	v_mfma_f32_16x16x32_bf16 v[120:123], v[216:219], v[234:237], v[120:123]
	s_setprio 2
	s_barrier
	v_mfma_f32_16x16x32_bf16 v[124:127], v[208:211], v[242:245], v[124:127]
	v_mfma_f32_16x16x32_bf16 v[128:131], v[216:219], v[242:245], v[128:131]
	s_setprio 0
	s_add_i32 s42, s42, 2
	s_cmp_ge_i32 s42, s38
	s_cbranch_scc0 .LBB0_641
	v_mov_b32_e32 v192, v2
	s_branch .LBB0_644

.LBB0_649:
	s_or_b32 s38, s28, 1
	s_lshl_b64 s[42:43], s[38:39], 7
	s_sub_u32 s38, 0, s42
	s_subb_u32 s42, 0, s43
	s_add_u32 s38, s6, s38
	s_addc_u32 s43, s7, s42
	s_add_i32 s71, 0, 0x10000
	s_add_i32 s72, 0, 0x14000
	v_add_u32_e32 v144, s71, v232
	v_add_u32_e32 v160, s72, v232
	s_waitcnt lgkmcnt(0)
	ds_read_b128 v[132:135], v144
	ds_read_b128 v[136:139], v144 offset:1024
	ds_read_b128 v[140:143], v144 offset:2048
	ds_read_b128 v[144:147], v144 offset:3072
	ds_read_b128 v[148:151], v160
	ds_read_b128 v[152:155], v160 offset:1024
	ds_read_b128 v[156:159], v160 offset:2048
	ds_read_b128 v[160:163], v160 offset:3072
	s_add_u32 s42, s38, 0x160000
	s_mov_b32 m0, s64
	v_add_u32_e32 v210, 0, v231
	s_addc_u32 s43, s43, 0
	ds_read_b128 v[164:167], v210
	ds_read_b128 v[168:171], v210 offset:1024
	ds_read_b128 v[172:175], v210 offset:2048
	ds_read_b128 v[176:179], v210 offset:3072
	ds_read_b128 v[180:183], v210 offset:4096
	ds_read_b128 v[184:187], v210 offset:5120
	ds_read_b128 v[194:197], v210 offset:6144
	ds_read_b128 v[198:201], v210 offset:7168
	global_load_lds_dwordx4 v2, s[42:43]
	s_mov_b32 m0, s65
	v_mov_b32_e32 v189, v3
	global_load_lds_dwordx4 v188, s[42:43]
	s_waitcnt vmcnt(8)
	s_waitcnt lgkmcnt(0)
	s_barrier
	s_setprio 1
	v_mfma_f32_16x16x32_bf16 v[4:7], v[132:135], v[164:167], v[4:7]
	v_mfma_f32_16x16x32_bf16 v[4:7], v[136:139], v[168:171], v[4:7]
	v_mfma_f32_16x16x32_bf16 v[8:11], v[144:147], v[168:171], v[8:11]
	v_mfma_f32_16x16x32_bf16 v[8:11], v[140:143], v[164:167], v[8:11]
	v_mfma_f32_16x16x32_bf16 v[16:19], v[140:143], v[172:175], v[16:19]
	v_mfma_f32_16x16x32_bf16 v[16:19], v[144:147], v[176:179], v[16:19]
	v_mfma_f32_16x16x32_bf16 v[12:15], v[136:139], v[176:179], v[12:15]
	v_mfma_f32_16x16x32_bf16 v[12:15], v[132:135], v[172:175], v[12:15]
	v_mfma_f32_16x16x32_bf16 v[20:23], v[132:135], v[180:183], v[20:23]
	v_mfma_f32_16x16x32_bf16 v[20:23], v[136:139], v[184:187], v[20:23]
	v_mfma_f32_16x16x32_bf16 v[24:27], v[144:147], v[184:187], v[24:27]
	v_mfma_f32_16x16x32_bf16 v[24:27], v[140:143], v[180:183], v[24:27]
	v_mfma_f32_16x16x32_bf16 v[32:35], v[140:143], v[194:197], v[32:35]
	v_mfma_f32_16x16x32_bf16 v[32:35], v[144:147], v[198:201], v[32:35]
	v_mfma_f32_16x16x32_bf16 v[28:31], v[136:139], v[198:201], v[28:31]
	v_mfma_f32_16x16x32_bf16 v[28:31], v[132:135], v[194:197], v[28:31]
	v_mfma_f32_16x16x32_bf16 v[36:39], v[148:151], v[164:167], v[36:39]
	v_mfma_f32_16x16x32_bf16 v[36:39], v[152:155], v[168:171], v[36:39]
	v_mfma_f32_16x16x32_bf16 v[40:43], v[160:163], v[168:171], v[40:43]
	v_mfma_f32_16x16x32_bf16 v[40:43], v[156:159], v[164:167], v[40:43]
	v_mfma_f32_16x16x32_bf16 v[48:51], v[156:159], v[172:175], v[48:51]
	v_mfma_f32_16x16x32_bf16 v[48:51], v[160:163], v[176:179], v[48:51]
	v_mfma_f32_16x16x32_bf16 v[44:47], v[152:155], v[176:179], v[44:47]
	v_mfma_f32_16x16x32_bf16 v[44:47], v[148:151], v[172:175], v[44:47]
	v_mfma_f32_16x16x32_bf16 v[52:55], v[148:151], v[180:183], v[52:55]
	v_mfma_f32_16x16x32_bf16 v[52:55], v[152:155], v[184:187], v[52:55]
	v_mfma_f32_16x16x32_bf16 v[56:59], v[160:163], v[184:187], v[56:59]
	v_mfma_f32_16x16x32_bf16 v[56:59], v[156:159], v[180:183], v[56:59]
	v_mfma_f32_16x16x32_bf16 v[64:67], v[156:159], v[194:197], v[64:67]
	v_mfma_f32_16x16x32_bf16 v[64:67], v[160:163], v[198:201], v[64:67]
	s_setprio 2
	s_barrier
	v_mfma_f32_16x16x32_bf16 v[60:63], v[152:155], v[198:201], v[60:63]
	v_mfma_f32_16x16x32_bf16 v[60:63], v[148:151], v[194:197], v[60:63]
	s_setprio 0
	s_add_i32 s38, s71, s54
	s_mov_b32 m0, s38
	ds_read_b128 v[164:167], v210 offset:16384
	ds_read_b128 v[168:171], v210 offset:17408
	ds_read_b128 v[172:175], v210 offset:18432
	ds_read_b128 v[176:179], v210 offset:19456
	ds_read_b128 v[180:183], v210 offset:20480
	ds_read_b128 v[184:187], v210 offset:21504
	ds_read_b128 v[194:197], v210 offset:22528
	ds_read_b128 v[198:201], v210 offset:23552
	global_load_lds_dwordx4 v192, s[16:17]
	s_add_i32 m0, s38, 0x2000
	s_add_u32 s42, s16, 0x160000
	s_addc_u32 s43, s17, 0
	s_add_i32 s38, s72, s54
	global_load_lds_dwordx4 v190, s[16:17]
	s_mov_b32 m0, s38
	v_mov_b32_e32 v193, v3
	global_load_lds_dwordx4 v192, s[42:43]
	s_add_i32 m0, s38, 0x2000
	v_mov_b32_e32 v191, v3
	global_load_lds_dwordx4 v190, s[42:43]
	s_mov_b32 m0, s55
	v_lshl_add_u64 v[202:203], s[16:17], 0, v[192:193]
	global_load_lds_dwordx4 v2, s[26:27]
	s_mov_b32 m0, s56
	v_lshl_add_u64 v[204:205], s[16:17], 0, v[190:191]
	global_load_lds_dwordx4 v188, s[26:27]
	s_waitcnt vmcnt(8)
	s_waitcnt lgkmcnt(0)
	v_lshl_add_u64 v[206:207], s[26:27], 0, v[2:3]
	v_lshl_add_u64 v[208:209], s[26:27], 0, v[188:189]
	s_barrier
	s_setprio 1
	v_mfma_f32_16x16x32_bf16 v[68:71], v[132:135], v[164:167], v[68:71]
	v_mfma_f32_16x16x32_bf16 v[68:71], v[136:139], v[168:171], v[68:71]
	v_mfma_f32_16x16x32_bf16 v[72:75], v[144:147], v[168:171], v[72:75]
	v_mfma_f32_16x16x32_bf16 v[72:75], v[140:143], v[164:167], v[72:75]
	v_mfma_f32_16x16x32_bf16 v[80:83], v[140:143], v[172:175], v[80:83]
	v_mfma_f32_16x16x32_bf16 v[80:83], v[144:147], v[176:179], v[80:83]
	v_mfma_f32_16x16x32_bf16 v[76:79], v[136:139], v[176:179], v[76:79]
	v_mfma_f32_16x16x32_bf16 v[76:79], v[132:135], v[172:175], v[76:79]
	v_mfma_f32_16x16x32_bf16 v[84:87], v[132:135], v[180:183], v[84:87]
	v_mfma_f32_16x16x32_bf16 v[84:87], v[136:139], v[184:187], v[84:87]
	v_mfma_f32_16x16x32_bf16 v[88:91], v[144:147], v[184:187], v[88:91]
	v_mfma_f32_16x16x32_bf16 v[88:91], v[140:143], v[180:183], v[88:91]
	v_mfma_f32_16x16x32_bf16 v[96:99], v[140:143], v[194:197], v[96:99]
	v_mfma_f32_16x16x32_bf16 v[96:99], v[144:147], v[198:201], v[96:99]
	v_mfma_f32_16x16x32_bf16 v[92:95], v[136:139], v[198:201], v[92:95]
	v_mfma_f32_16x16x32_bf16 v[92:95], v[132:135], v[194:197], v[92:95]
	v_mfma_f32_16x16x32_bf16 v[100:103], v[148:151], v[164:167], v[100:103]
	v_mfma_f32_16x16x32_bf16 v[100:103], v[152:155], v[168:171], v[100:103]
	v_mfma_f32_16x16x32_bf16 v[104:107], v[160:163], v[168:171], v[104:107]
	v_mfma_f32_16x16x32_bf16 v[104:107], v[156:159], v[164:167], v[104:107]
	v_mfma_f32_16x16x32_bf16 v[112:115], v[156:159], v[172:175], v[112:115]
	v_mfma_f32_16x16x32_bf16 v[112:115], v[160:163], v[176:179], v[112:115]
	v_mfma_f32_16x16x32_bf16 v[108:111], v[152:155], v[176:179], v[108:111]
	v_mfma_f32_16x16x32_bf16 v[108:111], v[148:151], v[172:175], v[108:111]
	v_mfma_f32_16x16x32_bf16 v[116:119], v[148:151], v[180:183], v[116:119]
	v_mfma_f32_16x16x32_bf16 v[116:119], v[152:155], v[184:187], v[116:119]
	v_mfma_f32_16x16x32_bf16 v[120:123], v[160:163], v[184:187], v[120:123]
	v_mfma_f32_16x16x32_bf16 v[120:123], v[156:159], v[180:183], v[120:123]
	v_mfma_f32_16x16x32_bf16 v[128:131], v[156:159], v[194:197], v[128:131]
	v_mfma_f32_16x16x32_bf16 v[128:131], v[160:163], v[198:201], v[128:131]
	s_setprio 2
	s_barrier
	v_mfma_f32_16x16x32_bf16 v[124:127], v[152:155], v[198:201], v[124:127]
	v_mfma_f32_16x16x32_bf16 v[124:127], v[148:151], v[194:197], v[124:127]
	s_setprio 0
	s_add_i32 s38, 0, 0x18000
	s_add_i32 s42, 0, 0x1c000
	v_add_u32_e32 v144, s38, v232
	v_add_u32_e32 v160, s42, v232
	ds_read_b128 v[132:135], v144
	ds_read_b128 v[136:139], v144 offset:1024
	ds_read_b128 v[140:143], v144 offset:2048
	ds_read_b128 v[144:147], v144 offset:3072
	ds_read_b128 v[148:151], v160
	ds_read_b128 v[152:155], v160 offset:1024
	ds_read_b128 v[156:159], v160 offset:2048
	ds_read_b128 v[160:163], v160 offset:3072
	s_add_u32 s26, s26, 0x160000
	s_addc_u32 s27, s27, 0
	s_mov_b32 m0, s57
	ds_read_b128 v[164:167], v210 offset:32768
	ds_read_b128 v[168:171], v210 offset:33792
	ds_read_b128 v[172:175], v210 offset:34816
	ds_read_b128 v[176:179], v210 offset:35840
	ds_read_b128 v[180:183], v210 offset:36864
	ds_read_b128 v[184:187], v210 offset:37888
	ds_read_b128 v[194:197], v210 offset:38912
	ds_read_b128 v[198:201], v210 offset:39936
	global_load_lds_dwordx4 v2, s[26:27]
	s_mov_b32 m0, s58
	s_nop 0
	global_load_lds_dwordx4 v188, s[26:27]
	s_waitcnt vmcnt(8)
	s_waitcnt lgkmcnt(0)
	s_barrier
	s_setprio 1
	v_mfma_f32_16x16x32_bf16 v[4:7], v[132:135], v[164:167], v[4:7]
	v_mfma_f32_16x16x32_bf16 v[4:7], v[136:139], v[168:171], v[4:7]
	v_mfma_f32_16x16x32_bf16 v[8:11], v[144:147], v[168:171], v[8:11]
	v_mfma_f32_16x16x32_bf16 v[8:11], v[140:143], v[164:167], v[8:11]
	v_mfma_f32_16x16x32_bf16 v[16:19], v[140:143], v[172:175], v[16:19]
	v_mfma_f32_16x16x32_bf16 v[16:19], v[144:147], v[176:179], v[16:19]
	v_mfma_f32_16x16x32_bf16 v[12:15], v[136:139], v[176:179], v[12:15]
	v_mfma_f32_16x16x32_bf16 v[12:15], v[132:135], v[172:175], v[12:15]
	v_mfma_f32_16x16x32_bf16 v[20:23], v[132:135], v[180:183], v[20:23]
	v_mfma_f32_16x16x32_bf16 v[20:23], v[136:139], v[184:187], v[20:23]
	v_mfma_f32_16x16x32_bf16 v[24:27], v[144:147], v[184:187], v[24:27]
	v_mfma_f32_16x16x32_bf16 v[24:27], v[140:143], v[180:183], v[24:27]
	v_mfma_f32_16x16x32_bf16 v[32:35], v[140:143], v[194:197], v[32:35]
	v_mfma_f32_16x16x32_bf16 v[32:35], v[144:147], v[198:201], v[32:35]
	v_mfma_f32_16x16x32_bf16 v[28:31], v[136:139], v[198:201], v[28:31]
	v_mfma_f32_16x16x32_bf16 v[28:31], v[132:135], v[194:197], v[28:31]
	v_mfma_f32_16x16x32_bf16 v[36:39], v[148:151], v[164:167], v[36:39]
	v_mfma_f32_16x16x32_bf16 v[36:39], v[152:155], v[168:171], v[36:39]
	v_mfma_f32_16x16x32_bf16 v[40:43], v[160:163], v[168:171], v[40:43]
	v_mfma_f32_16x16x32_bf16 v[40:43], v[156:159], v[164:167], v[40:43]
	v_mfma_f32_16x16x32_bf16 v[48:51], v[156:159], v[172:175], v[48:51]
	v_mfma_f32_16x16x32_bf16 v[48:51], v[160:163], v[176:179], v[48:51]
	v_mfma_f32_16x16x32_bf16 v[44:47], v[152:155], v[176:179], v[44:47]
	v_mfma_f32_16x16x32_bf16 v[44:47], v[148:151], v[172:175], v[44:47]
	v_mfma_f32_16x16x32_bf16 v[52:55], v[148:151], v[180:183], v[52:55]
	v_mfma_f32_16x16x32_bf16 v[52:55], v[152:155], v[184:187], v[52:55]
	v_mfma_f32_16x16x32_bf16 v[56:59], v[160:163], v[184:187], v[56:59]
	v_mfma_f32_16x16x32_bf16 v[56:59], v[156:159], v[180:183], v[56:59]
	v_mfma_f32_16x16x32_bf16 v[64:67], v[156:159], v[194:197], v[64:67]
	v_mfma_f32_16x16x32_bf16 v[64:67], v[160:163], v[198:201], v[64:67]
	s_setprio 2
	s_barrier
	v_mfma_f32_16x16x32_bf16 v[60:63], v[152:155], v[198:201], v[60:63]
	v_mfma_f32_16x16x32_bf16 v[60:63], v[148:151], v[194:197], v[60:63]
	s_setprio 0
	s_add_i32 s26, s38, s54
	v_lshl_add_u64 v[202:203], v[202:203], 0, s[4:5]
	s_mov_b32 m0, s26
	ds_read_b128 v[164:167], v210 offset:49152
	ds_read_b128 v[168:171], v210 offset:50176
	ds_read_b128 v[172:175], v210 offset:51200
	ds_read_b128 v[176:179], v210 offset:52224
	ds_read_b128 v[180:183], v210 offset:53248
	ds_read_b128 v[184:187], v210 offset:54272
	ds_read_b128 v[194:197], v210 offset:55296
	ds_read_b128 v[198:201], v210 offset:56320
	global_load_lds_dwordx4 v[202:203], off
	s_add_i32 m0, s26, 0x2000
	s_add_u32 s16, s16, 0x15ff80
	v_lshl_add_u64 v[202:203], v[204:205], 0, s[4:5]
	s_addc_u32 s17, s17, 0
	s_add_i32 s26, s42, s54
	global_load_lds_dwordx4 v[202:203], off
	s_mov_b32 m0, s26
	v_lshl_add_u64 v[202:203], v[206:207], 0, s[4:5]
	global_load_lds_dwordx4 v192, s[16:17]
	s_add_i32 m0, s26, 0x2000
	s_nop 0
	global_load_lds_dwordx4 v190, s[16:17]
	s_mov_b32 m0, s62
	s_nop 0
	global_load_lds_dwordx4 v[202:203], off
	v_lshl_add_u64 v[202:203], v[208:209], 0, s[4:5]
	s_mov_b32 m0, s63
	s_nop 0
	global_load_lds_dwordx4 v[202:203], off
	s_waitcnt vmcnt(8)
	s_waitcnt lgkmcnt(0)
	s_barrier
	s_setprio 1
	v_mfma_f32_16x16x32_bf16 v[68:71], v[132:135], v[164:167], v[68:71]
	v_mfma_f32_16x16x32_bf16 v[68:71], v[136:139], v[168:171], v[68:71]
	v_mfma_f32_16x16x32_bf16 v[72:75], v[144:147], v[168:171], v[72:75]
	v_mfma_f32_16x16x32_bf16 v[72:75], v[140:143], v[164:167], v[72:75]
	v_mfma_f32_16x16x32_bf16 v[80:83], v[140:143], v[172:175], v[80:83]
	v_mfma_f32_16x16x32_bf16 v[80:83], v[144:147], v[176:179], v[80:83]
	v_mfma_f32_16x16x32_bf16 v[76:79], v[136:139], v[176:179], v[76:79]
	v_mfma_f32_16x16x32_bf16 v[76:79], v[132:135], v[172:175], v[76:79]
	v_mfma_f32_16x16x32_bf16 v[84:87], v[132:135], v[180:183], v[84:87]
	v_mfma_f32_16x16x32_bf16 v[84:87], v[136:139], v[184:187], v[84:87]
	v_mfma_f32_16x16x32_bf16 v[88:91], v[144:147], v[184:187], v[88:91]
	v_mfma_f32_16x16x32_bf16 v[88:91], v[140:143], v[180:183], v[88:91]
	v_mfma_f32_16x16x32_bf16 v[96:99], v[140:143], v[194:197], v[96:99]
	v_mfma_f32_16x16x32_bf16 v[96:99], v[144:147], v[198:201], v[96:99]
	v_mfma_f32_16x16x32_bf16 v[92:95], v[136:139], v[198:201], v[92:95]
	v_mfma_f32_16x16x32_bf16 v[92:95], v[132:135], v[194:197], v[92:95]
	v_mfma_f32_16x16x32_bf16 v[100:103], v[148:151], v[164:167], v[100:103]
	v_mfma_f32_16x16x32_bf16 v[100:103], v[152:155], v[168:171], v[100:103]
	v_mfma_f32_16x16x32_bf16 v[104:107], v[160:163], v[168:171], v[104:107]
	v_mfma_f32_16x16x32_bf16 v[104:107], v[156:159], v[164:167], v[104:107]
	v_mfma_f32_16x16x32_bf16 v[112:115], v[156:159], v[172:175], v[112:115]
	v_mfma_f32_16x16x32_bf16 v[112:115], v[160:163], v[176:179], v[112:115]
	v_mfma_f32_16x16x32_bf16 v[108:111], v[152:155], v[176:179], v[108:111]
	v_mfma_f32_16x16x32_bf16 v[108:111], v[148:151], v[172:175], v[108:111]
	v_mfma_f32_16x16x32_bf16 v[116:119], v[148:151], v[180:183], v[116:119]
	v_mfma_f32_16x16x32_bf16 v[116:119], v[152:155], v[184:187], v[116:119]
	v_mfma_f32_16x16x32_bf16 v[120:123], v[160:163], v[184:187], v[120:123]
	v_mfma_f32_16x16x32_bf16 v[120:123], v[156:159], v[180:183], v[120:123]
	v_mfma_f32_16x16x32_bf16 v[128:131], v[156:159], v[194:197], v[128:131]
	v_mfma_f32_16x16x32_bf16 v[128:131], v[160:163], v[198:201], v[128:131]
	s_setprio 2
	s_barrier
	v_mfma_f32_16x16x32_bf16 v[124:127], v[152:155], v[198:201], v[124:127]
	v_mfma_f32_16x16x32_bf16 v[124:127], v[148:151], v[194:197], v[124:127]
	s_setprio 0
	s_cmpk_gt_u32 s28, 0x55
	s_cbranch_scc1 .LBB0_651
	s_mov_b32 s28, s29
	s_branch .LBB0_645

.LBB0_749:
	s_add_i32 s47, 0, 0x10000
	s_add_i32 s49, 0, 0x14000
	v_add_u32_e32 v16, s47, v147
	v_add_u32_e32 v32, s49, v147
	ds_read_b128 v[4:7], v16
	ds_read_b128 v[8:11], v16 offset:1024
	ds_read_b128 v[12:15], v16 offset:2048
	ds_read_b128 v[16:19], v16 offset:3072
	ds_read_b128 v[20:23], v32
	ds_read_b128 v[24:27], v32 offset:1024
	ds_read_b128 v[28:31], v32 offset:2048
	ds_read_b128 v[32:35], v32 offset:3072
	v_add_u32_e32 v231, 0, v146
	ds_read_b128 v[36:39], v231
	ds_read_b128 v[40:43], v231 offset:1024
	ds_read_b128 v[44:47], v231 offset:2048
	ds_read_b128 v[48:51], v231 offset:3072
	ds_read_b128 v[52:55], v231 offset:4096
	ds_read_b128 v[56:59], v231 offset:5120
	ds_read_b128 v[60:63], v231 offset:6144
	ds_read_b128 v[64:67], v231 offset:7168
	s_waitcnt vmcnt(8)
	s_waitcnt lgkmcnt(0)
	s_barrier
	s_setprio 1
	v_mfma_f32_16x16x32_f16 v[68:71], v[4:7], v[36:39], 0
	v_mfma_f32_16x16x32_f16 v[68:71], v[8:11], v[40:43], v[68:71]
	v_mfma_f32_16x16x32_f16 v[72:75], v[12:15], v[36:39], 0
	v_mfma_f32_16x16x32_f16 v[72:75], v[16:19], v[40:43], v[72:75]
	v_mfma_f32_16x16x32_f16 v[80:83], v[12:15], v[44:47], 0
	v_mfma_f32_16x16x32_f16 v[80:83], v[16:19], v[48:51], v[80:83]
	v_mfma_f32_16x16x32_f16 v[76:79], v[4:7], v[44:47], 0
	v_mfma_f32_16x16x32_f16 v[76:79], v[8:11], v[48:51], v[76:79]
	v_mfma_f32_16x16x32_f16 v[84:87], v[4:7], v[52:55], 0
	v_mfma_f32_16x16x32_f16 v[84:87], v[8:11], v[56:59], v[84:87]
	v_mfma_f32_16x16x32_f16 v[88:91], v[12:15], v[52:55], 0
	v_mfma_f32_16x16x32_f16 v[88:91], v[16:19], v[56:59], v[88:91]
	v_mfma_f32_16x16x32_f16 v[96:99], v[12:15], v[60:63], 0
	v_mfma_f32_16x16x32_f16 v[96:99], v[16:19], v[64:67], v[96:99]
	v_mfma_f32_16x16x32_f16 v[92:95], v[4:7], v[60:63], 0
	v_mfma_f32_16x16x32_f16 v[92:95], v[8:11], v[64:67], v[92:95]
	v_mfma_f32_16x16x32_f16 v[100:103], v[20:23], v[36:39], 0
	v_mfma_f32_16x16x32_f16 v[36:39], v[28:31], v[36:39], 0
	v_mfma_f32_16x16x32_f16 v[104:107], v[20:23], v[44:47], 0
	v_mfma_f32_16x16x32_f16 v[44:47], v[28:31], v[44:47], 0
	v_mfma_f32_16x16x32_f16 v[108:111], v[20:23], v[52:55], 0
	v_mfma_f32_16x16x32_f16 v[52:55], v[28:31], v[52:55], 0
	v_mfma_f32_16x16x32_f16 v[112:115], v[20:23], v[60:63], 0
	v_mfma_f32_16x16x32_f16 v[60:63], v[28:31], v[60:63], 0
	v_mfma_f32_16x16x32_f16 v[100:103], v[24:27], v[40:43], v[100:103]
	v_mfma_f32_16x16x32_f16 v[40:43], v[32:35], v[40:43], v[36:39]
	v_mfma_f32_16x16x32_f16 v[104:107], v[24:27], v[48:51], v[104:107]
	v_mfma_f32_16x16x32_f16 v[48:51], v[32:35], v[48:51], v[44:47]
	v_mfma_f32_16x16x32_f16 v[108:111], v[24:27], v[56:59], v[108:111]
	v_mfma_f32_16x16x32_f16 v[56:59], v[32:35], v[56:59], v[52:55]
	s_setprio 2
	s_barrier
	v_mfma_f32_16x16x32_f16 v[112:115], v[24:27], v[64:67], v[112:115]
	v_mfma_f32_16x16x32_f16 v[64:67], v[32:35], v[64:67], v[60:63]
	s_setprio 0
	v_lshl_add_u64 v[136:137], s[6:7], 0, v[2:3]
	s_add_i32 s47, s47, s62
	v_mov_b32_e32 v135, v3
	v_lshl_add_u64 v[140:141], v[136:137], 0, s[74:75]
	s_mov_b32 m0, s47
	v_lshl_add_u64 v[144:145], s[6:7], 0, v[134:135]
	ds_read_b128 v[36:39], v231 offset:16384
	ds_read_b128 v[44:47], v231 offset:17408
	ds_read_b128 v[52:55], v231 offset:18432
	ds_read_b128 v[60:63], v231 offset:19456
	ds_read_b128 v[116:119], v231 offset:20480
	ds_read_b128 v[120:123], v231 offset:21504
	ds_read_b128 v[124:127], v231 offset:22528
	ds_read_b128 v[128:131], v231 offset:23552
	global_load_lds_dwordx4 v[140:141], off
	v_lshl_add_u64 v[140:141], v[144:145], 0, s[74:75]
	s_add_i32 m0, s47, 0x2000
	s_add_i32 s47, s49, s62
	global_load_lds_dwordx4 v[140:141], off
	s_mov_b32 m0, s47
	v_mov_b32_e32 v139, v3
	global_load_lds_dwordx4 v2, s[16:17]
	s_add_i32 m0, s47, 0x2000
	v_lshl_add_u64 v[248:249], s[8:9], 0, v[138:139]
	v_mov_b32_e32 v133, v3
	global_load_lds_dwordx4 v134, s[16:17]
	v_lshl_add_u64 v[140:141], v[248:249], 0, s[74:75]
	s_mov_b32 m0, s63
	v_lshl_add_u64 v[250:251], s[8:9], 0, v[132:133]
	global_load_lds_dwordx4 v[140:141], off
	v_lshl_add_u64 v[140:141], v[250:251], 0, s[74:75]
	s_mov_b32 m0, s64
	s_nop 0
	global_load_lds_dwordx4 v[140:141], off
	s_waitcnt vmcnt(8)
	s_waitcnt lgkmcnt(0)
	s_barrier
	s_setprio 1
	v_mfma_f32_16x16x32_f16 v[140:143], v[4:7], v[36:39], 0
	v_mfma_f32_16x16x32_f16 v[148:151], v[12:15], v[36:39], 0
	v_mfma_f32_16x16x32_f16 v[152:155], v[4:7], v[52:55], 0
	v_mfma_f32_16x16x32_f16 v[156:159], v[12:15], v[52:55], 0
	v_mfma_f32_16x16x32_f16 v[160:163], v[4:7], v[116:119], 0
	v_mfma_f32_16x16x32_f16 v[164:167], v[12:15], v[116:119], 0
	v_mfma_f32_16x16x32_f16 v[4:7], v[4:7], v[124:127], 0
	v_mfma_f32_16x16x32_f16 v[12:15], v[12:15], v[124:127], 0
	v_mfma_f32_16x16x32_f16 v[140:143], v[8:11], v[44:47], v[140:143]
	v_mfma_f32_16x16x32_f16 v[148:151], v[16:19], v[44:47], v[148:151]
	v_mfma_f32_16x16x32_f16 v[152:155], v[8:11], v[60:63], v[152:155]
	v_mfma_f32_16x16x32_f16 v[156:159], v[16:19], v[60:63], v[156:159]
	v_mfma_f32_16x16x32_f16 v[160:163], v[8:11], v[120:123], v[160:163]
	v_mfma_f32_16x16x32_f16 v[164:167], v[16:19], v[120:123], v[164:167]
	v_mfma_f32_16x16x32_f16 v[168:171], v[8:11], v[128:131], v[4:7]
	v_mfma_f32_16x16x32_f16 v[172:175], v[16:19], v[128:131], v[12:15]
	v_mfma_f32_16x16x32_f16 v[4:7], v[20:23], v[36:39], 0
	v_mfma_f32_16x16x32_f16 v[8:11], v[28:31], v[36:39], 0
	v_mfma_f32_16x16x32_f16 v[12:15], v[20:23], v[52:55], 0
	v_mfma_f32_16x16x32_f16 v[16:19], v[28:31], v[52:55], 0
	v_mfma_f32_16x16x32_f16 v[36:39], v[20:23], v[116:119], 0
	v_mfma_f32_16x16x32_f16 v[52:55], v[28:31], v[116:119], 0
	v_mfma_f32_16x16x32_f16 v[20:23], v[20:23], v[124:127], 0
	v_mfma_f32_16x16x32_f16 v[28:31], v[28:31], v[124:127], 0
	v_mfma_f32_16x16x32_f16 v[116:119], v[24:27], v[44:47], v[4:7]
	v_mfma_f32_16x16x32_f16 v[124:127], v[32:35], v[44:47], v[8:11]
	v_mfma_f32_16x16x32_f16 v[184:187], v[24:27], v[120:123], v[36:39]
	v_mfma_f32_16x16x32_f16 v[120:123], v[32:35], v[120:123], v[52:55]
	v_mfma_f32_16x16x32_f16 v[188:191], v[24:27], v[128:131], v[20:23]
	v_mfma_f32_16x16x32_f16 v[128:131], v[32:35], v[128:131], v[28:31]
	s_setprio 2
	s_barrier
	v_mfma_f32_16x16x32_f16 v[176:179], v[24:27], v[60:63], v[12:15]
	v_mfma_f32_16x16x32_f16 v[180:183], v[32:35], v[60:63], v[16:19]
	s_setprio 0
	s_add_i32 s47, 0, 0x18000
	v_add_u32_e32 v4, s47, v147
	s_add_i32 s49, 0, 0x1c000
	ds_read_b128 v[192:195], v4
	ds_read_b128 v[196:199], v4 offset:1024
	ds_read_b128 v[200:203], v4 offset:2048
	ds_read_b128 v[204:207], v4 offset:3072
	v_add_u32_e32 v4, s49, v147
	ds_read_b128 v[208:211], v4
	ds_read_b128 v[212:215], v4 offset:1024
	ds_read_b128 v[216:219], v4 offset:2048
	ds_read_b128 v[220:223], v4 offset:3072
	s_mov_b32 m0, s65
	ds_read_b128 v[44:47], v231 offset:32768
	ds_read_b128 v[52:55], v231 offset:33792
	ds_read_b128 v[60:63], v231 offset:34816
	ds_read_b128 v[224:227], v231 offset:35840
	ds_read_b128 v[232:235], v231 offset:36864
	ds_read_b128 v[236:239], v231 offset:37888
	ds_read_b128 v[240:243], v231 offset:38912
	ds_read_b128 v[244:247], v231 offset:39936
	global_load_lds_dwordx4 v138, s[26:27]
	s_mov_b32 m0, s66
	s_nop 0
	global_load_lds_dwordx4 v132, s[26:27]
	s_waitcnt vmcnt(8)
	s_waitcnt lgkmcnt(0)
	s_barrier
	s_setprio 1
	v_mfma_f32_16x16x32_f16 v[4:7], v[192:195], v[44:47], v[68:71]
	v_mfma_f32_16x16x32_f16 v[8:11], v[200:203], v[44:47], v[72:75]
	v_mfma_f32_16x16x32_f16 v[12:15], v[192:195], v[60:63], v[76:79]
	v_mfma_f32_16x16x32_f16 v[16:19], v[200:203], v[60:63], v[80:83]
	v_mfma_f32_16x16x32_f16 v[20:23], v[192:195], v[232:235], v[84:87]
	v_mfma_f32_16x16x32_f16 v[24:27], v[200:203], v[232:235], v[88:91]
	v_mfma_f32_16x16x32_f16 v[28:31], v[192:195], v[240:243], v[92:95]
	v_mfma_f32_16x16x32_f16 v[32:35], v[200:203], v[240:243], v[96:99]
	v_mfma_f32_16x16x32_f16 v[4:7], v[196:199], v[52:55], v[4:7]
	v_mfma_f32_16x16x32_f16 v[8:11], v[204:207], v[52:55], v[8:11]
	v_mfma_f32_16x16x32_f16 v[12:15], v[196:199], v[224:227], v[12:15]
	v_mfma_f32_16x16x32_f16 v[16:19], v[204:207], v[224:227], v[16:19]
	v_mfma_f32_16x16x32_f16 v[20:23], v[196:199], v[236:239], v[20:23]
	v_mfma_f32_16x16x32_f16 v[24:27], v[204:207], v[236:239], v[24:27]
	v_mfma_f32_16x16x32_f16 v[28:31], v[196:199], v[244:247], v[28:31]
	v_mfma_f32_16x16x32_f16 v[32:35], v[204:207], v[244:247], v[32:35]
	v_mfma_f32_16x16x32_f16 v[36:39], v[208:211], v[44:47], v[100:103]
	v_mfma_f32_16x16x32_f16 v[40:43], v[216:219], v[44:47], v[40:43]
	v_mfma_f32_16x16x32_f16 v[36:39], v[212:215], v[52:55], v[36:39]
	v_mfma_f32_16x16x32_f16 v[40:43], v[220:223], v[52:55], v[40:43]
	v_mfma_f32_16x16x32_f16 v[44:47], v[208:211], v[60:63], v[104:107]
	v_mfma_f32_16x16x32_f16 v[48:51], v[216:219], v[60:63], v[48:51]
	v_mfma_f32_16x16x32_f16 v[52:55], v[208:211], v[232:235], v[108:111]
	v_mfma_f32_16x16x32_f16 v[56:59], v[216:219], v[232:235], v[56:59]
	v_mfma_f32_16x16x32_f16 v[60:63], v[208:211], v[240:243], v[112:115]
	v_mfma_f32_16x16x32_f16 v[64:67], v[216:219], v[240:243], v[64:67]
	v_mfma_f32_16x16x32_f16 v[44:47], v[212:215], v[224:227], v[44:47]
	v_mfma_f32_16x16x32_f16 v[48:51], v[220:223], v[224:227], v[48:51]
	v_mfma_f32_16x16x32_f16 v[52:55], v[212:215], v[236:239], v[52:55]
	v_mfma_f32_16x16x32_f16 v[56:59], v[220:223], v[236:239], v[56:59]
	s_setprio 2
	s_barrier
	v_mfma_f32_16x16x32_f16 v[60:63], v[212:215], v[244:247], v[60:63]
	v_mfma_f32_16x16x32_f16 v[64:67], v[220:223], v[244:247], v[64:67]
	s_setprio 0
	s_add_i32 s47, s47, s62
	v_lshl_add_u64 v[68:69], v[136:137], 0, s[24:25]
	s_mov_b32 m0, s47
	ds_read_b128 v[104:107], v231 offset:49152
	ds_read_b128 v[108:111], v231 offset:50176
	ds_read_b128 v[112:115], v231 offset:51200
	ds_read_b128 v[224:227], v231 offset:52224
	ds_read_b128 v[232:235], v231 offset:53248
	ds_read_b128 v[236:239], v231 offset:54272
	ds_read_b128 v[240:243], v231 offset:55296
	ds_read_b128 v[244:247], v231 offset:56320
	global_load_lds_dwordx4 v[68:69], off
	v_lshl_add_u64 v[68:69], v[144:145], 0, s[24:25]
	s_add_i32 m0, s47, 0x2000
	s_add_i32 s47, s49, s62
	global_load_lds_dwordx4 v[68:69], off
	s_mov_b32 m0, s47
	v_lshl_add_u64 v[68:69], v[248:249], 0, s[24:25]
	global_load_lds_dwordx4 v2, s[28:29]
	s_add_i32 m0, s47, 0x2000
	s_nop 0
	global_load_lds_dwordx4 v134, s[28:29]
	s_mov_b32 m0, s69
	s_nop 0
	global_load_lds_dwordx4 v[68:69], off
	v_lshl_add_u64 v[68:69], v[250:251], 0, s[24:25]
	s_mov_b32 m0, s70
	s_nop 0
	global_load_lds_dwordx4 v[68:69], off
	s_waitcnt vmcnt(8)
	s_waitcnt lgkmcnt(0)
	s_barrier
	s_setprio 1
	v_mfma_f32_16x16x32_f16 v[68:71], v[192:195], v[104:107], v[140:143]
	v_mfma_f32_16x16x32_f16 v[72:75], v[200:203], v[104:107], v[148:151]
	v_mfma_f32_16x16x32_f16 v[76:79], v[192:195], v[112:115], v[152:155]
	v_mfma_f32_16x16x32_f16 v[80:83], v[200:203], v[112:115], v[156:159]
	v_mfma_f32_16x16x32_f16 v[84:87], v[192:195], v[232:235], v[160:163]
	v_mfma_f32_16x16x32_f16 v[88:91], v[200:203], v[232:235], v[164:167]
	v_mfma_f32_16x16x32_f16 v[92:95], v[192:195], v[240:243], v[168:171]
	v_mfma_f32_16x16x32_f16 v[96:99], v[200:203], v[240:243], v[172:175]
	v_mfma_f32_16x16x32_f16 v[68:71], v[196:199], v[108:111], v[68:71]
	v_mfma_f32_16x16x32_f16 v[72:75], v[204:207], v[108:111], v[72:75]
	v_mfma_f32_16x16x32_f16 v[76:79], v[196:199], v[224:227], v[76:79]
	v_mfma_f32_16x16x32_f16 v[80:83], v[204:207], v[224:227], v[80:83]
	v_mfma_f32_16x16x32_f16 v[84:87], v[196:199], v[236:239], v[84:87]
	v_mfma_f32_16x16x32_f16 v[88:91], v[204:207], v[236:239], v[88:91]
	v_mfma_f32_16x16x32_f16 v[92:95], v[196:199], v[244:247], v[92:95]
	v_mfma_f32_16x16x32_f16 v[96:99], v[204:207], v[244:247], v[96:99]
	v_mfma_f32_16x16x32_f16 v[100:103], v[208:211], v[104:107], v[116:119]
	v_mfma_f32_16x16x32_f16 v[104:107], v[216:219], v[104:107], v[124:127]
	v_mfma_f32_16x16x32_f16 v[100:103], v[212:215], v[108:111], v[100:103]
	v_mfma_f32_16x16x32_f16 v[104:107], v[220:223], v[108:111], v[104:107]
	v_mfma_f32_16x16x32_f16 v[108:111], v[208:211], v[112:115], v[176:179]
	v_mfma_f32_16x16x32_f16 v[112:115], v[216:219], v[112:115], v[180:183]
	v_mfma_f32_16x16x32_f16 v[116:119], v[208:211], v[232:235], v[184:187]
	v_mfma_f32_16x16x32_f16 v[120:123], v[216:219], v[232:235], v[120:123]
	v_mfma_f32_16x16x32_f16 v[124:127], v[208:211], v[240:243], v[188:191]
	v_mfma_f32_16x16x32_f16 v[128:131], v[216:219], v[240:243], v[128:131]
	v_mfma_f32_16x16x32_f16 v[108:111], v[212:215], v[224:227], v[108:111]
	v_mfma_f32_16x16x32_f16 v[112:115], v[220:223], v[224:227], v[112:115]
	v_mfma_f32_16x16x32_f16 v[116:119], v[212:215], v[236:239], v[116:119]
	v_mfma_f32_16x16x32_f16 v[120:123], v[220:223], v[236:239], v[120:123]
	s_setprio 2
	s_barrier
	v_mfma_f32_16x16x32_f16 v[124:127], v[212:215], v[244:247], v[124:127]
	v_mfma_f32_16x16x32_f16 v[128:131], v[220:223], v[244:247], v[128:131]
	s_setprio 0
	s_add_i32 s45, s45, 2
	s_cmp_ge_i32 s45, s44
	s_cbranch_scc0 .LBB0_749
	v_mov_b32_e32 v136, v2
	s_branch .LBB0_752

.LBB0_753:
	s_add_u32 s6, s8, 0xfff80080
	s_addc_u32 s7, s9, -1
	s_add_i32 s29, 0, 0x10000
	s_cmp_eq_u32 s28, 28
	s_cselect_b32 s17, s13, s7
	s_cselect_b32 s16, s12, s6
	v_add_u32_e32 v133, s29, v147
	s_cselect_b32 s7, s15, s27
	s_cselect_b32 s6, s14, s26
	s_add_i32 s47, 0, 0x14000
	ds_read_b128 v[138:141], v133
	ds_read_b128 v[142:145], v133 offset:1024
	ds_read_b128 v[148:151], v133 offset:2048
	ds_read_b128 v[152:155], v133 offset:3072
	v_add_u32_e32 v133, s47, v147
	ds_read_b128 v[156:159], v133
	ds_read_b128 v[160:163], v133 offset:1024
	ds_read_b128 v[164:167], v133 offset:2048
	ds_read_b128 v[168:171], v133 offset:3072
	s_mov_b32 m0, s71
	v_add_u32_e32 v212, 0, v146
	ds_read_b128 v[172:175], v212
	ds_read_b128 v[176:179], v212 offset:1024
	ds_read_b128 v[180:183], v212 offset:2048
	ds_read_b128 v[184:187], v212 offset:3072
	ds_read_b128 v[188:191], v212 offset:4096
	ds_read_b128 v[192:195], v212 offset:5120
	ds_read_b128 v[196:199], v212 offset:6144
	ds_read_b128 v[200:203], v212 offset:7168
	global_load_lds_dwordx4 v2, s[8:9]
	s_mov_b32 m0, s72
	v_mov_b32_e32 v133, v3
	global_load_lds_dwordx4 v132, s[8:9]
	s_waitcnt vmcnt(8)
	s_waitcnt lgkmcnt(0)
	s_barrier
	s_setprio 1
	v_mfma_f32_16x16x32_f16 v[4:7], v[138:141], v[172:175], v[4:7]
	v_mfma_f32_16x16x32_f16 v[4:7], v[142:145], v[176:179], v[4:7]
	v_mfma_f32_16x16x32_f16 v[8:11], v[152:155], v[176:179], v[8:11]
	v_mfma_f32_16x16x32_f16 v[8:11], v[148:151], v[172:175], v[8:11]
	v_mfma_f32_16x16x32_f16 v[16:19], v[148:151], v[180:183], v[16:19]
	v_mfma_f32_16x16x32_f16 v[16:19], v[152:155], v[184:187], v[16:19]
	v_mfma_f32_16x16x32_f16 v[12:15], v[142:145], v[184:187], v[12:15]
	v_mfma_f32_16x16x32_f16 v[12:15], v[138:141], v[180:183], v[12:15]
	v_mfma_f32_16x16x32_f16 v[20:23], v[138:141], v[188:191], v[20:23]
	v_mfma_f32_16x16x32_f16 v[20:23], v[142:145], v[192:195], v[20:23]
	v_mfma_f32_16x16x32_f16 v[24:27], v[152:155], v[192:195], v[24:27]
	v_mfma_f32_16x16x32_f16 v[24:27], v[148:151], v[188:191], v[24:27]
	v_mfma_f32_16x16x32_f16 v[32:35], v[148:151], v[196:199], v[32:35]
	v_mfma_f32_16x16x32_f16 v[32:35], v[152:155], v[200:203], v[32:35]
	v_mfma_f32_16x16x32_f16 v[28:31], v[142:145], v[200:203], v[28:31]
	v_mfma_f32_16x16x32_f16 v[28:31], v[138:141], v[196:199], v[28:31]
	v_mfma_f32_16x16x32_f16 v[36:39], v[156:159], v[172:175], v[36:39]
	v_mfma_f32_16x16x32_f16 v[36:39], v[160:163], v[176:179], v[36:39]
	v_mfma_f32_16x16x32_f16 v[40:43], v[168:171], v[176:179], v[40:43]
	v_mfma_f32_16x16x32_f16 v[40:43], v[164:167], v[172:175], v[40:43]
	v_mfma_f32_16x16x32_f16 v[48:51], v[164:167], v[180:183], v[48:51]
	v_mfma_f32_16x16x32_f16 v[48:51], v[168:171], v[184:187], v[48:51]
	v_mfma_f32_16x16x32_f16 v[44:47], v[160:163], v[184:187], v[44:47]
	v_mfma_f32_16x16x32_f16 v[44:47], v[156:159], v[180:183], v[44:47]
	v_mfma_f32_16x16x32_f16 v[52:55], v[156:159], v[188:191], v[52:55]
	v_mfma_f32_16x16x32_f16 v[52:55], v[160:163], v[192:195], v[52:55]
	v_mfma_f32_16x16x32_f16 v[56:59], v[168:171], v[192:195], v[56:59]
	v_mfma_f32_16x16x32_f16 v[56:59], v[164:167], v[188:191], v[56:59]
	v_mfma_f32_16x16x32_f16 v[64:67], v[164:167], v[196:199], v[64:67]
	v_mfma_f32_16x16x32_f16 v[64:67], v[168:171], v[200:203], v[64:67]
	s_setprio 2
	s_barrier
	v_mfma_f32_16x16x32_f16 v[60:63], v[160:163], v[200:203], v[60:63]
	v_mfma_f32_16x16x32_f16 v[60:63], v[156:159], v[196:199], v[60:63]
	s_setprio 0
	s_add_i32 s29, s29, s62
	s_mov_b32 m0, s29
	ds_read_b128 v[172:175], v212 offset:16384
	ds_read_b128 v[176:179], v212 offset:17408
	ds_read_b128 v[180:183], v212 offset:18432
	ds_read_b128 v[184:187], v212 offset:19456
	ds_read_b128 v[188:191], v212 offset:20480
	ds_read_b128 v[192:195], v212 offset:21504
	ds_read_b128 v[196:199], v212 offset:22528
	ds_read_b128 v[200:203], v212 offset:23552
	global_load_lds_dwordx4 v136, s[6:7]
	s_add_i32 m0, s29, 0x2000
	s_add_u32 s44, s6, 0x80000
	s_addc_u32 s45, s7, 0
	s_add_i32 s29, s47, s62
	global_load_lds_dwordx4 v134, s[6:7]
	s_mov_b32 m0, s29
	v_mov_b32_e32 v137, v3
	global_load_lds_dwordx4 v136, s[44:45]
	s_add_i32 m0, s29, 0x2000
	v_mov_b32_e32 v135, v3
	global_load_lds_dwordx4 v134, s[44:45]
	s_mov_b32 m0, s63
	v_lshl_add_u64 v[204:205], s[6:7], 0, v[136:137]
	global_load_lds_dwordx4 v2, s[16:17]
	s_mov_b32 m0, s64
	v_lshl_add_u64 v[206:207], s[6:7], 0, v[134:135]
	global_load_lds_dwordx4 v132, s[16:17]
	s_waitcnt vmcnt(8)
	s_waitcnt lgkmcnt(0)
	v_lshl_add_u64 v[208:209], s[16:17], 0, v[2:3]
	v_lshl_add_u64 v[210:211], s[16:17], 0, v[132:133]
	s_barrier
	s_setprio 1
	v_mfma_f32_16x16x32_f16 v[68:71], v[138:141], v[172:175], v[68:71]
	v_mfma_f32_16x16x32_f16 v[68:71], v[142:145], v[176:179], v[68:71]
	v_mfma_f32_16x16x32_f16 v[72:75], v[152:155], v[176:179], v[72:75]
	v_mfma_f32_16x16x32_f16 v[72:75], v[148:151], v[172:175], v[72:75]
	v_mfma_f32_16x16x32_f16 v[80:83], v[148:151], v[180:183], v[80:83]
	v_mfma_f32_16x16x32_f16 v[80:83], v[152:155], v[184:187], v[80:83]
	v_mfma_f32_16x16x32_f16 v[76:79], v[142:145], v[184:187], v[76:79]
	v_mfma_f32_16x16x32_f16 v[76:79], v[138:141], v[180:183], v[76:79]
	v_mfma_f32_16x16x32_f16 v[84:87], v[138:141], v[188:191], v[84:87]
	v_mfma_f32_16x16x32_f16 v[84:87], v[142:145], v[192:195], v[84:87]
	v_mfma_f32_16x16x32_f16 v[88:91], v[152:155], v[192:195], v[88:91]
	v_mfma_f32_16x16x32_f16 v[88:91], v[148:151], v[188:191], v[88:91]
	v_mfma_f32_16x16x32_f16 v[96:99], v[148:151], v[196:199], v[96:99]
	v_mfma_f32_16x16x32_f16 v[96:99], v[152:155], v[200:203], v[96:99]
	v_mfma_f32_16x16x32_f16 v[92:95], v[142:145], v[200:203], v[92:95]
	v_mfma_f32_16x16x32_f16 v[92:95], v[138:141], v[196:199], v[92:95]
	v_mfma_f32_16x16x32_f16 v[100:103], v[156:159], v[172:175], v[100:103]
	v_mfma_f32_16x16x32_f16 v[100:103], v[160:163], v[176:179], v[100:103]
	v_mfma_f32_16x16x32_f16 v[104:107], v[168:171], v[176:179], v[104:107]
	v_mfma_f32_16x16x32_f16 v[104:107], v[164:167], v[172:175], v[104:107]
	v_mfma_f32_16x16x32_f16 v[112:115], v[164:167], v[180:183], v[112:115]
	v_mfma_f32_16x16x32_f16 v[112:115], v[168:171], v[184:187], v[112:115]
	v_mfma_f32_16x16x32_f16 v[108:111], v[160:163], v[184:187], v[108:111]
	v_mfma_f32_16x16x32_f16 v[108:111], v[156:159], v[180:183], v[108:111]
	v_mfma_f32_16x16x32_f16 v[116:119], v[156:159], v[188:191], v[116:119]
	v_mfma_f32_16x16x32_f16 v[116:119], v[160:163], v[192:195], v[116:119]
	v_mfma_f32_16x16x32_f16 v[120:123], v[168:171], v[192:195], v[120:123]
	v_mfma_f32_16x16x32_f16 v[120:123], v[164:167], v[188:191], v[120:123]
	v_mfma_f32_16x16x32_f16 v[128:131], v[164:167], v[196:199], v[128:131]
	v_mfma_f32_16x16x32_f16 v[128:131], v[168:171], v[200:203], v[128:131]
	s_setprio 2
	s_barrier
	v_mfma_f32_16x16x32_f16 v[124:127], v[160:163], v[200:203], v[124:127]
	v_mfma_f32_16x16x32_f16 v[124:127], v[156:159], v[196:199], v[124:127]
	s_setprio 0
	s_add_i32 s29, 0, 0x18000
	v_add_u32_e32 v135, s29, v147
	s_add_i32 s44, 0, 0x1c000
	ds_read_b128 v[138:141], v135
	ds_read_b128 v[142:145], v135 offset:1024
	ds_read_b128 v[148:151], v135 offset:2048
	ds_read_b128 v[152:155], v135 offset:3072
	v_add_u32_e32 v135, s44, v147
	ds_read_b128 v[156:159], v135
	ds_read_b128 v[160:163], v135 offset:1024
	ds_read_b128 v[164:167], v135 offset:2048
	ds_read_b128 v[168:171], v135 offset:3072
	s_add_u32 s16, s16, 0x80000
	s_addc_u32 s17, s17, 0
	s_mov_b32 m0, s65
	ds_read_b128 v[172:175], v212 offset:32768
	ds_read_b128 v[176:179], v212 offset:33792
	ds_read_b128 v[180:183], v212 offset:34816
	ds_read_b128 v[184:187], v212 offset:35840
	ds_read_b128 v[188:191], v212 offset:36864
	ds_read_b128 v[192:195], v212 offset:37888
	ds_read_b128 v[196:199], v212 offset:38912
	ds_read_b128 v[200:203], v212 offset:39936
	global_load_lds_dwordx4 v2, s[16:17]
	s_mov_b32 m0, s66
	s_nop 0
	global_load_lds_dwordx4 v132, s[16:17]
	s_waitcnt vmcnt(8)
	s_waitcnt lgkmcnt(0)
	s_barrier
	s_setprio 1
	v_mfma_f32_16x16x32_f16 v[4:7], v[138:141], v[172:175], v[4:7]
	v_mfma_f32_16x16x32_f16 v[4:7], v[142:145], v[176:179], v[4:7]
	v_mfma_f32_16x16x32_f16 v[8:11], v[152:155], v[176:179], v[8:11]
	v_mfma_f32_16x16x32_f16 v[8:11], v[148:151], v[172:175], v[8:11]
	v_mfma_f32_16x16x32_f16 v[16:19], v[148:151], v[180:183], v[16:19]
	v_mfma_f32_16x16x32_f16 v[16:19], v[152:155], v[184:187], v[16:19]
	v_mfma_f32_16x16x32_f16 v[12:15], v[142:145], v[184:187], v[12:15]
	v_mfma_f32_16x16x32_f16 v[12:15], v[138:141], v[180:183], v[12:15]
	v_mfma_f32_16x16x32_f16 v[20:23], v[138:141], v[188:191], v[20:23]
	v_mfma_f32_16x16x32_f16 v[20:23], v[142:145], v[192:195], v[20:23]
	v_mfma_f32_16x16x32_f16 v[24:27], v[152:155], v[192:195], v[24:27]
	v_mfma_f32_16x16x32_f16 v[24:27], v[148:151], v[188:191], v[24:27]
	v_mfma_f32_16x16x32_f16 v[32:35], v[148:151], v[196:199], v[32:35]
	v_mfma_f32_16x16x32_f16 v[32:35], v[152:155], v[200:203], v[32:35]
	v_mfma_f32_16x16x32_f16 v[28:31], v[142:145], v[200:203], v[28:31]
	v_mfma_f32_16x16x32_f16 v[28:31], v[138:141], v[196:199], v[28:31]
	v_mfma_f32_16x16x32_f16 v[36:39], v[156:159], v[172:175], v[36:39]
	v_mfma_f32_16x16x32_f16 v[36:39], v[160:163], v[176:179], v[36:39]
	v_mfma_f32_16x16x32_f16 v[40:43], v[168:171], v[176:179], v[40:43]
	v_mfma_f32_16x16x32_f16 v[40:43], v[164:167], v[172:175], v[40:43]
	v_mfma_f32_16x16x32_f16 v[48:51], v[164:167], v[180:183], v[48:51]
	v_mfma_f32_16x16x32_f16 v[48:51], v[168:171], v[184:187], v[48:51]
	v_mfma_f32_16x16x32_f16 v[44:47], v[160:163], v[184:187], v[44:47]
	v_mfma_f32_16x16x32_f16 v[44:47], v[156:159], v[180:183], v[44:47]
	v_mfma_f32_16x16x32_f16 v[52:55], v[156:159], v[188:191], v[52:55]
	v_mfma_f32_16x16x32_f16 v[52:55], v[160:163], v[192:195], v[52:55]
	v_mfma_f32_16x16x32_f16 v[56:59], v[168:171], v[192:195], v[56:59]
	v_mfma_f32_16x16x32_f16 v[56:59], v[164:167], v[188:191], v[56:59]
	v_mfma_f32_16x16x32_f16 v[64:67], v[164:167], v[196:199], v[64:67]
	v_mfma_f32_16x16x32_f16 v[64:67], v[168:171], v[200:203], v[64:67]
	s_setprio 2
	s_barrier
	v_mfma_f32_16x16x32_f16 v[60:63], v[160:163], v[200:203], v[60:63]
	v_mfma_f32_16x16x32_f16 v[60:63], v[156:159], v[196:199], v[60:63]
	s_setprio 0
	s_add_i32 s16, s29, s62
	v_lshl_add_u64 v[204:205], v[204:205], 0, s[86:87]
	s_mov_b32 m0, s16
	ds_read_b128 v[172:175], v212 offset:49152
	ds_read_b128 v[176:179], v212 offset:50176
	ds_read_b128 v[180:183], v212 offset:51200
	ds_read_b128 v[184:187], v212 offset:52224
	ds_read_b128 v[188:191], v212 offset:53248
	ds_read_b128 v[192:195], v212 offset:54272
	ds_read_b128 v[196:199], v212 offset:55296
	ds_read_b128 v[200:203], v212 offset:56320
	global_load_lds_dwordx4 v[204:205], off
	s_add_i32 m0, s16, 0x2000
	s_add_u32 s6, s6, 0x80080
	v_lshl_add_u64 v[204:205], v[206:207], 0, s[86:87]
	s_addc_u32 s7, s7, 0
	s_add_i32 s16, s44, s62
	global_load_lds_dwordx4 v[204:205], off
	s_mov_b32 m0, s16
	v_lshl_add_u64 v[204:205], v[208:209], 0, s[86:87]
	global_load_lds_dwordx4 v136, s[6:7]
	s_add_i32 m0, s16, 0x2000
	s_nop 0
	global_load_lds_dwordx4 v134, s[6:7]
	s_mov_b32 m0, s69
	s_nop 0
	global_load_lds_dwordx4 v[204:205], off
	v_lshl_add_u64 v[204:205], v[210:211], 0, s[86:87]
	s_mov_b32 m0, s70
	s_nop 0
	global_load_lds_dwordx4 v[204:205], off
	s_waitcnt vmcnt(8)
	s_waitcnt lgkmcnt(0)
	s_barrier
	s_setprio 1
	v_mfma_f32_16x16x32_f16 v[68:71], v[138:141], v[172:175], v[68:71]
	v_mfma_f32_16x16x32_f16 v[68:71], v[142:145], v[176:179], v[68:71]
	v_mfma_f32_16x16x32_f16 v[72:75], v[152:155], v[176:179], v[72:75]
	v_mfma_f32_16x16x32_f16 v[72:75], v[148:151], v[172:175], v[72:75]
	v_mfma_f32_16x16x32_f16 v[80:83], v[148:151], v[180:183], v[80:83]
	v_mfma_f32_16x16x32_f16 v[80:83], v[152:155], v[184:187], v[80:83]
	v_mfma_f32_16x16x32_f16 v[76:79], v[142:145], v[184:187], v[76:79]
	v_mfma_f32_16x16x32_f16 v[76:79], v[138:141], v[180:183], v[76:79]
	v_mfma_f32_16x16x32_f16 v[84:87], v[138:141], v[188:191], v[84:87]
	v_mfma_f32_16x16x32_f16 v[84:87], v[142:145], v[192:195], v[84:87]
	v_mfma_f32_16x16x32_f16 v[88:91], v[152:155], v[192:195], v[88:91]
	v_mfma_f32_16x16x32_f16 v[88:91], v[148:151], v[188:191], v[88:91]
	v_mfma_f32_16x16x32_f16 v[96:99], v[148:151], v[196:199], v[96:99]
	v_mfma_f32_16x16x32_f16 v[96:99], v[152:155], v[200:203], v[96:99]
	v_mfma_f32_16x16x32_f16 v[92:95], v[142:145], v[200:203], v[92:95]
	v_mfma_f32_16x16x32_f16 v[92:95], v[138:141], v[196:199], v[92:95]
	v_mfma_f32_16x16x32_f16 v[100:103], v[156:159], v[172:175], v[100:103]
	v_mfma_f32_16x16x32_f16 v[100:103], v[160:163], v[176:179], v[100:103]
	v_mfma_f32_16x16x32_f16 v[104:107], v[168:171], v[176:179], v[104:107]
	v_mfma_f32_16x16x32_f16 v[104:107], v[164:167], v[172:175], v[104:107]
	v_mfma_f32_16x16x32_f16 v[112:115], v[164:167], v[180:183], v[112:115]
	v_mfma_f32_16x16x32_f16 v[112:115], v[168:171], v[184:187], v[112:115]
	v_mfma_f32_16x16x32_f16 v[108:111], v[160:163], v[184:187], v[108:111]
	v_mfma_f32_16x16x32_f16 v[108:111], v[156:159], v[180:183], v[108:111]
	v_mfma_f32_16x16x32_f16 v[116:119], v[156:159], v[188:191], v[116:119]
	v_mfma_f32_16x16x32_f16 v[116:119], v[160:163], v[192:195], v[116:119]
	v_mfma_f32_16x16x32_f16 v[120:123], v[168:171], v[192:195], v[120:123]
	v_mfma_f32_16x16x32_f16 v[120:123], v[164:167], v[188:191], v[120:123]
	v_mfma_f32_16x16x32_f16 v[128:131], v[164:167], v[196:199], v[128:131]
	v_mfma_f32_16x16x32_f16 v[128:131], v[168:171], v[200:203], v[128:131]
	s_setprio 2
	s_barrier
	v_mfma_f32_16x16x32_f16 v[124:127], v[160:163], v[200:203], v[124:127]
	v_mfma_f32_16x16x32_f16 v[124:127], v[156:159], v[196:199], v[124:127]
	s_setprio 0
	s_add_i32 s28, s28, 2
	s_add_u32 s8, s8, 0x100
	s_addc_u32 s9, s9, 0
	s_add_u32 s26, s26, 0x100
	s_addc_u32 s27, s27, 0
	s_cmp_gt_u32 s28, 29
	s_cbranch_scc0 .LBB0_753
	s_and_b64 vcc, exec, s[52:53]
	s_cbranch_vccz .LBB0_756
	s_barrier

.LBB0_1175:
	s_add_i32 s61, 0, 0x10000
	s_add_i32 s79, 0, 0x14000
	v_add_u32_e32 v16, s61, v209
	v_add_u32_e32 v32, s79, v209
	ds_read_b128 v[4:7], v16
	ds_read_b128 v[8:11], v16 offset:1024
	ds_read_b128 v[12:15], v16 offset:2048
	ds_read_b128 v[16:19], v16 offset:3072
	ds_read_b128 v[20:23], v32
	ds_read_b128 v[24:27], v32 offset:1024
	ds_read_b128 v[28:31], v32 offset:2048
	ds_read_b128 v[32:35], v32 offset:3072
	v_add_u32_e32 v231, 0, v208
	ds_read_b128 v[36:39], v231
	ds_read_b128 v[40:43], v231 offset:1024
	ds_read_b128 v[44:47], v231 offset:2048
	ds_read_b128 v[48:51], v231 offset:3072
	ds_read_b128 v[52:55], v231 offset:4096
	ds_read_b128 v[56:59], v231 offset:5120
	ds_read_b128 v[60:63], v231 offset:6144
	ds_read_b128 v[64:67], v231 offset:7168
	s_waitcnt vmcnt(8)
	s_waitcnt lgkmcnt(0)
	s_barrier
	s_setprio 1
	v_mfma_f32_16x16x32_bf16 v[68:71], v[4:7], v[36:39], 0
	v_mfma_f32_16x16x32_bf16 v[68:71], v[8:11], v[40:43], v[68:71]
	v_mfma_f32_16x16x32_bf16 v[72:75], v[12:15], v[36:39], 0
	v_mfma_f32_16x16x32_bf16 v[72:75], v[16:19], v[40:43], v[72:75]
	v_mfma_f32_16x16x32_bf16 v[80:83], v[12:15], v[44:47], 0
	v_mfma_f32_16x16x32_bf16 v[80:83], v[16:19], v[48:51], v[80:83]
	v_mfma_f32_16x16x32_bf16 v[76:79], v[4:7], v[44:47], 0
	v_mfma_f32_16x16x32_bf16 v[76:79], v[8:11], v[48:51], v[76:79]
	v_mfma_f32_16x16x32_bf16 v[84:87], v[4:7], v[52:55], 0
	v_mfma_f32_16x16x32_bf16 v[84:87], v[8:11], v[56:59], v[84:87]
	v_mfma_f32_16x16x32_bf16 v[88:91], v[12:15], v[52:55], 0
	v_mfma_f32_16x16x32_bf16 v[88:91], v[16:19], v[56:59], v[88:91]
	v_mfma_f32_16x16x32_bf16 v[96:99], v[12:15], v[60:63], 0
	v_mfma_f32_16x16x32_bf16 v[96:99], v[16:19], v[64:67], v[96:99]
	v_mfma_f32_16x16x32_bf16 v[92:95], v[4:7], v[60:63], 0
	v_mfma_f32_16x16x32_bf16 v[92:95], v[8:11], v[64:67], v[92:95]
	v_mfma_f32_16x16x32_bf16 v[100:103], v[20:23], v[36:39], 0
	v_mfma_f32_16x16x32_bf16 v[36:39], v[28:31], v[36:39], 0
	v_mfma_f32_16x16x32_bf16 v[104:107], v[20:23], v[44:47], 0
	v_mfma_f32_16x16x32_bf16 v[44:47], v[28:31], v[44:47], 0
	v_mfma_f32_16x16x32_bf16 v[108:111], v[20:23], v[52:55], 0
	v_mfma_f32_16x16x32_bf16 v[52:55], v[28:31], v[52:55], 0
	v_mfma_f32_16x16x32_bf16 v[112:115], v[20:23], v[60:63], 0
	v_mfma_f32_16x16x32_bf16 v[60:63], v[28:31], v[60:63], 0
	v_mfma_f32_16x16x32_bf16 v[100:103], v[24:27], v[40:43], v[100:103]
	v_mfma_f32_16x16x32_bf16 v[40:43], v[32:35], v[40:43], v[36:39]
	v_mfma_f32_16x16x32_bf16 v[104:107], v[24:27], v[48:51], v[104:107]
	v_mfma_f32_16x16x32_bf16 v[48:51], v[32:35], v[48:51], v[44:47]
	v_mfma_f32_16x16x32_bf16 v[108:111], v[24:27], v[56:59], v[108:111]
	v_mfma_f32_16x16x32_bf16 v[56:59], v[32:35], v[56:59], v[52:55]
	s_setprio 2
	s_barrier
	v_mfma_f32_16x16x32_bf16 v[112:115], v[24:27], v[64:67], v[112:115]
	v_mfma_f32_16x16x32_bf16 v[64:67], v[32:35], v[64:67], v[60:63]
	s_setprio 0
	v_lshl_add_u64 v[186:187], s[12:13], 0, v[2:3]
	s_add_i32 s61, s61, s36
	v_mov_b32_e32 v191, v3
	v_lshl_add_u64 v[134:135], v[186:187], 0, s[74:75]
	s_mov_b32 m0, s61
	v_lshl_add_u64 v[226:227], s[12:13], 0, v[190:191]
	ds_read_b128 v[36:39], v231 offset:16384
	ds_read_b128 v[44:47], v231 offset:17408
	ds_read_b128 v[52:55], v231 offset:18432
	ds_read_b128 v[60:63], v231 offset:19456
	ds_read_b128 v[116:119], v231 offset:20480
	ds_read_b128 v[120:123], v231 offset:21504
	ds_read_b128 v[124:127], v231 offset:22528
	ds_read_b128 v[128:131], v231 offset:23552
	global_load_lds_dwordx4 v[134:135], off
	v_lshl_add_u64 v[134:135], v[226:227], 0, s[74:75]
	s_add_i32 m0, s61, 0x2000
	s_add_i32 s61, s79, s36
	global_load_lds_dwordx4 v[134:135], off
	s_mov_b32 m0, s61
	v_mov_b32_e32 v133, v3
	global_load_lds_dwordx4 v2, s[16:17]
	s_add_i32 m0, s61, 0x2000
	v_lshl_add_u64 v[248:249], s[6:7], 0, v[132:133]
	v_mov_b32_e32 v189, v3
	global_load_lds_dwordx4 v190, s[16:17]
	v_lshl_add_u64 v[134:135], v[248:249], 0, s[74:75]
	s_mov_b32 m0, s37
	v_lshl_add_u64 v[250:251], s[6:7], 0, v[188:189]
	global_load_lds_dwordx4 v[134:135], off
	v_lshl_add_u64 v[134:135], v[250:251], 0, s[74:75]
	s_mov_b32 m0, s66
	s_nop 0
	global_load_lds_dwordx4 v[134:135], off
	s_waitcnt vmcnt(8)
	s_waitcnt lgkmcnt(0)
	s_barrier
	s_setprio 1
	v_mfma_f32_16x16x32_bf16 v[134:137], v[4:7], v[36:39], 0
	v_mfma_f32_16x16x32_bf16 v[138:141], v[12:15], v[36:39], 0
	v_mfma_f32_16x16x32_bf16 v[142:145], v[4:7], v[52:55], 0
	v_mfma_f32_16x16x32_bf16 v[146:149], v[12:15], v[52:55], 0
	v_mfma_f32_16x16x32_bf16 v[150:153], v[4:7], v[116:119], 0
	v_mfma_f32_16x16x32_bf16 v[154:157], v[12:15], v[116:119], 0
	v_mfma_f32_16x16x32_bf16 v[4:7], v[4:7], v[124:127], 0
	v_mfma_f32_16x16x32_bf16 v[12:15], v[12:15], v[124:127], 0
	v_mfma_f32_16x16x32_bf16 v[134:137], v[8:11], v[44:47], v[134:137]
	v_mfma_f32_16x16x32_bf16 v[138:141], v[16:19], v[44:47], v[138:141]
	v_mfma_f32_16x16x32_bf16 v[142:145], v[8:11], v[60:63], v[142:145]
	v_mfma_f32_16x16x32_bf16 v[146:149], v[16:19], v[60:63], v[146:149]
	v_mfma_f32_16x16x32_bf16 v[150:153], v[8:11], v[120:123], v[150:153]
	v_mfma_f32_16x16x32_bf16 v[154:157], v[16:19], v[120:123], v[154:157]
	v_mfma_f32_16x16x32_bf16 v[158:161], v[8:11], v[128:131], v[4:7]
	v_mfma_f32_16x16x32_bf16 v[162:165], v[16:19], v[128:131], v[12:15]
	v_mfma_f32_16x16x32_bf16 v[4:7], v[20:23], v[36:39], 0
	v_mfma_f32_16x16x32_bf16 v[8:11], v[28:31], v[36:39], 0
	v_mfma_f32_16x16x32_bf16 v[12:15], v[20:23], v[52:55], 0
	v_mfma_f32_16x16x32_bf16 v[16:19], v[28:31], v[52:55], 0
	v_mfma_f32_16x16x32_bf16 v[36:39], v[20:23], v[116:119], 0
	v_mfma_f32_16x16x32_bf16 v[52:55], v[28:31], v[116:119], 0
	v_mfma_f32_16x16x32_bf16 v[20:23], v[20:23], v[124:127], 0
	v_mfma_f32_16x16x32_bf16 v[28:31], v[28:31], v[124:127], 0
	v_mfma_f32_16x16x32_bf16 v[116:119], v[24:27], v[44:47], v[4:7]
	v_mfma_f32_16x16x32_bf16 v[124:127], v[32:35], v[44:47], v[8:11]
	v_mfma_f32_16x16x32_bf16 v[174:177], v[24:27], v[120:123], v[36:39]
	v_mfma_f32_16x16x32_bf16 v[120:123], v[32:35], v[120:123], v[52:55]
	v_mfma_f32_16x16x32_bf16 v[178:181], v[24:27], v[128:131], v[20:23]
	v_mfma_f32_16x16x32_bf16 v[128:131], v[32:35], v[128:131], v[28:31]
	s_setprio 2
	s_barrier
	v_mfma_f32_16x16x32_bf16 v[166:169], v[24:27], v[60:63], v[12:15]
	v_mfma_f32_16x16x32_bf16 v[170:173], v[32:35], v[60:63], v[16:19]
	s_setprio 0
	s_add_i32 s61, 0, 0x18000
	v_add_u32_e32 v4, s61, v209
	s_add_i32 s79, 0, 0x1c000
	ds_read_b128 v[182:185], v4
	ds_read_b128 v[192:195], v4 offset:1024
	ds_read_b128 v[196:199], v4 offset:2048
	ds_read_b128 v[200:203], v4 offset:3072
	v_add_u32_e32 v4, s79, v209
	ds_read_b128 v[204:207], v4
	ds_read_b128 v[210:213], v4 offset:1024
	ds_read_b128 v[214:217], v4 offset:2048
	ds_read_b128 v[218:221], v4 offset:3072
	s_mov_b32 m0, s67
	ds_read_b128 v[44:47], v231 offset:32768
	ds_read_b128 v[52:55], v231 offset:33792
	ds_read_b128 v[60:63], v231 offset:34816
	ds_read_b128 v[222:225], v231 offset:35840
	ds_read_b128 v[232:235], v231 offset:36864
	ds_read_b128 v[236:239], v231 offset:37888
	ds_read_b128 v[240:243], v231 offset:38912
	ds_read_b128 v[244:247], v231 offset:39936
	global_load_lds_dwordx4 v132, s[26:27]
	s_mov_b32 m0, s68
	s_nop 0
	global_load_lds_dwordx4 v188, s[26:27]
	s_waitcnt vmcnt(8)
	s_waitcnt lgkmcnt(0)
	s_barrier
	s_setprio 1
	v_mfma_f32_16x16x32_bf16 v[4:7], v[182:185], v[44:47], v[68:71]
	v_mfma_f32_16x16x32_bf16 v[8:11], v[196:199], v[44:47], v[72:75]
	v_mfma_f32_16x16x32_bf16 v[12:15], v[182:185], v[60:63], v[76:79]
	v_mfma_f32_16x16x32_bf16 v[16:19], v[196:199], v[60:63], v[80:83]
	v_mfma_f32_16x16x32_bf16 v[20:23], v[182:185], v[232:235], v[84:87]
	v_mfma_f32_16x16x32_bf16 v[24:27], v[196:199], v[232:235], v[88:91]
	v_mfma_f32_16x16x32_bf16 v[28:31], v[182:185], v[240:243], v[92:95]
	v_mfma_f32_16x16x32_bf16 v[32:35], v[196:199], v[240:243], v[96:99]
	v_mfma_f32_16x16x32_bf16 v[4:7], v[192:195], v[52:55], v[4:7]
	v_mfma_f32_16x16x32_bf16 v[8:11], v[200:203], v[52:55], v[8:11]
	v_mfma_f32_16x16x32_bf16 v[12:15], v[192:195], v[222:225], v[12:15]
	v_mfma_f32_16x16x32_bf16 v[16:19], v[200:203], v[222:225], v[16:19]
	v_mfma_f32_16x16x32_bf16 v[20:23], v[192:195], v[236:239], v[20:23]
	v_mfma_f32_16x16x32_bf16 v[24:27], v[200:203], v[236:239], v[24:27]
	v_mfma_f32_16x16x32_bf16 v[28:31], v[192:195], v[244:247], v[28:31]
	v_mfma_f32_16x16x32_bf16 v[32:35], v[200:203], v[244:247], v[32:35]
	v_mfma_f32_16x16x32_bf16 v[36:39], v[204:207], v[44:47], v[100:103]
	v_mfma_f32_16x16x32_bf16 v[40:43], v[214:217], v[44:47], v[40:43]
	v_mfma_f32_16x16x32_bf16 v[36:39], v[210:213], v[52:55], v[36:39]
	v_mfma_f32_16x16x32_bf16 v[40:43], v[218:221], v[52:55], v[40:43]
	v_mfma_f32_16x16x32_bf16 v[44:47], v[204:207], v[60:63], v[104:107]
	v_mfma_f32_16x16x32_bf16 v[48:51], v[214:217], v[60:63], v[48:51]
	v_mfma_f32_16x16x32_bf16 v[52:55], v[204:207], v[232:235], v[108:111]
	v_mfma_f32_16x16x32_bf16 v[56:59], v[214:217], v[232:235], v[56:59]
	v_mfma_f32_16x16x32_bf16 v[60:63], v[204:207], v[240:243], v[112:115]
	v_mfma_f32_16x16x32_bf16 v[64:67], v[214:217], v[240:243], v[64:67]
	v_mfma_f32_16x16x32_bf16 v[44:47], v[210:213], v[222:225], v[44:47]
	v_mfma_f32_16x16x32_bf16 v[48:51], v[218:221], v[222:225], v[48:51]
	v_mfma_f32_16x16x32_bf16 v[52:55], v[210:213], v[236:239], v[52:55]
	v_mfma_f32_16x16x32_bf16 v[56:59], v[218:221], v[236:239], v[56:59]
	s_setprio 2
	s_barrier
	v_mfma_f32_16x16x32_bf16 v[60:63], v[210:213], v[244:247], v[60:63]
	v_mfma_f32_16x16x32_bf16 v[64:67], v[218:221], v[244:247], v[64:67]
	s_setprio 0
	s_add_i32 s61, s61, s36
	v_lshl_add_u64 v[68:69], v[186:187], 0, s[24:25]
	s_mov_b32 m0, s61
	ds_read_b128 v[104:107], v231 offset:49152
	ds_read_b128 v[108:111], v231 offset:50176
	ds_read_b128 v[112:115], v231 offset:51200
	ds_read_b128 v[222:225], v231 offset:52224
	ds_read_b128 v[232:235], v231 offset:53248
	ds_read_b128 v[236:239], v231 offset:54272
	ds_read_b128 v[240:243], v231 offset:55296
	ds_read_b128 v[244:247], v231 offset:56320
	global_load_lds_dwordx4 v[68:69], off
	v_lshl_add_u64 v[68:69], v[226:227], 0, s[24:25]
	s_add_i32 m0, s61, 0x2000
	s_add_i32 s61, s79, s36
	global_load_lds_dwordx4 v[68:69], off
	s_mov_b32 m0, s61
	v_lshl_add_u64 v[68:69], v[248:249], 0, s[24:25]
	global_load_lds_dwordx4 v2, s[28:29]
	s_add_i32 m0, s61, 0x2000
	s_nop 0
	global_load_lds_dwordx4 v190, s[28:29]
	s_mov_b32 m0, s71
	s_nop 0
	global_load_lds_dwordx4 v[68:69], off
	v_lshl_add_u64 v[68:69], v[250:251], 0, s[24:25]
	s_mov_b32 m0, s72
	s_nop 0
	global_load_lds_dwordx4 v[68:69], off
	s_waitcnt vmcnt(8)
	s_waitcnt lgkmcnt(0)
	s_barrier
	s_setprio 1
	v_mfma_f32_16x16x32_bf16 v[68:71], v[182:185], v[104:107], v[134:137]
	v_mfma_f32_16x16x32_bf16 v[72:75], v[196:199], v[104:107], v[138:141]
	v_mfma_f32_16x16x32_bf16 v[76:79], v[182:185], v[112:115], v[142:145]
	v_mfma_f32_16x16x32_bf16 v[80:83], v[196:199], v[112:115], v[146:149]
	v_mfma_f32_16x16x32_bf16 v[84:87], v[182:185], v[232:235], v[150:153]
	v_mfma_f32_16x16x32_bf16 v[88:91], v[196:199], v[232:235], v[154:157]
	v_mfma_f32_16x16x32_bf16 v[92:95], v[182:185], v[240:243], v[158:161]
	v_mfma_f32_16x16x32_bf16 v[96:99], v[196:199], v[240:243], v[162:165]
	v_mfma_f32_16x16x32_bf16 v[68:71], v[192:195], v[108:111], v[68:71]
	v_mfma_f32_16x16x32_bf16 v[72:75], v[200:203], v[108:111], v[72:75]
	v_mfma_f32_16x16x32_bf16 v[76:79], v[192:195], v[222:225], v[76:79]
	v_mfma_f32_16x16x32_bf16 v[80:83], v[200:203], v[222:225], v[80:83]
	v_mfma_f32_16x16x32_bf16 v[84:87], v[192:195], v[236:239], v[84:87]
	v_mfma_f32_16x16x32_bf16 v[88:91], v[200:203], v[236:239], v[88:91]
	v_mfma_f32_16x16x32_bf16 v[92:95], v[192:195], v[244:247], v[92:95]
	v_mfma_f32_16x16x32_bf16 v[96:99], v[200:203], v[244:247], v[96:99]
	v_mfma_f32_16x16x32_bf16 v[100:103], v[204:207], v[104:107], v[116:119]
	v_mfma_f32_16x16x32_bf16 v[104:107], v[214:217], v[104:107], v[124:127]
	v_mfma_f32_16x16x32_bf16 v[100:103], v[210:213], v[108:111], v[100:103]
	v_mfma_f32_16x16x32_bf16 v[104:107], v[218:221], v[108:111], v[104:107]
	v_mfma_f32_16x16x32_bf16 v[108:111], v[204:207], v[112:115], v[166:169]
	v_mfma_f32_16x16x32_bf16 v[112:115], v[214:217], v[112:115], v[170:173]
	v_mfma_f32_16x16x32_bf16 v[116:119], v[204:207], v[232:235], v[174:177]
	v_mfma_f32_16x16x32_bf16 v[120:123], v[214:217], v[232:235], v[120:123]
	v_mfma_f32_16x16x32_bf16 v[124:127], v[204:207], v[240:243], v[178:181]
	v_mfma_f32_16x16x32_bf16 v[128:131], v[214:217], v[240:243], v[128:131]
	v_mfma_f32_16x16x32_bf16 v[108:111], v[210:213], v[222:225], v[108:111]
	v_mfma_f32_16x16x32_bf16 v[112:115], v[218:221], v[222:225], v[112:115]
	v_mfma_f32_16x16x32_bf16 v[116:119], v[210:213], v[236:239], v[116:119]
	v_mfma_f32_16x16x32_bf16 v[120:123], v[218:221], v[236:239], v[120:123]
	s_setprio 2
	s_barrier
	v_mfma_f32_16x16x32_bf16 v[124:127], v[210:213], v[244:247], v[124:127]
	v_mfma_f32_16x16x32_bf16 v[128:131], v[218:221], v[244:247], v[128:131]
	s_setprio 0
	s_add_i32 s43, s43, 2
	s_cmp_ge_i32 s43, s42
	s_cbranch_scc0 .LBB0_1175
.LBB0_1176:
	s_add_i32 s12, 0, 0x10000
	s_add_i32 s13, 0, 0x14000
	v_mov_b32_e32 v192, v2
	v_mov_b32_e32 v2, v132
	v_add_u32_e32 v144, s12, v209
	v_add_u32_e32 v160, s13, v209
	ds_read_b128 v[132:135], v144
	ds_read_b128 v[136:139], v144 offset:1024
	ds_read_b128 v[140:143], v144 offset:2048
	ds_read_b128 v[144:147], v144 offset:3072
	ds_read_b128 v[148:151], v160
	ds_read_b128 v[152:155], v160 offset:1024
	ds_read_b128 v[156:159], v160 offset:2048
	ds_read_b128 v[160:163], v160 offset:3072
	s_add_u32 s6, s6, 0x80180
	s_mov_b32 m0, s73
	v_add_u32_e32 v212, 0, v208
	s_addc_u32 s7, s7, 0
	ds_read_b128 v[164:167], v212
	ds_read_b128 v[168:171], v212 offset:1024
	ds_read_b128 v[172:175], v212 offset:2048
	ds_read_b128 v[176:179], v212 offset:3072
	ds_read_b128 v[180:183], v212 offset:4096
	ds_read_b128 v[184:187], v212 offset:5120
	ds_read_b128 v[194:197], v212 offset:6144
	ds_read_b128 v[198:201], v212 offset:7168
	global_load_lds_dwordx4 v2, s[6:7]
	s_mov_b32 m0, s76
	v_mov_b32_e32 v189, v3
	global_load_lds_dwordx4 v188, s[6:7]
	s_waitcnt vmcnt(8)
	s_waitcnt lgkmcnt(0)
	s_barrier
	s_setprio 1
	v_mfma_f32_16x16x32_bf16 v[4:7], v[132:135], v[164:167], v[4:7]
	v_mfma_f32_16x16x32_bf16 v[4:7], v[136:139], v[168:171], v[4:7]
	v_mfma_f32_16x16x32_bf16 v[8:11], v[144:147], v[168:171], v[8:11]
	v_mfma_f32_16x16x32_bf16 v[8:11], v[140:143], v[164:167], v[8:11]
	v_mfma_f32_16x16x32_bf16 v[16:19], v[140:143], v[172:175], v[16:19]
	v_mfma_f32_16x16x32_bf16 v[16:19], v[144:147], v[176:179], v[16:19]
	v_mfma_f32_16x16x32_bf16 v[12:15], v[136:139], v[176:179], v[12:15]
	v_mfma_f32_16x16x32_bf16 v[12:15], v[132:135], v[172:175], v[12:15]
	v_mfma_f32_16x16x32_bf16 v[20:23], v[132:135], v[180:183], v[20:23]
	v_mfma_f32_16x16x32_bf16 v[20:23], v[136:139], v[184:187], v[20:23]
	v_mfma_f32_16x16x32_bf16 v[24:27], v[144:147], v[184:187], v[24:27]
	v_mfma_f32_16x16x32_bf16 v[24:27], v[140:143], v[180:183], v[24:27]
	v_mfma_f32_16x16x32_bf16 v[32:35], v[140:143], v[194:197], v[32:35]
	v_mfma_f32_16x16x32_bf16 v[32:35], v[144:147], v[198:201], v[32:35]
	v_mfma_f32_16x16x32_bf16 v[28:31], v[136:139], v[198:201], v[28:31]
	v_mfma_f32_16x16x32_bf16 v[28:31], v[132:135], v[194:197], v[28:31]
	v_mfma_f32_16x16x32_bf16 v[36:39], v[148:151], v[164:167], v[36:39]
	v_mfma_f32_16x16x32_bf16 v[36:39], v[152:155], v[168:171], v[36:39]
	v_mfma_f32_16x16x32_bf16 v[40:43], v[160:163], v[168:171], v[40:43]
	v_mfma_f32_16x16x32_bf16 v[40:43], v[156:159], v[164:167], v[40:43]
	v_mfma_f32_16x16x32_bf16 v[48:51], v[156:159], v[172:175], v[48:51]
	v_mfma_f32_16x16x32_bf16 v[48:51], v[160:163], v[176:179], v[48:51]
	v_mfma_f32_16x16x32_bf16 v[44:47], v[152:155], v[176:179], v[44:47]
	v_mfma_f32_16x16x32_bf16 v[44:47], v[148:151], v[172:175], v[44:47]
	v_mfma_f32_16x16x32_bf16 v[52:55], v[148:151], v[180:183], v[52:55]
	v_mfma_f32_16x16x32_bf16 v[52:55], v[152:155], v[184:187], v[52:55]
	v_mfma_f32_16x16x32_bf16 v[56:59], v[160:163], v[184:187], v[56:59]
	v_mfma_f32_16x16x32_bf16 v[56:59], v[156:159], v[180:183], v[56:59]
	v_mfma_f32_16x16x32_bf16 v[64:67], v[156:159], v[194:197], v[64:67]
	v_mfma_f32_16x16x32_bf16 v[64:67], v[160:163], v[198:201], v[64:67]
	s_setprio 2
	s_barrier
	v_mfma_f32_16x16x32_bf16 v[60:63], v[152:155], v[198:201], v[60:63]
	v_mfma_f32_16x16x32_bf16 v[60:63], v[148:151], v[194:197], v[60:63]
	s_setprio 0
	s_add_i32 s6, s12, s36
	s_mov_b32 m0, s6
	ds_read_b128 v[164:167], v212 offset:16384
	ds_read_b128 v[168:171], v212 offset:17408
	ds_read_b128 v[172:175], v212 offset:18432
	ds_read_b128 v[176:179], v212 offset:19456
	ds_read_b128 v[180:183], v212 offset:20480
	ds_read_b128 v[184:187], v212 offset:21504
	ds_read_b128 v[194:197], v212 offset:22528
	ds_read_b128 v[198:201], v212 offset:23552
	global_load_lds_dwordx4 v192, s[14:15]
	s_add_i32 m0, s6, 0x2000
	s_add_u32 s6, s14, 0x10000
	s_addc_u32 s7, s15, 0
	s_add_i32 s12, s13, s36
	global_load_lds_dwordx4 v190, s[14:15]
	s_mov_b32 m0, s12
	v_mov_b32_e32 v193, v3
	global_load_lds_dwordx4 v192, s[6:7]
	s_add_i32 m0, s12, 0x2000
	v_mov_b32_e32 v191, v3
	global_load_lds_dwordx4 v190, s[6:7]
	s_mov_b32 m0, s37
	v_lshl_add_u64 v[202:203], s[14:15], 0, v[192:193]
	global_load_lds_dwordx4 v2, s[10:11]
	s_mov_b32 m0, s66
	v_lshl_add_u64 v[204:205], s[14:15], 0, v[190:191]
	global_load_lds_dwordx4 v188, s[10:11]
	s_waitcnt vmcnt(8)
	s_waitcnt lgkmcnt(0)
	v_lshl_add_u64 v[206:207], s[10:11], 0, v[2:3]
	v_lshl_add_u64 v[210:211], s[10:11], 0, v[188:189]
	s_barrier
	s_setprio 1
	v_mfma_f32_16x16x32_bf16 v[68:71], v[132:135], v[164:167], v[68:71]
	v_mfma_f32_16x16x32_bf16 v[68:71], v[136:139], v[168:171], v[68:71]
	v_mfma_f32_16x16x32_bf16 v[72:75], v[144:147], v[168:171], v[72:75]
	v_mfma_f32_16x16x32_bf16 v[72:75], v[140:143], v[164:167], v[72:75]
	v_mfma_f32_16x16x32_bf16 v[80:83], v[140:143], v[172:175], v[80:83]
	v_mfma_f32_16x16x32_bf16 v[80:83], v[144:147], v[176:179], v[80:83]
	v_mfma_f32_16x16x32_bf16 v[76:79], v[136:139], v[176:179], v[76:79]
	v_mfma_f32_16x16x32_bf16 v[76:79], v[132:135], v[172:175], v[76:79]
	v_mfma_f32_16x16x32_bf16 v[84:87], v[132:135], v[180:183], v[84:87]
	v_mfma_f32_16x16x32_bf16 v[84:87], v[136:139], v[184:187], v[84:87]
	v_mfma_f32_16x16x32_bf16 v[88:91], v[144:147], v[184:187], v[88:91]
	v_mfma_f32_16x16x32_bf16 v[88:91], v[140:143], v[180:183], v[88:91]
	v_mfma_f32_16x16x32_bf16 v[96:99], v[140:143], v[194:197], v[96:99]
	v_mfma_f32_16x16x32_bf16 v[96:99], v[144:147], v[198:201], v[96:99]
	v_mfma_f32_16x16x32_bf16 v[92:95], v[136:139], v[198:201], v[92:95]
	v_mfma_f32_16x16x32_bf16 v[92:95], v[132:135], v[194:197], v[92:95]
	v_mfma_f32_16x16x32_bf16 v[100:103], v[148:151], v[164:167], v[100:103]
	v_mfma_f32_16x16x32_bf16 v[100:103], v[152:155], v[168:171], v[100:103]
	v_mfma_f32_16x16x32_bf16 v[104:107], v[160:163], v[168:171], v[104:107]
	v_mfma_f32_16x16x32_bf16 v[104:107], v[156:159], v[164:167], v[104:107]
	v_mfma_f32_16x16x32_bf16 v[112:115], v[156:159], v[172:175], v[112:115]
	v_mfma_f32_16x16x32_bf16 v[112:115], v[160:163], v[176:179], v[112:115]
	v_mfma_f32_16x16x32_bf16 v[108:111], v[152:155], v[176:179], v[108:111]
	v_mfma_f32_16x16x32_bf16 v[108:111], v[148:151], v[172:175], v[108:111]
	v_mfma_f32_16x16x32_bf16 v[116:119], v[148:151], v[180:183], v[116:119]
	v_mfma_f32_16x16x32_bf16 v[116:119], v[152:155], v[184:187], v[116:119]
	v_mfma_f32_16x16x32_bf16 v[120:123], v[160:163], v[184:187], v[120:123]
	v_mfma_f32_16x16x32_bf16 v[120:123], v[156:159], v[180:183], v[120:123]
	v_mfma_f32_16x16x32_bf16 v[128:131], v[156:159], v[194:197], v[128:131]
	v_mfma_f32_16x16x32_bf16 v[128:131], v[160:163], v[198:201], v[128:131]
	s_setprio 2
	s_barrier
	v_mfma_f32_16x16x32_bf16 v[124:127], v[152:155], v[198:201], v[124:127]
	v_mfma_f32_16x16x32_bf16 v[124:127], v[148:151], v[194:197], v[124:127]
	s_setprio 0
	s_add_i32 s12, 0, 0x18000
	s_add_i32 s13, 0, 0x1c000
	v_add_u32_e32 v144, s12, v209
	v_add_u32_e32 v160, s13, v209
	ds_read_b128 v[132:135], v144
	ds_read_b128 v[136:139], v144 offset:1024
	ds_read_b128 v[140:143], v144 offset:2048
	ds_read_b128 v[144:147], v144 offset:3072
	ds_read_b128 v[148:151], v160
	ds_read_b128 v[152:155], v160 offset:1024
	ds_read_b128 v[156:159], v160 offset:2048
	ds_read_b128 v[160:163], v160 offset:3072
	s_add_u32 s6, s10, 0x80000
	s_addc_u32 s7, s11, 0
	s_mov_b32 m0, s67
	ds_read_b128 v[164:167], v212 offset:32768
	ds_read_b128 v[168:171], v212 offset:33792
	ds_read_b128 v[172:175], v212 offset:34816
	ds_read_b128 v[176:179], v212 offset:35840
	ds_read_b128 v[180:183], v212 offset:36864
	ds_read_b128 v[184:187], v212 offset:37888
	ds_read_b128 v[194:197], v212 offset:38912
	ds_read_b128 v[198:201], v212 offset:39936
	global_load_lds_dwordx4 v2, s[6:7]
	s_mov_b32 m0, s68
	s_nop 0
	global_load_lds_dwordx4 v188, s[6:7]
	s_waitcnt vmcnt(8)
	s_waitcnt lgkmcnt(0)
	s_barrier
	s_setprio 1
	v_mfma_f32_16x16x32_bf16 v[4:7], v[132:135], v[164:167], v[4:7]
	v_mfma_f32_16x16x32_bf16 v[4:7], v[136:139], v[168:171], v[4:7]
	v_mfma_f32_16x16x32_bf16 v[8:11], v[144:147], v[168:171], v[8:11]
	v_mfma_f32_16x16x32_bf16 v[8:11], v[140:143], v[164:167], v[8:11]
	v_mfma_f32_16x16x32_bf16 v[16:19], v[140:143], v[172:175], v[16:19]
	v_mfma_f32_16x16x32_bf16 v[16:19], v[144:147], v[176:179], v[16:19]
	v_mfma_f32_16x16x32_bf16 v[12:15], v[136:139], v[176:179], v[12:15]
	v_mfma_f32_16x16x32_bf16 v[12:15], v[132:135], v[172:175], v[12:15]
	v_mfma_f32_16x16x32_bf16 v[20:23], v[132:135], v[180:183], v[20:23]
	v_mfma_f32_16x16x32_bf16 v[20:23], v[136:139], v[184:187], v[20:23]
	v_mfma_f32_16x16x32_bf16 v[24:27], v[144:147], v[184:187], v[24:27]
	v_mfma_f32_16x16x32_bf16 v[24:27], v[140:143], v[180:183], v[24:27]
	v_mfma_f32_16x16x32_bf16 v[32:35], v[140:143], v[194:197], v[32:35]
	v_mfma_f32_16x16x32_bf16 v[32:35], v[144:147], v[198:201], v[32:35]
	v_mfma_f32_16x16x32_bf16 v[28:31], v[136:139], v[198:201], v[28:31]
	v_mfma_f32_16x16x32_bf16 v[28:31], v[132:135], v[194:197], v[28:31]
	v_mfma_f32_16x16x32_bf16 v[36:39], v[148:151], v[164:167], v[36:39]
	v_mfma_f32_16x16x32_bf16 v[36:39], v[152:155], v[168:171], v[36:39]
	v_mfma_f32_16x16x32_bf16 v[40:43], v[160:163], v[168:171], v[40:43]
	v_mfma_f32_16x16x32_bf16 v[40:43], v[156:159], v[164:167], v[40:43]
	v_mfma_f32_16x16x32_bf16 v[48:51], v[156:159], v[172:175], v[48:51]
	v_mfma_f32_16x16x32_bf16 v[48:51], v[160:163], v[176:179], v[48:51]
	v_mfma_f32_16x16x32_bf16 v[44:47], v[152:155], v[176:179], v[44:47]
	v_mfma_f32_16x16x32_bf16 v[44:47], v[148:151], v[172:175], v[44:47]
	v_mfma_f32_16x16x32_bf16 v[52:55], v[148:151], v[180:183], v[52:55]
	v_mfma_f32_16x16x32_bf16 v[52:55], v[152:155], v[184:187], v[52:55]
	v_mfma_f32_16x16x32_bf16 v[56:59], v[160:163], v[184:187], v[56:59]
	v_mfma_f32_16x16x32_bf16 v[56:59], v[156:159], v[180:183], v[56:59]
	v_mfma_f32_16x16x32_bf16 v[64:67], v[156:159], v[194:197], v[64:67]
	v_mfma_f32_16x16x32_bf16 v[64:67], v[160:163], v[198:201], v[64:67]
	s_setprio 2
	s_barrier
	v_mfma_f32_16x16x32_bf16 v[60:63], v[152:155], v[198:201], v[60:63]
	v_mfma_f32_16x16x32_bf16 v[60:63], v[148:151], v[194:197], v[60:63]
	s_setprio 0
	s_add_i32 s6, s12, s36
	v_lshl_add_u64 v[202:203], v[202:203], 0, s[86:87]
	s_mov_b32 m0, s6
	ds_read_b128 v[164:167], v212 offset:49152
	ds_read_b128 v[168:171], v212 offset:50176
	ds_read_b128 v[172:175], v212 offset:51200
	ds_read_b128 v[176:179], v212 offset:52224
	ds_read_b128 v[180:183], v212 offset:53248
	ds_read_b128 v[184:187], v212 offset:54272
	ds_read_b128 v[194:197], v212 offset:55296
	ds_read_b128 v[198:201], v212 offset:56320
	global_load_lds_dwordx4 v[202:203], off
	s_add_i32 m0, s6, 0x2000
	s_add_u32 s6, s14, 0x10080
	v_lshl_add_u64 v[202:203], v[204:205], 0, s[86:87]
	s_addc_u32 s7, s15, 0
	s_add_i32 s12, s13, s36
	global_load_lds_dwordx4 v[202:203], off
	s_mov_b32 m0, s12
	v_lshl_add_u64 v[202:203], v[206:207], 0, s[86:87]
	global_load_lds_dwordx4 v192, s[6:7]
	s_add_i32 m0, s12, 0x2000
	s_nop 0
	global_load_lds_dwordx4 v190, s[6:7]
	s_mov_b32 m0, s71
	s_nop 0
	global_load_lds_dwordx4 v[202:203], off
	v_lshl_add_u64 v[202:203], v[210:211], 0, s[86:87]
	s_mov_b32 m0, s72
	s_nop 0
	global_load_lds_dwordx4 v[202:203], off
	s_waitcnt vmcnt(8)
	s_waitcnt lgkmcnt(0)
	s_barrier
	s_setprio 1
	v_mfma_f32_16x16x32_bf16 v[68:71], v[132:135], v[164:167], v[68:71]
	v_mfma_f32_16x16x32_bf16 v[68:71], v[136:139], v[168:171], v[68:71]
	v_mfma_f32_16x16x32_bf16 v[72:75], v[144:147], v[168:171], v[72:75]
	v_mfma_f32_16x16x32_bf16 v[72:75], v[140:143], v[164:167], v[72:75]
	v_mfma_f32_16x16x32_bf16 v[80:83], v[140:143], v[172:175], v[80:83]
	v_mfma_f32_16x16x32_bf16 v[80:83], v[144:147], v[176:179], v[80:83]
	v_mfma_f32_16x16x32_bf16 v[76:79], v[136:139], v[176:179], v[76:79]
	v_mfma_f32_16x16x32_bf16 v[76:79], v[132:135], v[172:175], v[76:79]
	v_mfma_f32_16x16x32_bf16 v[84:87], v[132:135], v[180:183], v[84:87]
	v_mfma_f32_16x16x32_bf16 v[84:87], v[136:139], v[184:187], v[84:87]
	v_mfma_f32_16x16x32_bf16 v[88:91], v[144:147], v[184:187], v[88:91]
	v_mfma_f32_16x16x32_bf16 v[88:91], v[140:143], v[180:183], v[88:91]
	v_mfma_f32_16x16x32_bf16 v[96:99], v[140:143], v[194:197], v[96:99]
	v_mfma_f32_16x16x32_bf16 v[96:99], v[144:147], v[198:201], v[96:99]
	v_mfma_f32_16x16x32_bf16 v[92:95], v[136:139], v[198:201], v[92:95]
	v_mfma_f32_16x16x32_bf16 v[92:95], v[132:135], v[194:197], v[92:95]
	v_mfma_f32_16x16x32_bf16 v[100:103], v[148:151], v[164:167], v[100:103]
	v_mfma_f32_16x16x32_bf16 v[100:103], v[152:155], v[168:171], v[100:103]
	v_mfma_f32_16x16x32_bf16 v[104:107], v[160:163], v[168:171], v[104:107]
	v_mfma_f32_16x16x32_bf16 v[104:107], v[156:159], v[164:167], v[104:107]
	v_mfma_f32_16x16x32_bf16 v[112:115], v[156:159], v[172:175], v[112:115]
	v_mfma_f32_16x16x32_bf16 v[112:115], v[160:163], v[176:179], v[112:115]
	v_mfma_f32_16x16x32_bf16 v[108:111], v[152:155], v[176:179], v[108:111]
	v_mfma_f32_16x16x32_bf16 v[108:111], v[148:151], v[172:175], v[108:111]
	v_mfma_f32_16x16x32_bf16 v[116:119], v[148:151], v[180:183], v[116:119]
	v_mfma_f32_16x16x32_bf16 v[116:119], v[152:155], v[184:187], v[116:119]
	v_mfma_f32_16x16x32_bf16 v[120:123], v[160:163], v[184:187], v[120:123]
	v_mfma_f32_16x16x32_bf16 v[120:123], v[156:159], v[180:183], v[120:123]
	v_mfma_f32_16x16x32_bf16 v[128:131], v[156:159], v[194:197], v[128:131]
	v_mfma_f32_16x16x32_bf16 v[128:131], v[160:163], v[198:201], v[128:131]
	s_setprio 2
	s_barrier
	v_mfma_f32_16x16x32_bf16 v[124:127], v[152:155], v[198:201], v[124:127]
	v_mfma_f32_16x16x32_bf16 v[124:127], v[148:151], v[194:197], v[124:127]
	s_setprio 0
	s_and_b64 vcc, exec, s[58:59]
	s_cbranch_vccz .LBB0_1178
	s_barrier

.LBB0_1625:
	s_add_i32 s51, 0, 0x10000
	s_add_i32 s72, 0, 0x14000
	v_add_u32_e32 v16, s51, v232
	v_add_u32_e32 v32, s72, v232
	ds_read_b128 v[4:7], v16
	ds_read_b128 v[8:11], v16 offset:1024
	ds_read_b128 v[12:15], v16 offset:2048
	ds_read_b128 v[16:19], v16 offset:3072
	ds_read_b128 v[20:23], v32
	ds_read_b128 v[24:27], v32 offset:1024
	ds_read_b128 v[28:31], v32 offset:2048
	ds_read_b128 v[32:35], v32 offset:3072
	v_add_u32_e32 v233, 0, v231
	ds_read_b128 v[36:39], v233
	ds_read_b128 v[40:43], v233 offset:1024
	ds_read_b128 v[44:47], v233 offset:2048
	ds_read_b128 v[48:51], v233 offset:3072
	ds_read_b128 v[52:55], v233 offset:4096
	ds_read_b128 v[56:59], v233 offset:5120
	ds_read_b128 v[60:63], v233 offset:6144
	ds_read_b128 v[64:67], v233 offset:7168
	s_waitcnt vmcnt(8)
	s_waitcnt lgkmcnt(0)
	s_barrier
	s_setprio 1
	v_mfma_f32_16x16x32_bf16 v[68:71], v[4:7], v[36:39], 0
	v_mfma_f32_16x16x32_bf16 v[68:71], v[8:11], v[40:43], v[68:71]
	v_mfma_f32_16x16x32_bf16 v[72:75], v[12:15], v[36:39], 0
	v_mfma_f32_16x16x32_bf16 v[72:75], v[16:19], v[40:43], v[72:75]
	v_mfma_f32_16x16x32_bf16 v[80:83], v[12:15], v[44:47], 0
	v_mfma_f32_16x16x32_bf16 v[80:83], v[16:19], v[48:51], v[80:83]
	v_mfma_f32_16x16x32_bf16 v[76:79], v[4:7], v[44:47], 0
	v_mfma_f32_16x16x32_bf16 v[76:79], v[8:11], v[48:51], v[76:79]
	v_mfma_f32_16x16x32_bf16 v[84:87], v[4:7], v[52:55], 0
	v_mfma_f32_16x16x32_bf16 v[84:87], v[8:11], v[56:59], v[84:87]
	v_mfma_f32_16x16x32_bf16 v[88:91], v[12:15], v[52:55], 0
	v_mfma_f32_16x16x32_bf16 v[88:91], v[16:19], v[56:59], v[88:91]
	v_mfma_f32_16x16x32_bf16 v[96:99], v[12:15], v[60:63], 0
	v_mfma_f32_16x16x32_bf16 v[96:99], v[16:19], v[64:67], v[96:99]
	v_mfma_f32_16x16x32_bf16 v[92:95], v[4:7], v[60:63], 0
	v_mfma_f32_16x16x32_bf16 v[92:95], v[8:11], v[64:67], v[92:95]
	v_mfma_f32_16x16x32_bf16 v[100:103], v[20:23], v[36:39], 0
	v_mfma_f32_16x16x32_bf16 v[36:39], v[28:31], v[36:39], 0
	v_mfma_f32_16x16x32_bf16 v[104:107], v[20:23], v[44:47], 0
	v_mfma_f32_16x16x32_bf16 v[44:47], v[28:31], v[44:47], 0
	v_mfma_f32_16x16x32_bf16 v[108:111], v[20:23], v[52:55], 0
	v_mfma_f32_16x16x32_bf16 v[52:55], v[28:31], v[52:55], 0
	v_mfma_f32_16x16x32_bf16 v[112:115], v[20:23], v[60:63], 0
	v_mfma_f32_16x16x32_bf16 v[60:63], v[28:31], v[60:63], 0
	v_mfma_f32_16x16x32_bf16 v[100:103], v[24:27], v[40:43], v[100:103]
	v_mfma_f32_16x16x32_bf16 v[40:43], v[32:35], v[40:43], v[36:39]
	v_mfma_f32_16x16x32_bf16 v[104:107], v[24:27], v[48:51], v[104:107]
	v_mfma_f32_16x16x32_bf16 v[48:51], v[32:35], v[48:51], v[44:47]
	v_mfma_f32_16x16x32_bf16 v[108:111], v[24:27], v[56:59], v[108:111]
	v_mfma_f32_16x16x32_bf16 v[56:59], v[32:35], v[56:59], v[52:55]
	s_setprio 2
	s_barrier
	v_mfma_f32_16x16x32_bf16 v[112:115], v[24:27], v[64:67], v[112:115]
	v_mfma_f32_16x16x32_bf16 v[64:67], v[32:35], v[64:67], v[60:63]
	s_setprio 0
	v_lshl_add_u64 v[186:187], s[12:13], 0, v[2:3]
	s_add_i32 s51, s51, s56
	v_mov_b32_e32 v191, v3
	v_lshl_add_u64 v[134:135], v[186:187], 0, s[74:75]
	s_mov_b32 m0, s51
	v_lshl_add_u64 v[246:247], s[12:13], 0, v[190:191]
	ds_read_b128 v[36:39], v233 offset:16384
	ds_read_b128 v[44:47], v233 offset:17408
	ds_read_b128 v[52:55], v233 offset:18432
	ds_read_b128 v[60:63], v233 offset:19456
	ds_read_b128 v[116:119], v233 offset:20480
	ds_read_b128 v[120:123], v233 offset:21504
	ds_read_b128 v[124:127], v233 offset:22528
	ds_read_b128 v[128:131], v233 offset:23552
	global_load_lds_dwordx4 v[134:135], off
	v_lshl_add_u64 v[134:135], v[246:247], 0, s[74:75]
	s_add_i32 m0, s51, 0x2000
	s_add_i32 s51, s72, s56
	global_load_lds_dwordx4 v[134:135], off
	s_mov_b32 m0, s51
	v_mov_b32_e32 v133, v3
	global_load_lds_dwordx4 v2, s[16:17]
	s_add_i32 m0, s51, 0x2000
	v_lshl_add_u64 v[248:249], s[14:15], 0, v[132:133]
	v_mov_b32_e32 v189, v3
	global_load_lds_dwordx4 v190, s[16:17]
	v_lshl_add_u64 v[134:135], v[248:249], 0, s[74:75]
	s_mov_b32 m0, s57
	v_lshl_add_u64 v[250:251], s[14:15], 0, v[188:189]
	global_load_lds_dwordx4 v[134:135], off
	v_lshl_add_u64 v[134:135], v[250:251], 0, s[74:75]
	s_mov_b32 m0, s58
	s_nop 0
	global_load_lds_dwordx4 v[134:135], off
	s_waitcnt vmcnt(8)
	s_waitcnt lgkmcnt(0)
	s_barrier
	s_setprio 1
	v_mfma_f32_16x16x32_bf16 v[134:137], v[4:7], v[36:39], 0
	v_mfma_f32_16x16x32_bf16 v[138:141], v[12:15], v[36:39], 0
	v_mfma_f32_16x16x32_bf16 v[142:145], v[4:7], v[52:55], 0
	v_mfma_f32_16x16x32_bf16 v[146:149], v[12:15], v[52:55], 0
	v_mfma_f32_16x16x32_bf16 v[150:153], v[4:7], v[116:119], 0
	v_mfma_f32_16x16x32_bf16 v[154:157], v[12:15], v[116:119], 0
	v_mfma_f32_16x16x32_bf16 v[4:7], v[4:7], v[124:127], 0
	v_mfma_f32_16x16x32_bf16 v[12:15], v[12:15], v[124:127], 0
	v_mfma_f32_16x16x32_bf16 v[134:137], v[8:11], v[44:47], v[134:137]
	v_mfma_f32_16x16x32_bf16 v[138:141], v[16:19], v[44:47], v[138:141]
	v_mfma_f32_16x16x32_bf16 v[142:145], v[8:11], v[60:63], v[142:145]
	v_mfma_f32_16x16x32_bf16 v[146:149], v[16:19], v[60:63], v[146:149]
	v_mfma_f32_16x16x32_bf16 v[150:153], v[8:11], v[120:123], v[150:153]
	v_mfma_f32_16x16x32_bf16 v[154:157], v[16:19], v[120:123], v[154:157]
	v_mfma_f32_16x16x32_bf16 v[158:161], v[8:11], v[128:131], v[4:7]
	v_mfma_f32_16x16x32_bf16 v[162:165], v[16:19], v[128:131], v[12:15]
	v_mfma_f32_16x16x32_bf16 v[4:7], v[20:23], v[36:39], 0
	v_mfma_f32_16x16x32_bf16 v[8:11], v[28:31], v[36:39], 0
	v_mfma_f32_16x16x32_bf16 v[12:15], v[20:23], v[52:55], 0
	v_mfma_f32_16x16x32_bf16 v[16:19], v[28:31], v[52:55], 0
	v_mfma_f32_16x16x32_bf16 v[36:39], v[20:23], v[116:119], 0
	v_mfma_f32_16x16x32_bf16 v[52:55], v[28:31], v[116:119], 0
	v_mfma_f32_16x16x32_bf16 v[20:23], v[20:23], v[124:127], 0
	v_mfma_f32_16x16x32_bf16 v[28:31], v[28:31], v[124:127], 0
	v_mfma_f32_16x16x32_bf16 v[116:119], v[24:27], v[44:47], v[4:7]
	v_mfma_f32_16x16x32_bf16 v[124:127], v[32:35], v[44:47], v[8:11]
	v_mfma_f32_16x16x32_bf16 v[174:177], v[24:27], v[120:123], v[36:39]
	v_mfma_f32_16x16x32_bf16 v[120:123], v[32:35], v[120:123], v[52:55]
	v_mfma_f32_16x16x32_bf16 v[178:181], v[24:27], v[128:131], v[20:23]
	v_mfma_f32_16x16x32_bf16 v[128:131], v[32:35], v[128:131], v[28:31]
	s_setprio 2
	s_barrier
	v_mfma_f32_16x16x32_bf16 v[166:169], v[24:27], v[60:63], v[12:15]
	v_mfma_f32_16x16x32_bf16 v[170:173], v[32:35], v[60:63], v[16:19]
	s_setprio 0
	s_add_i32 s51, 0, 0x18000
	v_add_u32_e32 v4, s51, v232
	s_add_i32 s72, 0, 0x1c000
	ds_read_b128 v[182:185], v4
	ds_read_b128 v[192:195], v4 offset:1024
	ds_read_b128 v[196:199], v4 offset:2048
	ds_read_b128 v[200:203], v4 offset:3072
	v_add_u32_e32 v4, s72, v232
	ds_read_b128 v[204:207], v4
	ds_read_b128 v[208:211], v4 offset:1024
	ds_read_b128 v[212:215], v4 offset:2048
	ds_read_b128 v[216:219], v4 offset:3072
	s_mov_b32 m0, s59
	ds_read_b128 v[44:47], v233 offset:32768
	ds_read_b128 v[52:55], v233 offset:33792
	ds_read_b128 v[60:63], v233 offset:34816
	ds_read_b128 v[220:223], v233 offset:35840
	ds_read_b128 v[224:227], v233 offset:36864
	ds_read_b128 v[234:237], v233 offset:37888
	ds_read_b128 v[238:241], v233 offset:38912
	ds_read_b128 v[242:245], v233 offset:39936
	global_load_lds_dwordx4 v132, s[26:27]
	s_mov_b32 m0, s60
	s_nop 0
	global_load_lds_dwordx4 v188, s[26:27]
	s_waitcnt vmcnt(8)
	s_waitcnt lgkmcnt(0)
	s_barrier
	s_setprio 1
	v_mfma_f32_16x16x32_bf16 v[4:7], v[182:185], v[44:47], v[68:71]
	v_mfma_f32_16x16x32_bf16 v[8:11], v[196:199], v[44:47], v[72:75]
	v_mfma_f32_16x16x32_bf16 v[12:15], v[182:185], v[60:63], v[76:79]
	v_mfma_f32_16x16x32_bf16 v[16:19], v[196:199], v[60:63], v[80:83]
	v_mfma_f32_16x16x32_bf16 v[20:23], v[182:185], v[224:227], v[84:87]
	v_mfma_f32_16x16x32_bf16 v[24:27], v[196:199], v[224:227], v[88:91]
	v_mfma_f32_16x16x32_bf16 v[28:31], v[182:185], v[238:241], v[92:95]
	v_mfma_f32_16x16x32_bf16 v[32:35], v[196:199], v[238:241], v[96:99]
	v_mfma_f32_16x16x32_bf16 v[4:7], v[192:195], v[52:55], v[4:7]
	v_mfma_f32_16x16x32_bf16 v[8:11], v[200:203], v[52:55], v[8:11]
	v_mfma_f32_16x16x32_bf16 v[12:15], v[192:195], v[220:223], v[12:15]
	v_mfma_f32_16x16x32_bf16 v[16:19], v[200:203], v[220:223], v[16:19]
	v_mfma_f32_16x16x32_bf16 v[20:23], v[192:195], v[234:237], v[20:23]
	v_mfma_f32_16x16x32_bf16 v[24:27], v[200:203], v[234:237], v[24:27]
	v_mfma_f32_16x16x32_bf16 v[28:31], v[192:195], v[242:245], v[28:31]
	v_mfma_f32_16x16x32_bf16 v[32:35], v[200:203], v[242:245], v[32:35]
	v_mfma_f32_16x16x32_bf16 v[36:39], v[204:207], v[44:47], v[100:103]
	v_mfma_f32_16x16x32_bf16 v[40:43], v[212:215], v[44:47], v[40:43]
	v_mfma_f32_16x16x32_bf16 v[36:39], v[208:211], v[52:55], v[36:39]
	v_mfma_f32_16x16x32_bf16 v[40:43], v[216:219], v[52:55], v[40:43]
	v_mfma_f32_16x16x32_bf16 v[44:47], v[204:207], v[60:63], v[104:107]
	v_mfma_f32_16x16x32_bf16 v[48:51], v[212:215], v[60:63], v[48:51]
	v_mfma_f32_16x16x32_bf16 v[52:55], v[204:207], v[224:227], v[108:111]
	v_mfma_f32_16x16x32_bf16 v[56:59], v[212:215], v[224:227], v[56:59]
	v_mfma_f32_16x16x32_bf16 v[60:63], v[204:207], v[238:241], v[112:115]
	v_mfma_f32_16x16x32_bf16 v[64:67], v[212:215], v[238:241], v[64:67]
	v_mfma_f32_16x16x32_bf16 v[44:47], v[208:211], v[220:223], v[44:47]
	v_mfma_f32_16x16x32_bf16 v[48:51], v[216:219], v[220:223], v[48:51]
	v_mfma_f32_16x16x32_bf16 v[52:55], v[208:211], v[234:237], v[52:55]
	v_mfma_f32_16x16x32_bf16 v[56:59], v[216:219], v[234:237], v[56:59]
	s_setprio 2
	s_barrier
	v_mfma_f32_16x16x32_bf16 v[60:63], v[208:211], v[242:245], v[60:63]
	v_mfma_f32_16x16x32_bf16 v[64:67], v[216:219], v[242:245], v[64:67]
	s_setprio 0
	s_add_i32 s51, s51, s56
	v_lshl_add_u64 v[68:69], v[186:187], 0, s[24:25]
	s_mov_b32 m0, s51
	ds_read_b128 v[104:107], v233 offset:49152
	ds_read_b128 v[108:111], v233 offset:50176
	ds_read_b128 v[112:115], v233 offset:51200
	ds_read_b128 v[220:223], v233 offset:52224
	ds_read_b128 v[224:227], v233 offset:53248
	ds_read_b128 v[234:237], v233 offset:54272
	ds_read_b128 v[238:241], v233 offset:55296
	ds_read_b128 v[242:245], v233 offset:56320
	global_load_lds_dwordx4 v[68:69], off
	v_lshl_add_u64 v[68:69], v[246:247], 0, s[24:25]
	s_add_i32 m0, s51, 0x2000
	s_add_i32 s51, s72, s56
	global_load_lds_dwordx4 v[68:69], off
	s_mov_b32 m0, s51
	v_lshl_add_u64 v[68:69], v[248:249], 0, s[24:25]
	global_load_lds_dwordx4 v2, s[28:29]
	s_add_i32 m0, s51, 0x2000
	s_nop 0
	global_load_lds_dwordx4 v190, s[28:29]
	s_mov_b32 m0, s64
	s_nop 0
	global_load_lds_dwordx4 v[68:69], off
	v_lshl_add_u64 v[68:69], v[250:251], 0, s[24:25]
	s_mov_b32 m0, s65
	s_nop 0
	global_load_lds_dwordx4 v[68:69], off
	s_waitcnt vmcnt(8)
	s_waitcnt lgkmcnt(0)
	s_barrier
	s_setprio 1
	v_mfma_f32_16x16x32_bf16 v[68:71], v[182:185], v[104:107], v[134:137]
	v_mfma_f32_16x16x32_bf16 v[72:75], v[196:199], v[104:107], v[138:141]
	v_mfma_f32_16x16x32_bf16 v[76:79], v[182:185], v[112:115], v[142:145]
	v_mfma_f32_16x16x32_bf16 v[80:83], v[196:199], v[112:115], v[146:149]
	v_mfma_f32_16x16x32_bf16 v[84:87], v[182:185], v[224:227], v[150:153]
	v_mfma_f32_16x16x32_bf16 v[88:91], v[196:199], v[224:227], v[154:157]
	v_mfma_f32_16x16x32_bf16 v[92:95], v[182:185], v[238:241], v[158:161]
	v_mfma_f32_16x16x32_bf16 v[96:99], v[196:199], v[238:241], v[162:165]
	v_mfma_f32_16x16x32_bf16 v[68:71], v[192:195], v[108:111], v[68:71]
	v_mfma_f32_16x16x32_bf16 v[72:75], v[200:203], v[108:111], v[72:75]
	v_mfma_f32_16x16x32_bf16 v[76:79], v[192:195], v[220:223], v[76:79]
	v_mfma_f32_16x16x32_bf16 v[80:83], v[200:203], v[220:223], v[80:83]
	v_mfma_f32_16x16x32_bf16 v[84:87], v[192:195], v[234:237], v[84:87]
	v_mfma_f32_16x16x32_bf16 v[88:91], v[200:203], v[234:237], v[88:91]
	v_mfma_f32_16x16x32_bf16 v[92:95], v[192:195], v[242:245], v[92:95]
	v_mfma_f32_16x16x32_bf16 v[96:99], v[200:203], v[242:245], v[96:99]
	v_mfma_f32_16x16x32_bf16 v[100:103], v[204:207], v[104:107], v[116:119]
	v_mfma_f32_16x16x32_bf16 v[104:107], v[212:215], v[104:107], v[124:127]
	v_mfma_f32_16x16x32_bf16 v[100:103], v[208:211], v[108:111], v[100:103]
	v_mfma_f32_16x16x32_bf16 v[104:107], v[216:219], v[108:111], v[104:107]
	v_mfma_f32_16x16x32_bf16 v[108:111], v[204:207], v[112:115], v[166:169]
	v_mfma_f32_16x16x32_bf16 v[112:115], v[212:215], v[112:115], v[170:173]
	v_mfma_f32_16x16x32_bf16 v[116:119], v[204:207], v[224:227], v[174:177]
	v_mfma_f32_16x16x32_bf16 v[120:123], v[212:215], v[224:227], v[120:123]
	v_mfma_f32_16x16x32_bf16 v[124:127], v[204:207], v[238:241], v[178:181]
	v_mfma_f32_16x16x32_bf16 v[128:131], v[212:215], v[238:241], v[128:131]
	v_mfma_f32_16x16x32_bf16 v[108:111], v[208:211], v[220:223], v[108:111]
	v_mfma_f32_16x16x32_bf16 v[112:115], v[216:219], v[220:223], v[112:115]
	v_mfma_f32_16x16x32_bf16 v[116:119], v[208:211], v[234:237], v[116:119]
	v_mfma_f32_16x16x32_bf16 v[120:123], v[216:219], v[234:237], v[120:123]
	s_setprio 2
	s_barrier
	v_mfma_f32_16x16x32_bf16 v[124:127], v[208:211], v[242:245], v[124:127]
	v_mfma_f32_16x16x32_bf16 v[128:131], v[216:219], v[242:245], v[128:131]
	s_setprio 0
	s_add_i32 s43, s43, 2
	s_cmp_ge_i32 s43, s42
	s_cbranch_scc0 .LBB0_1625
	v_mov_b32_e32 v192, v2
	s_branch .LBB0_1628

.LBB0_1629:
	s_add_u32 s12, s14, 0xfff80080
	s_addc_u32 s13, s15, -1
	s_add_i32 s29, 0, 0x10000
	s_cmp_eq_u32 s28, 28
	s_cselect_b32 s17, s9, s13
	s_cselect_b32 s16, s8, s12
	s_cselect_b32 s13, s11, s27
	s_cselect_b32 s12, s10, s26
	s_add_i32 s51, 0, 0x14000
	v_add_u32_e32 v144, s29, v232
	v_add_u32_e32 v160, s51, v232
	s_waitcnt lgkmcnt(0)
	ds_read_b128 v[132:135], v144
	ds_read_b128 v[136:139], v144 offset:1024
	ds_read_b128 v[140:143], v144 offset:2048
	ds_read_b128 v[144:147], v144 offset:3072
	ds_read_b128 v[148:151], v160
	ds_read_b128 v[152:155], v160 offset:1024
	ds_read_b128 v[156:159], v160 offset:2048
	ds_read_b128 v[160:163], v160 offset:3072
	s_mov_b32 m0, s66
	v_add_u32_e32 v210, 0, v231
	ds_read_b128 v[164:167], v210
	ds_read_b128 v[168:171], v210 offset:1024
	ds_read_b128 v[172:175], v210 offset:2048
	ds_read_b128 v[176:179], v210 offset:3072
	ds_read_b128 v[180:183], v210 offset:4096
	ds_read_b128 v[184:187], v210 offset:5120
	ds_read_b128 v[194:197], v210 offset:6144
	ds_read_b128 v[198:201], v210 offset:7168
	global_load_lds_dwordx4 v2, s[14:15]
	s_mov_b32 m0, s67
	v_mov_b32_e32 v189, v3
	global_load_lds_dwordx4 v188, s[14:15]
	s_waitcnt vmcnt(8)
	s_waitcnt lgkmcnt(0)
	s_barrier
	s_setprio 1
	v_mfma_f32_16x16x32_bf16 v[4:7], v[132:135], v[164:167], v[4:7]
	v_mfma_f32_16x16x32_bf16 v[4:7], v[136:139], v[168:171], v[4:7]
	v_mfma_f32_16x16x32_bf16 v[8:11], v[144:147], v[168:171], v[8:11]
	v_mfma_f32_16x16x32_bf16 v[8:11], v[140:143], v[164:167], v[8:11]
	v_mfma_f32_16x16x32_bf16 v[16:19], v[140:143], v[172:175], v[16:19]
	v_mfma_f32_16x16x32_bf16 v[16:19], v[144:147], v[176:179], v[16:19]
	v_mfma_f32_16x16x32_bf16 v[12:15], v[136:139], v[176:179], v[12:15]
	v_mfma_f32_16x16x32_bf16 v[12:15], v[132:135], v[172:175], v[12:15]
	v_mfma_f32_16x16x32_bf16 v[20:23], v[132:135], v[180:183], v[20:23]
	v_mfma_f32_16x16x32_bf16 v[20:23], v[136:139], v[184:187], v[20:23]
	v_mfma_f32_16x16x32_bf16 v[24:27], v[144:147], v[184:187], v[24:27]
	v_mfma_f32_16x16x32_bf16 v[24:27], v[140:143], v[180:183], v[24:27]
	v_mfma_f32_16x16x32_bf16 v[32:35], v[140:143], v[194:197], v[32:35]
	v_mfma_f32_16x16x32_bf16 v[32:35], v[144:147], v[198:201], v[32:35]
	v_mfma_f32_16x16x32_bf16 v[28:31], v[136:139], v[198:201], v[28:31]
	v_mfma_f32_16x16x32_bf16 v[28:31], v[132:135], v[194:197], v[28:31]
	v_mfma_f32_16x16x32_bf16 v[36:39], v[148:151], v[164:167], v[36:39]
	v_mfma_f32_16x16x32_bf16 v[36:39], v[152:155], v[168:171], v[36:39]
	v_mfma_f32_16x16x32_bf16 v[40:43], v[160:163], v[168:171], v[40:43]
	v_mfma_f32_16x16x32_bf16 v[40:43], v[156:159], v[164:167], v[40:43]
	v_mfma_f32_16x16x32_bf16 v[48:51], v[156:159], v[172:175], v[48:51]
	v_mfma_f32_16x16x32_bf16 v[48:51], v[160:163], v[176:179], v[48:51]
	v_mfma_f32_16x16x32_bf16 v[44:47], v[152:155], v[176:179], v[44:47]
	v_mfma_f32_16x16x32_bf16 v[44:47], v[148:151], v[172:175], v[44:47]
	v_mfma_f32_16x16x32_bf16 v[52:55], v[148:151], v[180:183], v[52:55]
	v_mfma_f32_16x16x32_bf16 v[52:55], v[152:155], v[184:187], v[52:55]
	v_mfma_f32_16x16x32_bf16 v[56:59], v[160:163], v[184:187], v[56:59]
	v_mfma_f32_16x16x32_bf16 v[56:59], v[156:159], v[180:183], v[56:59]
	v_mfma_f32_16x16x32_bf16 v[64:67], v[156:159], v[194:197], v[64:67]
	v_mfma_f32_16x16x32_bf16 v[64:67], v[160:163], v[198:201], v[64:67]
	s_setprio 2
	s_barrier
	v_mfma_f32_16x16x32_bf16 v[60:63], v[152:155], v[198:201], v[60:63]
	v_mfma_f32_16x16x32_bf16 v[60:63], v[148:151], v[194:197], v[60:63]
	s_setprio 0
	s_add_i32 s29, s29, s56
	s_mov_b32 m0, s29
	ds_read_b128 v[164:167], v210 offset:16384
	ds_read_b128 v[168:171], v210 offset:17408
	ds_read_b128 v[172:175], v210 offset:18432
	ds_read_b128 v[176:179], v210 offset:19456
	ds_read_b128 v[180:183], v210 offset:20480
	ds_read_b128 v[184:187], v210 offset:21504
	ds_read_b128 v[194:197], v210 offset:22528
	ds_read_b128 v[198:201], v210 offset:23552
	global_load_lds_dwordx4 v192, s[12:13]
	s_add_i32 m0, s29, 0x2000
	s_add_u32 s42, s12, 0x80000
	s_addc_u32 s43, s13, 0
	s_add_i32 s29, s51, s56
	global_load_lds_dwordx4 v190, s[12:13]
	s_mov_b32 m0, s29
	v_mov_b32_e32 v193, v3
	global_load_lds_dwordx4 v192, s[42:43]
	s_add_i32 m0, s29, 0x2000
	v_mov_b32_e32 v191, v3
	global_load_lds_dwordx4 v190, s[42:43]
	s_mov_b32 m0, s57
	v_lshl_add_u64 v[202:203], s[12:13], 0, v[192:193]
	global_load_lds_dwordx4 v2, s[16:17]
	s_mov_b32 m0, s58
	v_lshl_add_u64 v[204:205], s[12:13], 0, v[190:191]
	global_load_lds_dwordx4 v188, s[16:17]
	s_waitcnt vmcnt(8)
	s_waitcnt lgkmcnt(0)
	v_lshl_add_u64 v[206:207], s[16:17], 0, v[2:3]
	v_lshl_add_u64 v[208:209], s[16:17], 0, v[188:189]
	s_barrier
	s_setprio 1
	v_mfma_f32_16x16x32_bf16 v[68:71], v[132:135], v[164:167], v[68:71]
	v_mfma_f32_16x16x32_bf16 v[68:71], v[136:139], v[168:171], v[68:71]
	v_mfma_f32_16x16x32_bf16 v[72:75], v[144:147], v[168:171], v[72:75]
	v_mfma_f32_16x16x32_bf16 v[72:75], v[140:143], v[164:167], v[72:75]
	v_mfma_f32_16x16x32_bf16 v[80:83], v[140:143], v[172:175], v[80:83]
	v_mfma_f32_16x16x32_bf16 v[80:83], v[144:147], v[176:179], v[80:83]
	v_mfma_f32_16x16x32_bf16 v[76:79], v[136:139], v[176:179], v[76:79]
	v_mfma_f32_16x16x32_bf16 v[76:79], v[132:135], v[172:175], v[76:79]
	v_mfma_f32_16x16x32_bf16 v[84:87], v[132:135], v[180:183], v[84:87]
	v_mfma_f32_16x16x32_bf16 v[84:87], v[136:139], v[184:187], v[84:87]
	v_mfma_f32_16x16x32_bf16 v[88:91], v[144:147], v[184:187], v[88:91]
	v_mfma_f32_16x16x32_bf16 v[88:91], v[140:143], v[180:183], v[88:91]
	v_mfma_f32_16x16x32_bf16 v[96:99], v[140:143], v[194:197], v[96:99]
	v_mfma_f32_16x16x32_bf16 v[96:99], v[144:147], v[198:201], v[96:99]
	v_mfma_f32_16x16x32_bf16 v[92:95], v[136:139], v[198:201], v[92:95]
	v_mfma_f32_16x16x32_bf16 v[92:95], v[132:135], v[194:197], v[92:95]
	v_mfma_f32_16x16x32_bf16 v[100:103], v[148:151], v[164:167], v[100:103]
	v_mfma_f32_16x16x32_bf16 v[100:103], v[152:155], v[168:171], v[100:103]
	v_mfma_f32_16x16x32_bf16 v[104:107], v[160:163], v[168:171], v[104:107]
	v_mfma_f32_16x16x32_bf16 v[104:107], v[156:159], v[164:167], v[104:107]
	v_mfma_f32_16x16x32_bf16 v[112:115], v[156:159], v[172:175], v[112:115]
	v_mfma_f32_16x16x32_bf16 v[112:115], v[160:163], v[176:179], v[112:115]
	v_mfma_f32_16x16x32_bf16 v[108:111], v[152:155], v[176:179], v[108:111]
	v_mfma_f32_16x16x32_bf16 v[108:111], v[148:151], v[172:175], v[108:111]
	v_mfma_f32_16x16x32_bf16 v[116:119], v[148:151], v[180:183], v[116:119]
	v_mfma_f32_16x16x32_bf16 v[116:119], v[152:155], v[184:187], v[116:119]
	v_mfma_f32_16x16x32_bf16 v[120:123], v[160:163], v[184:187], v[120:123]
	v_mfma_f32_16x16x32_bf16 v[120:123], v[156:159], v[180:183], v[120:123]
	v_mfma_f32_16x16x32_bf16 v[128:131], v[156:159], v[194:197], v[128:131]
	v_mfma_f32_16x16x32_bf16 v[128:131], v[160:163], v[198:201], v[128:131]
	s_setprio 2
	s_barrier
	v_mfma_f32_16x16x32_bf16 v[124:127], v[152:155], v[198:201], v[124:127]
	v_mfma_f32_16x16x32_bf16 v[124:127], v[148:151], v[194:197], v[124:127]
	s_setprio 0
	s_add_i32 s29, 0, 0x18000
	s_add_i32 s42, 0, 0x1c000
	v_add_u32_e32 v144, s29, v232
	v_add_u32_e32 v160, s42, v232
	ds_read_b128 v[132:135], v144
	ds_read_b128 v[136:139], v144 offset:1024
	ds_read_b128 v[140:143], v144 offset:2048
	ds_read_b128 v[144:147], v144 offset:3072
	ds_read_b128 v[148:151], v160
	ds_read_b128 v[152:155], v160 offset:1024
	ds_read_b128 v[156:159], v160 offset:2048
	ds_read_b128 v[160:163], v160 offset:3072
	s_add_u32 s16, s16, 0x80000
	s_addc_u32 s17, s17, 0
	s_mov_b32 m0, s59
	ds_read_b128 v[164:167], v210 offset:32768
	ds_read_b128 v[168:171], v210 offset:33792
	ds_read_b128 v[172:175], v210 offset:34816
	ds_read_b128 v[176:179], v210 offset:35840
	ds_read_b128 v[180:183], v210 offset:36864
	ds_read_b128 v[184:187], v210 offset:37888
	ds_read_b128 v[194:197], v210 offset:38912
	ds_read_b128 v[198:201], v210 offset:39936
	global_load_lds_dwordx4 v2, s[16:17]
	s_mov_b32 m0, s60
	s_nop 0
	global_load_lds_dwordx4 v188, s[16:17]
	s_waitcnt vmcnt(8)
	s_waitcnt lgkmcnt(0)
	s_barrier
	s_setprio 1
	v_mfma_f32_16x16x32_bf16 v[4:7], v[132:135], v[164:167], v[4:7]
	v_mfma_f32_16x16x32_bf16 v[4:7], v[136:139], v[168:171], v[4:7]
	v_mfma_f32_16x16x32_bf16 v[8:11], v[144:147], v[168:171], v[8:11]
	v_mfma_f32_16x16x32_bf16 v[8:11], v[140:143], v[164:167], v[8:11]
	v_mfma_f32_16x16x32_bf16 v[16:19], v[140:143], v[172:175], v[16:19]
	v_mfma_f32_16x16x32_bf16 v[16:19], v[144:147], v[176:179], v[16:19]
	v_mfma_f32_16x16x32_bf16 v[12:15], v[136:139], v[176:179], v[12:15]
	v_mfma_f32_16x16x32_bf16 v[12:15], v[132:135], v[172:175], v[12:15]
	v_mfma_f32_16x16x32_bf16 v[20:23], v[132:135], v[180:183], v[20:23]
	v_mfma_f32_16x16x32_bf16 v[20:23], v[136:139], v[184:187], v[20:23]
	v_mfma_f32_16x16x32_bf16 v[24:27], v[144:147], v[184:187], v[24:27]
	v_mfma_f32_16x16x32_bf16 v[24:27], v[140:143], v[180:183], v[24:27]
	v_mfma_f32_16x16x32_bf16 v[32:35], v[140:143], v[194:197], v[32:35]
	v_mfma_f32_16x16x32_bf16 v[32:35], v[144:147], v[198:201], v[32:35]
	v_mfma_f32_16x16x32_bf16 v[28:31], v[136:139], v[198:201], v[28:31]
	v_mfma_f32_16x16x32_bf16 v[28:31], v[132:135], v[194:197], v[28:31]
	v_mfma_f32_16x16x32_bf16 v[36:39], v[148:151], v[164:167], v[36:39]
	v_mfma_f32_16x16x32_bf16 v[36:39], v[152:155], v[168:171], v[36:39]
	v_mfma_f32_16x16x32_bf16 v[40:43], v[160:163], v[168:171], v[40:43]
	v_mfma_f32_16x16x32_bf16 v[40:43], v[156:159], v[164:167], v[40:43]
	v_mfma_f32_16x16x32_bf16 v[48:51], v[156:159], v[172:175], v[48:51]
	v_mfma_f32_16x16x32_bf16 v[48:51], v[160:163], v[176:179], v[48:51]
	v_mfma_f32_16x16x32_bf16 v[44:47], v[152:155], v[176:179], v[44:47]
	v_mfma_f32_16x16x32_bf16 v[44:47], v[148:151], v[172:175], v[44:47]
	v_mfma_f32_16x16x32_bf16 v[52:55], v[148:151], v[180:183], v[52:55]
	v_mfma_f32_16x16x32_bf16 v[52:55], v[152:155], v[184:187], v[52:55]
	v_mfma_f32_16x16x32_bf16 v[56:59], v[160:163], v[184:187], v[56:59]
	v_mfma_f32_16x16x32_bf16 v[56:59], v[156:159], v[180:183], v[56:59]
	v_mfma_f32_16x16x32_bf16 v[64:67], v[156:159], v[194:197], v[64:67]
	v_mfma_f32_16x16x32_bf16 v[64:67], v[160:163], v[198:201], v[64:67]
	s_setprio 2
	s_barrier
	v_mfma_f32_16x16x32_bf16 v[60:63], v[152:155], v[198:201], v[60:63]
	v_mfma_f32_16x16x32_bf16 v[60:63], v[148:151], v[194:197], v[60:63]
	s_setprio 0
	s_add_i32 s16, s29, s56
	v_lshl_add_u64 v[202:203], v[202:203], 0, s[86:87]
	s_mov_b32 m0, s16
	ds_read_b128 v[164:167], v210 offset:49152
	ds_read_b128 v[168:171], v210 offset:50176
	ds_read_b128 v[172:175], v210 offset:51200
	ds_read_b128 v[176:179], v210 offset:52224
	ds_read_b128 v[180:183], v210 offset:53248
	ds_read_b128 v[184:187], v210 offset:54272
	ds_read_b128 v[194:197], v210 offset:55296
	ds_read_b128 v[198:201], v210 offset:56320
	global_load_lds_dwordx4 v[202:203], off
	s_add_i32 m0, s16, 0x2000
	s_add_u32 s12, s12, 0x80080
	v_lshl_add_u64 v[202:203], v[204:205], 0, s[86:87]
	s_addc_u32 s13, s13, 0
	s_add_i32 s16, s42, s56
	global_load_lds_dwordx4 v[202:203], off
	s_mov_b32 m0, s16
	v_lshl_add_u64 v[202:203], v[206:207], 0, s[86:87]
	global_load_lds_dwordx4 v192, s[12:13]
	s_add_i32 m0, s16, 0x2000
	s_nop 0
	global_load_lds_dwordx4 v190, s[12:13]
	s_mov_b32 m0, s64
	s_nop 0
	global_load_lds_dwordx4 v[202:203], off
	v_lshl_add_u64 v[202:203], v[208:209], 0, s[86:87]
	s_mov_b32 m0, s65
	s_nop 0
	global_load_lds_dwordx4 v[202:203], off
	s_waitcnt vmcnt(8)
	s_waitcnt lgkmcnt(0)
	s_barrier
	s_setprio 1
	v_mfma_f32_16x16x32_bf16 v[68:71], v[132:135], v[164:167], v[68:71]
	v_mfma_f32_16x16x32_bf16 v[68:71], v[136:139], v[168:171], v[68:71]
	v_mfma_f32_16x16x32_bf16 v[72:75], v[144:147], v[168:171], v[72:75]
	v_mfma_f32_16x16x32_bf16 v[72:75], v[140:143], v[164:167], v[72:75]
	v_mfma_f32_16x16x32_bf16 v[80:83], v[140:143], v[172:175], v[80:83]
	v_mfma_f32_16x16x32_bf16 v[80:83], v[144:147], v[176:179], v[80:83]
	v_mfma_f32_16x16x32_bf16 v[76:79], v[136:139], v[176:179], v[76:79]
	v_mfma_f32_16x16x32_bf16 v[76:79], v[132:135], v[172:175], v[76:79]
	v_mfma_f32_16x16x32_bf16 v[84:87], v[132:135], v[180:183], v[84:87]
	v_mfma_f32_16x16x32_bf16 v[84:87], v[136:139], v[184:187], v[84:87]
	v_mfma_f32_16x16x32_bf16 v[88:91], v[144:147], v[184:187], v[88:91]
	v_mfma_f32_16x16x32_bf16 v[88:91], v[140:143], v[180:183], v[88:91]
	v_mfma_f32_16x16x32_bf16 v[96:99], v[140:143], v[194:197], v[96:99]
	v_mfma_f32_16x16x32_bf16 v[96:99], v[144:147], v[198:201], v[96:99]
	v_mfma_f32_16x16x32_bf16 v[92:95], v[136:139], v[198:201], v[92:95]
	v_mfma_f32_16x16x32_bf16 v[92:95], v[132:135], v[194:197], v[92:95]
	v_mfma_f32_16x16x32_bf16 v[100:103], v[148:151], v[164:167], v[100:103]
	v_mfma_f32_16x16x32_bf16 v[100:103], v[152:155], v[168:171], v[100:103]
	v_mfma_f32_16x16x32_bf16 v[104:107], v[160:163], v[168:171], v[104:107]
	v_mfma_f32_16x16x32_bf16 v[104:107], v[156:159], v[164:167], v[104:107]
	v_mfma_f32_16x16x32_bf16 v[112:115], v[156:159], v[172:175], v[112:115]
	v_mfma_f32_16x16x32_bf16 v[112:115], v[160:163], v[176:179], v[112:115]
	v_mfma_f32_16x16x32_bf16 v[108:111], v[152:155], v[176:179], v[108:111]
	v_mfma_f32_16x16x32_bf16 v[108:111], v[148:151], v[172:175], v[108:111]
	v_mfma_f32_16x16x32_bf16 v[116:119], v[148:151], v[180:183], v[116:119]
	v_mfma_f32_16x16x32_bf16 v[116:119], v[152:155], v[184:187], v[116:119]
	v_mfma_f32_16x16x32_bf16 v[120:123], v[160:163], v[184:187], v[120:123]
	v_mfma_f32_16x16x32_bf16 v[120:123], v[156:159], v[180:183], v[120:123]
	v_mfma_f32_16x16x32_bf16 v[128:131], v[156:159], v[194:197], v[128:131]
	v_mfma_f32_16x16x32_bf16 v[128:131], v[160:163], v[198:201], v[128:131]
	s_setprio 2
	s_barrier
	v_mfma_f32_16x16x32_bf16 v[124:127], v[152:155], v[198:201], v[124:127]
	v_mfma_f32_16x16x32_bf16 v[124:127], v[148:151], v[194:197], v[124:127]
	s_setprio 0
	s_add_i32 s28, s28, 2
	s_add_u32 s14, s14, 0x100
	s_addc_u32 s15, s15, 0
	s_add_u32 s26, s26, 0x100
	s_addc_u32 s27, s27, 0
	s_cmp_gt_u32 s28, 29
	s_cbranch_scc0 .LBB0_1629
	s_and_b64 vcc, exec, s[48:49]
	s_cbranch_vccz .LBB0_1632
	s_barrier

.LBB0_2065:
	s_add_i32 s51, 0, 0x10000
	s_add_i32 s71, 0, 0x14000
	v_add_u32_e32 v16, s51, v232
	v_add_u32_e32 v32, s71, v232
	ds_read_b128 v[4:7], v16
	ds_read_b128 v[8:11], v16 offset:1024
	ds_read_b128 v[12:15], v16 offset:2048
	ds_read_b128 v[16:19], v16 offset:3072
	ds_read_b128 v[20:23], v32
	ds_read_b128 v[24:27], v32 offset:1024
	ds_read_b128 v[28:31], v32 offset:2048
	ds_read_b128 v[32:35], v32 offset:3072
	v_add_u32_e32 v233, 0, v231
	ds_read_b128 v[36:39], v233
	ds_read_b128 v[40:43], v233 offset:1024
	ds_read_b128 v[44:47], v233 offset:2048
	ds_read_b128 v[48:51], v233 offset:3072
	ds_read_b128 v[52:55], v233 offset:4096
	ds_read_b128 v[56:59], v233 offset:5120
	ds_read_b128 v[60:63], v233 offset:6144
	ds_read_b128 v[64:67], v233 offset:7168
	s_waitcnt vmcnt(8)
	s_waitcnt lgkmcnt(0)
	s_barrier
	s_setprio 1
	v_mfma_f32_16x16x32_bf16 v[68:71], v[4:7], v[36:39], 0
	v_mfma_f32_16x16x32_bf16 v[68:71], v[8:11], v[40:43], v[68:71]
	v_mfma_f32_16x16x32_bf16 v[72:75], v[12:15], v[36:39], 0
	v_mfma_f32_16x16x32_bf16 v[72:75], v[16:19], v[40:43], v[72:75]
	v_mfma_f32_16x16x32_bf16 v[80:83], v[12:15], v[44:47], 0
	v_mfma_f32_16x16x32_bf16 v[80:83], v[16:19], v[48:51], v[80:83]
	v_mfma_f32_16x16x32_bf16 v[76:79], v[4:7], v[44:47], 0
	v_mfma_f32_16x16x32_bf16 v[76:79], v[8:11], v[48:51], v[76:79]
	v_mfma_f32_16x16x32_bf16 v[84:87], v[4:7], v[52:55], 0
	v_mfma_f32_16x16x32_bf16 v[84:87], v[8:11], v[56:59], v[84:87]
	v_mfma_f32_16x16x32_bf16 v[88:91], v[12:15], v[52:55], 0
	v_mfma_f32_16x16x32_bf16 v[88:91], v[16:19], v[56:59], v[88:91]
	v_mfma_f32_16x16x32_bf16 v[96:99], v[12:15], v[60:63], 0
	v_mfma_f32_16x16x32_bf16 v[96:99], v[16:19], v[64:67], v[96:99]
	v_mfma_f32_16x16x32_bf16 v[92:95], v[4:7], v[60:63], 0
	v_mfma_f32_16x16x32_bf16 v[92:95], v[8:11], v[64:67], v[92:95]
	v_mfma_f32_16x16x32_bf16 v[100:103], v[20:23], v[36:39], 0
	v_mfma_f32_16x16x32_bf16 v[36:39], v[28:31], v[36:39], 0
	v_mfma_f32_16x16x32_bf16 v[104:107], v[20:23], v[44:47], 0
	v_mfma_f32_16x16x32_bf16 v[44:47], v[28:31], v[44:47], 0
	v_mfma_f32_16x16x32_bf16 v[108:111], v[20:23], v[52:55], 0
	v_mfma_f32_16x16x32_bf16 v[52:55], v[28:31], v[52:55], 0
	v_mfma_f32_16x16x32_bf16 v[112:115], v[20:23], v[60:63], 0
	v_mfma_f32_16x16x32_bf16 v[60:63], v[28:31], v[60:63], 0
	v_mfma_f32_16x16x32_bf16 v[100:103], v[24:27], v[40:43], v[100:103]
	v_mfma_f32_16x16x32_bf16 v[40:43], v[32:35], v[40:43], v[36:39]
	v_mfma_f32_16x16x32_bf16 v[104:107], v[24:27], v[48:51], v[104:107]
	v_mfma_f32_16x16x32_bf16 v[48:51], v[32:35], v[48:51], v[44:47]
	v_mfma_f32_16x16x32_bf16 v[108:111], v[24:27], v[56:59], v[108:111]
	v_mfma_f32_16x16x32_bf16 v[56:59], v[32:35], v[56:59], v[52:55]
	s_setprio 2
	s_barrier
	v_mfma_f32_16x16x32_bf16 v[112:115], v[24:27], v[64:67], v[112:115]
	v_mfma_f32_16x16x32_bf16 v[64:67], v[32:35], v[64:67], v[60:63]
	s_setprio 0
	v_lshl_add_u64 v[186:187], s[12:13], 0, v[2:3]
	s_add_i32 s51, s51, s38
	v_mov_b32_e32 v191, v3
	v_lshl_add_u64 v[134:135], v[186:187], 0, s[74:75]
	s_mov_b32 m0, s51
	v_lshl_add_u64 v[246:247], s[12:13], 0, v[190:191]
	ds_read_b128 v[36:39], v233 offset:16384
	ds_read_b128 v[44:47], v233 offset:17408
	ds_read_b128 v[52:55], v233 offset:18432
	ds_read_b128 v[60:63], v233 offset:19456
	ds_read_b128 v[116:119], v233 offset:20480
	ds_read_b128 v[120:123], v233 offset:21504
	ds_read_b128 v[124:127], v233 offset:22528
	ds_read_b128 v[128:131], v233 offset:23552
	global_load_lds_dwordx4 v[134:135], off
	v_lshl_add_u64 v[134:135], v[246:247], 0, s[74:75]
	s_add_i32 m0, s51, 0x2000
	s_add_i32 s51, s71, s38
	global_load_lds_dwordx4 v[134:135], off
	s_mov_b32 m0, s51
	v_mov_b32_e32 v133, v3
	global_load_lds_dwordx4 v2, s[16:17]
	s_add_i32 m0, s51, 0x2000
	v_lshl_add_u64 v[248:249], s[14:15], 0, v[132:133]
	v_mov_b32_e32 v189, v3
	global_load_lds_dwordx4 v190, s[16:17]
	v_lshl_add_u64 v[134:135], v[248:249], 0, s[74:75]
	s_mov_b32 m0, s56
	v_lshl_add_u64 v[250:251], s[14:15], 0, v[188:189]
	global_load_lds_dwordx4 v[134:135], off
	v_lshl_add_u64 v[134:135], v[250:251], 0, s[74:75]
	s_mov_b32 m0, s57
	s_nop 0
	global_load_lds_dwordx4 v[134:135], off
	s_waitcnt vmcnt(8)
	s_waitcnt lgkmcnt(0)
	s_barrier
	s_setprio 1
	v_mfma_f32_16x16x32_bf16 v[134:137], v[4:7], v[36:39], 0
	v_mfma_f32_16x16x32_bf16 v[138:141], v[12:15], v[36:39], 0
	v_mfma_f32_16x16x32_bf16 v[142:145], v[4:7], v[52:55], 0
	v_mfma_f32_16x16x32_bf16 v[146:149], v[12:15], v[52:55], 0
	v_mfma_f32_16x16x32_bf16 v[150:153], v[4:7], v[116:119], 0
	v_mfma_f32_16x16x32_bf16 v[154:157], v[12:15], v[116:119], 0
	v_mfma_f32_16x16x32_bf16 v[4:7], v[4:7], v[124:127], 0
	v_mfma_f32_16x16x32_bf16 v[12:15], v[12:15], v[124:127], 0
	v_mfma_f32_16x16x32_bf16 v[134:137], v[8:11], v[44:47], v[134:137]
	v_mfma_f32_16x16x32_bf16 v[138:141], v[16:19], v[44:47], v[138:141]
	v_mfma_f32_16x16x32_bf16 v[142:145], v[8:11], v[60:63], v[142:145]
	v_mfma_f32_16x16x32_bf16 v[146:149], v[16:19], v[60:63], v[146:149]
	v_mfma_f32_16x16x32_bf16 v[150:153], v[8:11], v[120:123], v[150:153]
	v_mfma_f32_16x16x32_bf16 v[154:157], v[16:19], v[120:123], v[154:157]
	v_mfma_f32_16x16x32_bf16 v[158:161], v[8:11], v[128:131], v[4:7]
	v_mfma_f32_16x16x32_bf16 v[162:165], v[16:19], v[128:131], v[12:15]
	v_mfma_f32_16x16x32_bf16 v[4:7], v[20:23], v[36:39], 0
	v_mfma_f32_16x16x32_bf16 v[8:11], v[28:31], v[36:39], 0
	v_mfma_f32_16x16x32_bf16 v[12:15], v[20:23], v[52:55], 0
	v_mfma_f32_16x16x32_bf16 v[16:19], v[28:31], v[52:55], 0
	v_mfma_f32_16x16x32_bf16 v[36:39], v[20:23], v[116:119], 0
	v_mfma_f32_16x16x32_bf16 v[52:55], v[28:31], v[116:119], 0
	v_mfma_f32_16x16x32_bf16 v[20:23], v[20:23], v[124:127], 0
	v_mfma_f32_16x16x32_bf16 v[28:31], v[28:31], v[124:127], 0
	v_mfma_f32_16x16x32_bf16 v[116:119], v[24:27], v[44:47], v[4:7]
	v_mfma_f32_16x16x32_bf16 v[124:127], v[32:35], v[44:47], v[8:11]
	v_mfma_f32_16x16x32_bf16 v[174:177], v[24:27], v[120:123], v[36:39]
	v_mfma_f32_16x16x32_bf16 v[120:123], v[32:35], v[120:123], v[52:55]
	v_mfma_f32_16x16x32_bf16 v[178:181], v[24:27], v[128:131], v[20:23]
	v_mfma_f32_16x16x32_bf16 v[128:131], v[32:35], v[128:131], v[28:31]
	s_setprio 2
	s_barrier
	v_mfma_f32_16x16x32_bf16 v[166:169], v[24:27], v[60:63], v[12:15]
	v_mfma_f32_16x16x32_bf16 v[170:173], v[32:35], v[60:63], v[16:19]
	s_setprio 0
	s_add_i32 s51, 0, 0x18000
	v_add_u32_e32 v4, s51, v232
	s_add_i32 s71, 0, 0x1c000
	ds_read_b128 v[182:185], v4
	ds_read_b128 v[192:195], v4 offset:1024
	ds_read_b128 v[196:199], v4 offset:2048
	ds_read_b128 v[200:203], v4 offset:3072
	v_add_u32_e32 v4, s71, v232
	ds_read_b128 v[204:207], v4
	ds_read_b128 v[208:211], v4 offset:1024
	ds_read_b128 v[212:215], v4 offset:2048
	ds_read_b128 v[216:219], v4 offset:3072
	s_mov_b32 m0, s58
	ds_read_b128 v[44:47], v233 offset:32768
	ds_read_b128 v[52:55], v233 offset:33792
	ds_read_b128 v[60:63], v233 offset:34816
	ds_read_b128 v[220:223], v233 offset:35840
	ds_read_b128 v[224:227], v233 offset:36864
	ds_read_b128 v[234:237], v233 offset:37888
	ds_read_b128 v[238:241], v233 offset:38912
	ds_read_b128 v[242:245], v233 offset:39936
	global_load_lds_dwordx4 v132, s[26:27]
	s_mov_b32 m0, s59
	s_nop 0
	global_load_lds_dwordx4 v188, s[26:27]
	s_waitcnt vmcnt(8)
	s_waitcnt lgkmcnt(0)
	s_barrier
	s_setprio 1
	v_mfma_f32_16x16x32_bf16 v[4:7], v[182:185], v[44:47], v[68:71]
	v_mfma_f32_16x16x32_bf16 v[8:11], v[196:199], v[44:47], v[72:75]
	v_mfma_f32_16x16x32_bf16 v[12:15], v[182:185], v[60:63], v[76:79]
	v_mfma_f32_16x16x32_bf16 v[16:19], v[196:199], v[60:63], v[80:83]
	v_mfma_f32_16x16x32_bf16 v[20:23], v[182:185], v[224:227], v[84:87]
	v_mfma_f32_16x16x32_bf16 v[24:27], v[196:199], v[224:227], v[88:91]
	v_mfma_f32_16x16x32_bf16 v[28:31], v[182:185], v[238:241], v[92:95]
	v_mfma_f32_16x16x32_bf16 v[32:35], v[196:199], v[238:241], v[96:99]
	v_mfma_f32_16x16x32_bf16 v[4:7], v[192:195], v[52:55], v[4:7]
	v_mfma_f32_16x16x32_bf16 v[8:11], v[200:203], v[52:55], v[8:11]
	v_mfma_f32_16x16x32_bf16 v[12:15], v[192:195], v[220:223], v[12:15]
	v_mfma_f32_16x16x32_bf16 v[16:19], v[200:203], v[220:223], v[16:19]
	v_mfma_f32_16x16x32_bf16 v[20:23], v[192:195], v[234:237], v[20:23]
	v_mfma_f32_16x16x32_bf16 v[24:27], v[200:203], v[234:237], v[24:27]
	v_mfma_f32_16x16x32_bf16 v[28:31], v[192:195], v[242:245], v[28:31]
	v_mfma_f32_16x16x32_bf16 v[32:35], v[200:203], v[242:245], v[32:35]
	v_mfma_f32_16x16x32_bf16 v[36:39], v[204:207], v[44:47], v[100:103]
	v_mfma_f32_16x16x32_bf16 v[40:43], v[212:215], v[44:47], v[40:43]
	v_mfma_f32_16x16x32_bf16 v[36:39], v[208:211], v[52:55], v[36:39]
	v_mfma_f32_16x16x32_bf16 v[40:43], v[216:219], v[52:55], v[40:43]
	v_mfma_f32_16x16x32_bf16 v[44:47], v[204:207], v[60:63], v[104:107]
	v_mfma_f32_16x16x32_bf16 v[48:51], v[212:215], v[60:63], v[48:51]
	v_mfma_f32_16x16x32_bf16 v[52:55], v[204:207], v[224:227], v[108:111]
	v_mfma_f32_16x16x32_bf16 v[56:59], v[212:215], v[224:227], v[56:59]
	v_mfma_f32_16x16x32_bf16 v[60:63], v[204:207], v[238:241], v[112:115]
	v_mfma_f32_16x16x32_bf16 v[64:67], v[212:215], v[238:241], v[64:67]
	v_mfma_f32_16x16x32_bf16 v[44:47], v[208:211], v[220:223], v[44:47]
	v_mfma_f32_16x16x32_bf16 v[48:51], v[216:219], v[220:223], v[48:51]
	v_mfma_f32_16x16x32_bf16 v[52:55], v[208:211], v[234:237], v[52:55]
	v_mfma_f32_16x16x32_bf16 v[56:59], v[216:219], v[234:237], v[56:59]
	s_setprio 2
	s_barrier
	v_mfma_f32_16x16x32_bf16 v[60:63], v[208:211], v[242:245], v[60:63]
	v_mfma_f32_16x16x32_bf16 v[64:67], v[216:219], v[242:245], v[64:67]
	s_setprio 0
	s_add_i32 s51, s51, s38
	v_lshl_add_u64 v[68:69], v[186:187], 0, s[24:25]
	s_mov_b32 m0, s51
	ds_read_b128 v[104:107], v233 offset:49152
	ds_read_b128 v[108:111], v233 offset:50176
	ds_read_b128 v[112:115], v233 offset:51200
	ds_read_b128 v[220:223], v233 offset:52224
	ds_read_b128 v[224:227], v233 offset:53248
	ds_read_b128 v[234:237], v233 offset:54272
	ds_read_b128 v[238:241], v233 offset:55296
	ds_read_b128 v[242:245], v233 offset:56320
	global_load_lds_dwordx4 v[68:69], off
	v_lshl_add_u64 v[68:69], v[246:247], 0, s[24:25]
	s_add_i32 m0, s51, 0x2000
	s_add_i32 s51, s71, s38
	global_load_lds_dwordx4 v[68:69], off
	s_mov_b32 m0, s51
	v_lshl_add_u64 v[68:69], v[248:249], 0, s[24:25]
	global_load_lds_dwordx4 v2, s[28:29]
	s_add_i32 m0, s51, 0x2000
	s_nop 0
	global_load_lds_dwordx4 v190, s[28:29]
	s_mov_b32 m0, s63
	s_nop 0
	global_load_lds_dwordx4 v[68:69], off
	v_lshl_add_u64 v[68:69], v[250:251], 0, s[24:25]
	s_mov_b32 m0, s64
	s_nop 0
	global_load_lds_dwordx4 v[68:69], off
	s_waitcnt vmcnt(8)
	s_waitcnt lgkmcnt(0)
	s_barrier
	s_setprio 1
	v_mfma_f32_16x16x32_bf16 v[68:71], v[182:185], v[104:107], v[134:137]
	v_mfma_f32_16x16x32_bf16 v[72:75], v[196:199], v[104:107], v[138:141]
	v_mfma_f32_16x16x32_bf16 v[76:79], v[182:185], v[112:115], v[142:145]
	v_mfma_f32_16x16x32_bf16 v[80:83], v[196:199], v[112:115], v[146:149]
	v_mfma_f32_16x16x32_bf16 v[84:87], v[182:185], v[224:227], v[150:153]
	v_mfma_f32_16x16x32_bf16 v[88:91], v[196:199], v[224:227], v[154:157]
	v_mfma_f32_16x16x32_bf16 v[92:95], v[182:185], v[238:241], v[158:161]
	v_mfma_f32_16x16x32_bf16 v[96:99], v[196:199], v[238:241], v[162:165]
	v_mfma_f32_16x16x32_bf16 v[68:71], v[192:195], v[108:111], v[68:71]
	v_mfma_f32_16x16x32_bf16 v[72:75], v[200:203], v[108:111], v[72:75]
	v_mfma_f32_16x16x32_bf16 v[76:79], v[192:195], v[220:223], v[76:79]
	v_mfma_f32_16x16x32_bf16 v[80:83], v[200:203], v[220:223], v[80:83]
	v_mfma_f32_16x16x32_bf16 v[84:87], v[192:195], v[234:237], v[84:87]
	v_mfma_f32_16x16x32_bf16 v[88:91], v[200:203], v[234:237], v[88:91]
	v_mfma_f32_16x16x32_bf16 v[92:95], v[192:195], v[242:245], v[92:95]
	v_mfma_f32_16x16x32_bf16 v[96:99], v[200:203], v[242:245], v[96:99]
	v_mfma_f32_16x16x32_bf16 v[100:103], v[204:207], v[104:107], v[116:119]
	v_mfma_f32_16x16x32_bf16 v[104:107], v[212:215], v[104:107], v[124:127]
	v_mfma_f32_16x16x32_bf16 v[100:103], v[208:211], v[108:111], v[100:103]
	v_mfma_f32_16x16x32_bf16 v[104:107], v[216:219], v[108:111], v[104:107]
	v_mfma_f32_16x16x32_bf16 v[108:111], v[204:207], v[112:115], v[166:169]
	v_mfma_f32_16x16x32_bf16 v[112:115], v[212:215], v[112:115], v[170:173]
	v_mfma_f32_16x16x32_bf16 v[116:119], v[204:207], v[224:227], v[174:177]
	v_mfma_f32_16x16x32_bf16 v[120:123], v[212:215], v[224:227], v[120:123]
	v_mfma_f32_16x16x32_bf16 v[124:127], v[204:207], v[238:241], v[178:181]
	v_mfma_f32_16x16x32_bf16 v[128:131], v[212:215], v[238:241], v[128:131]
	v_mfma_f32_16x16x32_bf16 v[108:111], v[208:211], v[220:223], v[108:111]
	v_mfma_f32_16x16x32_bf16 v[112:115], v[216:219], v[220:223], v[112:115]
	v_mfma_f32_16x16x32_bf16 v[116:119], v[208:211], v[234:237], v[116:119]
	v_mfma_f32_16x16x32_bf16 v[120:123], v[216:219], v[234:237], v[120:123]
	s_setprio 2
	s_barrier
	v_mfma_f32_16x16x32_bf16 v[124:127], v[208:211], v[242:245], v[124:127]
	v_mfma_f32_16x16x32_bf16 v[128:131], v[216:219], v[242:245], v[128:131]
	s_setprio 0
	s_add_i32 s45, s45, 2
	s_cmp_ge_i32 s45, s44
	s_cbranch_scc0 .LBB0_2065
	v_mov_b32_e32 v192, v2
	s_branch .LBB0_2068

.LBB0_2069:
	s_add_u32 s12, s14, 0xfff80080
	s_addc_u32 s13, s15, -1
	s_add_i32 s29, 0, 0x10000
	s_cmp_eq_u32 s28, 4
	s_cselect_b32 s17, s9, s13
	s_cselect_b32 s16, s8, s12
	s_cselect_b32 s13, s11, s27
	s_cselect_b32 s12, s10, s26
	s_add_i32 s51, 0, 0x14000
	v_add_u32_e32 v144, s29, v232
	v_add_u32_e32 v160, s51, v232
	s_waitcnt lgkmcnt(0)
	ds_read_b128 v[132:135], v144
	ds_read_b128 v[136:139], v144 offset:1024
	ds_read_b128 v[140:143], v144 offset:2048
	ds_read_b128 v[144:147], v144 offset:3072
	ds_read_b128 v[148:151], v160
	ds_read_b128 v[152:155], v160 offset:1024
	ds_read_b128 v[156:159], v160 offset:2048
	ds_read_b128 v[160:163], v160 offset:3072
	s_mov_b32 m0, s65
	v_add_u32_e32 v210, 0, v231
	ds_read_b128 v[164:167], v210
	ds_read_b128 v[168:171], v210 offset:1024
	ds_read_b128 v[172:175], v210 offset:2048
	ds_read_b128 v[176:179], v210 offset:3072
	ds_read_b128 v[180:183], v210 offset:4096
	ds_read_b128 v[184:187], v210 offset:5120
	ds_read_b128 v[194:197], v210 offset:6144
	ds_read_b128 v[198:201], v210 offset:7168
	global_load_lds_dwordx4 v2, s[14:15]
	s_mov_b32 m0, s66
	v_mov_b32_e32 v189, v3
	global_load_lds_dwordx4 v188, s[14:15]
	s_waitcnt vmcnt(8)
	s_waitcnt lgkmcnt(0)
	s_barrier
	s_setprio 1
	v_mfma_f32_16x16x32_bf16 v[4:7], v[132:135], v[164:167], v[4:7]
	v_mfma_f32_16x16x32_bf16 v[4:7], v[136:139], v[168:171], v[4:7]
	v_mfma_f32_16x16x32_bf16 v[8:11], v[144:147], v[168:171], v[8:11]
	v_mfma_f32_16x16x32_bf16 v[8:11], v[140:143], v[164:167], v[8:11]
	v_mfma_f32_16x16x32_bf16 v[16:19], v[140:143], v[172:175], v[16:19]
	v_mfma_f32_16x16x32_bf16 v[16:19], v[144:147], v[176:179], v[16:19]
	v_mfma_f32_16x16x32_bf16 v[12:15], v[136:139], v[176:179], v[12:15]
	v_mfma_f32_16x16x32_bf16 v[12:15], v[132:135], v[172:175], v[12:15]
	v_mfma_f32_16x16x32_bf16 v[20:23], v[132:135], v[180:183], v[20:23]
	v_mfma_f32_16x16x32_bf16 v[20:23], v[136:139], v[184:187], v[20:23]
	v_mfma_f32_16x16x32_bf16 v[24:27], v[144:147], v[184:187], v[24:27]
	v_mfma_f32_16x16x32_bf16 v[24:27], v[140:143], v[180:183], v[24:27]
	v_mfma_f32_16x16x32_bf16 v[32:35], v[140:143], v[194:197], v[32:35]
	v_mfma_f32_16x16x32_bf16 v[32:35], v[144:147], v[198:201], v[32:35]
	v_mfma_f32_16x16x32_bf16 v[28:31], v[136:139], v[198:201], v[28:31]
	v_mfma_f32_16x16x32_bf16 v[28:31], v[132:135], v[194:197], v[28:31]
	v_mfma_f32_16x16x32_bf16 v[36:39], v[148:151], v[164:167], v[36:39]
	v_mfma_f32_16x16x32_bf16 v[36:39], v[152:155], v[168:171], v[36:39]
	v_mfma_f32_16x16x32_bf16 v[40:43], v[160:163], v[168:171], v[40:43]
	v_mfma_f32_16x16x32_bf16 v[40:43], v[156:159], v[164:167], v[40:43]
	v_mfma_f32_16x16x32_bf16 v[48:51], v[156:159], v[172:175], v[48:51]
	v_mfma_f32_16x16x32_bf16 v[48:51], v[160:163], v[176:179], v[48:51]
	v_mfma_f32_16x16x32_bf16 v[44:47], v[152:155], v[176:179], v[44:47]
	v_mfma_f32_16x16x32_bf16 v[44:47], v[148:151], v[172:175], v[44:47]
	v_mfma_f32_16x16x32_bf16 v[52:55], v[148:151], v[180:183], v[52:55]
	v_mfma_f32_16x16x32_bf16 v[52:55], v[152:155], v[184:187], v[52:55]
	v_mfma_f32_16x16x32_bf16 v[56:59], v[160:163], v[184:187], v[56:59]
	v_mfma_f32_16x16x32_bf16 v[56:59], v[156:159], v[180:183], v[56:59]
	v_mfma_f32_16x16x32_bf16 v[64:67], v[156:159], v[194:197], v[64:67]
	v_mfma_f32_16x16x32_bf16 v[64:67], v[160:163], v[198:201], v[64:67]
	s_setprio 2
	s_barrier
	v_mfma_f32_16x16x32_bf16 v[60:63], v[152:155], v[198:201], v[60:63]
	v_mfma_f32_16x16x32_bf16 v[60:63], v[148:151], v[194:197], v[60:63]
	s_setprio 0
	s_add_i32 s29, s29, s38
	s_mov_b32 m0, s29
	ds_read_b128 v[164:167], v210 offset:16384
	ds_read_b128 v[168:171], v210 offset:17408
	ds_read_b128 v[172:175], v210 offset:18432
	ds_read_b128 v[176:179], v210 offset:19456
	ds_read_b128 v[180:183], v210 offset:20480
	ds_read_b128 v[184:187], v210 offset:21504
	ds_read_b128 v[194:197], v210 offset:22528
	ds_read_b128 v[198:201], v210 offset:23552
	global_load_lds_dwordx4 v192, s[12:13]
	s_add_i32 m0, s29, 0x2000
	s_add_u32 s44, s12, 0x20000
	s_addc_u32 s45, s13, 0
	s_add_i32 s29, s51, s38
	global_load_lds_dwordx4 v190, s[12:13]
	s_mov_b32 m0, s29
	v_mov_b32_e32 v193, v3
	global_load_lds_dwordx4 v192, s[44:45]
	s_add_i32 m0, s29, 0x2000
	v_mov_b32_e32 v191, v3
	global_load_lds_dwordx4 v190, s[44:45]
	s_mov_b32 m0, s56
	v_lshl_add_u64 v[202:203], s[12:13], 0, v[192:193]
	global_load_lds_dwordx4 v2, s[16:17]
	s_mov_b32 m0, s57
	v_lshl_add_u64 v[204:205], s[12:13], 0, v[190:191]
	global_load_lds_dwordx4 v188, s[16:17]
	s_waitcnt vmcnt(8)
	s_waitcnt lgkmcnt(0)
	v_lshl_add_u64 v[206:207], s[16:17], 0, v[2:3]
	v_lshl_add_u64 v[208:209], s[16:17], 0, v[188:189]
	s_barrier
	s_setprio 1
	v_mfma_f32_16x16x32_bf16 v[68:71], v[132:135], v[164:167], v[68:71]
	v_mfma_f32_16x16x32_bf16 v[68:71], v[136:139], v[168:171], v[68:71]
	v_mfma_f32_16x16x32_bf16 v[72:75], v[144:147], v[168:171], v[72:75]
	v_mfma_f32_16x16x32_bf16 v[72:75], v[140:143], v[164:167], v[72:75]
	v_mfma_f32_16x16x32_bf16 v[80:83], v[140:143], v[172:175], v[80:83]
	v_mfma_f32_16x16x32_bf16 v[80:83], v[144:147], v[176:179], v[80:83]
	v_mfma_f32_16x16x32_bf16 v[76:79], v[136:139], v[176:179], v[76:79]
	v_mfma_f32_16x16x32_bf16 v[76:79], v[132:135], v[172:175], v[76:79]
	v_mfma_f32_16x16x32_bf16 v[84:87], v[132:135], v[180:183], v[84:87]
	v_mfma_f32_16x16x32_bf16 v[84:87], v[136:139], v[184:187], v[84:87]
	v_mfma_f32_16x16x32_bf16 v[88:91], v[144:147], v[184:187], v[88:91]
	v_mfma_f32_16x16x32_bf16 v[88:91], v[140:143], v[180:183], v[88:91]
	v_mfma_f32_16x16x32_bf16 v[96:99], v[140:143], v[194:197], v[96:99]
	v_mfma_f32_16x16x32_bf16 v[96:99], v[144:147], v[198:201], v[96:99]
	v_mfma_f32_16x16x32_bf16 v[92:95], v[136:139], v[198:201], v[92:95]
	v_mfma_f32_16x16x32_bf16 v[92:95], v[132:135], v[194:197], v[92:95]
	v_mfma_f32_16x16x32_bf16 v[100:103], v[148:151], v[164:167], v[100:103]
	v_mfma_f32_16x16x32_bf16 v[100:103], v[152:155], v[168:171], v[100:103]
	v_mfma_f32_16x16x32_bf16 v[104:107], v[160:163], v[168:171], v[104:107]
	v_mfma_f32_16x16x32_bf16 v[104:107], v[156:159], v[164:167], v[104:107]
	v_mfma_f32_16x16x32_bf16 v[112:115], v[156:159], v[172:175], v[112:115]
	v_mfma_f32_16x16x32_bf16 v[112:115], v[160:163], v[176:179], v[112:115]
	v_mfma_f32_16x16x32_bf16 v[108:111], v[152:155], v[176:179], v[108:111]
	v_mfma_f32_16x16x32_bf16 v[108:111], v[148:151], v[172:175], v[108:111]
	v_mfma_f32_16x16x32_bf16 v[116:119], v[148:151], v[180:183], v[116:119]
	v_mfma_f32_16x16x32_bf16 v[116:119], v[152:155], v[184:187], v[116:119]
	v_mfma_f32_16x16x32_bf16 v[120:123], v[160:163], v[184:187], v[120:123]
	v_mfma_f32_16x16x32_bf16 v[120:123], v[156:159], v[180:183], v[120:123]
	v_mfma_f32_16x16x32_bf16 v[128:131], v[156:159], v[194:197], v[128:131]
	v_mfma_f32_16x16x32_bf16 v[128:131], v[160:163], v[198:201], v[128:131]
	s_setprio 2
	s_barrier
	v_mfma_f32_16x16x32_bf16 v[124:127], v[152:155], v[198:201], v[124:127]
	v_mfma_f32_16x16x32_bf16 v[124:127], v[148:151], v[194:197], v[124:127]
	s_setprio 0
	s_add_i32 s29, 0, 0x18000
	s_add_i32 s44, 0, 0x1c000
	v_add_u32_e32 v144, s29, v232
	v_add_u32_e32 v160, s44, v232
	ds_read_b128 v[132:135], v144
	ds_read_b128 v[136:139], v144 offset:1024
	ds_read_b128 v[140:143], v144 offset:2048
	ds_read_b128 v[144:147], v144 offset:3072
	ds_read_b128 v[148:151], v160
	ds_read_b128 v[152:155], v160 offset:1024
	ds_read_b128 v[156:159], v160 offset:2048
	ds_read_b128 v[160:163], v160 offset:3072
	s_add_u32 s16, s16, 0x80000
	s_addc_u32 s17, s17, 0
	s_mov_b32 m0, s58
	ds_read_b128 v[164:167], v210 offset:32768
	ds_read_b128 v[168:171], v210 offset:33792
	ds_read_b128 v[172:175], v210 offset:34816
	ds_read_b128 v[176:179], v210 offset:35840
	ds_read_b128 v[180:183], v210 offset:36864
	ds_read_b128 v[184:187], v210 offset:37888
	ds_read_b128 v[194:197], v210 offset:38912
	ds_read_b128 v[198:201], v210 offset:39936
	global_load_lds_dwordx4 v2, s[16:17]
	s_mov_b32 m0, s59
	s_nop 0
	global_load_lds_dwordx4 v188, s[16:17]
	s_waitcnt vmcnt(8)
	s_waitcnt lgkmcnt(0)
	s_barrier
	s_setprio 1
	v_mfma_f32_16x16x32_bf16 v[4:7], v[132:135], v[164:167], v[4:7]
	v_mfma_f32_16x16x32_bf16 v[4:7], v[136:139], v[168:171], v[4:7]
	v_mfma_f32_16x16x32_bf16 v[8:11], v[144:147], v[168:171], v[8:11]
	v_mfma_f32_16x16x32_bf16 v[8:11], v[140:143], v[164:167], v[8:11]
	v_mfma_f32_16x16x32_bf16 v[16:19], v[140:143], v[172:175], v[16:19]
	v_mfma_f32_16x16x32_bf16 v[16:19], v[144:147], v[176:179], v[16:19]
	v_mfma_f32_16x16x32_bf16 v[12:15], v[136:139], v[176:179], v[12:15]
	v_mfma_f32_16x16x32_bf16 v[12:15], v[132:135], v[172:175], v[12:15]
	v_mfma_f32_16x16x32_bf16 v[20:23], v[132:135], v[180:183], v[20:23]
	v_mfma_f32_16x16x32_bf16 v[20:23], v[136:139], v[184:187], v[20:23]
	v_mfma_f32_16x16x32_bf16 v[24:27], v[144:147], v[184:187], v[24:27]
	v_mfma_f32_16x16x32_bf16 v[24:27], v[140:143], v[180:183], v[24:27]
	v_mfma_f32_16x16x32_bf16 v[32:35], v[140:143], v[194:197], v[32:35]
	v_mfma_f32_16x16x32_bf16 v[32:35], v[144:147], v[198:201], v[32:35]
	v_mfma_f32_16x16x32_bf16 v[28:31], v[136:139], v[198:201], v[28:31]
	v_mfma_f32_16x16x32_bf16 v[28:31], v[132:135], v[194:197], v[28:31]
	v_mfma_f32_16x16x32_bf16 v[36:39], v[148:151], v[164:167], v[36:39]
	v_mfma_f32_16x16x32_bf16 v[36:39], v[152:155], v[168:171], v[36:39]
	v_mfma_f32_16x16x32_bf16 v[40:43], v[160:163], v[168:171], v[40:43]
	v_mfma_f32_16x16x32_bf16 v[40:43], v[156:159], v[164:167], v[40:43]
	v_mfma_f32_16x16x32_bf16 v[48:51], v[156:159], v[172:175], v[48:51]
	v_mfma_f32_16x16x32_bf16 v[48:51], v[160:163], v[176:179], v[48:51]
	v_mfma_f32_16x16x32_bf16 v[44:47], v[152:155], v[176:179], v[44:47]
	v_mfma_f32_16x16x32_bf16 v[44:47], v[148:151], v[172:175], v[44:47]
	v_mfma_f32_16x16x32_bf16 v[52:55], v[148:151], v[180:183], v[52:55]
	v_mfma_f32_16x16x32_bf16 v[52:55], v[152:155], v[184:187], v[52:55]
	v_mfma_f32_16x16x32_bf16 v[56:59], v[160:163], v[184:187], v[56:59]
	v_mfma_f32_16x16x32_bf16 v[56:59], v[156:159], v[180:183], v[56:59]
	v_mfma_f32_16x16x32_bf16 v[64:67], v[156:159], v[194:197], v[64:67]
	v_mfma_f32_16x16x32_bf16 v[64:67], v[160:163], v[198:201], v[64:67]
	s_setprio 2
	s_barrier
	v_mfma_f32_16x16x32_bf16 v[60:63], v[152:155], v[198:201], v[60:63]
	v_mfma_f32_16x16x32_bf16 v[60:63], v[148:151], v[194:197], v[60:63]
	s_setprio 0
	s_add_i32 s16, s29, s38
	v_lshl_add_u64 v[202:203], v[202:203], 0, s[86:87]
	s_mov_b32 m0, s16
	ds_read_b128 v[164:167], v210 offset:49152
	ds_read_b128 v[168:171], v210 offset:50176
	ds_read_b128 v[172:175], v210 offset:51200
	ds_read_b128 v[176:179], v210 offset:52224
	ds_read_b128 v[180:183], v210 offset:53248
	ds_read_b128 v[184:187], v210 offset:54272
	ds_read_b128 v[194:197], v210 offset:55296
	ds_read_b128 v[198:201], v210 offset:56320
	global_load_lds_dwordx4 v[202:203], off
	s_add_i32 m0, s16, 0x2000
	s_add_u32 s12, s12, 0x20080
	v_lshl_add_u64 v[202:203], v[204:205], 0, s[86:87]
	s_addc_u32 s13, s13, 0
	s_add_i32 s16, s44, s38
	global_load_lds_dwordx4 v[202:203], off
	s_mov_b32 m0, s16
	v_lshl_add_u64 v[202:203], v[206:207], 0, s[86:87]
	global_load_lds_dwordx4 v192, s[12:13]
	s_add_i32 m0, s16, 0x2000
	s_nop 0
	global_load_lds_dwordx4 v190, s[12:13]
	s_mov_b32 m0, s63
	s_nop 0
	global_load_lds_dwordx4 v[202:203], off
	v_lshl_add_u64 v[202:203], v[208:209], 0, s[86:87]
	s_mov_b32 m0, s64
	s_nop 0
	global_load_lds_dwordx4 v[202:203], off
	s_waitcnt vmcnt(8)
	s_waitcnt lgkmcnt(0)
	s_barrier
	s_setprio 1
	v_mfma_f32_16x16x32_bf16 v[68:71], v[132:135], v[164:167], v[68:71]
	v_mfma_f32_16x16x32_bf16 v[68:71], v[136:139], v[168:171], v[68:71]
	v_mfma_f32_16x16x32_bf16 v[72:75], v[144:147], v[168:171], v[72:75]
	v_mfma_f32_16x16x32_bf16 v[72:75], v[140:143], v[164:167], v[72:75]
	v_mfma_f32_16x16x32_bf16 v[80:83], v[140:143], v[172:175], v[80:83]
	v_mfma_f32_16x16x32_bf16 v[80:83], v[144:147], v[176:179], v[80:83]
	v_mfma_f32_16x16x32_bf16 v[76:79], v[136:139], v[176:179], v[76:79]
	v_mfma_f32_16x16x32_bf16 v[76:79], v[132:135], v[172:175], v[76:79]
	v_mfma_f32_16x16x32_bf16 v[84:87], v[132:135], v[180:183], v[84:87]
	v_mfma_f32_16x16x32_bf16 v[84:87], v[136:139], v[184:187], v[84:87]
	v_mfma_f32_16x16x32_bf16 v[88:91], v[144:147], v[184:187], v[88:91]
	v_mfma_f32_16x16x32_bf16 v[88:91], v[140:143], v[180:183], v[88:91]
	v_mfma_f32_16x16x32_bf16 v[96:99], v[140:143], v[194:197], v[96:99]
	v_mfma_f32_16x16x32_bf16 v[96:99], v[144:147], v[198:201], v[96:99]
	v_mfma_f32_16x16x32_bf16 v[92:95], v[136:139], v[198:201], v[92:95]
	v_mfma_f32_16x16x32_bf16 v[92:95], v[132:135], v[194:197], v[92:95]
	v_mfma_f32_16x16x32_bf16 v[100:103], v[148:151], v[164:167], v[100:103]
	v_mfma_f32_16x16x32_bf16 v[100:103], v[152:155], v[168:171], v[100:103]
	v_mfma_f32_16x16x32_bf16 v[104:107], v[160:163], v[168:171], v[104:107]
	v_mfma_f32_16x16x32_bf16 v[104:107], v[156:159], v[164:167], v[104:107]
	v_mfma_f32_16x16x32_bf16 v[112:115], v[156:159], v[172:175], v[112:115]
	v_mfma_f32_16x16x32_bf16 v[112:115], v[160:163], v[176:179], v[112:115]
	v_mfma_f32_16x16x32_bf16 v[108:111], v[152:155], v[176:179], v[108:111]
	v_mfma_f32_16x16x32_bf16 v[108:111], v[148:151], v[172:175], v[108:111]
	v_mfma_f32_16x16x32_bf16 v[116:119], v[148:151], v[180:183], v[116:119]
	v_mfma_f32_16x16x32_bf16 v[116:119], v[152:155], v[184:187], v[116:119]
	v_mfma_f32_16x16x32_bf16 v[120:123], v[160:163], v[184:187], v[120:123]
	v_mfma_f32_16x16x32_bf16 v[120:123], v[156:159], v[180:183], v[120:123]
	v_mfma_f32_16x16x32_bf16 v[128:131], v[156:159], v[194:197], v[128:131]
	v_mfma_f32_16x16x32_bf16 v[128:131], v[160:163], v[198:201], v[128:131]
	s_setprio 2
	s_barrier
	v_mfma_f32_16x16x32_bf16 v[124:127], v[152:155], v[198:201], v[124:127]
	v_mfma_f32_16x16x32_bf16 v[124:127], v[148:151], v[194:197], v[124:127]
	s_setprio 0
	s_add_i32 s28, s28, 2
	s_add_u32 s14, s14, 0x100
	s_addc_u32 s15, s15, 0
	s_add_u32 s26, s26, 0x100
	s_addc_u32 s27, s27, 0
	s_cmp_gt_u32 s28, 5
	s_cbranch_scc0 .LBB0_2069
	s_and_b64 vcc, exec, s[48:49]
	s_cbranch_vccz .LBB0_2072
	s_barrier

.LBB0_2159:
	s_add_i32 s68, 0, 0x10000
	s_add_i32 s69, 0, 0x14000
	v_add_u32_e32 v16, s68, v143
	v_add_u32_e32 v32, s69, v143
	ds_read_b128 v[4:7], v16
	ds_read_b128 v[8:11], v16 offset:1024
	ds_read_b128 v[12:15], v16 offset:2048
	ds_read_b128 v[16:19], v16 offset:3072
	ds_read_b128 v[20:23], v32
	ds_read_b128 v[24:27], v32 offset:1024
	ds_read_b128 v[28:31], v32 offset:2048
	ds_read_b128 v[32:35], v32 offset:3072
	v_add_u32_e32 v231, 0, v142
	ds_read_b128 v[36:39], v231
	ds_read_b128 v[40:43], v231 offset:1024
	ds_read_b128 v[44:47], v231 offset:2048
	ds_read_b128 v[48:51], v231 offset:3072
	ds_read_b128 v[52:55], v231 offset:4096
	ds_read_b128 v[56:59], v231 offset:5120
	ds_read_b128 v[60:63], v231 offset:6144
	ds_read_b128 v[64:67], v231 offset:7168
	s_waitcnt vmcnt(8)
	s_waitcnt lgkmcnt(0)
	s_barrier
	s_setprio 1
	v_mfma_f32_16x16x32_f16 v[68:71], v[4:7], v[36:39], 0
	v_mfma_f32_16x16x32_f16 v[72:75], v[12:15], v[36:39], 0
	v_mfma_f32_16x16x32_f16 v[76:79], v[4:7], v[44:47], 0
	v_mfma_f32_16x16x32_f16 v[80:83], v[12:15], v[44:47], 0
	v_mfma_f32_16x16x32_f16 v[84:87], v[4:7], v[52:55], 0
	v_mfma_f32_16x16x32_f16 v[88:91], v[12:15], v[52:55], 0
	v_mfma_f32_16x16x32_f16 v[92:95], v[4:7], v[60:63], 0
	v_mfma_f32_16x16x32_f16 v[96:99], v[12:15], v[60:63], 0
	v_mfma_f32_16x16x32_f16 v[68:71], v[8:11], v[40:43], v[68:71]
	v_mfma_f32_16x16x32_f16 v[72:75], v[16:19], v[40:43], v[72:75]
	v_mfma_f32_16x16x32_f16 v[76:79], v[8:11], v[48:51], v[76:79]
	v_mfma_f32_16x16x32_f16 v[80:83], v[16:19], v[48:51], v[80:83]
	v_mfma_f32_16x16x32_f16 v[84:87], v[8:11], v[56:59], v[84:87]
	v_mfma_f32_16x16x32_f16 v[88:91], v[16:19], v[56:59], v[88:91]
	v_mfma_f32_16x16x32_f16 v[92:95], v[8:11], v[64:67], v[92:95]
	v_mfma_f32_16x16x32_f16 v[100:103], v[16:19], v[64:67], v[96:99]
	v_mfma_f32_16x16x32_f16 v[96:99], v[20:23], v[36:39], 0
	v_mfma_f32_16x16x32_f16 v[36:39], v[28:31], v[36:39], 0
	v_mfma_f32_16x16x32_f16 v[104:107], v[20:23], v[44:47], 0
	v_mfma_f32_16x16x32_f16 v[44:47], v[28:31], v[44:47], 0
	v_mfma_f32_16x16x32_f16 v[108:111], v[20:23], v[52:55], 0
	v_mfma_f32_16x16x32_f16 v[52:55], v[28:31], v[52:55], 0
	v_mfma_f32_16x16x32_f16 v[112:115], v[20:23], v[60:63], 0
	v_mfma_f32_16x16x32_f16 v[60:63], v[28:31], v[60:63], 0
	v_mfma_f32_16x16x32_f16 v[116:119], v[24:27], v[40:43], v[96:99]
	v_mfma_f32_16x16x32_f16 v[36:39], v[32:35], v[40:43], v[36:39]
	v_mfma_f32_16x16x32_f16 v[40:43], v[24:27], v[48:51], v[104:107]
	v_mfma_f32_16x16x32_f16 v[44:47], v[32:35], v[48:51], v[44:47]
	v_mfma_f32_16x16x32_f16 v[48:51], v[24:27], v[56:59], v[108:111]
	v_mfma_f32_16x16x32_f16 v[52:55], v[32:35], v[56:59], v[52:55]
	s_setprio 2
	s_barrier
	v_mfma_f32_16x16x32_f16 v[56:59], v[24:27], v[64:67], v[112:115]
	v_mfma_f32_16x16x32_f16 v[60:63], v[32:35], v[64:67], v[60:63]
	s_setprio 0
	v_lshl_add_u64 v[138:139], s[8:9], 0, v[2:3]
	s_add_i32 s68, s68, s53
	v_mov_b32_e32 v135, v3
	v_lshl_add_u64 v[144:145], v[138:139], 0, s[74:75]
	s_mov_b32 m0, s68
	v_lshl_add_u64 v[192:193], s[8:9], 0, v[134:135]
	ds_read_b128 v[64:67], v231 offset:16384
	ds_read_b128 v[96:99], v231 offset:17408
	ds_read_b128 v[104:107], v231 offset:18432
	ds_read_b128 v[108:111], v231 offset:19456
	ds_read_b128 v[112:115], v231 offset:20480
	ds_read_b128 v[120:123], v231 offset:21504
	ds_read_b128 v[124:127], v231 offset:22528
	ds_read_b128 v[128:131], v231 offset:23552
	global_load_lds_dwordx4 v[144:145], off
	v_lshl_add_u64 v[144:145], v[192:193], 0, s[74:75]
	s_add_i32 m0, s68, 0x2000
	s_add_i32 s68, s69, s53
	global_load_lds_dwordx4 v[144:145], off
	s_mov_b32 m0, s68
	v_mov_b32_e32 v137, v3
	global_load_lds_dwordx4 v2, s[40:41]
	s_add_i32 m0, s68, 0x2000
	v_lshl_add_u64 v[248:249], s[6:7], 0, v[136:137]
	v_mov_b32_e32 v133, v3
	global_load_lds_dwordx4 v134, s[40:41]
	v_lshl_add_u64 v[144:145], v[248:249], 0, s[74:75]
	s_mov_b32 m0, s54
	v_lshl_add_u64 v[250:251], s[6:7], 0, v[132:133]
	global_load_lds_dwordx4 v[144:145], off
	v_lshl_add_u64 v[144:145], v[250:251], 0, s[74:75]
	s_mov_b32 m0, s55
	s_nop 0
	global_load_lds_dwordx4 v[144:145], off
	s_waitcnt vmcnt(8)
	s_waitcnt lgkmcnt(0)
	s_barrier
	s_setprio 1
	v_mfma_f32_16x16x32_f16 v[144:147], v[4:7], v[64:67], 0
	v_mfma_f32_16x16x32_f16 v[148:151], v[12:15], v[64:67], 0
	v_mfma_f32_16x16x32_f16 v[152:155], v[4:7], v[104:107], 0
	v_mfma_f32_16x16x32_f16 v[156:159], v[12:15], v[104:107], 0
	v_mfma_f32_16x16x32_f16 v[160:163], v[4:7], v[112:115], 0
	v_mfma_f32_16x16x32_f16 v[164:167], v[12:15], v[112:115], 0
	v_mfma_f32_16x16x32_f16 v[4:7], v[4:7], v[124:127], 0
	v_mfma_f32_16x16x32_f16 v[12:15], v[12:15], v[124:127], 0
	v_mfma_f32_16x16x32_f16 v[144:147], v[8:11], v[96:99], v[144:147]
	v_mfma_f32_16x16x32_f16 v[152:155], v[8:11], v[108:111], v[152:155]
	v_mfma_f32_16x16x32_f16 v[160:163], v[8:11], v[120:123], v[160:163]
	v_mfma_f32_16x16x32_f16 v[4:7], v[8:11], v[128:131], v[4:7]
	v_mfma_f32_16x16x32_f16 v[8:11], v[16:19], v[128:131], v[12:15]
	v_mfma_f32_16x16x32_f16 v[148:151], v[16:19], v[96:99], v[148:151]
	v_mfma_f32_16x16x32_f16 v[156:159], v[16:19], v[108:111], v[156:159]
	v_mfma_f32_16x16x32_f16 v[164:167], v[16:19], v[120:123], v[164:167]
	v_mfma_f32_16x16x32_f16 v[12:15], v[20:23], v[64:67], 0
	v_mfma_f32_16x16x32_f16 v[16:19], v[28:31], v[64:67], 0
	v_mfma_f32_16x16x32_f16 v[64:67], v[20:23], v[104:107], 0
	v_mfma_f32_16x16x32_f16 v[104:107], v[28:31], v[104:107], 0
	v_mfma_f32_16x16x32_f16 v[168:171], v[20:23], v[112:115], 0
	v_mfma_f32_16x16x32_f16 v[112:115], v[28:31], v[112:115], 0
	v_mfma_f32_16x16x32_f16 v[20:23], v[20:23], v[124:127], 0
	v_mfma_f32_16x16x32_f16 v[28:31], v[28:31], v[124:127], 0
	v_mfma_f32_16x16x32_f16 v[12:15], v[24:27], v[96:99], v[12:15]
	v_mfma_f32_16x16x32_f16 v[172:175], v[32:35], v[96:99], v[16:19]
	v_mfma_f32_16x16x32_f16 v[176:179], v[24:27], v[108:111], v[64:67]
	v_mfma_f32_16x16x32_f16 v[180:183], v[32:35], v[108:111], v[104:107]
	v_mfma_f32_16x16x32_f16 v[168:171], v[24:27], v[120:123], v[168:171]
	v_mfma_f32_16x16x32_f16 v[184:187], v[32:35], v[120:123], v[112:115]
	s_setprio 2
	s_barrier
	v_mfma_f32_16x16x32_f16 v[188:191], v[24:27], v[128:131], v[20:23]
	v_mfma_f32_16x16x32_f16 v[196:199], v[32:35], v[128:131], v[28:31]
	s_setprio 0
	s_add_i32 s68, 0, 0x18000
	v_add_u32_e32 v24, s68, v143
	s_add_i32 s69, 0, 0x1c000
	ds_read_b128 v[16:19], v24
	ds_read_b128 v[20:23], v24 offset:1024
	ds_read_b128 v[28:31], v24 offset:2048
	ds_read_b128 v[200:203], v24 offset:3072
	v_add_u32_e32 v24, s69, v143
	ds_read_b128 v[204:207], v24
	ds_read_b128 v[208:211], v24 offset:1024
	ds_read_b128 v[212:215], v24 offset:2048
	ds_read_b128 v[216:219], v24 offset:3072
	s_mov_b32 m0, s56
	ds_read_b128 v[24:27], v231 offset:32768
	ds_read_b128 v[32:35], v231 offset:33792
	ds_read_b128 v[64:67], v231 offset:34816
	ds_read_b128 v[220:223], v231 offset:35840
	ds_read_b128 v[224:227], v231 offset:36864
	ds_read_b128 v[232:235], v231 offset:37888
	ds_read_b128 v[236:239], v231 offset:38912
	ds_read_b128 v[240:243], v231 offset:39936
	global_load_lds_dwordx4 v136, s[42:43]
	s_mov_b32 m0, s57
	s_nop 0
	global_load_lds_dwordx4 v132, s[42:43]
	s_waitcnt vmcnt(8)
	s_waitcnt lgkmcnt(0)
	s_barrier
	s_setprio 1
	v_mfma_f32_16x16x32_f16 v[68:71], v[16:19], v[24:27], v[68:71]
	v_mfma_f32_16x16x32_f16 v[128:131], v[20:23], v[32:35], v[68:71]
	v_mfma_f32_16x16x32_f16 v[68:71], v[28:31], v[24:27], v[72:75]
	v_mfma_f32_16x16x32_f16 v[120:123], v[200:203], v[32:35], v[68:71]
	v_mfma_f32_16x16x32_f16 v[68:71], v[16:19], v[64:67], v[76:79]
	v_mfma_f32_16x16x32_f16 v[112:115], v[20:23], v[220:223], v[68:71]
	v_mfma_f32_16x16x32_f16 v[68:71], v[28:31], v[64:67], v[80:83]
	v_mfma_f32_16x16x32_f16 v[104:107], v[200:203], v[220:223], v[68:71]
	v_mfma_f32_16x16x32_f16 v[68:71], v[16:19], v[224:227], v[84:87]
	v_mfma_f32_16x16x32_f16 v[96:99], v[20:23], v[232:235], v[68:71]
	v_mfma_f32_16x16x32_f16 v[68:71], v[28:31], v[224:227], v[88:91]
	v_mfma_f32_16x16x32_f16 v[88:91], v[200:203], v[232:235], v[68:71]
	v_mfma_f32_16x16x32_f16 v[68:71], v[16:19], v[236:239], v[92:95]
	v_mfma_f32_16x16x32_f16 v[80:83], v[20:23], v[240:243], v[68:71]
	v_mfma_f32_16x16x32_f16 v[68:71], v[28:31], v[236:239], v[100:103]
	v_mfma_f32_16x16x32_f16 v[72:75], v[200:203], v[240:243], v[68:71]
	v_mfma_f32_16x16x32_f16 v[68:71], v[204:207], v[24:27], v[116:119]
	v_mfma_f32_16x16x32_f16 v[24:27], v[212:215], v[24:27], v[36:39]
	v_mfma_f32_16x16x32_f16 v[116:119], v[216:219], v[32:35], v[24:27]
	v_mfma_f32_16x16x32_f16 v[24:27], v[204:207], v[64:67], v[40:43]
	v_mfma_f32_16x16x32_f16 v[108:111], v[208:211], v[220:223], v[24:27]
	v_mfma_f32_16x16x32_f16 v[24:27], v[212:215], v[64:67], v[44:47]
	v_mfma_f32_16x16x32_f16 v[100:103], v[216:219], v[220:223], v[24:27]
	v_mfma_f32_16x16x32_f16 v[24:27], v[204:207], v[224:227], v[48:51]
	v_mfma_f32_16x16x32_f16 v[92:95], v[208:211], v[232:235], v[24:27]
	v_mfma_f32_16x16x32_f16 v[24:27], v[212:215], v[224:227], v[52:55]
	v_mfma_f32_16x16x32_f16 v[84:87], v[216:219], v[232:235], v[24:27]
	v_mfma_f32_16x16x32_f16 v[24:27], v[204:207], v[236:239], v[56:59]
	v_mfma_f32_16x16x32_f16 v[76:79], v[208:211], v[240:243], v[24:27]
	v_mfma_f32_16x16x32_f16 v[24:27], v[212:215], v[236:239], v[60:63]
	s_setprio 2
	s_barrier
	v_mfma_f32_16x16x32_f16 v[124:127], v[208:211], v[32:35], v[68:71]
	v_mfma_f32_16x16x32_f16 v[68:71], v[216:219], v[240:243], v[24:27]
	s_setprio 0
	s_add_i32 s68, s68, s53
	s_nop 2
	v_lshl_add_u64 v[24:25], v[138:139], 0, s[24:25]
	s_mov_b32 m0, s68
	ds_read_b128 v[36:39], v231 offset:49152
	ds_read_b128 v[44:47], v231 offset:50176
	ds_read_b128 v[220:223], v231 offset:51200
	ds_read_b128 v[224:227], v231 offset:52224
	ds_read_b128 v[232:235], v231 offset:53248
	ds_read_b128 v[236:239], v231 offset:54272
	ds_read_b128 v[240:243], v231 offset:55296
	ds_read_b128 v[244:247], v231 offset:56320
	global_load_lds_dwordx4 v[24:25], off
	v_lshl_add_u64 v[24:25], v[192:193], 0, s[24:25]
	s_add_i32 m0, s68, 0x2000
	s_add_i32 s68, s69, s53
	global_load_lds_dwordx4 v[24:25], off
	s_mov_b32 m0, s68
	v_lshl_add_u64 v[24:25], v[248:249], 0, s[24:25]
	global_load_lds_dwordx4 v2, s[44:45]
	s_add_i32 m0, s68, 0x2000
	s_nop 0
	global_load_lds_dwordx4 v134, s[44:45]
	s_mov_b32 m0, s59
	s_nop 0
	global_load_lds_dwordx4 v[24:25], off
	v_lshl_add_u64 v[24:25], v[250:251], 0, s[24:25]
	s_mov_b32 m0, s60
	s_nop 0
	global_load_lds_dwordx4 v[24:25], off
	s_waitcnt vmcnt(8)
	s_waitcnt lgkmcnt(0)
	s_barrier
	s_setprio 1
	v_mfma_f32_16x16x32_f16 v[24:27], v[16:19], v[36:39], v[144:147]
	v_mfma_f32_16x16x32_f16 v[64:67], v[20:23], v[44:47], v[24:27]
	v_mfma_f32_16x16x32_f16 v[24:27], v[28:31], v[36:39], v[148:151]
	v_mfma_f32_16x16x32_f16 v[56:59], v[200:203], v[44:47], v[24:27]
	v_mfma_f32_16x16x32_f16 v[24:27], v[16:19], v[220:223], v[152:155]
	v_mfma_f32_16x16x32_f16 v[48:51], v[20:23], v[224:227], v[24:27]
	v_mfma_f32_16x16x32_f16 v[24:27], v[28:31], v[220:223], v[156:159]
	v_mfma_f32_16x16x32_f16 v[40:43], v[200:203], v[224:227], v[24:27]
	v_mfma_f32_16x16x32_f16 v[24:27], v[16:19], v[232:235], v[160:163]
	v_mfma_f32_16x16x32_f16 v[4:7], v[16:19], v[240:243], v[4:7]
	v_mfma_f32_16x16x32_f16 v[32:35], v[20:23], v[236:239], v[24:27]
	v_mfma_f32_16x16x32_f16 v[24:27], v[28:31], v[232:235], v[164:167]
	v_mfma_f32_16x16x32_f16 v[16:19], v[20:23], v[244:247], v[4:7]
	v_mfma_f32_16x16x32_f16 v[4:7], v[28:31], v[240:243], v[8:11]
	v_mfma_f32_16x16x32_f16 v[24:27], v[200:203], v[236:239], v[24:27]
	v_mfma_f32_16x16x32_f16 v[8:11], v[200:203], v[244:247], v[4:7]
	v_mfma_f32_16x16x32_f16 v[4:7], v[204:207], v[36:39], v[12:15]
	v_mfma_f32_16x16x32_f16 v[60:63], v[208:211], v[44:47], v[4:7]
	v_mfma_f32_16x16x32_f16 v[4:7], v[212:215], v[36:39], v[172:175]
	v_mfma_f32_16x16x32_f16 v[52:55], v[216:219], v[44:47], v[4:7]
	v_mfma_f32_16x16x32_f16 v[4:7], v[204:207], v[220:223], v[176:179]
	v_mfma_f32_16x16x32_f16 v[44:47], v[208:211], v[224:227], v[4:7]
	v_mfma_f32_16x16x32_f16 v[4:7], v[212:215], v[220:223], v[180:183]
	v_mfma_f32_16x16x32_f16 v[36:39], v[216:219], v[224:227], v[4:7]
	v_mfma_f32_16x16x32_f16 v[4:7], v[204:207], v[232:235], v[168:171]
	v_mfma_f32_16x16x32_f16 v[28:31], v[208:211], v[236:239], v[4:7]
	v_mfma_f32_16x16x32_f16 v[4:7], v[212:215], v[232:235], v[184:187]
	v_mfma_f32_16x16x32_f16 v[20:23], v[216:219], v[236:239], v[4:7]
	v_mfma_f32_16x16x32_f16 v[4:7], v[204:207], v[240:243], v[188:191]
	v_mfma_f32_16x16x32_f16 v[12:15], v[208:211], v[244:247], v[4:7]
	s_setprio 2
	s_barrier
	v_mfma_f32_16x16x32_f16 v[4:7], v[212:215], v[240:243], v[196:199]
	v_mfma_f32_16x16x32_f16 v[4:7], v[216:219], v[244:247], v[4:7]
	s_setprio 0
	s_add_i32 s67, s67, 2
	s_cmp_ge_i32 s67, s11
	s_cbranch_scc0 .LBB0_2159

.LBB0_2161:
	s_add_u32 s68, s6, s40
	s_addc_u32 s69, s7, s41
	s_add_u32 s42, s68, 0x200
	s_addc_u32 s43, s69, 0
	s_add_u32 s44, s8, s40
	s_addc_u32 s45, s9, s41
	s_add_u32 s67, s44, 0x200
	s_addc_u32 s70, s45, 0
	s_add_i32 s71, 0, 0x10000
	s_cmp_eq_u32 s11, 28
	s_cselect_b32 s45, s29, s43
	s_cselect_b32 s44, s28, s42
	v_add_u32_e32 v133, s71, v143
	s_cselect_b32 s43, s37, s70
	s_cselect_b32 s42, s36, s67
	s_add_i32 s67, 0, 0x14000
	ds_read_b128 v[144:147], v133
	ds_read_b128 v[148:151], v133 offset:1024
	ds_read_b128 v[152:155], v133 offset:2048
	ds_read_b128 v[156:159], v133 offset:3072
	v_add_u32_e32 v133, s67, v143
	ds_read_b128 v[160:163], v133
	ds_read_b128 v[164:167], v133 offset:1024
	ds_read_b128 v[168:171], v133 offset:2048
	ds_read_b128 v[172:175], v133 offset:3072
	v_lshl_add_u64 v[136:137], s[68:69], 0, v[2:3]
	s_mov_b32 m0, s61
	v_add_u32_e32 v216, 0, v142
	v_lshl_add_u64 v[136:137], v[136:137], 0, s[34:35]
	v_mov_b32_e32 v133, v3
	ds_read_b128 v[176:179], v216
	ds_read_b128 v[180:183], v216 offset:1024
	ds_read_b128 v[184:187], v216 offset:2048
	ds_read_b128 v[188:191], v216 offset:3072
	ds_read_b128 v[196:199], v216 offset:4096
	ds_read_b128 v[200:203], v216 offset:5120
	ds_read_b128 v[204:207], v216 offset:6144
	ds_read_b128 v[208:211], v216 offset:7168
	global_load_lds_dwordx4 v[136:137], off
	v_lshl_add_u64 v[136:137], s[68:69], 0, v[132:133]
	v_lshl_add_u64 v[136:137], v[136:137], 0, s[34:35]
	s_mov_b32 m0, s62
	s_nop 0
	global_load_lds_dwordx4 v[136:137], off
	s_waitcnt vmcnt(8)
	s_waitcnt lgkmcnt(0)
	s_barrier
	s_setprio 1
	v_mfma_f32_16x16x32_f16 v[128:131], v[144:147], v[176:179], v[128:131]
	v_mfma_f32_16x16x32_f16 v[128:131], v[148:151], v[180:183], v[128:131]
	v_mfma_f32_16x16x32_f16 v[120:123], v[156:159], v[180:183], v[120:123]
	v_mfma_f32_16x16x32_f16 v[120:123], v[152:155], v[176:179], v[120:123]
	v_mfma_f32_16x16x32_f16 v[104:107], v[152:155], v[184:187], v[104:107]
	v_mfma_f32_16x16x32_f16 v[104:107], v[156:159], v[188:191], v[104:107]
	v_mfma_f32_16x16x32_f16 v[112:115], v[148:151], v[188:191], v[112:115]
	v_mfma_f32_16x16x32_f16 v[112:115], v[144:147], v[184:187], v[112:115]
	v_mfma_f32_16x16x32_f16 v[96:99], v[144:147], v[196:199], v[96:99]
	v_mfma_f32_16x16x32_f16 v[96:99], v[148:151], v[200:203], v[96:99]
	v_mfma_f32_16x16x32_f16 v[88:91], v[156:159], v[200:203], v[88:91]
	v_mfma_f32_16x16x32_f16 v[88:91], v[152:155], v[196:199], v[88:91]
	v_mfma_f32_16x16x32_f16 v[72:75], v[152:155], v[204:207], v[72:75]
	v_mfma_f32_16x16x32_f16 v[72:75], v[156:159], v[208:211], v[72:75]
	v_mfma_f32_16x16x32_f16 v[80:83], v[148:151], v[208:211], v[80:83]
	v_mfma_f32_16x16x32_f16 v[80:83], v[144:147], v[204:207], v[80:83]
	v_mfma_f32_16x16x32_f16 v[124:127], v[160:163], v[176:179], v[124:127]
	v_mfma_f32_16x16x32_f16 v[124:127], v[164:167], v[180:183], v[124:127]
	v_mfma_f32_16x16x32_f16 v[116:119], v[172:175], v[180:183], v[116:119]
	v_mfma_f32_16x16x32_f16 v[116:119], v[168:171], v[176:179], v[116:119]
	v_mfma_f32_16x16x32_f16 v[100:103], v[168:171], v[184:187], v[100:103]
	v_mfma_f32_16x16x32_f16 v[100:103], v[172:175], v[188:191], v[100:103]
	v_mfma_f32_16x16x32_f16 v[108:111], v[164:167], v[188:191], v[108:111]
	v_mfma_f32_16x16x32_f16 v[108:111], v[160:163], v[184:187], v[108:111]
	v_mfma_f32_16x16x32_f16 v[92:95], v[160:163], v[196:199], v[92:95]
	v_mfma_f32_16x16x32_f16 v[92:95], v[164:167], v[200:203], v[92:95]
	v_mfma_f32_16x16x32_f16 v[84:87], v[172:175], v[200:203], v[84:87]
	v_mfma_f32_16x16x32_f16 v[84:87], v[168:171], v[196:199], v[84:87]
	v_mfma_f32_16x16x32_f16 v[68:71], v[168:171], v[204:207], v[68:71]
	v_mfma_f32_16x16x32_f16 v[68:71], v[172:175], v[208:211], v[68:71]
	s_setprio 2
	s_barrier
	v_mfma_f32_16x16x32_f16 v[76:79], v[164:167], v[208:211], v[76:79]
	v_mfma_f32_16x16x32_f16 v[76:79], v[160:163], v[204:207], v[76:79]
	s_setprio 0
	s_add_i32 s68, s71, s53
	s_mov_b32 m0, s68
	ds_read_b128 v[176:179], v216 offset:16384
	ds_read_b128 v[180:183], v216 offset:17408
	ds_read_b128 v[184:187], v216 offset:18432
	ds_read_b128 v[188:191], v216 offset:19456
	ds_read_b128 v[196:199], v216 offset:20480
	ds_read_b128 v[200:203], v216 offset:21504
	ds_read_b128 v[204:207], v216 offset:22528
	ds_read_b128 v[208:211], v216 offset:23552
	global_load_lds_dwordx4 v138, s[42:43]
	s_add_i32 m0, s68, 0x2000
	s_add_u32 s68, s42, 0x80000
	s_addc_u32 s69, s43, 0
	s_add_i32 s67, s67, s53
	global_load_lds_dwordx4 v134, s[42:43]
	s_mov_b32 m0, s67
	v_mov_b32_e32 v139, v3
	global_load_lds_dwordx4 v138, s[68:69]
	s_add_i32 m0, s67, 0x2000
	v_mov_b32_e32 v135, v3
	global_load_lds_dwordx4 v134, s[68:69]
	s_mov_b32 m0, s54
	v_lshl_add_u64 v[136:137], s[42:43], 0, v[138:139]
	global_load_lds_dwordx4 v2, s[44:45]
	s_mov_b32 m0, s55
	v_lshl_add_u64 v[192:193], s[42:43], 0, v[134:135]
	global_load_lds_dwordx4 v132, s[44:45]
	s_waitcnt vmcnt(8)
	s_waitcnt lgkmcnt(0)
	v_lshl_add_u64 v[212:213], s[44:45], 0, v[2:3]
	v_lshl_add_u64 v[214:215], s[44:45], 0, v[132:133]
	s_barrier
	s_setprio 1
	v_mfma_f32_16x16x32_f16 v[64:67], v[144:147], v[176:179], v[64:67]
	v_mfma_f32_16x16x32_f16 v[64:67], v[148:151], v[180:183], v[64:67]
	v_mfma_f32_16x16x32_f16 v[56:59], v[156:159], v[180:183], v[56:59]
	v_mfma_f32_16x16x32_f16 v[56:59], v[152:155], v[176:179], v[56:59]
	v_mfma_f32_16x16x32_f16 v[40:43], v[152:155], v[184:187], v[40:43]
	v_mfma_f32_16x16x32_f16 v[40:43], v[156:159], v[188:191], v[40:43]
	v_mfma_f32_16x16x32_f16 v[48:51], v[148:151], v[188:191], v[48:51]
	v_mfma_f32_16x16x32_f16 v[48:51], v[144:147], v[184:187], v[48:51]
	v_mfma_f32_16x16x32_f16 v[32:35], v[144:147], v[196:199], v[32:35]
	v_mfma_f32_16x16x32_f16 v[32:35], v[148:151], v[200:203], v[32:35]
	v_mfma_f32_16x16x32_f16 v[24:27], v[156:159], v[200:203], v[24:27]
	v_mfma_f32_16x16x32_f16 v[24:27], v[152:155], v[196:199], v[24:27]
	v_mfma_f32_16x16x32_f16 v[8:11], v[152:155], v[204:207], v[8:11]
	v_mfma_f32_16x16x32_f16 v[8:11], v[156:159], v[208:211], v[8:11]
	v_mfma_f32_16x16x32_f16 v[16:19], v[148:151], v[208:211], v[16:19]
	v_mfma_f32_16x16x32_f16 v[16:19], v[144:147], v[204:207], v[16:19]
	v_mfma_f32_16x16x32_f16 v[60:63], v[160:163], v[176:179], v[60:63]
	v_mfma_f32_16x16x32_f16 v[60:63], v[164:167], v[180:183], v[60:63]
	v_mfma_f32_16x16x32_f16 v[52:55], v[172:175], v[180:183], v[52:55]
	v_mfma_f32_16x16x32_f16 v[52:55], v[168:171], v[176:179], v[52:55]
	v_mfma_f32_16x16x32_f16 v[36:39], v[168:171], v[184:187], v[36:39]
	v_mfma_f32_16x16x32_f16 v[36:39], v[172:175], v[188:191], v[36:39]
	v_mfma_f32_16x16x32_f16 v[44:47], v[164:167], v[188:191], v[44:47]
	v_mfma_f32_16x16x32_f16 v[44:47], v[160:163], v[184:187], v[44:47]
	v_mfma_f32_16x16x32_f16 v[28:31], v[160:163], v[196:199], v[28:31]
	v_mfma_f32_16x16x32_f16 v[28:31], v[164:167], v[200:203], v[28:31]
	v_mfma_f32_16x16x32_f16 v[20:23], v[172:175], v[200:203], v[20:23]
	v_mfma_f32_16x16x32_f16 v[20:23], v[168:171], v[196:199], v[20:23]
	v_mfma_f32_16x16x32_f16 v[4:7], v[168:171], v[204:207], v[4:7]
	v_mfma_f32_16x16x32_f16 v[4:7], v[172:175], v[208:211], v[4:7]
	s_setprio 2
	s_barrier
	v_mfma_f32_16x16x32_f16 v[12:15], v[164:167], v[208:211], v[12:15]
	v_mfma_f32_16x16x32_f16 v[12:15], v[160:163], v[204:207], v[12:15]
	s_setprio 0
	s_add_i32 s67, 0, 0x18000
	v_add_u32_e32 v135, s67, v143
	s_add_i32 s68, 0, 0x1c000
	ds_read_b128 v[144:147], v135
	ds_read_b128 v[148:151], v135 offset:1024
	ds_read_b128 v[152:155], v135 offset:2048
	ds_read_b128 v[156:159], v135 offset:3072
	v_add_u32_e32 v135, s68, v143
	ds_read_b128 v[160:163], v135
	ds_read_b128 v[164:167], v135 offset:1024
	ds_read_b128 v[168:171], v135 offset:2048
	ds_read_b128 v[172:175], v135 offset:3072
	s_add_u32 s44, s44, 0x80000
	s_addc_u32 s45, s45, 0
	s_mov_b32 m0, s56
	ds_read_b128 v[176:179], v216 offset:32768
	ds_read_b128 v[180:183], v216 offset:33792
	ds_read_b128 v[184:187], v216 offset:34816
	ds_read_b128 v[188:191], v216 offset:35840
	ds_read_b128 v[196:199], v216 offset:36864
	ds_read_b128 v[200:203], v216 offset:37888
	ds_read_b128 v[204:207], v216 offset:38912
	ds_read_b128 v[208:211], v216 offset:39936
	global_load_lds_dwordx4 v2, s[44:45]
	s_mov_b32 m0, s57
	s_nop 0
	global_load_lds_dwordx4 v132, s[44:45]
	s_waitcnt vmcnt(8)
	s_waitcnt lgkmcnt(0)
	s_barrier
	s_setprio 1
	v_mfma_f32_16x16x32_f16 v[128:131], v[144:147], v[176:179], v[128:131]
	v_mfma_f32_16x16x32_f16 v[128:131], v[148:151], v[180:183], v[128:131]
	v_mfma_f32_16x16x32_f16 v[120:123], v[156:159], v[180:183], v[120:123]
	v_mfma_f32_16x16x32_f16 v[120:123], v[152:155], v[176:179], v[120:123]
	v_mfma_f32_16x16x32_f16 v[104:107], v[152:155], v[184:187], v[104:107]
	v_mfma_f32_16x16x32_f16 v[104:107], v[156:159], v[188:191], v[104:107]
	v_mfma_f32_16x16x32_f16 v[112:115], v[148:151], v[188:191], v[112:115]
	v_mfma_f32_16x16x32_f16 v[112:115], v[144:147], v[184:187], v[112:115]
	v_mfma_f32_16x16x32_f16 v[96:99], v[144:147], v[196:199], v[96:99]
	v_mfma_f32_16x16x32_f16 v[96:99], v[148:151], v[200:203], v[96:99]
	v_mfma_f32_16x16x32_f16 v[88:91], v[156:159], v[200:203], v[88:91]
	v_mfma_f32_16x16x32_f16 v[88:91], v[152:155], v[196:199], v[88:91]
	v_mfma_f32_16x16x32_f16 v[72:75], v[152:155], v[204:207], v[72:75]
	v_mfma_f32_16x16x32_f16 v[72:75], v[156:159], v[208:211], v[72:75]
	v_mfma_f32_16x16x32_f16 v[80:83], v[148:151], v[208:211], v[80:83]
	v_mfma_f32_16x16x32_f16 v[80:83], v[144:147], v[204:207], v[80:83]
	v_mfma_f32_16x16x32_f16 v[124:127], v[160:163], v[176:179], v[124:127]
	v_mfma_f32_16x16x32_f16 v[124:127], v[164:167], v[180:183], v[124:127]
	v_mfma_f32_16x16x32_f16 v[116:119], v[172:175], v[180:183], v[116:119]
	v_mfma_f32_16x16x32_f16 v[116:119], v[168:171], v[176:179], v[116:119]
	v_mfma_f32_16x16x32_f16 v[100:103], v[168:171], v[184:187], v[100:103]
	v_mfma_f32_16x16x32_f16 v[100:103], v[172:175], v[188:191], v[100:103]
	v_mfma_f32_16x16x32_f16 v[108:111], v[164:167], v[188:191], v[108:111]
	v_mfma_f32_16x16x32_f16 v[108:111], v[160:163], v[184:187], v[108:111]
	v_mfma_f32_16x16x32_f16 v[92:95], v[160:163], v[196:199], v[92:95]
	v_mfma_f32_16x16x32_f16 v[92:95], v[164:167], v[200:203], v[92:95]
	v_mfma_f32_16x16x32_f16 v[84:87], v[172:175], v[200:203], v[84:87]
	v_mfma_f32_16x16x32_f16 v[84:87], v[168:171], v[196:199], v[84:87]
	v_mfma_f32_16x16x32_f16 v[68:71], v[168:171], v[204:207], v[68:71]
	v_mfma_f32_16x16x32_f16 v[68:71], v[172:175], v[208:211], v[68:71]
	s_setprio 2
	s_barrier
	v_mfma_f32_16x16x32_f16 v[76:79], v[164:167], v[208:211], v[76:79]
	v_mfma_f32_16x16x32_f16 v[76:79], v[160:163], v[204:207], v[76:79]
	s_setprio 0
	s_add_i32 s44, s67, s53
	v_lshl_add_u64 v[136:137], v[136:137], 0, s[86:87]
	s_mov_b32 m0, s44
	ds_read_b128 v[176:179], v216 offset:49152
	ds_read_b128 v[180:183], v216 offset:50176
	ds_read_b128 v[184:187], v216 offset:51200
	ds_read_b128 v[188:191], v216 offset:52224
	ds_read_b128 v[196:199], v216 offset:53248
	ds_read_b128 v[200:203], v216 offset:54272
	ds_read_b128 v[204:207], v216 offset:55296
	ds_read_b128 v[208:211], v216 offset:56320
	global_load_lds_dwordx4 v[136:137], off
	s_add_i32 m0, s44, 0x2000
	s_add_u32 s42, s42, 0x80080
	v_lshl_add_u64 v[136:137], v[192:193], 0, s[86:87]
	s_addc_u32 s43, s43, 0
	s_add_i32 s44, s68, s53
	global_load_lds_dwordx4 v[136:137], off
	s_mov_b32 m0, s44
	v_lshl_add_u64 v[136:137], v[212:213], 0, s[86:87]
	global_load_lds_dwordx4 v138, s[42:43]
	s_add_i32 m0, s44, 0x2000
	s_nop 0
	global_load_lds_dwordx4 v134, s[42:43]
	s_mov_b32 m0, s59
	s_nop 0
	global_load_lds_dwordx4 v[136:137], off
	v_lshl_add_u64 v[136:137], v[214:215], 0, s[86:87]
	s_mov_b32 m0, s60
	s_nop 0
	global_load_lds_dwordx4 v[136:137], off
	s_waitcnt vmcnt(8)
	s_waitcnt lgkmcnt(0)
	s_barrier
	s_setprio 1
	v_mfma_f32_16x16x32_f16 v[64:67], v[144:147], v[176:179], v[64:67]
	v_mfma_f32_16x16x32_f16 v[64:67], v[148:151], v[180:183], v[64:67]
	v_mfma_f32_16x16x32_f16 v[56:59], v[156:159], v[180:183], v[56:59]
	v_mfma_f32_16x16x32_f16 v[56:59], v[152:155], v[176:179], v[56:59]
	v_mfma_f32_16x16x32_f16 v[40:43], v[152:155], v[184:187], v[40:43]
	v_mfma_f32_16x16x32_f16 v[40:43], v[156:159], v[188:191], v[40:43]
	v_mfma_f32_16x16x32_f16 v[48:51], v[148:151], v[188:191], v[48:51]
	v_mfma_f32_16x16x32_f16 v[48:51], v[144:147], v[184:187], v[48:51]
	v_mfma_f32_16x16x32_f16 v[32:35], v[144:147], v[196:199], v[32:35]
	v_mfma_f32_16x16x32_f16 v[32:35], v[148:151], v[200:203], v[32:35]
	v_mfma_f32_16x16x32_f16 v[24:27], v[156:159], v[200:203], v[24:27]
	v_mfma_f32_16x16x32_f16 v[24:27], v[152:155], v[196:199], v[24:27]
	v_mfma_f32_16x16x32_f16 v[8:11], v[152:155], v[204:207], v[8:11]
	v_mfma_f32_16x16x32_f16 v[8:11], v[156:159], v[208:211], v[8:11]
	v_mfma_f32_16x16x32_f16 v[16:19], v[148:151], v[208:211], v[16:19]
	v_mfma_f32_16x16x32_f16 v[16:19], v[144:147], v[204:207], v[16:19]
	v_mfma_f32_16x16x32_f16 v[60:63], v[160:163], v[176:179], v[60:63]
	v_mfma_f32_16x16x32_f16 v[60:63], v[164:167], v[180:183], v[60:63]
	v_mfma_f32_16x16x32_f16 v[52:55], v[172:175], v[180:183], v[52:55]
	v_mfma_f32_16x16x32_f16 v[52:55], v[168:171], v[176:179], v[52:55]
	v_mfma_f32_16x16x32_f16 v[36:39], v[168:171], v[184:187], v[36:39]
	v_mfma_f32_16x16x32_f16 v[36:39], v[172:175], v[188:191], v[36:39]
	v_mfma_f32_16x16x32_f16 v[44:47], v[164:167], v[188:191], v[44:47]
	v_mfma_f32_16x16x32_f16 v[44:47], v[160:163], v[184:187], v[44:47]
	v_mfma_f32_16x16x32_f16 v[28:31], v[160:163], v[196:199], v[28:31]
	v_mfma_f32_16x16x32_f16 v[28:31], v[164:167], v[200:203], v[28:31]
	v_mfma_f32_16x16x32_f16 v[20:23], v[172:175], v[200:203], v[20:23]
	v_mfma_f32_16x16x32_f16 v[20:23], v[168:171], v[196:199], v[20:23]
	v_mfma_f32_16x16x32_f16 v[4:7], v[168:171], v[204:207], v[4:7]
	v_mfma_f32_16x16x32_f16 v[4:7], v[172:175], v[208:211], v[4:7]
	s_setprio 2
	s_barrier
	v_mfma_f32_16x16x32_f16 v[12:15], v[164:167], v[208:211], v[12:15]
	v_mfma_f32_16x16x32_f16 v[12:15], v[160:163], v[204:207], v[12:15]
	s_setprio 0
	s_add_i32 s11, s11, 2
	s_add_u32 s40, s40, 0x100
	s_addc_u32 s41, s41, 0
	s_cmp_gt_u32 s11, 29
	s_cbranch_scc0 .LBB0_2161
	s_andn2_b64 vcc, exec, s[26:27]
	s_cbranch_vccnz .LBB0_2164
	s_add_u32 s6, s28, 0x80080
	s_addc_u32 s7, s29, 0
	s_mov_b32 m0, s61
	v_lshl_add_u64 v[144:145], s[6:7], 0, v[2:3]
	v_lshl_add_u64 v[136:137], s[6:7], 0, v[132:133]
	global_load_lds_dwordx4 v[144:145], off
	s_mov_b32 m0, s62
	s_mov_b32 s47, s65
	global_load_lds_dwordx4 v[136:137], off
	s_mov_b32 s64, s10
	s_mov_b64 s[8:9], s[14:15]
	s_mov_b64 s[6:7], s[12:13]
	s_mov_b32 s63, s66

.LBB0_2269:
	s_add_i32 s51, 0, 0x10000
	s_add_i32 s71, 0, 0x14000
	v_add_u32_e32 v16, s51, v232
	v_add_u32_e32 v32, s71, v232
	ds_read_b128 v[4:7], v16
	ds_read_b128 v[8:11], v16 offset:1024
	ds_read_b128 v[12:15], v16 offset:2048
	ds_read_b128 v[16:19], v16 offset:3072
	ds_read_b128 v[20:23], v32
	ds_read_b128 v[24:27], v32 offset:1024
	ds_read_b128 v[28:31], v32 offset:2048
	ds_read_b128 v[32:35], v32 offset:3072
	v_add_u32_e32 v233, 0, v231
	ds_read_b128 v[36:39], v233
	ds_read_b128 v[40:43], v233 offset:1024
	ds_read_b128 v[44:47], v233 offset:2048
	ds_read_b128 v[48:51], v233 offset:3072
	ds_read_b128 v[52:55], v233 offset:4096
	ds_read_b128 v[56:59], v233 offset:5120
	ds_read_b128 v[60:63], v233 offset:6144
	ds_read_b128 v[64:67], v233 offset:7168
	s_waitcnt vmcnt(8)
	s_waitcnt lgkmcnt(0)
	s_barrier
	s_setprio 1
	v_mfma_f32_16x16x32_bf16 v[68:71], v[4:7], v[36:39], 0
	v_mfma_f32_16x16x32_bf16 v[68:71], v[8:11], v[40:43], v[68:71]
	v_mfma_f32_16x16x32_bf16 v[72:75], v[12:15], v[36:39], 0
	v_mfma_f32_16x16x32_bf16 v[72:75], v[16:19], v[40:43], v[72:75]
	v_mfma_f32_16x16x32_bf16 v[80:83], v[12:15], v[44:47], 0
	v_mfma_f32_16x16x32_bf16 v[80:83], v[16:19], v[48:51], v[80:83]
	v_mfma_f32_16x16x32_bf16 v[76:79], v[4:7], v[44:47], 0
	v_mfma_f32_16x16x32_bf16 v[76:79], v[8:11], v[48:51], v[76:79]
	v_mfma_f32_16x16x32_bf16 v[84:87], v[4:7], v[52:55], 0
	v_mfma_f32_16x16x32_bf16 v[84:87], v[8:11], v[56:59], v[84:87]
	v_mfma_f32_16x16x32_bf16 v[88:91], v[12:15], v[52:55], 0
	v_mfma_f32_16x16x32_bf16 v[88:91], v[16:19], v[56:59], v[88:91]
	v_mfma_f32_16x16x32_bf16 v[96:99], v[12:15], v[60:63], 0
	v_mfma_f32_16x16x32_bf16 v[96:99], v[16:19], v[64:67], v[96:99]
	v_mfma_f32_16x16x32_bf16 v[92:95], v[4:7], v[60:63], 0
	v_mfma_f32_16x16x32_bf16 v[92:95], v[8:11], v[64:67], v[92:95]
	v_mfma_f32_16x16x32_bf16 v[100:103], v[20:23], v[36:39], 0
	v_mfma_f32_16x16x32_bf16 v[36:39], v[28:31], v[36:39], 0
	v_mfma_f32_16x16x32_bf16 v[104:107], v[20:23], v[44:47], 0
	v_mfma_f32_16x16x32_bf16 v[44:47], v[28:31], v[44:47], 0
	v_mfma_f32_16x16x32_bf16 v[108:111], v[20:23], v[52:55], 0
	v_mfma_f32_16x16x32_bf16 v[52:55], v[28:31], v[52:55], 0
	v_mfma_f32_16x16x32_bf16 v[112:115], v[20:23], v[60:63], 0
	v_mfma_f32_16x16x32_bf16 v[60:63], v[28:31], v[60:63], 0
	v_mfma_f32_16x16x32_bf16 v[100:103], v[24:27], v[40:43], v[100:103]
	v_mfma_f32_16x16x32_bf16 v[40:43], v[32:35], v[40:43], v[36:39]
	v_mfma_f32_16x16x32_bf16 v[104:107], v[24:27], v[48:51], v[104:107]
	v_mfma_f32_16x16x32_bf16 v[48:51], v[32:35], v[48:51], v[44:47]
	v_mfma_f32_16x16x32_bf16 v[108:111], v[24:27], v[56:59], v[108:111]
	v_mfma_f32_16x16x32_bf16 v[56:59], v[32:35], v[56:59], v[52:55]
	s_setprio 2
	s_barrier
	v_mfma_f32_16x16x32_bf16 v[112:115], v[24:27], v[64:67], v[112:115]
	v_mfma_f32_16x16x32_bf16 v[64:67], v[32:35], v[64:67], v[60:63]
	s_setprio 0
	v_lshl_add_u64 v[186:187], s[12:13], 0, v[2:3]
	s_add_i32 s51, s51, s38
	v_mov_b32_e32 v191, v3
	v_lshl_add_u64 v[134:135], v[186:187], 0, s[74:75]
	s_mov_b32 m0, s51
	v_lshl_add_u64 v[246:247], s[12:13], 0, v[190:191]
	ds_read_b128 v[36:39], v233 offset:16384
	ds_read_b128 v[44:47], v233 offset:17408
	ds_read_b128 v[52:55], v233 offset:18432
	ds_read_b128 v[60:63], v233 offset:19456
	ds_read_b128 v[116:119], v233 offset:20480
	ds_read_b128 v[120:123], v233 offset:21504
	ds_read_b128 v[124:127], v233 offset:22528
	ds_read_b128 v[128:131], v233 offset:23552
	global_load_lds_dwordx4 v[134:135], off
	v_lshl_add_u64 v[134:135], v[246:247], 0, s[74:75]
	s_add_i32 m0, s51, 0x2000
	s_add_i32 s51, s71, s38
	global_load_lds_dwordx4 v[134:135], off
	s_mov_b32 m0, s51
	v_mov_b32_e32 v133, v3
	global_load_lds_dwordx4 v2, s[16:17]
	s_add_i32 m0, s51, 0x2000
	v_lshl_add_u64 v[248:249], s[14:15], 0, v[132:133]
	v_mov_b32_e32 v189, v3
	global_load_lds_dwordx4 v190, s[16:17]
	v_lshl_add_u64 v[134:135], v[248:249], 0, s[74:75]
	s_mov_b32 m0, s56
	v_lshl_add_u64 v[250:251], s[14:15], 0, v[188:189]
	global_load_lds_dwordx4 v[134:135], off
	v_lshl_add_u64 v[134:135], v[250:251], 0, s[74:75]
	s_mov_b32 m0, s57
	s_nop 0
	global_load_lds_dwordx4 v[134:135], off
	s_waitcnt vmcnt(8)
	s_waitcnt lgkmcnt(0)
	s_barrier
	s_setprio 1
	v_mfma_f32_16x16x32_bf16 v[134:137], v[4:7], v[36:39], 0
	v_mfma_f32_16x16x32_bf16 v[138:141], v[12:15], v[36:39], 0
	v_mfma_f32_16x16x32_bf16 v[142:145], v[4:7], v[52:55], 0
	v_mfma_f32_16x16x32_bf16 v[146:149], v[12:15], v[52:55], 0
	v_mfma_f32_16x16x32_bf16 v[150:153], v[4:7], v[116:119], 0
	v_mfma_f32_16x16x32_bf16 v[154:157], v[12:15], v[116:119], 0
	v_mfma_f32_16x16x32_bf16 v[4:7], v[4:7], v[124:127], 0
	v_mfma_f32_16x16x32_bf16 v[12:15], v[12:15], v[124:127], 0
	v_mfma_f32_16x16x32_bf16 v[134:137], v[8:11], v[44:47], v[134:137]
	v_mfma_f32_16x16x32_bf16 v[138:141], v[16:19], v[44:47], v[138:141]
	v_mfma_f32_16x16x32_bf16 v[142:145], v[8:11], v[60:63], v[142:145]
	v_mfma_f32_16x16x32_bf16 v[146:149], v[16:19], v[60:63], v[146:149]
	v_mfma_f32_16x16x32_bf16 v[150:153], v[8:11], v[120:123], v[150:153]
	v_mfma_f32_16x16x32_bf16 v[154:157], v[16:19], v[120:123], v[154:157]
	v_mfma_f32_16x16x32_bf16 v[158:161], v[8:11], v[128:131], v[4:7]
	v_mfma_f32_16x16x32_bf16 v[162:165], v[16:19], v[128:131], v[12:15]
	v_mfma_f32_16x16x32_bf16 v[4:7], v[20:23], v[36:39], 0
	v_mfma_f32_16x16x32_bf16 v[8:11], v[28:31], v[36:39], 0
	v_mfma_f32_16x16x32_bf16 v[12:15], v[20:23], v[52:55], 0
	v_mfma_f32_16x16x32_bf16 v[16:19], v[28:31], v[52:55], 0
	v_mfma_f32_16x16x32_bf16 v[36:39], v[20:23], v[116:119], 0
	v_mfma_f32_16x16x32_bf16 v[52:55], v[28:31], v[116:119], 0
	v_mfma_f32_16x16x32_bf16 v[20:23], v[20:23], v[124:127], 0
	v_mfma_f32_16x16x32_bf16 v[28:31], v[28:31], v[124:127], 0
	v_mfma_f32_16x16x32_bf16 v[116:119], v[24:27], v[44:47], v[4:7]
	v_mfma_f32_16x16x32_bf16 v[124:127], v[32:35], v[44:47], v[8:11]
	v_mfma_f32_16x16x32_bf16 v[174:177], v[24:27], v[120:123], v[36:39]
	v_mfma_f32_16x16x32_bf16 v[120:123], v[32:35], v[120:123], v[52:55]
	v_mfma_f32_16x16x32_bf16 v[178:181], v[24:27], v[128:131], v[20:23]
	v_mfma_f32_16x16x32_bf16 v[128:131], v[32:35], v[128:131], v[28:31]
	s_setprio 2
	s_barrier
	v_mfma_f32_16x16x32_bf16 v[166:169], v[24:27], v[60:63], v[12:15]
	v_mfma_f32_16x16x32_bf16 v[170:173], v[32:35], v[60:63], v[16:19]
	s_setprio 0
	s_add_i32 s51, 0, 0x18000
	v_add_u32_e32 v4, s51, v232
	s_add_i32 s71, 0, 0x1c000
	ds_read_b128 v[182:185], v4
	ds_read_b128 v[192:195], v4 offset:1024
	ds_read_b128 v[196:199], v4 offset:2048
	ds_read_b128 v[200:203], v4 offset:3072
	v_add_u32_e32 v4, s71, v232
	ds_read_b128 v[204:207], v4
	ds_read_b128 v[208:211], v4 offset:1024
	ds_read_b128 v[212:215], v4 offset:2048
	ds_read_b128 v[216:219], v4 offset:3072
	s_mov_b32 m0, s58
	ds_read_b128 v[44:47], v233 offset:32768
	ds_read_b128 v[52:55], v233 offset:33792
	ds_read_b128 v[60:63], v233 offset:34816
	ds_read_b128 v[220:223], v233 offset:35840
	ds_read_b128 v[224:227], v233 offset:36864
	ds_read_b128 v[234:237], v233 offset:37888
	ds_read_b128 v[238:241], v233 offset:38912
	ds_read_b128 v[242:245], v233 offset:39936
	global_load_lds_dwordx4 v132, s[26:27]
	s_mov_b32 m0, s59
	s_nop 0
	global_load_lds_dwordx4 v188, s[26:27]
	s_waitcnt vmcnt(8)
	s_waitcnt lgkmcnt(0)
	s_barrier
	s_setprio 1
	v_mfma_f32_16x16x32_bf16 v[4:7], v[182:185], v[44:47], v[68:71]
	v_mfma_f32_16x16x32_bf16 v[8:11], v[196:199], v[44:47], v[72:75]
	v_mfma_f32_16x16x32_bf16 v[12:15], v[182:185], v[60:63], v[76:79]
	v_mfma_f32_16x16x32_bf16 v[16:19], v[196:199], v[60:63], v[80:83]
	v_mfma_f32_16x16x32_bf16 v[20:23], v[182:185], v[224:227], v[84:87]
	v_mfma_f32_16x16x32_bf16 v[24:27], v[196:199], v[224:227], v[88:91]
	v_mfma_f32_16x16x32_bf16 v[28:31], v[182:185], v[238:241], v[92:95]
	v_mfma_f32_16x16x32_bf16 v[32:35], v[196:199], v[238:241], v[96:99]
	v_mfma_f32_16x16x32_bf16 v[4:7], v[192:195], v[52:55], v[4:7]
	v_mfma_f32_16x16x32_bf16 v[8:11], v[200:203], v[52:55], v[8:11]
	v_mfma_f32_16x16x32_bf16 v[12:15], v[192:195], v[220:223], v[12:15]
	v_mfma_f32_16x16x32_bf16 v[16:19], v[200:203], v[220:223], v[16:19]
	v_mfma_f32_16x16x32_bf16 v[20:23], v[192:195], v[234:237], v[20:23]
	v_mfma_f32_16x16x32_bf16 v[24:27], v[200:203], v[234:237], v[24:27]
	v_mfma_f32_16x16x32_bf16 v[28:31], v[192:195], v[242:245], v[28:31]
	v_mfma_f32_16x16x32_bf16 v[32:35], v[200:203], v[242:245], v[32:35]
	v_mfma_f32_16x16x32_bf16 v[36:39], v[204:207], v[44:47], v[100:103]
	v_mfma_f32_16x16x32_bf16 v[40:43], v[212:215], v[44:47], v[40:43]
	v_mfma_f32_16x16x32_bf16 v[36:39], v[208:211], v[52:55], v[36:39]
	v_mfma_f32_16x16x32_bf16 v[40:43], v[216:219], v[52:55], v[40:43]
	v_mfma_f32_16x16x32_bf16 v[44:47], v[204:207], v[60:63], v[104:107]
	v_mfma_f32_16x16x32_bf16 v[48:51], v[212:215], v[60:63], v[48:51]
	v_mfma_f32_16x16x32_bf16 v[52:55], v[204:207], v[224:227], v[108:111]
	v_mfma_f32_16x16x32_bf16 v[56:59], v[212:215], v[224:227], v[56:59]
	v_mfma_f32_16x16x32_bf16 v[60:63], v[204:207], v[238:241], v[112:115]
	v_mfma_f32_16x16x32_bf16 v[64:67], v[212:215], v[238:241], v[64:67]
	v_mfma_f32_16x16x32_bf16 v[44:47], v[208:211], v[220:223], v[44:47]
	v_mfma_f32_16x16x32_bf16 v[48:51], v[216:219], v[220:223], v[48:51]
	v_mfma_f32_16x16x32_bf16 v[52:55], v[208:211], v[234:237], v[52:55]
	v_mfma_f32_16x16x32_bf16 v[56:59], v[216:219], v[234:237], v[56:59]
	s_setprio 2
	s_barrier
	v_mfma_f32_16x16x32_bf16 v[60:63], v[208:211], v[242:245], v[60:63]
	v_mfma_f32_16x16x32_bf16 v[64:67], v[216:219], v[242:245], v[64:67]
	s_setprio 0
	s_add_i32 s51, s51, s38
	v_lshl_add_u64 v[68:69], v[186:187], 0, s[24:25]
	s_mov_b32 m0, s51
	ds_read_b128 v[104:107], v233 offset:49152
	ds_read_b128 v[108:111], v233 offset:50176
	ds_read_b128 v[112:115], v233 offset:51200
	ds_read_b128 v[220:223], v233 offset:52224
	ds_read_b128 v[224:227], v233 offset:53248
	ds_read_b128 v[234:237], v233 offset:54272
	ds_read_b128 v[238:241], v233 offset:55296
	ds_read_b128 v[242:245], v233 offset:56320
	global_load_lds_dwordx4 v[68:69], off
	v_lshl_add_u64 v[68:69], v[246:247], 0, s[24:25]
	s_add_i32 m0, s51, 0x2000
	s_add_i32 s51, s71, s38
	global_load_lds_dwordx4 v[68:69], off
	s_mov_b32 m0, s51
	v_lshl_add_u64 v[68:69], v[248:249], 0, s[24:25]
	global_load_lds_dwordx4 v2, s[28:29]
	s_add_i32 m0, s51, 0x2000
	s_nop 0
	global_load_lds_dwordx4 v190, s[28:29]
	s_mov_b32 m0, s63
	s_nop 0
	global_load_lds_dwordx4 v[68:69], off
	v_lshl_add_u64 v[68:69], v[250:251], 0, s[24:25]
	s_mov_b32 m0, s64
	s_nop 0
	global_load_lds_dwordx4 v[68:69], off
	s_waitcnt vmcnt(8)
	s_waitcnt lgkmcnt(0)
	s_barrier
	s_setprio 1
	v_mfma_f32_16x16x32_bf16 v[68:71], v[182:185], v[104:107], v[134:137]
	v_mfma_f32_16x16x32_bf16 v[72:75], v[196:199], v[104:107], v[138:141]
	v_mfma_f32_16x16x32_bf16 v[76:79], v[182:185], v[112:115], v[142:145]
	v_mfma_f32_16x16x32_bf16 v[80:83], v[196:199], v[112:115], v[146:149]
	v_mfma_f32_16x16x32_bf16 v[84:87], v[182:185], v[224:227], v[150:153]
	v_mfma_f32_16x16x32_bf16 v[88:91], v[196:199], v[224:227], v[154:157]
	v_mfma_f32_16x16x32_bf16 v[92:95], v[182:185], v[238:241], v[158:161]
	v_mfma_f32_16x16x32_bf16 v[96:99], v[196:199], v[238:241], v[162:165]
	v_mfma_f32_16x16x32_bf16 v[68:71], v[192:195], v[108:111], v[68:71]
	v_mfma_f32_16x16x32_bf16 v[72:75], v[200:203], v[108:111], v[72:75]
	v_mfma_f32_16x16x32_bf16 v[76:79], v[192:195], v[220:223], v[76:79]
	v_mfma_f32_16x16x32_bf16 v[80:83], v[200:203], v[220:223], v[80:83]
	v_mfma_f32_16x16x32_bf16 v[84:87], v[192:195], v[234:237], v[84:87]
	v_mfma_f32_16x16x32_bf16 v[88:91], v[200:203], v[234:237], v[88:91]
	v_mfma_f32_16x16x32_bf16 v[92:95], v[192:195], v[242:245], v[92:95]
	v_mfma_f32_16x16x32_bf16 v[96:99], v[200:203], v[242:245], v[96:99]
	v_mfma_f32_16x16x32_bf16 v[100:103], v[204:207], v[104:107], v[116:119]
	v_mfma_f32_16x16x32_bf16 v[104:107], v[212:215], v[104:107], v[124:127]
	v_mfma_f32_16x16x32_bf16 v[100:103], v[208:211], v[108:111], v[100:103]
	v_mfma_f32_16x16x32_bf16 v[104:107], v[216:219], v[108:111], v[104:107]
	v_mfma_f32_16x16x32_bf16 v[108:111], v[204:207], v[112:115], v[166:169]
	v_mfma_f32_16x16x32_bf16 v[112:115], v[212:215], v[112:115], v[170:173]
	v_mfma_f32_16x16x32_bf16 v[116:119], v[204:207], v[224:227], v[174:177]
	v_mfma_f32_16x16x32_bf16 v[120:123], v[212:215], v[224:227], v[120:123]
	v_mfma_f32_16x16x32_bf16 v[124:127], v[204:207], v[238:241], v[178:181]
	v_mfma_f32_16x16x32_bf16 v[128:131], v[212:215], v[238:241], v[128:131]
	v_mfma_f32_16x16x32_bf16 v[108:111], v[208:211], v[220:223], v[108:111]
	v_mfma_f32_16x16x32_bf16 v[112:115], v[216:219], v[220:223], v[112:115]
	v_mfma_f32_16x16x32_bf16 v[116:119], v[208:211], v[234:237], v[116:119]
	v_mfma_f32_16x16x32_bf16 v[120:123], v[216:219], v[234:237], v[120:123]
	s_setprio 2
	s_barrier
	v_mfma_f32_16x16x32_bf16 v[124:127], v[208:211], v[242:245], v[124:127]
	v_mfma_f32_16x16x32_bf16 v[128:131], v[216:219], v[242:245], v[128:131]
	s_setprio 0
	s_add_i32 s41, s41, 2
	s_cmp_ge_i32 s41, s40
	s_cbranch_scc0 .LBB0_2269
	v_mov_b32_e32 v192, v2
	s_branch .LBB0_2272

.LBB0_2273:
	s_add_u32 s12, s14, 0xfffc0080
	s_addc_u32 s13, s15, -1
	s_add_i32 s29, 0, 0x10000
	s_cmp_eq_u32 s28, 12
	s_cselect_b32 s17, s9, s13
	s_cselect_b32 s16, s8, s12
	s_cselect_b32 s13, s11, s27
	s_cselect_b32 s12, s10, s26
	s_add_i32 s51, 0, 0x14000
	v_add_u32_e32 v144, s29, v232
	v_add_u32_e32 v160, s51, v232
	s_waitcnt lgkmcnt(0)
	ds_read_b128 v[132:135], v144
	ds_read_b128 v[136:139], v144 offset:1024
	ds_read_b128 v[140:143], v144 offset:2048
	ds_read_b128 v[144:147], v144 offset:3072
	ds_read_b128 v[148:151], v160
	ds_read_b128 v[152:155], v160 offset:1024
	ds_read_b128 v[156:159], v160 offset:2048
	ds_read_b128 v[160:163], v160 offset:3072
	s_mov_b32 m0, s65
	v_add_u32_e32 v210, 0, v231
	ds_read_b128 v[164:167], v210
	ds_read_b128 v[168:171], v210 offset:1024
	ds_read_b128 v[172:175], v210 offset:2048
	ds_read_b128 v[176:179], v210 offset:3072
	ds_read_b128 v[180:183], v210 offset:4096
	ds_read_b128 v[184:187], v210 offset:5120
	ds_read_b128 v[194:197], v210 offset:6144
	ds_read_b128 v[198:201], v210 offset:7168
	global_load_lds_dwordx4 v2, s[14:15]
	s_mov_b32 m0, s66
	v_mov_b32_e32 v189, v3
	global_load_lds_dwordx4 v188, s[14:15]
	s_waitcnt vmcnt(8)
	s_waitcnt lgkmcnt(0)
	s_barrier
	s_setprio 1
	v_mfma_f32_16x16x32_bf16 v[4:7], v[132:135], v[164:167], v[4:7]
	v_mfma_f32_16x16x32_bf16 v[4:7], v[136:139], v[168:171], v[4:7]
	v_mfma_f32_16x16x32_bf16 v[8:11], v[144:147], v[168:171], v[8:11]
	v_mfma_f32_16x16x32_bf16 v[8:11], v[140:143], v[164:167], v[8:11]
	v_mfma_f32_16x16x32_bf16 v[16:19], v[140:143], v[172:175], v[16:19]
	v_mfma_f32_16x16x32_bf16 v[16:19], v[144:147], v[176:179], v[16:19]
	v_mfma_f32_16x16x32_bf16 v[12:15], v[136:139], v[176:179], v[12:15]
	v_mfma_f32_16x16x32_bf16 v[12:15], v[132:135], v[172:175], v[12:15]
	v_mfma_f32_16x16x32_bf16 v[20:23], v[132:135], v[180:183], v[20:23]
	v_mfma_f32_16x16x32_bf16 v[20:23], v[136:139], v[184:187], v[20:23]
	v_mfma_f32_16x16x32_bf16 v[24:27], v[144:147], v[184:187], v[24:27]
	v_mfma_f32_16x16x32_bf16 v[24:27], v[140:143], v[180:183], v[24:27]
	v_mfma_f32_16x16x32_bf16 v[32:35], v[140:143], v[194:197], v[32:35]
	v_mfma_f32_16x16x32_bf16 v[32:35], v[144:147], v[198:201], v[32:35]
	v_mfma_f32_16x16x32_bf16 v[28:31], v[136:139], v[198:201], v[28:31]
	v_mfma_f32_16x16x32_bf16 v[28:31], v[132:135], v[194:197], v[28:31]
	v_mfma_f32_16x16x32_bf16 v[36:39], v[148:151], v[164:167], v[36:39]
	v_mfma_f32_16x16x32_bf16 v[36:39], v[152:155], v[168:171], v[36:39]
	v_mfma_f32_16x16x32_bf16 v[40:43], v[160:163], v[168:171], v[40:43]
	v_mfma_f32_16x16x32_bf16 v[40:43], v[156:159], v[164:167], v[40:43]
	v_mfma_f32_16x16x32_bf16 v[48:51], v[156:159], v[172:175], v[48:51]
	v_mfma_f32_16x16x32_bf16 v[48:51], v[160:163], v[176:179], v[48:51]
	v_mfma_f32_16x16x32_bf16 v[44:47], v[152:155], v[176:179], v[44:47]
	v_mfma_f32_16x16x32_bf16 v[44:47], v[148:151], v[172:175], v[44:47]
	v_mfma_f32_16x16x32_bf16 v[52:55], v[148:151], v[180:183], v[52:55]
	v_mfma_f32_16x16x32_bf16 v[52:55], v[152:155], v[184:187], v[52:55]
	v_mfma_f32_16x16x32_bf16 v[56:59], v[160:163], v[184:187], v[56:59]
	v_mfma_f32_16x16x32_bf16 v[56:59], v[156:159], v[180:183], v[56:59]
	v_mfma_f32_16x16x32_bf16 v[64:67], v[156:159], v[194:197], v[64:67]
	v_mfma_f32_16x16x32_bf16 v[64:67], v[160:163], v[198:201], v[64:67]
	s_setprio 2
	s_barrier
	v_mfma_f32_16x16x32_bf16 v[60:63], v[152:155], v[198:201], v[60:63]
	v_mfma_f32_16x16x32_bf16 v[60:63], v[148:151], v[194:197], v[60:63]
	s_setprio 0
	s_add_i32 s29, s29, s38
	s_mov_b32 m0, s29
	ds_read_b128 v[164:167], v210 offset:16384
	ds_read_b128 v[168:171], v210 offset:17408
	ds_read_b128 v[172:175], v210 offset:18432
	ds_read_b128 v[176:179], v210 offset:19456
	ds_read_b128 v[180:183], v210 offset:20480
	ds_read_b128 v[184:187], v210 offset:21504
	ds_read_b128 v[194:197], v210 offset:22528
	ds_read_b128 v[198:201], v210 offset:23552
	global_load_lds_dwordx4 v192, s[12:13]
	s_add_i32 m0, s29, 0x2000
	s_add_u32 s40, s12, 0x100000
	s_addc_u32 s41, s13, 0
	s_add_i32 s29, s51, s38
	global_load_lds_dwordx4 v190, s[12:13]
	s_mov_b32 m0, s29
	v_mov_b32_e32 v193, v3
	global_load_lds_dwordx4 v192, s[40:41]
	s_add_i32 m0, s29, 0x2000
	v_mov_b32_e32 v191, v3
	global_load_lds_dwordx4 v190, s[40:41]
	s_mov_b32 m0, s56
	v_lshl_add_u64 v[202:203], s[12:13], 0, v[192:193]
	global_load_lds_dwordx4 v2, s[16:17]
	s_mov_b32 m0, s57
	v_lshl_add_u64 v[204:205], s[12:13], 0, v[190:191]
	global_load_lds_dwordx4 v188, s[16:17]
	s_waitcnt vmcnt(8)
	s_waitcnt lgkmcnt(0)
	v_lshl_add_u64 v[206:207], s[16:17], 0, v[2:3]
	v_lshl_add_u64 v[208:209], s[16:17], 0, v[188:189]
	s_barrier
	s_setprio 1
	v_mfma_f32_16x16x32_bf16 v[68:71], v[132:135], v[164:167], v[68:71]
	v_mfma_f32_16x16x32_bf16 v[68:71], v[136:139], v[168:171], v[68:71]
	v_mfma_f32_16x16x32_bf16 v[72:75], v[144:147], v[168:171], v[72:75]
	v_mfma_f32_16x16x32_bf16 v[72:75], v[140:143], v[164:167], v[72:75]
	v_mfma_f32_16x16x32_bf16 v[80:83], v[140:143], v[172:175], v[80:83]
	v_mfma_f32_16x16x32_bf16 v[80:83], v[144:147], v[176:179], v[80:83]
	v_mfma_f32_16x16x32_bf16 v[76:79], v[136:139], v[176:179], v[76:79]
	v_mfma_f32_16x16x32_bf16 v[76:79], v[132:135], v[172:175], v[76:79]
	v_mfma_f32_16x16x32_bf16 v[84:87], v[132:135], v[180:183], v[84:87]
	v_mfma_f32_16x16x32_bf16 v[84:87], v[136:139], v[184:187], v[84:87]
	v_mfma_f32_16x16x32_bf16 v[88:91], v[144:147], v[184:187], v[88:91]
	v_mfma_f32_16x16x32_bf16 v[88:91], v[140:143], v[180:183], v[88:91]
	v_mfma_f32_16x16x32_bf16 v[96:99], v[140:143], v[194:197], v[96:99]
	v_mfma_f32_16x16x32_bf16 v[96:99], v[144:147], v[198:201], v[96:99]
	v_mfma_f32_16x16x32_bf16 v[92:95], v[136:139], v[198:201], v[92:95]
	v_mfma_f32_16x16x32_bf16 v[92:95], v[132:135], v[194:197], v[92:95]
	v_mfma_f32_16x16x32_bf16 v[100:103], v[148:151], v[164:167], v[100:103]
	v_mfma_f32_16x16x32_bf16 v[100:103], v[152:155], v[168:171], v[100:103]
	v_mfma_f32_16x16x32_bf16 v[104:107], v[160:163], v[168:171], v[104:107]
	v_mfma_f32_16x16x32_bf16 v[104:107], v[156:159], v[164:167], v[104:107]
	v_mfma_f32_16x16x32_bf16 v[112:115], v[156:159], v[172:175], v[112:115]
	v_mfma_f32_16x16x32_bf16 v[112:115], v[160:163], v[176:179], v[112:115]
	v_mfma_f32_16x16x32_bf16 v[108:111], v[152:155], v[176:179], v[108:111]
	v_mfma_f32_16x16x32_bf16 v[108:111], v[148:151], v[172:175], v[108:111]
	v_mfma_f32_16x16x32_bf16 v[116:119], v[148:151], v[180:183], v[116:119]
	v_mfma_f32_16x16x32_bf16 v[116:119], v[152:155], v[184:187], v[116:119]
	v_mfma_f32_16x16x32_bf16 v[120:123], v[160:163], v[184:187], v[120:123]
	v_mfma_f32_16x16x32_bf16 v[120:123], v[156:159], v[180:183], v[120:123]
	v_mfma_f32_16x16x32_bf16 v[128:131], v[156:159], v[194:197], v[128:131]
	v_mfma_f32_16x16x32_bf16 v[128:131], v[160:163], v[198:201], v[128:131]
	s_setprio 2
	s_barrier
	v_mfma_f32_16x16x32_bf16 v[124:127], v[152:155], v[198:201], v[124:127]
	v_mfma_f32_16x16x32_bf16 v[124:127], v[148:151], v[194:197], v[124:127]
	s_setprio 0
	s_add_i32 s29, 0, 0x18000
	s_add_i32 s40, 0, 0x1c000
	v_add_u32_e32 v144, s29, v232
	v_add_u32_e32 v160, s40, v232
	ds_read_b128 v[132:135], v144
	ds_read_b128 v[136:139], v144 offset:1024
	ds_read_b128 v[140:143], v144 offset:2048
	ds_read_b128 v[144:147], v144 offset:3072
	ds_read_b128 v[148:151], v160
	ds_read_b128 v[152:155], v160 offset:1024
	ds_read_b128 v[156:159], v160 offset:2048
	ds_read_b128 v[160:163], v160 offset:3072
	s_add_u32 s16, s16, 0x40000
	s_addc_u32 s17, s17, 0
	s_mov_b32 m0, s58
	ds_read_b128 v[164:167], v210 offset:32768
	ds_read_b128 v[168:171], v210 offset:33792
	ds_read_b128 v[172:175], v210 offset:34816
	ds_read_b128 v[176:179], v210 offset:35840
	ds_read_b128 v[180:183], v210 offset:36864
	ds_read_b128 v[184:187], v210 offset:37888
	ds_read_b128 v[194:197], v210 offset:38912
	ds_read_b128 v[198:201], v210 offset:39936
	global_load_lds_dwordx4 v2, s[16:17]
	s_mov_b32 m0, s59
	s_nop 0
	global_load_lds_dwordx4 v188, s[16:17]
	s_waitcnt vmcnt(8)
	s_waitcnt lgkmcnt(0)
	s_barrier
	s_setprio 1
	v_mfma_f32_16x16x32_bf16 v[4:7], v[132:135], v[164:167], v[4:7]
	v_mfma_f32_16x16x32_bf16 v[4:7], v[136:139], v[168:171], v[4:7]
	v_mfma_f32_16x16x32_bf16 v[8:11], v[144:147], v[168:171], v[8:11]
	v_mfma_f32_16x16x32_bf16 v[8:11], v[140:143], v[164:167], v[8:11]
	v_mfma_f32_16x16x32_bf16 v[16:19], v[140:143], v[172:175], v[16:19]
	v_mfma_f32_16x16x32_bf16 v[16:19], v[144:147], v[176:179], v[16:19]
	v_mfma_f32_16x16x32_bf16 v[12:15], v[136:139], v[176:179], v[12:15]
	v_mfma_f32_16x16x32_bf16 v[12:15], v[132:135], v[172:175], v[12:15]
	v_mfma_f32_16x16x32_bf16 v[20:23], v[132:135], v[180:183], v[20:23]
	v_mfma_f32_16x16x32_bf16 v[20:23], v[136:139], v[184:187], v[20:23]
	v_mfma_f32_16x16x32_bf16 v[24:27], v[144:147], v[184:187], v[24:27]
	v_mfma_f32_16x16x32_bf16 v[24:27], v[140:143], v[180:183], v[24:27]
	v_mfma_f32_16x16x32_bf16 v[32:35], v[140:143], v[194:197], v[32:35]
	v_mfma_f32_16x16x32_bf16 v[32:35], v[144:147], v[198:201], v[32:35]
	v_mfma_f32_16x16x32_bf16 v[28:31], v[136:139], v[198:201], v[28:31]
	v_mfma_f32_16x16x32_bf16 v[28:31], v[132:135], v[194:197], v[28:31]
	v_mfma_f32_16x16x32_bf16 v[36:39], v[148:151], v[164:167], v[36:39]
	v_mfma_f32_16x16x32_bf16 v[36:39], v[152:155], v[168:171], v[36:39]
	v_mfma_f32_16x16x32_bf16 v[40:43], v[160:163], v[168:171], v[40:43]
	v_mfma_f32_16x16x32_bf16 v[40:43], v[156:159], v[164:167], v[40:43]
	v_mfma_f32_16x16x32_bf16 v[48:51], v[156:159], v[172:175], v[48:51]
	v_mfma_f32_16x16x32_bf16 v[48:51], v[160:163], v[176:179], v[48:51]
	v_mfma_f32_16x16x32_bf16 v[44:47], v[152:155], v[176:179], v[44:47]
	v_mfma_f32_16x16x32_bf16 v[44:47], v[148:151], v[172:175], v[44:47]
	v_mfma_f32_16x16x32_bf16 v[52:55], v[148:151], v[180:183], v[52:55]
	v_mfma_f32_16x16x32_bf16 v[52:55], v[152:155], v[184:187], v[52:55]
	v_mfma_f32_16x16x32_bf16 v[56:59], v[160:163], v[184:187], v[56:59]
	v_mfma_f32_16x16x32_bf16 v[56:59], v[156:159], v[180:183], v[56:59]
	v_mfma_f32_16x16x32_bf16 v[64:67], v[156:159], v[194:197], v[64:67]
	v_mfma_f32_16x16x32_bf16 v[64:67], v[160:163], v[198:201], v[64:67]
	s_setprio 2
	s_barrier
	v_mfma_f32_16x16x32_bf16 v[60:63], v[152:155], v[198:201], v[60:63]
	v_mfma_f32_16x16x32_bf16 v[60:63], v[148:151], v[194:197], v[60:63]
	s_setprio 0
	s_add_i32 s16, s29, s38
	v_lshl_add_u64 v[202:203], v[202:203], 0, s[86:87]
	s_mov_b32 m0, s16
	ds_read_b128 v[164:167], v210 offset:49152
	ds_read_b128 v[168:171], v210 offset:50176
	ds_read_b128 v[172:175], v210 offset:51200
	ds_read_b128 v[176:179], v210 offset:52224
	ds_read_b128 v[180:183], v210 offset:53248
	ds_read_b128 v[184:187], v210 offset:54272
	ds_read_b128 v[194:197], v210 offset:55296
	ds_read_b128 v[198:201], v210 offset:56320
	global_load_lds_dwordx4 v[202:203], off
	s_add_i32 m0, s16, 0x2000
	s_add_u32 s12, s12, 0x100080
	v_lshl_add_u64 v[202:203], v[204:205], 0, s[86:87]
	s_addc_u32 s13, s13, 0
	s_add_i32 s16, s40, s38
	global_load_lds_dwordx4 v[202:203], off
	s_mov_b32 m0, s16
	v_lshl_add_u64 v[202:203], v[206:207], 0, s[86:87]
	global_load_lds_dwordx4 v192, s[12:13]
	s_add_i32 m0, s16, 0x2000
	s_nop 0
	global_load_lds_dwordx4 v190, s[12:13]
	s_mov_b32 m0, s63
	s_nop 0
	global_load_lds_dwordx4 v[202:203], off
	v_lshl_add_u64 v[202:203], v[208:209], 0, s[86:87]
	s_mov_b32 m0, s64
	s_nop 0
	global_load_lds_dwordx4 v[202:203], off
	s_waitcnt vmcnt(8)
	s_waitcnt lgkmcnt(0)
	s_barrier
	s_setprio 1
	v_mfma_f32_16x16x32_bf16 v[68:71], v[132:135], v[164:167], v[68:71]
	v_mfma_f32_16x16x32_bf16 v[68:71], v[136:139], v[168:171], v[68:71]
	v_mfma_f32_16x16x32_bf16 v[72:75], v[144:147], v[168:171], v[72:75]
	v_mfma_f32_16x16x32_bf16 v[72:75], v[140:143], v[164:167], v[72:75]
	v_mfma_f32_16x16x32_bf16 v[80:83], v[140:143], v[172:175], v[80:83]
	v_mfma_f32_16x16x32_bf16 v[80:83], v[144:147], v[176:179], v[80:83]
	v_mfma_f32_16x16x32_bf16 v[76:79], v[136:139], v[176:179], v[76:79]
	v_mfma_f32_16x16x32_bf16 v[76:79], v[132:135], v[172:175], v[76:79]
	v_mfma_f32_16x16x32_bf16 v[84:87], v[132:135], v[180:183], v[84:87]
	v_mfma_f32_16x16x32_bf16 v[84:87], v[136:139], v[184:187], v[84:87]
	v_mfma_f32_16x16x32_bf16 v[88:91], v[144:147], v[184:187], v[88:91]
	v_mfma_f32_16x16x32_bf16 v[88:91], v[140:143], v[180:183], v[88:91]
	v_mfma_f32_16x16x32_bf16 v[96:99], v[140:143], v[194:197], v[96:99]
	v_mfma_f32_16x16x32_bf16 v[96:99], v[144:147], v[198:201], v[96:99]
	v_mfma_f32_16x16x32_bf16 v[92:95], v[136:139], v[198:201], v[92:95]
	v_mfma_f32_16x16x32_bf16 v[92:95], v[132:135], v[194:197], v[92:95]
	v_mfma_f32_16x16x32_bf16 v[100:103], v[148:151], v[164:167], v[100:103]
	v_mfma_f32_16x16x32_bf16 v[100:103], v[152:155], v[168:171], v[100:103]
	v_mfma_f32_16x16x32_bf16 v[104:107], v[160:163], v[168:171], v[104:107]
	v_mfma_f32_16x16x32_bf16 v[104:107], v[156:159], v[164:167], v[104:107]
	v_mfma_f32_16x16x32_bf16 v[112:115], v[156:159], v[172:175], v[112:115]
	v_mfma_f32_16x16x32_bf16 v[112:115], v[160:163], v[176:179], v[112:115]
	v_mfma_f32_16x16x32_bf16 v[108:111], v[152:155], v[176:179], v[108:111]
	v_mfma_f32_16x16x32_bf16 v[108:111], v[148:151], v[172:175], v[108:111]
	v_mfma_f32_16x16x32_bf16 v[116:119], v[148:151], v[180:183], v[116:119]
	v_mfma_f32_16x16x32_bf16 v[116:119], v[152:155], v[184:187], v[116:119]
	v_mfma_f32_16x16x32_bf16 v[120:123], v[160:163], v[184:187], v[120:123]
	v_mfma_f32_16x16x32_bf16 v[120:123], v[156:159], v[180:183], v[120:123]
	v_mfma_f32_16x16x32_bf16 v[128:131], v[156:159], v[194:197], v[128:131]
	v_mfma_f32_16x16x32_bf16 v[128:131], v[160:163], v[198:201], v[128:131]
	s_setprio 2
	s_barrier
	v_mfma_f32_16x16x32_bf16 v[124:127], v[152:155], v[198:201], v[124:127]
	v_mfma_f32_16x16x32_bf16 v[124:127], v[148:151], v[194:197], v[124:127]
	s_setprio 0
	s_add_i32 s28, s28, 2
	s_add_u32 s14, s14, 0x100
	s_addc_u32 s15, s15, 0
	s_add_u32 s26, s26, 0x100
	s_addc_u32 s27, s27, 0
	s_cmp_gt_u32 s28, 13
	s_cbranch_scc0 .LBB0_2273
	s_and_b64 vcc, exec, s[48:49]
	s_cbranch_vccz .LBB0_2276
	s_barrier
